# v20 + younger half runs next-unit header before its re-stagger barrier + older half's alignment barrier moved into the epilogue (P1A,P1B,P4,P5,P6), run 1
# baseline (speedup 1.0000x reference)
; #define PG8_STAGE(bufoff, gbase, voff) do { _Pragma("unroll") for (int _i = 0; _i < 2; ++_i) \
;         __builtin_amdgcn_global_load_lds((const unsigned*)((const char*)(gbase) + (voff)[_i]), (LAS unsigned*)(lds + (bufoff) + ldsw + _i * 8192), 16, 0, 0); } while (0)
; #define PG8_WAIT_V(n) asm volatile("s_waitcnt vmcnt(" #n ")" ::: "memory")
; #define PG8_BAR __builtin_amdgcn_s_barrier()
; template <class Epi, bool ALIGN_EPI, bool SPLITA>
; __device__ __forceinline__ void gemm_phase(LAS unsigned char* lds, const Gemm g, const StaticOrder& S, const Epi& E) {
;     ...
;     const unsigned ldsw = (unsigned)wid * 1024u;
;     const int aoff = lds_byte(wr * 64 + fr, fq * 8), boff = lds_byte(wc * 32 + fr, fq * 8);
;     ...
;     Unit cur, nxt; int ui = 0;
;     if (!S.next(0, cur)) return;
;     Acc acc;
; #pragma unroll
;     for (int a = 0; a < 2; ++a)
; #pragma unroll
;         for (int b = 0; b < 2; ++b)
; #pragma unroll
;             for (int m = 0; m < 4; ++m)
; #pragma unroll
;                 for (int n = 0; n < 2; ++n) acc[a][b][m][n] = (f32x4){0.f, 0.f, 0.f, 0.f};
;     bf16x8 At[4][2], B0[2][2], B1[2][2];
;     const char* cA = baseA1(cur); const char* cB = baseB(cur);
;     const char* cA2 = SPLITA ? (const char*)g.A2 + (size_t)cur.pm * tstepA : cA;
;     bool mirC = mirrored(cur);
;     { const unsigned vo[2] = {mirC ? voffAm[0] : voffA[0], mirC ? voffAm[1] : voffA[1]}; const char* cAh = mirC ? cA - hstepA : cA + hstepA;
;       PG8_STAGE(PG8_SB(0, 0), cB, voffB); PG8_STAGE(PG8_SB(0, 1), cB + hstepB, voffB); PG8_STAGE(PG8_SA(0, 0), cA, vo); PG8_STAGE(PG8_SA(0, 1), cAh, vo);
;       if (wr == 1) PG8_BAR;
;       PG8_WAIT_V(2); PG8_BAR;
;       PG8_STAGE(PG8_SB(1, 0), cB + kstepB, voffB); PG8_STAGE(PG8_SA(1, 0), cA + kofs(1), vo); PG8_STAGE(PG8_SB(1, 1), cB + hstepB + kstepB, voffB); }
;     PG8_WAIT_V(6); PG8_BAR;
.LBB0_223:
	s_and_b32 s92, s8, 3
	s_mov_b64 s[8:9], 0x80
	s_add_i32 m0, s87, 0x18000
	v_lshl_add_u64 v[8:9], v[8:9], 0, s[8:9]
	s_lshl_b32 s93, s7, 6
	s_lshl_b32 s0, s7, 13
	s_lshl_b32 s1, s92, 5
	s_lshl_b32 s11, s92, 12
	s_waitcnt vmcnt(2)
	s_barrier
	global_load_lds_dwordx4 v[8:9], off
	v_lshl_add_u64 v[6:7], v[6:7], 0, s[8:9]
	s_add_i32 m0, s87, 0x1a000
	s_add_i32 s94, s87, 0x8000
	s_add_i32 s95, s87, 0xa000
	global_load_lds_dwordx4 v[6:7], off
	v_lshl_add_u64 v[2:3], v[2:3], 0, s[8:9]
	s_mov_b32 m0, s94
	s_add_u32 s26, s44, 0x40080
	global_load_lds_dwordx4 v[2:3], off
	v_lshl_add_u64 v[2:3], v[4:5], 0, s[8:9]
	s_mov_b32 m0, s95
	s_addc_u32 s27, s45, 0
	global_load_lds_dwordx4 v[2:3], off
	s_add_i32 m0, s87, 0x1c000
	v_lshl_add_u64 v[2:3], s[26:27], 0, v[168:169]
	global_load_lds_dwordx4 v[2:3], off
	v_lshl_add_u64 v[2:3], s[26:27], 0, v[164:165]
	s_add_i32 m0, s87, 0x1e000
	v_and_b32_e32 v1, 15, v12
	global_load_lds_dwordx4 v[2:3], off
	v_lshrrev_b32_e32 v2, 1, v12
	v_and_b32_e32 v174, 24, v2
	v_lshlrev_b32_e32 v2, 1, v174
	v_lshlrev_b32_e32 v3, 2, v12
	v_lshl_or_b32 v2, v1, 6, v2
	v_and_b32_e32 v3, 32, v3
	v_lshlrev_b32_e32 v172, 2, v174
	v_bitop3_b32 v4, v2, s0, v3 bitop3:0xde
	v_bitop3_b32 v163, v2, s11, v3 bitop3:0xde
	v_lshl_add_u64 v[178:179], s[2:3], 0, v[172:173]
	v_lshl_add_u64 v[2:3], s[62:63], 0, v[172:173]
	s_mov_b64 s[2:3], 0x1e340000
	v_lshl_add_u64 v[180:181], v[2:3], 0, s[2:3]
	v_lshlrev_b32_e32 v2, 14, v15
	v_and_b32_e32 v2, 0xffff8000, v2
	v_lshl_add_u32 v2, v14, 11, v2
	v_and_b32_e32 v3, 1, v15
	s_or_b32 s96, s1, 0xfffffa00
	v_lshl_or_b32 v2, v3, 6, v2
	s_cmpk_lt_u32 s6, 0x100
	v_lshl_add_u32 v182, v16, 1, v2
	v_lshlrev_b32_e32 v2, 14, v10
	s_sext_i32_i16 s7, s12
	s_cselect_b64 s[12:13], -1, 0
	s_add_i32 s0, 0, 0x22000
	v_and_b32_e32 v2, 0xffff8000, v2
	s_waitcnt vmcnt(6)
	v_add_u32_e32 v175, s0, v172
	s_add_i32 s0, 0, 0x22200
	v_lshl_add_u32 v2, v11, 11, v2
	v_and_b32_e32 v3, 1, v10
	v_add_u32_e32 v177, s0, v172
	s_add_i32 s0, 0, 0x22280
	v_lshl_or_b32 v2, v3, 6, v2
	s_add_i32 s97, 0, 0x10000
	s_add_i32 s64, 0, 0x14000
	s_mov_b32 s11, 0
	v_lshlrev_b32_e32 v176, 5, v1
	v_add_u32_e32 v190, s0, v172
	v_mov_b32_e32 v183, v173
	v_lshl_add_u32 v184, v13, 1, v2
	v_mov_b32_e32 v185, v173
	v_mov_b64_e32 v[186:187], 0xf00
	v_mov_b64_e32 v[188:189], 0xeff
	v_add_u32_e32 v191, s97, v163
	v_add_u32_e32 v192, s64, v163
	v_add_u32_e32 v193, 0, v4
	v_mov_b32_e32 v194, 0x3b808081
	s_movk_i32 s65, 0x1000
	v_mov_b32_e32 v195, 0x358637bd
	v_mov_b32_e32 v196, 0x3e38aa3b
	s_mov_b32 s6, 0
	s_barrier
	s_mov_b32 s99, 0
	s_branch .LBB0_226

; #define PG8_WAIT_V(n) asm volatile("s_waitcnt vmcnt(" #n ")" ::: "memory")
; #define PG8_BAR __builtin_amdgcn_s_barrier()
; template <class Epi, bool ALIGN_EPI, bool SPLITA>
; __device__ __forceinline__ void gemm_phase(LAS unsigned char* lds, const Gemm g, const StaticOrder& S, const Epi& E) {
;     ...
;         const bool has_next = S.next(ui + 1, nxt);
;         const char* nA = has_next ? baseA1(nxt) : cA;
;         const char* nB = has_next ? baseB(nxt) : cB;
;         const bool mirN = has_next ? mirrored(nxt) : mirC;
;         for (int t = 0; t < nt; t += 2) {
;             const bool last = (t == nt - 2);
;             if constexpr (Epi::MIDK) { if (t == g.ksplit) E.mid(acc, cur, wr, wc, fr, fq); }
;             const char *a1, *a2;
;             if constexpr (SPLITA) {
;                 a1 = (t + 1 < g.ksplit) ? cA + (size_t)(t + 1) * kstep : cA2 + (size_t)(t + 1 - g.ksplit) * 2048;
;                 a2 = last ? nA : ((t + 2 < g.ksplit) ? cA + (size_t)(t + 2) * kstep : cA2 + (size_t)(t + 2 - g.ksplit) * 2048);
;             } else { a1 = cA + kofs(t + 1); a2 = last ? nA : cA + kofs(t + 2); }
;             const char* b2 = last ? nB : cB + (size_t)(t + 2) * kstepB;
;             const bool s2a = SPLITA && (t + 1 >= g.ksplit), s2b = SPLITA && !last && (t + 2 >= g.ksplit);
;             const char* a3 = a2 + ((Epi::KSUB || s2b) ? (size_t)2048 : kstep); const char* b3 = b2 + kstepB;
;             const bool m1 = SPLITA && mirC && (t + 1 < g.ksplit), m2 = SPLITA && (last ? mirN : (mirC && (t + 2 < g.ksplit)));
;             const unsigned vo1[2] = {s2a ? voffA2[0] : m1 ? voffAm[0] : voffA[0], s2a ? voffA2[1] : m1 ? voffAm[1] : voffA[1]}, vo2[2] = {s2b ? voffA2[0] : m2 ? voffAm[0] : voffA[0], s2b ? voffA2[1] : m2 ? voffAm[1] : voffA[1]};
;             const char* a1h = m1 ? a1 - hstepA : a1 + hstepA; const char* a2h = m2 ? a2 - hstepA : a2 + hstepA;
;             PG8_LDB(B0, 0, 0); PG8_LDB(B1, 0, 1); PG8_SCHED; PG8_LDA(At, 0, 0); PG8_STAGE(PG8_SA(1, 1), a1h, vo1);
;             PG8_WAIT_V(8); PG8_WAIT_L(0); PG8_BAR; PG8_MMA(0, 0, At, B0); PG8_MMA(0, 1, At, B1); PG8_BAR; PG8_SCHED;
;             PG8_LDA(At, 0, 1); PG8_STAGE(PG8_SB(0, 0), b2, voffB); PG8_STAGE(PG8_SB(0, 1), b2 + hstepB, voffB); PG8_STAGE(PG8_SA(0, 0), a2, vo2);
;             PG8_WAIT_V(8); PG8_WAIT_L(0); PG8_BAR; PG8_MMA(1, 0, At, B0); PG8_MMA(1, 1, At, B1); PG8_BAR; PG8_SCHED;
.LBB0_228:
	s_ashr_i32 s27, s26, 31
	s_lshl_b64 s[38:39], s[26:27], 19
	s_add_u32 s38, s34, s38
	s_addc_u32 s39, s35, s39
	s_and_b64 s[40:41], s[2:3], exec
	s_cselect_b32 s27, s39, s43
	s_cselect_b32 s33, s38, s42
	s_ashr_i32 s29, s28, 31
	s_lshl_b64 s[40:41], s[28:29], 19
	s_add_u32 s40, s72, s40
	s_addc_u32 s41, s73, s41
	s_and_b64 s[46:47], s[2:3], exec
	s_cselect_b32 s29, s41, s45
	s_cselect_b32 s60, s40, s44
	s_add_u32 s42, s42, 0x40080
	s_addc_u32 s43, s43, 0
	s_add_u32 s61, s44, 0x100
	s_addc_u32 vcc_lo, s45, 0
	s_mov_b32 vcc_hi, -2
	s_cmp_lg_u32 s99, 0
	s_cbranch_scc0 .Lyd_p1a
	s_barrier
	s_mov_b32 s99, 0
.Lyd_p1a:
	ds_read_b128 v[130:133], v191
	ds_read_b128 v[134:137], v191 offset:1024
	ds_read_b128 v[138:141], v191 offset:2048
	ds_read_b128 v[142:145], v191 offset:3072
	ds_read_b128 v[146:149], v192
	ds_read_b128 v[150:153], v192 offset:1024
	ds_read_b128 v[154:157], v192 offset:2048
	ds_read_b128 v[158:161], v192 offset:3072
	s_add_u32 s0, s42, 0xfffc0080
	s_addc_u32 s1, s43, -1
	s_cmp_eq_u32 vcc_hi, 12
	s_cselect_b32 s47, s27, s1
	s_cselect_b32 s46, s33, s0
	s_cselect_b32 s45, s29, vcc_lo
	s_cselect_b32 s44, s60, s61
	s_add_i32 m0, s87, 0xc000
	ds_read_b128 v[198:201], v193
	ds_read_b128 v[202:205], v193 offset:1024
	ds_read_b128 v[206:209], v193 offset:2048
	ds_read_b128 v[210:213], v193 offset:3072
	ds_read_b128 v[214:217], v193 offset:4096
	ds_read_b128 v[218:221], v193 offset:5120
	ds_read_b128 v[222:225], v193 offset:6144
	ds_read_b128 v[226:229], v193 offset:7168
	global_load_lds_dwordx4 v182, s[42:43]
	s_add_i32 m0, s87, 0xe000
	s_nop 0
	global_load_lds_dwordx4 v184, s[42:43]
	s_waitcnt vmcnt(8)
	s_waitcnt lgkmcnt(0)
	s_barrier
	s_setprio 1
	s_waitcnt lgkmcnt(0)
	v_mfma_f32_16x16x32_bf16 v[126:129], v[130:133], v[198:201], 0
	v_mfma_f32_16x16x32_bf16 v[122:125], v[138:141], v[198:201], 0
	v_mfma_f32_16x16x32_bf16 v[110:113], v[130:133], v[206:209], 0
	v_mfma_f32_16x16x32_bf16 v[106:109], v[138:141], v[206:209], 0
	v_mfma_f32_16x16x32_bf16 v[94:97], v[130:133], v[214:217], 0
	v_mfma_f32_16x16x32_bf16 v[90:93], v[138:141], v[214:217], 0
	v_mfma_f32_16x16x32_bf16 v[78:81], v[130:133], v[222:225], 0
	v_mfma_f32_16x16x32_bf16 v[74:77], v[138:141], v[222:225], 0
	v_mfma_f32_16x16x32_bf16 v[126:129], v[134:137], v[202:205], v[126:129]
	v_mfma_f32_16x16x32_bf16 v[122:125], v[142:145], v[202:205], v[122:125]
	v_mfma_f32_16x16x32_bf16 v[110:113], v[134:137], v[210:213], v[110:113]
	v_mfma_f32_16x16x32_bf16 v[106:109], v[142:145], v[210:213], v[106:109]
	v_mfma_f32_16x16x32_bf16 v[94:97], v[134:137], v[218:221], v[94:97]
	v_mfma_f32_16x16x32_bf16 v[90:93], v[142:145], v[218:221], v[90:93]
	v_mfma_f32_16x16x32_bf16 v[78:81], v[134:137], v[226:229], v[78:81]
	v_mfma_f32_16x16x32_bf16 v[74:77], v[142:145], v[226:229], v[74:77]
	s_setprio 0
	s_setprio 1
	v_mfma_f32_16x16x32_bf16 v[118:121], v[146:149], v[198:201], 0
	v_mfma_f32_16x16x32_bf16 v[114:117], v[154:157], v[198:201], 0
	v_mfma_f32_16x16x32_bf16 v[102:105], v[146:149], v[206:209], 0
	v_mfma_f32_16x16x32_bf16 v[98:101], v[154:157], v[206:209], 0
	v_mfma_f32_16x16x32_bf16 v[86:89], v[146:149], v[214:217], 0
	v_mfma_f32_16x16x32_bf16 v[82:85], v[154:157], v[214:217], 0
	v_mfma_f32_16x16x32_bf16 v[70:73], v[146:149], v[222:225], 0
	v_mfma_f32_16x16x32_bf16 v[66:69], v[154:157], v[222:225], 0
	v_mfma_f32_16x16x32_bf16 v[118:121], v[150:153], v[202:205], v[118:121]
	v_mfma_f32_16x16x32_bf16 v[114:117], v[158:161], v[202:205], v[114:117]
	v_mfma_f32_16x16x32_bf16 v[102:105], v[150:153], v[210:213], v[102:105]
	v_mfma_f32_16x16x32_bf16 v[98:101], v[158:161], v[210:213], v[98:101]
	v_mfma_f32_16x16x32_bf16 v[86:89], v[150:153], v[218:221], v[86:89]
	v_mfma_f32_16x16x32_bf16 v[82:85], v[158:161], v[218:221], v[82:85]
	v_mfma_f32_16x16x32_bf16 v[70:73], v[150:153], v[226:229], v[70:73]
	v_mfma_f32_16x16x32_bf16 v[66:69], v[158:161], v[226:229], v[66:69]
	s_setprio 0
	s_barrier
	s_add_u32 s98, s44, s8
	s_addc_u32 s99, s45, s9
	s_add_u32 s100, s46, s8
	s_addc_u32 s101, s47, s9
	s_add_i32 s0, s97, s80
	s_mov_b32 m0, s0
	ds_read_b128 v[198:201], v193 offset:16384
	ds_read_b128 v[202:205], v193 offset:17408
	ds_read_b128 v[206:209], v193 offset:18432
	ds_read_b128 v[210:213], v193 offset:19456
	ds_read_b128 v[214:217], v193 offset:20480
	ds_read_b128 v[218:221], v193 offset:21504
	ds_read_b128 v[222:225], v193 offset:22528
	ds_read_b128 v[226:229], v193 offset:23552
	global_load_lds_dwordx4 v168, s[44:45]
	s_add_i32 m0, s0, 0x2000
	s_add_u32 s0, s44, 0x40000
	s_addc_u32 s1, s45, 0
	s_add_i32 s78, s64, s80
	global_load_lds_dwordx4 v164, s[44:45]
	s_mov_b32 m0, s78
	s_nop 0
	global_load_lds_dwordx4 v168, s[0:1]
	s_add_i32 m0, s78, 0x2000
	s_nop 0
	global_load_lds_dwordx4 v164, s[0:1]
	s_mov_b32 m0, s87
	s_nop 0
	global_load_lds_dwordx4 v170, s[46:47]
	s_mov_b32 m0, s88
	s_nop 0
	global_load_lds_dwordx4 v166, s[46:47]
	s_waitcnt vmcnt(8)
	s_waitcnt lgkmcnt(0)
	s_barrier
; #define PG8_STAGE(bufoff, gbase, voff) do { _Pragma("unroll") for (int _i = 0; _i < 2; ++_i) \
;         __builtin_amdgcn_global_load_lds((const unsigned*)((const char*)(gbase) + (voff)[_i]), (LAS unsigned*)(lds + (bufoff) + ldsw + _i * 8192), 16, 0, 0); } while (0)
; #define PG8_LDA(dst, b, h) do { _Pragma("unroll") for (int m = 0; m < 4; ++m) _Pragma("unroll") for (int k = 0; k < 2; ++k) dst[m][k] = *(const LAS bf16x8*)(lds + PG8_SA(b, h) + aoff + m * 2048 + k * 1024); } while (0)
; #define PG8_LDB(dst, b, h) do { _Pragma("unroll") for (int n = 0; n < 2; ++n) _Pragma("unroll") for (int k = 0; k < 2; ++k) dst[n][k] = *(const LAS bf16x8*)(lds + PG8_SB(b, h) + boff + n * 2048 + k * 1024); } while (0)
; #define PG8_MMA(ai, bj, At, Bt) do { __builtin_amdgcn_s_setprio(1); _Pragma("unroll") for (int m = 0; m < 4; ++m) _Pragma("unroll") for (int n = 0; n < 2; ++n) _Pragma("unroll") for (int k = 0; k < 2; ++k) \
;         acc[ai][bj][m][n] = __builtin_amdgcn_mfma_f32_16x16x32_bf16(Bt[n][k], At[m][k], acc[ai][bj][m][n], 0, 0, 0); __builtin_amdgcn_s_setprio(0); } while (0)
; #define PG8_WAIT_V(n) asm volatile("s_waitcnt vmcnt(" #n ")" ::: "memory")
; #define PG8_WAIT_L(n) asm volatile("s_waitcnt lgkmcnt(" #n ")" ::: "memory")
; #define PG8_BAR __builtin_amdgcn_s_barrier()
; #define PG8_SCHED __builtin_amdgcn_sched_barrier(0)
; template <class Epi, bool ALIGN_EPI, bool SPLITA>
; __device__ __forceinline__ void gemm_phase(LAS unsigned char* lds, const Gemm g, const StaticOrder& S, const Epi& E) {
;     ...
;             PG8_WAIT_V(8); PG8_WAIT_L(0); PG8_BAR; PG8_MMA(1, 0, At, B0); PG8_MMA(1, 1, At, B1); PG8_BAR; PG8_SCHED;
;             PG8_LDB(B0, 1, 0); PG8_LDB(B1, 1, 1); PG8_SCHED; PG8_LDA(At, 1, 0); PG8_STAGE(PG8_SA(0, 1), a2h, vo2);
;             PG8_WAIT_V(8); PG8_WAIT_L(0); PG8_BAR; PG8_MMA(0, 0, At, B0); PG8_MMA(0, 1, At, B1); PG8_BAR; PG8_SCHED;
	s_setprio 1
	s_waitcnt lgkmcnt(0)
	v_mfma_f32_16x16x32_bf16 v[62:65], v[130:133], v[198:201], 0
	v_mfma_f32_16x16x32_bf16 v[58:61], v[138:141], v[198:201], 0
	v_mfma_f32_16x16x32_bf16 v[38:41], v[130:133], v[206:209], 0
	v_mfma_f32_16x16x32_bf16 v[34:37], v[138:141], v[206:209], 0
	v_mfma_f32_16x16x32_bf16 v[22:25], v[130:133], v[214:217], 0
	v_mfma_f32_16x16x32_bf16 v[18:21], v[138:141], v[214:217], 0
	v_mfma_f32_16x16x32_bf16 v[6:9], v[130:133], v[222:225], 0
	v_mfma_f32_16x16x32_bf16 v[2:5], v[138:141], v[222:225], 0
	v_mfma_f32_16x16x32_bf16 v[62:65], v[134:137], v[202:205], v[62:65]
	v_mfma_f32_16x16x32_bf16 v[58:61], v[142:145], v[202:205], v[58:61]
	v_mfma_f32_16x16x32_bf16 v[38:41], v[134:137], v[210:213], v[38:41]
	v_mfma_f32_16x16x32_bf16 v[34:37], v[142:145], v[210:213], v[34:37]
	v_mfma_f32_16x16x32_bf16 v[22:25], v[134:137], v[218:221], v[22:25]
	v_mfma_f32_16x16x32_bf16 v[18:21], v[142:145], v[218:221], v[18:21]
	v_mfma_f32_16x16x32_bf16 v[6:9], v[134:137], v[226:229], v[6:9]
	v_mfma_f32_16x16x32_bf16 v[2:5], v[142:145], v[226:229], v[2:5]
	s_setprio 0
	s_setprio 1
	v_mfma_f32_16x16x32_bf16 v[54:57], v[146:149], v[198:201], 0
	v_mfma_f32_16x16x32_bf16 v[50:53], v[154:157], v[198:201], 0
	v_mfma_f32_16x16x32_bf16 v[42:45], v[146:149], v[206:209], 0
	v_mfma_f32_16x16x32_bf16 v[46:49], v[154:157], v[206:209], 0
	v_mfma_f32_16x16x32_bf16 v[26:29], v[146:149], v[214:217], 0
	v_mfma_f32_16x16x32_bf16 v[30:33], v[154:157], v[214:217], 0
	v_mfma_f32_16x16x32_bf16 v[10:13], v[146:149], v[222:225], 0
	v_mfma_f32_16x16x32_bf16 v[14:17], v[154:157], v[222:225], 0
	v_mfma_f32_16x16x32_bf16 v[54:57], v[150:153], v[202:205], v[54:57]
	v_mfma_f32_16x16x32_bf16 v[50:53], v[158:161], v[202:205], v[50:53]
	v_mfma_f32_16x16x32_bf16 v[42:45], v[150:153], v[210:213], v[42:45]
	v_mfma_f32_16x16x32_bf16 v[46:49], v[158:161], v[210:213], v[46:49]
	v_mfma_f32_16x16x32_bf16 v[26:29], v[150:153], v[218:221], v[26:29]
	v_mfma_f32_16x16x32_bf16 v[30:33], v[158:161], v[218:221], v[30:33]
	v_mfma_f32_16x16x32_bf16 v[10:13], v[150:153], v[226:229], v[10:13]
	v_mfma_f32_16x16x32_bf16 v[14:17], v[158:161], v[226:229], v[14:17]
	s_setprio 0
	s_barrier
	s_add_i32 s78, 0, 0x18000
	s_add_i32 s89, 0, 0x1c000
	v_add_u32_e32 v142, s78, v163
	v_add_u32_e32 v158, s89, v163
	ds_read_b128 v[130:133], v142
	ds_read_b128 v[134:137], v142 offset:1024
	ds_read_b128 v[138:141], v142 offset:2048
	ds_read_b128 v[142:145], v142 offset:3072
	ds_read_b128 v[146:149], v158
	ds_read_b128 v[150:153], v158 offset:1024
	ds_read_b128 v[154:157], v158 offset:2048
	ds_read_b128 v[158:161], v158 offset:3072
	s_add_u32 s0, s46, 0x40000
	s_addc_u32 s1, s47, 0
	s_mov_b32 m0, s90
	ds_read_b128 v[198:201], v193 offset:32768
	ds_read_b128 v[202:205], v193 offset:33792
	ds_read_b128 v[206:209], v193 offset:34816
	ds_read_b128 v[210:213], v193 offset:35840
	ds_read_b128 v[214:217], v193 offset:36864
	ds_read_b128 v[218:221], v193 offset:37888
	ds_read_b128 v[222:225], v193 offset:38912
	ds_read_b128 v[226:229], v193 offset:39936
	global_load_lds_dwordx4 v170, s[0:1]
	s_mov_b32 m0, s91
	s_nop 0
	global_load_lds_dwordx4 v166, s[0:1]
	s_waitcnt vmcnt(8)
	s_waitcnt lgkmcnt(0)
	s_barrier
	s_setprio 1
	s_waitcnt lgkmcnt(0)
	v_mfma_f32_16x16x32_bf16 v[126:129], v[130:133], v[198:201], v[126:129]
	v_mfma_f32_16x16x32_bf16 v[122:125], v[138:141], v[198:201], v[122:125]
	v_mfma_f32_16x16x32_bf16 v[110:113], v[130:133], v[206:209], v[110:113]
	v_mfma_f32_16x16x32_bf16 v[106:109], v[138:141], v[206:209], v[106:109]
	v_mfma_f32_16x16x32_bf16 v[94:97], v[130:133], v[214:217], v[94:97]
	v_mfma_f32_16x16x32_bf16 v[90:93], v[138:141], v[214:217], v[90:93]
	v_mfma_f32_16x16x32_bf16 v[78:81], v[130:133], v[222:225], v[78:81]
	v_mfma_f32_16x16x32_bf16 v[74:77], v[138:141], v[222:225], v[74:77]
	v_mfma_f32_16x16x32_bf16 v[126:129], v[134:137], v[202:205], v[126:129]
	v_mfma_f32_16x16x32_bf16 v[122:125], v[142:145], v[202:205], v[122:125]
	v_mfma_f32_16x16x32_bf16 v[110:113], v[134:137], v[210:213], v[110:113]
	v_mfma_f32_16x16x32_bf16 v[106:109], v[142:145], v[210:213], v[106:109]
	v_mfma_f32_16x16x32_bf16 v[94:97], v[134:137], v[218:221], v[94:97]
	v_mfma_f32_16x16x32_bf16 v[90:93], v[142:145], v[218:221], v[90:93]
	v_mfma_f32_16x16x32_bf16 v[78:81], v[134:137], v[226:229], v[78:81]
	v_mfma_f32_16x16x32_bf16 v[74:77], v[142:145], v[226:229], v[74:77]
	s_setprio 0
	s_setprio 1
	v_mfma_f32_16x16x32_bf16 v[118:121], v[146:149], v[198:201], v[118:121]
	v_mfma_f32_16x16x32_bf16 v[114:117], v[154:157], v[198:201], v[114:117]
	v_mfma_f32_16x16x32_bf16 v[102:105], v[146:149], v[206:209], v[102:105]
	v_mfma_f32_16x16x32_bf16 v[98:101], v[154:157], v[206:209], v[98:101]
	v_mfma_f32_16x16x32_bf16 v[86:89], v[146:149], v[214:217], v[86:89]
	v_mfma_f32_16x16x32_bf16 v[82:85], v[154:157], v[214:217], v[82:85]
	v_mfma_f32_16x16x32_bf16 v[70:73], v[146:149], v[222:225], v[70:73]
	v_mfma_f32_16x16x32_bf16 v[66:69], v[154:157], v[222:225], v[66:69]
	v_mfma_f32_16x16x32_bf16 v[118:121], v[150:153], v[202:205], v[118:121]
	v_mfma_f32_16x16x32_bf16 v[114:117], v[158:161], v[202:205], v[114:117]
	v_mfma_f32_16x16x32_bf16 v[102:105], v[150:153], v[210:213], v[102:105]
	v_mfma_f32_16x16x32_bf16 v[98:101], v[158:161], v[210:213], v[98:101]
	v_mfma_f32_16x16x32_bf16 v[86:89], v[150:153], v[218:221], v[86:89]
	v_mfma_f32_16x16x32_bf16 v[82:85], v[158:161], v[218:221], v[82:85]
	v_mfma_f32_16x16x32_bf16 v[70:73], v[150:153], v[226:229], v[70:73]
	v_mfma_f32_16x16x32_bf16 v[66:69], v[158:161], v[226:229], v[66:69]
	s_setprio 0
	s_barrier
; #define PG8_STAGE(bufoff, gbase, voff) do { _Pragma("unroll") for (int _i = 0; _i < 2; ++_i) \
;         __builtin_amdgcn_global_load_lds((const unsigned*)((const char*)(gbase) + (voff)[_i]), (LAS unsigned*)(lds + (bufoff) + ldsw + _i * 8192), 16, 0, 0); } while (0)
; #define PG8_LDA(dst, b, h) do { _Pragma("unroll") for (int m = 0; m < 4; ++m) _Pragma("unroll") for (int k = 0; k < 2; ++k) dst[m][k] = *(const LAS bf16x8*)(lds + PG8_SA(b, h) + aoff + m * 2048 + k * 1024); } while (0)
; #define PG8_LDB(dst, b, h) do { _Pragma("unroll") for (int n = 0; n < 2; ++n) _Pragma("unroll") for (int k = 0; k < 2; ++k) dst[n][k] = *(const LAS bf16x8*)(lds + PG8_SB(b, h) + boff + n * 2048 + k * 1024); } while (0)
; #define PG8_MMA(ai, bj, At, Bt) do { __builtin_amdgcn_s_setprio(1); _Pragma("unroll") for (int m = 0; m < 4; ++m) _Pragma("unroll") for (int n = 0; n < 2; ++n) _Pragma("unroll") for (int k = 0; k < 2; ++k) \
;         acc[ai][bj][m][n] = __builtin_amdgcn_mfma_f32_16x16x32_bf16(Bt[n][k], At[m][k], acc[ai][bj][m][n], 0, 0, 0); __builtin_amdgcn_s_setprio(0); } while (0)
; #define PG8_WAIT_V(n) asm volatile("s_waitcnt vmcnt(" #n ")" ::: "memory")
; #define PG8_WAIT_L(n) asm volatile("s_waitcnt lgkmcnt(" #n ")" ::: "memory")
; #define PG8_BAR __builtin_amdgcn_s_barrier()
; #define PG8_SCHED __builtin_amdgcn_sched_barrier(0)
; template <class Epi, bool ALIGN_EPI, bool SPLITA>
; __device__ __forceinline__ void gemm_phase(LAS unsigned char* lds, const Gemm g, const StaticOrder& S, const Epi& E) {
;     ...
;             PG8_LDB(B0, 0, 0); PG8_LDB(B1, 0, 1); PG8_SCHED; PG8_LDA(At, 0, 0); PG8_STAGE(PG8_SA(1, 1), a1h, vo1);
;             PG8_WAIT_V(8); PG8_WAIT_L(0); PG8_BAR; PG8_MMA(0, 0, At, B0); PG8_MMA(0, 1, At, B1); PG8_BAR; PG8_SCHED;
;     ...
;             PG8_LDA(At, 1, 1); PG8_STAGE(PG8_SB(1, 0), b3, voffB); PG8_STAGE(PG8_SB(1, 1), b3 + hstepB, voffB); PG8_STAGE(PG8_SA(1, 0), a3, vo2);
;             PG8_WAIT_V(8); PG8_WAIT_L(0); PG8_BAR; PG8_MMA(1, 0, At, B0); PG8_MMA(1, 1, At, B1); PG8_BAR; PG8_SCHED;
	s_add_i32 s0, s78, s80
	s_mov_b32 m0, s0
	ds_read_b128 v[198:201], v193 offset:49152
	ds_read_b128 v[202:205], v193 offset:50176
	ds_read_b128 v[206:209], v193 offset:51200
	ds_read_b128 v[210:213], v193 offset:52224
	ds_read_b128 v[214:217], v193 offset:53248
	ds_read_b128 v[218:221], v193 offset:54272
	ds_read_b128 v[222:225], v193 offset:55296
	ds_read_b128 v[226:229], v193 offset:56320
	global_load_lds_dwordx4 v168, s[98:99]
	s_add_i32 m0, s0, 0x2000
	s_add_u32 s0, s44, 0x40080
	s_addc_u32 s1, s45, 0
	s_add_i32 s44, s89, s80
	global_load_lds_dwordx4 v164, s[98:99]
	s_mov_b32 m0, s44
	s_nop 0
	global_load_lds_dwordx4 v168, s[0:1]
	s_add_i32 m0, s44, 0x2000
	s_nop 0
	global_load_lds_dwordx4 v164, s[0:1]
	s_mov_b32 m0, s94
	s_nop 0
	global_load_lds_dwordx4 v170, s[100:101]
	s_mov_b32 m0, s95
	s_nop 0
	global_load_lds_dwordx4 v166, s[100:101]
	s_waitcnt vmcnt(8)
	s_waitcnt lgkmcnt(0)
	s_barrier
	s_setprio 1
	s_waitcnt lgkmcnt(0)
	v_mfma_f32_16x16x32_bf16 v[62:65], v[130:133], v[198:201], v[62:65]
	v_mfma_f32_16x16x32_bf16 v[58:61], v[138:141], v[198:201], v[58:61]
	v_mfma_f32_16x16x32_bf16 v[38:41], v[130:133], v[206:209], v[38:41]
	v_mfma_f32_16x16x32_bf16 v[34:37], v[138:141], v[206:209], v[34:37]
	v_mfma_f32_16x16x32_bf16 v[22:25], v[130:133], v[214:217], v[22:25]
	v_mfma_f32_16x16x32_bf16 v[18:21], v[138:141], v[214:217], v[18:21]
	v_mfma_f32_16x16x32_bf16 v[6:9], v[130:133], v[222:225], v[6:9]
	v_mfma_f32_16x16x32_bf16 v[2:5], v[138:141], v[222:225], v[2:5]
	v_mfma_f32_16x16x32_bf16 v[62:65], v[134:137], v[202:205], v[62:65]
	v_mfma_f32_16x16x32_bf16 v[58:61], v[142:145], v[202:205], v[58:61]
	v_mfma_f32_16x16x32_bf16 v[38:41], v[134:137], v[210:213], v[38:41]
	v_mfma_f32_16x16x32_bf16 v[34:37], v[142:145], v[210:213], v[34:37]
	v_mfma_f32_16x16x32_bf16 v[22:25], v[134:137], v[218:221], v[22:25]
	v_mfma_f32_16x16x32_bf16 v[18:21], v[142:145], v[218:221], v[18:21]
	v_mfma_f32_16x16x32_bf16 v[6:9], v[134:137], v[226:229], v[6:9]
	v_mfma_f32_16x16x32_bf16 v[2:5], v[142:145], v[226:229], v[2:5]
	s_setprio 0
	s_setprio 1
	v_mfma_f32_16x16x32_bf16 v[54:57], v[146:149], v[198:201], v[54:57]
	v_mfma_f32_16x16x32_bf16 v[50:53], v[154:157], v[198:201], v[50:53]
	v_mfma_f32_16x16x32_bf16 v[42:45], v[146:149], v[206:209], v[42:45]
	v_mfma_f32_16x16x32_bf16 v[46:49], v[154:157], v[206:209], v[46:49]
	v_mfma_f32_16x16x32_bf16 v[26:29], v[146:149], v[214:217], v[26:29]
	v_mfma_f32_16x16x32_bf16 v[30:33], v[154:157], v[214:217], v[30:33]
	v_mfma_f32_16x16x32_bf16 v[10:13], v[146:149], v[222:225], v[10:13]
	v_mfma_f32_16x16x32_bf16 v[14:17], v[154:157], v[222:225], v[14:17]
	v_mfma_f32_16x16x32_bf16 v[54:57], v[150:153], v[202:205], v[54:57]
	v_mfma_f32_16x16x32_bf16 v[50:53], v[158:161], v[202:205], v[50:53]
	v_mfma_f32_16x16x32_bf16 v[42:45], v[150:153], v[210:213], v[42:45]
	v_mfma_f32_16x16x32_bf16 v[46:49], v[158:161], v[210:213], v[46:49]
	v_mfma_f32_16x16x32_bf16 v[26:29], v[150:153], v[218:221], v[26:29]
	v_mfma_f32_16x16x32_bf16 v[30:33], v[158:161], v[218:221], v[30:33]
	v_mfma_f32_16x16x32_bf16 v[10:13], v[150:153], v[226:229], v[10:13]
	v_mfma_f32_16x16x32_bf16 v[14:17], v[158:161], v[226:229], v[14:17]
	s_setprio 0
	s_barrier
	s_add_i32 vcc_hi, vcc_hi, 2
	s_add_u32 s42, s42, 0x100
	s_addc_u32 s43, s43, 0
	s_add_u32 s61, s61, 0x100
	s_addc_u32 vcc_lo, vcc_lo, 0
.LBB0_229:
	ds_read_b128 v[130:133], v191
	ds_read_b128 v[134:137], v191 offset:1024
	ds_read_b128 v[138:141], v191 offset:2048
	ds_read_b128 v[142:145], v191 offset:3072
	ds_read_b128 v[146:149], v192
	ds_read_b128 v[150:153], v192 offset:1024
	ds_read_b128 v[154:157], v192 offset:2048
	ds_read_b128 v[158:161], v192 offset:3072
	s_add_u32 s0, s42, 0xfffc0080
	s_addc_u32 s1, s43, -1
	s_cmp_eq_u32 vcc_hi, 12
	s_cselect_b32 s47, s27, s1
	s_cselect_b32 s46, s33, s0
	s_cselect_b32 s45, s29, vcc_lo
	s_cselect_b32 s44, s60, s61
	s_add_i32 m0, s87, 0xc000
	ds_read_b128 v[198:201], v193
	ds_read_b128 v[202:205], v193 offset:1024
	ds_read_b128 v[206:209], v193 offset:2048
	ds_read_b128 v[210:213], v193 offset:3072
	ds_read_b128 v[214:217], v193 offset:4096
	ds_read_b128 v[218:221], v193 offset:5120
	ds_read_b128 v[222:225], v193 offset:6144
	ds_read_b128 v[226:229], v193 offset:7168
	global_load_lds_dwordx4 v182, s[42:43]
	s_add_i32 m0, s87, 0xe000
	s_nop 0
	global_load_lds_dwordx4 v184, s[42:43]
	s_waitcnt vmcnt(8)
	s_waitcnt lgkmcnt(0)
	s_barrier
	s_setprio 1
	s_waitcnt lgkmcnt(0)
	v_mfma_f32_16x16x32_bf16 v[126:129], v[130:133], v[198:201], v[126:129]
	v_mfma_f32_16x16x32_bf16 v[122:125], v[138:141], v[198:201], v[122:125]
	v_mfma_f32_16x16x32_bf16 v[110:113], v[130:133], v[206:209], v[110:113]
	v_mfma_f32_16x16x32_bf16 v[106:109], v[138:141], v[206:209], v[106:109]
	v_mfma_f32_16x16x32_bf16 v[94:97], v[130:133], v[214:217], v[94:97]
	v_mfma_f32_16x16x32_bf16 v[90:93], v[138:141], v[214:217], v[90:93]
	v_mfma_f32_16x16x32_bf16 v[78:81], v[130:133], v[222:225], v[78:81]
	v_mfma_f32_16x16x32_bf16 v[74:77], v[138:141], v[222:225], v[74:77]
	v_mfma_f32_16x16x32_bf16 v[126:129], v[134:137], v[202:205], v[126:129]
	v_mfma_f32_16x16x32_bf16 v[122:125], v[142:145], v[202:205], v[122:125]
	v_mfma_f32_16x16x32_bf16 v[110:113], v[134:137], v[210:213], v[110:113]
	v_mfma_f32_16x16x32_bf16 v[106:109], v[142:145], v[210:213], v[106:109]
	v_mfma_f32_16x16x32_bf16 v[94:97], v[134:137], v[218:221], v[94:97]
	v_mfma_f32_16x16x32_bf16 v[90:93], v[142:145], v[218:221], v[90:93]
	v_mfma_f32_16x16x32_bf16 v[78:81], v[134:137], v[226:229], v[78:81]
	v_mfma_f32_16x16x32_bf16 v[74:77], v[142:145], v[226:229], v[74:77]
	s_setprio 0
	s_setprio 1
	v_mfma_f32_16x16x32_bf16 v[118:121], v[146:149], v[198:201], v[118:121]
	v_mfma_f32_16x16x32_bf16 v[114:117], v[154:157], v[198:201], v[114:117]
	v_mfma_f32_16x16x32_bf16 v[102:105], v[146:149], v[206:209], v[102:105]
	v_mfma_f32_16x16x32_bf16 v[98:101], v[154:157], v[206:209], v[98:101]
	v_mfma_f32_16x16x32_bf16 v[86:89], v[146:149], v[214:217], v[86:89]
	v_mfma_f32_16x16x32_bf16 v[82:85], v[154:157], v[214:217], v[82:85]
	v_mfma_f32_16x16x32_bf16 v[70:73], v[146:149], v[222:225], v[70:73]
	v_mfma_f32_16x16x32_bf16 v[66:69], v[154:157], v[222:225], v[66:69]
	v_mfma_f32_16x16x32_bf16 v[118:121], v[150:153], v[202:205], v[118:121]
	v_mfma_f32_16x16x32_bf16 v[114:117], v[158:161], v[202:205], v[114:117]
	v_mfma_f32_16x16x32_bf16 v[102:105], v[150:153], v[210:213], v[102:105]
	v_mfma_f32_16x16x32_bf16 v[98:101], v[158:161], v[210:213], v[98:101]
	v_mfma_f32_16x16x32_bf16 v[86:89], v[150:153], v[218:221], v[86:89]
	v_mfma_f32_16x16x32_bf16 v[82:85], v[158:161], v[218:221], v[82:85]
	v_mfma_f32_16x16x32_bf16 v[70:73], v[150:153], v[226:229], v[70:73]
	v_mfma_f32_16x16x32_bf16 v[66:69], v[158:161], v[226:229], v[66:69]
	s_setprio 0
	s_barrier
; #define PG8_STAGE(bufoff, gbase, voff) do { _Pragma("unroll") for (int _i = 0; _i < 2; ++_i) \
;         __builtin_amdgcn_global_load_lds((const unsigned*)((const char*)(gbase) + (voff)[_i]), (LAS unsigned*)(lds + (bufoff) + ldsw + _i * 8192), 16, 0, 0); } while (0)
; #define PG8_LDA(dst, b, h) do { _Pragma("unroll") for (int m = 0; m < 4; ++m) _Pragma("unroll") for (int k = 0; k < 2; ++k) dst[m][k] = *(const LAS bf16x8*)(lds + PG8_SA(b, h) + aoff + m * 2048 + k * 1024); } while (0)
; #define PG8_LDB(dst, b, h) do { _Pragma("unroll") for (int n = 0; n < 2; ++n) _Pragma("unroll") for (int k = 0; k < 2; ++k) dst[n][k] = *(const LAS bf16x8*)(lds + PG8_SB(b, h) + boff + n * 2048 + k * 1024); } while (0)
; #define PG8_MMA(ai, bj, At, Bt) do { __builtin_amdgcn_s_setprio(1); _Pragma("unroll") for (int m = 0; m < 4; ++m) _Pragma("unroll") for (int n = 0; n < 2; ++n) _Pragma("unroll") for (int k = 0; k < 2; ++k) \
;         acc[ai][bj][m][n] = __builtin_amdgcn_mfma_f32_16x16x32_bf16(Bt[n][k], At[m][k], acc[ai][bj][m][n], 0, 0, 0); __builtin_amdgcn_s_setprio(0); } while (0)
; #define PG8_WAIT_V(n) asm volatile("s_waitcnt vmcnt(" #n ")" ::: "memory")
; #define PG8_WAIT_L(n) asm volatile("s_waitcnt lgkmcnt(" #n ")" ::: "memory")
; #define PG8_BAR __builtin_amdgcn_s_barrier()
; #define PG8_SCHED __builtin_amdgcn_sched_barrier(0)
; template <class Epi, bool ALIGN_EPI, bool SPLITA>
; __device__ __forceinline__ void gemm_phase(LAS unsigned char* lds, const Gemm g, const StaticOrder& S, const Epi& E) {
;     ...
;             PG8_LDA(At, 0, 1); PG8_STAGE(PG8_SB(0, 0), b2, voffB); PG8_STAGE(PG8_SB(0, 1), b2 + hstepB, voffB); PG8_STAGE(PG8_SA(0, 0), a2, vo2);
;             PG8_WAIT_V(8); PG8_WAIT_L(0); PG8_BAR; PG8_MMA(1, 0, At, B0); PG8_MMA(1, 1, At, B1); PG8_BAR; PG8_SCHED;
;             PG8_LDB(B0, 1, 0); PG8_LDB(B1, 1, 1); PG8_SCHED; PG8_LDA(At, 1, 0); PG8_STAGE(PG8_SA(0, 1), a2h, vo2);
;             PG8_WAIT_V(8); PG8_WAIT_L(0); PG8_BAR; PG8_MMA(0, 0, At, B0); PG8_MMA(0, 1, At, B1); PG8_BAR; PG8_SCHED;
	s_add_u32 s98, s44, s8
	s_addc_u32 s99, s45, s9
	s_add_u32 s100, s46, s8
	s_addc_u32 s101, s47, s9
	s_add_i32 s0, s97, s80
	s_mov_b32 m0, s0
	ds_read_b128 v[198:201], v193 offset:16384
	ds_read_b128 v[202:205], v193 offset:17408
	ds_read_b128 v[206:209], v193 offset:18432
	ds_read_b128 v[210:213], v193 offset:19456
	ds_read_b128 v[214:217], v193 offset:20480
	ds_read_b128 v[218:221], v193 offset:21504
	ds_read_b128 v[222:225], v193 offset:22528
	ds_read_b128 v[226:229], v193 offset:23552
	global_load_lds_dwordx4 v168, s[44:45]
	s_add_i32 m0, s0, 0x2000
	s_add_u32 s0, s44, 0x40000
	s_addc_u32 s1, s45, 0
	s_add_i32 s78, s64, s80
	global_load_lds_dwordx4 v164, s[44:45]
	s_mov_b32 m0, s78
	s_nop 0
	global_load_lds_dwordx4 v168, s[0:1]
	s_add_i32 m0, s78, 0x2000
	s_nop 0
	global_load_lds_dwordx4 v164, s[0:1]
	s_mov_b32 m0, s87
	s_nop 0
	global_load_lds_dwordx4 v170, s[46:47]
	s_mov_b32 m0, s88
	s_nop 0
	global_load_lds_dwordx4 v166, s[46:47]
	s_waitcnt vmcnt(8)
	s_waitcnt lgkmcnt(0)
	s_barrier
	s_setprio 1
	s_waitcnt lgkmcnt(0)
	v_mfma_f32_16x16x32_bf16 v[62:65], v[130:133], v[198:201], v[62:65]
	v_mfma_f32_16x16x32_bf16 v[58:61], v[138:141], v[198:201], v[58:61]
	v_mfma_f32_16x16x32_bf16 v[38:41], v[130:133], v[206:209], v[38:41]
	v_mfma_f32_16x16x32_bf16 v[34:37], v[138:141], v[206:209], v[34:37]
	v_mfma_f32_16x16x32_bf16 v[22:25], v[130:133], v[214:217], v[22:25]
	v_mfma_f32_16x16x32_bf16 v[18:21], v[138:141], v[214:217], v[18:21]
	v_mfma_f32_16x16x32_bf16 v[6:9], v[130:133], v[222:225], v[6:9]
	v_mfma_f32_16x16x32_bf16 v[2:5], v[138:141], v[222:225], v[2:5]
	v_mfma_f32_16x16x32_bf16 v[62:65], v[134:137], v[202:205], v[62:65]
	v_mfma_f32_16x16x32_bf16 v[58:61], v[142:145], v[202:205], v[58:61]
	v_mfma_f32_16x16x32_bf16 v[38:41], v[134:137], v[210:213], v[38:41]
	v_mfma_f32_16x16x32_bf16 v[34:37], v[142:145], v[210:213], v[34:37]
	v_mfma_f32_16x16x32_bf16 v[22:25], v[134:137], v[218:221], v[22:25]
	v_mfma_f32_16x16x32_bf16 v[18:21], v[142:145], v[218:221], v[18:21]
	v_mfma_f32_16x16x32_bf16 v[6:9], v[134:137], v[226:229], v[6:9]
	v_mfma_f32_16x16x32_bf16 v[2:5], v[142:145], v[226:229], v[2:5]
	s_setprio 0
	s_setprio 1
	v_mfma_f32_16x16x32_bf16 v[54:57], v[146:149], v[198:201], v[54:57]
	v_mfma_f32_16x16x32_bf16 v[50:53], v[154:157], v[198:201], v[50:53]
	v_mfma_f32_16x16x32_bf16 v[42:45], v[146:149], v[206:209], v[42:45]
	v_mfma_f32_16x16x32_bf16 v[46:49], v[154:157], v[206:209], v[46:49]
	v_mfma_f32_16x16x32_bf16 v[26:29], v[146:149], v[214:217], v[26:29]
	v_mfma_f32_16x16x32_bf16 v[30:33], v[154:157], v[214:217], v[30:33]
	v_mfma_f32_16x16x32_bf16 v[10:13], v[146:149], v[222:225], v[10:13]
	v_mfma_f32_16x16x32_bf16 v[14:17], v[154:157], v[222:225], v[14:17]
	v_mfma_f32_16x16x32_bf16 v[54:57], v[150:153], v[202:205], v[54:57]
	v_mfma_f32_16x16x32_bf16 v[50:53], v[158:161], v[202:205], v[50:53]
	v_mfma_f32_16x16x32_bf16 v[42:45], v[150:153], v[210:213], v[42:45]
	v_mfma_f32_16x16x32_bf16 v[46:49], v[158:161], v[210:213], v[46:49]
	v_mfma_f32_16x16x32_bf16 v[26:29], v[150:153], v[218:221], v[26:29]
	v_mfma_f32_16x16x32_bf16 v[30:33], v[158:161], v[218:221], v[30:33]
	v_mfma_f32_16x16x32_bf16 v[10:13], v[150:153], v[226:229], v[10:13]
	v_mfma_f32_16x16x32_bf16 v[14:17], v[158:161], v[226:229], v[14:17]
	s_setprio 0
	s_barrier
	s_add_i32 s78, 0, 0x18000
	s_add_i32 s89, 0, 0x1c000
	v_add_u32_e32 v142, s78, v163
	v_add_u32_e32 v158, s89, v163
	ds_read_b128 v[130:133], v142
	ds_read_b128 v[134:137], v142 offset:1024
	ds_read_b128 v[138:141], v142 offset:2048
	ds_read_b128 v[142:145], v142 offset:3072
	ds_read_b128 v[146:149], v158
	ds_read_b128 v[150:153], v158 offset:1024
	ds_read_b128 v[154:157], v158 offset:2048
	ds_read_b128 v[158:161], v158 offset:3072
	s_add_u32 s0, s46, 0x40000
	s_addc_u32 s1, s47, 0
	s_mov_b32 m0, s90
	ds_read_b128 v[198:201], v193 offset:32768
	ds_read_b128 v[202:205], v193 offset:33792
	ds_read_b128 v[206:209], v193 offset:34816
	ds_read_b128 v[210:213], v193 offset:35840
	ds_read_b128 v[214:217], v193 offset:36864
	ds_read_b128 v[218:221], v193 offset:37888
	ds_read_b128 v[222:225], v193 offset:38912
	ds_read_b128 v[226:229], v193 offset:39936
	global_load_lds_dwordx4 v170, s[0:1]
	s_mov_b32 m0, s91
	s_nop 0
	global_load_lds_dwordx4 v166, s[0:1]
	s_waitcnt vmcnt(8)
	s_waitcnt lgkmcnt(0)
	s_barrier
; #define PG8_STAGE(bufoff, gbase, voff) do { _Pragma("unroll") for (int _i = 0; _i < 2; ++_i) \
;         __builtin_amdgcn_global_load_lds((const unsigned*)((const char*)(gbase) + (voff)[_i]), (LAS unsigned*)(lds + (bufoff) + ldsw + _i * 8192), 16, 0, 0); } while (0)
; #define PG8_LDA(dst, b, h) do { _Pragma("unroll") for (int m = 0; m < 4; ++m) _Pragma("unroll") for (int k = 0; k < 2; ++k) dst[m][k] = *(const LAS bf16x8*)(lds + PG8_SA(b, h) + aoff + m * 2048 + k * 1024); } while (0)
; #define PG8_MMA(ai, bj, At, Bt) do { __builtin_amdgcn_s_setprio(1); _Pragma("unroll") for (int m = 0; m < 4; ++m) _Pragma("unroll") for (int n = 0; n < 2; ++n) _Pragma("unroll") for (int k = 0; k < 2; ++k) \
;         acc[ai][bj][m][n] = __builtin_amdgcn_mfma_f32_16x16x32_bf16(Bt[n][k], At[m][k], acc[ai][bj][m][n], 0, 0, 0); __builtin_amdgcn_s_setprio(0); } while (0)
; #define PG8_WAIT_V(n) asm volatile("s_waitcnt vmcnt(" #n ")" ::: "memory")
; #define PG8_WAIT_L(n) asm volatile("s_waitcnt lgkmcnt(" #n ")" ::: "memory")
; #define PG8_BAR __builtin_amdgcn_s_barrier()
; #define PG8_SCHED __builtin_amdgcn_sched_barrier(0)
; template <class Epi, bool ALIGN_EPI, bool SPLITA>
; __device__ __forceinline__ void gemm_phase(LAS unsigned char* lds, const Gemm g, const StaticOrder& S, const Epi& E) {
;     ...
;             PG8_WAIT_V(8); PG8_WAIT_L(0); PG8_BAR; PG8_MMA(0, 0, At, B0); PG8_MMA(0, 1, At, B1); PG8_BAR; PG8_SCHED;
;             PG8_LDA(At, 1, 1); PG8_STAGE(PG8_SB(1, 0), b3, voffB); PG8_STAGE(PG8_SB(1, 1), b3 + hstepB, voffB); PG8_STAGE(PG8_SA(1, 0), a3, vo2);
;             PG8_WAIT_V(8); PG8_WAIT_L(0); PG8_BAR; PG8_MMA(1, 0, At, B0); PG8_MMA(1, 1, At, B1); PG8_BAR; PG8_SCHED;
;         }
;         if constexpr (ALIGN_EPI) { if (wr == 0) PG8_BAR; }
;         E(acc, cur, wr, wc, fr, fq);
;     __device__ __forceinline__ void operator()(const Acc& acc, const Unit& u, int wr, int wc, int fr, int fq) const {
;         const int row0 = u.pm * BM + wr * 64 + fr; const int pn = u.pn;
;         if (pn < 8) {
	s_setprio 1
	s_waitcnt lgkmcnt(0)
	v_mfma_f32_16x16x32_bf16 v[126:129], v[130:133], v[198:201], v[126:129]
	v_mfma_f32_16x16x32_bf16 v[122:125], v[138:141], v[198:201], v[122:125]
	v_mfma_f32_16x16x32_bf16 v[110:113], v[130:133], v[206:209], v[110:113]
	v_mfma_f32_16x16x32_bf16 v[106:109], v[138:141], v[206:209], v[106:109]
	v_mfma_f32_16x16x32_bf16 v[94:97], v[130:133], v[214:217], v[94:97]
	v_mfma_f32_16x16x32_bf16 v[90:93], v[138:141], v[214:217], v[90:93]
	v_mfma_f32_16x16x32_bf16 v[78:81], v[130:133], v[222:225], v[78:81]
	v_mfma_f32_16x16x32_bf16 v[74:77], v[138:141], v[222:225], v[74:77]
	v_mfma_f32_16x16x32_bf16 v[126:129], v[134:137], v[202:205], v[126:129]
	v_mfma_f32_16x16x32_bf16 v[122:125], v[142:145], v[202:205], v[122:125]
	v_mfma_f32_16x16x32_bf16 v[110:113], v[134:137], v[210:213], v[110:113]
	v_mfma_f32_16x16x32_bf16 v[106:109], v[142:145], v[210:213], v[106:109]
	v_mfma_f32_16x16x32_bf16 v[94:97], v[134:137], v[218:221], v[94:97]
	v_mfma_f32_16x16x32_bf16 v[90:93], v[142:145], v[218:221], v[90:93]
	v_mfma_f32_16x16x32_bf16 v[78:81], v[134:137], v[226:229], v[78:81]
	v_mfma_f32_16x16x32_bf16 v[74:77], v[142:145], v[226:229], v[74:77]
	s_setprio 0
	s_setprio 1
	v_mfma_f32_16x16x32_bf16 v[118:121], v[146:149], v[198:201], v[118:121]
	v_mfma_f32_16x16x32_bf16 v[114:117], v[154:157], v[198:201], v[114:117]
	v_mfma_f32_16x16x32_bf16 v[102:105], v[146:149], v[206:209], v[102:105]
	v_mfma_f32_16x16x32_bf16 v[98:101], v[154:157], v[206:209], v[98:101]
	v_mfma_f32_16x16x32_bf16 v[86:89], v[146:149], v[214:217], v[86:89]
	v_mfma_f32_16x16x32_bf16 v[82:85], v[154:157], v[214:217], v[82:85]
	v_mfma_f32_16x16x32_bf16 v[70:73], v[146:149], v[222:225], v[70:73]
	v_mfma_f32_16x16x32_bf16 v[66:69], v[154:157], v[222:225], v[66:69]
	v_mfma_f32_16x16x32_bf16 v[118:121], v[150:153], v[202:205], v[118:121]
	v_mfma_f32_16x16x32_bf16 v[114:117], v[158:161], v[202:205], v[114:117]
	v_mfma_f32_16x16x32_bf16 v[102:105], v[150:153], v[210:213], v[102:105]
	v_mfma_f32_16x16x32_bf16 v[98:101], v[158:161], v[210:213], v[98:101]
	v_mfma_f32_16x16x32_bf16 v[86:89], v[150:153], v[218:221], v[86:89]
	v_mfma_f32_16x16x32_bf16 v[82:85], v[158:161], v[218:221], v[82:85]
	v_mfma_f32_16x16x32_bf16 v[70:73], v[150:153], v[226:229], v[70:73]
	v_mfma_f32_16x16x32_bf16 v[66:69], v[158:161], v[226:229], v[66:69]
	s_setprio 0
	s_barrier
	s_add_i32 s0, s78, s80
	s_mov_b32 m0, s0
	ds_read_b128 v[198:201], v193 offset:49152
	ds_read_b128 v[202:205], v193 offset:50176
	ds_read_b128 v[206:209], v193 offset:51200
	ds_read_b128 v[210:213], v193 offset:52224
	ds_read_b128 v[214:217], v193 offset:53248
	ds_read_b128 v[218:221], v193 offset:54272
	ds_read_b128 v[222:225], v193 offset:55296
	ds_read_b128 v[226:229], v193 offset:56320
	global_load_lds_dwordx4 v168, s[98:99]
	s_add_i32 m0, s0, 0x2000
	s_add_u32 s0, s44, 0x40080
	s_addc_u32 s1, s45, 0
	s_add_i32 s44, s89, s80
	global_load_lds_dwordx4 v164, s[98:99]
	s_mov_b32 m0, s44
	s_nop 0
	global_load_lds_dwordx4 v168, s[0:1]
	s_add_i32 m0, s44, 0x2000
	s_nop 0
	global_load_lds_dwordx4 v164, s[0:1]
	s_mov_b32 m0, s94
	s_nop 0
	global_load_lds_dwordx4 v170, s[100:101]
	s_mov_b32 m0, s95
	s_nop 0
	global_load_lds_dwordx4 v166, s[100:101]
	s_waitcnt vmcnt(8)
	s_waitcnt lgkmcnt(0)
	s_barrier
	s_setprio 1
	s_waitcnt lgkmcnt(0)
	v_mfma_f32_16x16x32_bf16 v[62:65], v[130:133], v[198:201], v[62:65]
	v_mfma_f32_16x16x32_bf16 v[58:61], v[138:141], v[198:201], v[58:61]
	v_mfma_f32_16x16x32_bf16 v[38:41], v[130:133], v[206:209], v[38:41]
	v_mfma_f32_16x16x32_bf16 v[34:37], v[138:141], v[206:209], v[34:37]
	v_mfma_f32_16x16x32_bf16 v[22:25], v[130:133], v[214:217], v[22:25]
	v_mfma_f32_16x16x32_bf16 v[18:21], v[138:141], v[214:217], v[18:21]
	v_mfma_f32_16x16x32_bf16 v[6:9], v[130:133], v[222:225], v[6:9]
	v_mfma_f32_16x16x32_bf16 v[2:5], v[138:141], v[222:225], v[2:5]
	v_mfma_f32_16x16x32_bf16 v[62:65], v[134:137], v[202:205], v[62:65]
	v_mfma_f32_16x16x32_bf16 v[58:61], v[142:145], v[202:205], v[58:61]
	v_mfma_f32_16x16x32_bf16 v[38:41], v[134:137], v[210:213], v[38:41]
	v_mfma_f32_16x16x32_bf16 v[34:37], v[142:145], v[210:213], v[34:37]
	v_mfma_f32_16x16x32_bf16 v[22:25], v[134:137], v[218:221], v[22:25]
	v_mfma_f32_16x16x32_bf16 v[18:21], v[142:145], v[218:221], v[18:21]
	v_mfma_f32_16x16x32_bf16 v[6:9], v[134:137], v[226:229], v[6:9]
	v_mfma_f32_16x16x32_bf16 v[2:5], v[142:145], v[226:229], v[2:5]
	s_setprio 0
	s_setprio 1
	v_mfma_f32_16x16x32_bf16 v[54:57], v[146:149], v[198:201], v[54:57]
	v_mfma_f32_16x16x32_bf16 v[50:53], v[154:157], v[198:201], v[50:53]
	v_mfma_f32_16x16x32_bf16 v[42:45], v[146:149], v[206:209], v[42:45]
	v_mfma_f32_16x16x32_bf16 v[46:49], v[154:157], v[206:209], v[46:49]
	v_mfma_f32_16x16x32_bf16 v[26:29], v[146:149], v[214:217], v[26:29]
	v_mfma_f32_16x16x32_bf16 v[30:33], v[154:157], v[214:217], v[30:33]
	v_mfma_f32_16x16x32_bf16 v[10:13], v[146:149], v[222:225], v[10:13]
	v_mfma_f32_16x16x32_bf16 v[14:17], v[154:157], v[222:225], v[14:17]
	v_mfma_f32_16x16x32_bf16 v[54:57], v[150:153], v[202:205], v[54:57]
	v_mfma_f32_16x16x32_bf16 v[50:53], v[158:161], v[202:205], v[50:53]
	v_mfma_f32_16x16x32_bf16 v[42:45], v[150:153], v[210:213], v[42:45]
	v_mfma_f32_16x16x32_bf16 v[46:49], v[158:161], v[210:213], v[46:49]
	v_mfma_f32_16x16x32_bf16 v[26:29], v[150:153], v[218:221], v[26:29]
	v_mfma_f32_16x16x32_bf16 v[30:33], v[158:161], v[218:221], v[30:33]
	v_mfma_f32_16x16x32_bf16 v[10:13], v[150:153], v[226:229], v[10:13]
	v_mfma_f32_16x16x32_bf16 v[14:17], v[158:161], v[226:229], v[14:17]
	s_setprio 0
	s_barrier
	s_add_i32 vcc_hi, vcc_hi, 2
	s_add_u32 s42, s42, 0x100
	s_addc_u32 s43, s43, 0
	s_add_u32 s61, s61, 0x100
	s_addc_u32 vcc_lo, vcc_lo, 0
	s_cmp_gt_u32 vcc_hi, 13
	s_cbranch_scc0 .LBB0_229
.LBB0_232:
	s_lshl_b32 s27, s10, 8
	s_add_i32 s27, s27, s93
	s_cmp_gt_i32 s7, 7
	s_mov_b64 s[42:43], -1
	s_cbranch_scc1 .LBB0_235
	s_andn2_b64 vcc, exec, s[42:43]
	s_cbranch_vccz .LBB0_240

; #define LAS __attribute__((address_space(3)))
;     __device__ __forceinline__ void operator()(const Acc& acc, const Unit& u, int wr, int wc, int fr, int fq) const {
;     ...
;             const int col0 = (pn - 12) * 128 + wc * 32 + 8 * fq;
;             const f32x4 ba0 = *(const LAS f32x4*)(cst + col0), ba1 = *(const LAS f32x4*)(cst + col0 + 4), bb0 = *(const LAS f32x4*)(cst + 1024 + col0), bb1 = *(const LAS f32x4*)(cst + 1024 + col0 + 4);
;             const float NL2E = -1.4426950408889634f;
; #pragma unroll
;             for (int ai = 0; ai < 2; ++ai)
; #pragma unroll
;                 for (int m = 0; m < 4; ++m) {
;                     const int grow = row0 + ai * HALF + m * 16;
;                     const size_t off = ((size_t)(grow >> 4) * 32 + (col0 >> 5)) * 512 + (grow & 15) * 32 + (col0 & 31);
;                     f32x4 z0[2] = {acc[ai][0][m][0] + ba0, acc[ai][0][m][1] + ba1}, z1[2] = {acc[ai][1][m][0] + bb0, acc[ai][1][m][1] + bb1};
;                     u32x4 w = {0u, 0u, 0u, 0u}; const float C255 = 1.0f / 255.0f;
; #pragma unroll
;                     for (int n = 0; n < 2; ++n)
; #pragma unroll
;                         for (int e = 0; e < 4; ++e) {
;                             const float e0 = __builtin_amdgcn_exp2f(fminf(z0[n][e] * NL2E, 40.f)), e1 = __builtin_amdgcn_exp2f(fminf(z1[n][e] * NL2E, 40.f));
;                             const float q0 = fmaxf(__builtin_amdgcn_rcpf(__builtin_fmaf(e0, C255, C255)) + 0.5f, 1.0f), q1 = __builtin_amdgcn_rcpf(__builtin_fmaf(e1, C255, C255)) + 0.5f;
;                             w[n] = __builtin_amdgcn_cvt_pk_u8_f32(q0, (unsigned)e, w[n]); w[2 + n] = __builtin_amdgcn_cvt_pk_u8_f32(q1, (unsigned)e, w[2 + n]); }
;                     __builtin_nontemporal_store(w, (u32x4*)(G0 + off));
.LBB0_235:
	s_cmp_gt_u32 s7, 11
	s_cbranch_scc0 .LBB0_237
	s_lshl_b32 s0, s7, 7
	s_add_i32 s0, s96, s0
	v_or_b32_e32 v130, s0, v174
	v_lshl_add_u32 v130, v130, 2, 0
	v_add_u32_e32 v131, 0x20000, v130
	ds_read_b128 v[142:145], v131
	ds_read_b128 v[138:141], v131 offset:16
	v_add_u32_e32 v130, 0x21000, v130
	ds_read_b128 v[134:137], v130
	ds_read_b128 v[130:133], v130 offset:16
	s_ashr_i32 s44, s27, 4
	s_waitcnt lgkmcnt(0)
	v_pk_add_f32 v[148:149], v[126:127], v[142:143]
	v_pk_add_f32 v[146:147], v[128:129], v[144:145]
	v_mul_f32_e32 v148, 0xbfb8aa3b, v148
	v_min_f32_e32 v148, 0x42200000, v148
	v_mul_f32_e32 v149, 0xbfb8aa3b, v149
	v_exp_f32_e32 v148, v148
	v_min_f32_e32 v149, 0x42200000, v149
	v_mul_f32_e32 v146, 0xbfb8aa3b, v146
	v_exp_f32_e32 v149, v149
	v_min_f32_e32 v146, 0x42200000, v146
	v_exp_f32_e32 v146, v146
	v_pk_add_f32 v[156:157], v[118:119], v[134:135]
	v_fmamk_f32 v148, v148, 0x3b808081, v194
	v_mul_f32_e32 v156, 0xbfb8aa3b, v156
	v_pk_add_f32 v[154:155], v[120:121], v[136:137]
	v_min_f32_e32 v156, 0x42200000, v156
	v_rcp_f32_e32 v148, v148
	v_mul_f32_e32 v157, 0xbfb8aa3b, v157
	v_fmamk_f32 v149, v149, 0x3b808081, v194
	v_exp_f32_e32 v156, v156
	v_min_f32_e32 v157, 0x42200000, v157
	v_rcp_f32_e32 v149, v149
	v_mul_f32_e32 v154, 0xbfb8aa3b, v154
	v_fmamk_f32 v146, v146, 0x3b808081, v194
	v_exp_f32_e32 v157, v157
	v_min_f32_e32 v154, 0x42200000, v154
	v_rcp_f32_e32 v146, v146
	v_mul_f32_e32 v155, 0xbfb8aa3b, v155
	v_exp_f32_e32 v154, v154
	v_min_f32_e32 v155, 0x42200000, v155
	v_add_f32_e32 v148, 0.5, v148
	v_exp_f32_e32 v155, v155
	v_fmamk_f32 v156, v156, 0x3b808081, v194
	v_max_f32_e32 v148, 1.0, v148
	v_add_f32_e32 v149, 0.5, v149
	v_rcp_f32_e32 v156, v156
	v_cvt_pk_u8_f32 v148, v148, 0, 0
	v_fmamk_f32 v157, v157, 0x3b808081, v194
	v_max_f32_e32 v149, 1.0, v149
	v_add_f32_e32 v146, 0.5, v146
	v_mul_f32_e32 v147, 0xbfb8aa3b, v147
	v_rcp_f32_e32 v157, v157
	v_cvt_pk_u8_f32 v148, v149, 1, v148
	v_fmamk_f32 v149, v154, 0x3b808081, v194
	v_max_f32_e32 v146, 1.0, v146
	v_min_f32_e32 v147, 0x42200000, v147
	v_rcp_f32_e32 v149, v149
	v_exp_f32_e32 v147, v147
	v_cvt_pk_u8_f32 v146, v146, 2, v148
	v_fmamk_f32 v148, v155, 0x3b808081, v194
	v_rcp_f32_e32 v148, v148
	v_add_f32_e32 v156, 0.5, v156
	v_cvt_pk_u8_f32 v156, v156, 0, 0
	v_add_f32_e32 v157, 0.5, v157
	v_pk_add_f32 v[150:151], v[122:123], v[138:139]
	v_cvt_pk_u8_f32 v154, v157, 1, v156
	v_add_f32_e32 v149, 0.5, v149
	v_fmamk_f32 v147, v147, 0x3b808081, v194
	v_rcp_f32_e32 v147, v147
	v_cvt_pk_u8_f32 v149, v149, 2, v154
	v_add_f32_e32 v154, 0.5, v148
	v_mul_f32_e32 v148, 0xbfb8aa3b, v150
	v_min_f32_e32 v148, 0x42200000, v148
	v_exp_f32_e32 v150, v148
	v_pk_add_f32 v[160:161], v[114:115], v[130:131]
	v_add_f32_e32 v147, 0.5, v147
	v_mul_f32_e32 v148, 0xbfb8aa3b, v160
	v_max_f32_e32 v147, 1.0, v147
	v_min_f32_e32 v148, 0x42200000, v148
	v_exp_f32_e32 v155, v148
	v_cvt_pk_u8_f32 v148, v147, 3, v146
	v_fmamk_f32 v146, v150, 0x3b808081, v194
	v_cvt_pk_u8_f32 v150, v154, 3, v149
	v_mul_f32_e32 v149, 0xbfb8aa3b, v151
	v_min_f32_e32 v149, 0x42200000, v149
	v_exp_f32_e32 v149, v149
	v_pk_add_f32 v[152:153], v[124:125], v[140:141]
	v_pk_add_f32 v[158:159], v[116:117], v[132:133]
	v_rcp_f32_e32 v146, v146
	v_mul_f32_e32 v151, 0xbfb8aa3b, v161
	v_fmamk_f32 v149, v149, 0x3b808081, v194
	v_min_f32_e32 v151, 0x42200000, v151
	v_rcp_f32_e32 v149, v149
	v_mul_f32_e32 v152, 0xbfb8aa3b, v152
	v_mul_f32_e32 v154, 0xbfb8aa3b, v158
	v_exp_f32_e32 v151, v151
	v_min_f32_e32 v152, 0x42200000, v152
	v_min_f32_e32 v154, 0x42200000, v154
	v_exp_f32_e32 v152, v152
	v_exp_f32_e32 v154, v154
	v_add_f32_e32 v146, 0.5, v146
	v_fmamk_f32 v147, v155, 0x3b808081, v194
	v_max_f32_e32 v146, 1.0, v146
	v_add_f32_e32 v149, 0.5, v149
	v_rcp_f32_e32 v147, v147
	v_cvt_pk_u8_f32 v146, v146, 0, 0
	v_fmamk_f32 v151, v151, 0x3b808081, v194
	v_max_f32_e32 v149, 1.0, v149
	v_rcp_f32_e32 v151, v151
	v_cvt_pk_u8_f32 v146, v149, 1, v146
	v_fmamk_f32 v149, v152, 0x3b808081, v194
	v_fmamk_f32 v152, v154, 0x3b808081, v194
	v_rcp_f32_e32 v152, v152
	v_add_f32_e32 v147, 0.5, v147
	v_cvt_pk_u8_f32 v147, v147, 0, 0
	v_add_f32_e32 v151, 0.5, v151
	v_rcp_f32_e32 v149, v149
	v_cvt_pk_u8_f32 v147, v151, 1, v147
	v_add_f32_e32 v151, 0.5, v152
	v_mul_f32_e32 v152, 0xbfb8aa3b, v153
	v_min_f32_e32 v152, 0x42200000, v152
	v_mul_f32_e32 v153, 0xbfb8aa3b, v159
	v_exp_f32_e32 v152, v152
	v_min_f32_e32 v153, 0x42200000, v153
	v_exp_f32_e32 v153, v153
	v_add_f32_e32 v149, 0.5, v149
	v_max_f32_e32 v149, 1.0, v149
	v_cvt_pk_u8_f32 v146, v149, 2, v146
	v_fmamk_f32 v149, v152, 0x3b808081, v194
	s_lshr_b32 s10, s0, 5
	v_rcp_f32_e32 v149, v149
	v_fmamk_f32 v152, v153, 0x3b808081, v194
	s_ashr_i32 s45, s44, 31
	s_lshl_b64 s[42:43], s[10:11], 10
	v_rcp_f32_e32 v152, v152
	s_lshl_b64 s[0:1], s[44:45], 15
	s_add_u32 s0, s58, s0
	s_addc_u32 s1, s59, s1
	v_add_f32_e32 v149, 0.5, v149
	s_add_u32 s0, s0, s42
	v_cvt_pk_u8_f32 v147, v151, 2, v147
	v_max_f32_e32 v149, 1.0, v149
	v_add_f32_e32 v151, 0.5, v152
	s_addc_u32 s1, s1, s43
	v_lshlrev_b32_e32 v172, 1, v176
	v_cvt_pk_u8_f32 v149, v149, 3, v146
	v_cvt_pk_u8_f32 v151, v151, 3, v147
	v_lshl_add_u64 v[152:153], s[0:1], 0, v[172:173]
	v_lshlrev_b32_e32 v146, 1, v174
	v_mov_b32_e32 v147, v173
	v_lshl_add_u64 v[152:153], v[152:153], 0, v[146:147]
	global_store_dwordx4 v[152:153], v[148:151], off nt
	s_cmp_lg_u64 s[12:13], 0
	s_cbranch_scc0 .Lxs_p1a_2
	s_barrier
;     __device__ __forceinline__ void operator()(const Acc& acc, const Unit& u, int wr, int wc, int fr, int fq) const {
;     ...
; #pragma unroll
;             for (int ai = 0; ai < 2; ++ai)
; #pragma unroll
;                 for (int m = 0; m < 4; ++m) {
;                     const int grow = row0 + ai * HALF + m * 16;
;                     const size_t off = ((size_t)(grow >> 4) * 32 + (col0 >> 5)) * 512 + (grow & 15) * 32 + (col0 & 31);
;                     f32x4 z0[2] = {acc[ai][0][m][0] + ba0, acc[ai][0][m][1] + ba1}, z1[2] = {acc[ai][1][m][0] + bb0, acc[ai][1][m][1] + bb1};
;                     u32x4 w = {0u, 0u, 0u, 0u}; const float C255 = 1.0f / 255.0f;
; #pragma unroll
;                     for (int n = 0; n < 2; ++n)
; #pragma unroll
;                         for (int e = 0; e < 4; ++e) {
;                             const float e0 = __builtin_amdgcn_exp2f(fminf(z0[n][e] * NL2E, 40.f)), e1 = __builtin_amdgcn_exp2f(fminf(z1[n][e] * NL2E, 40.f));
;                             const float q0 = fmaxf(__builtin_amdgcn_rcpf(__builtin_fmaf(e0, C255, C255)) + 0.5f, 1.0f), q1 = __builtin_amdgcn_rcpf(__builtin_fmaf(e1, C255, C255)) + 0.5f;
;                             w[n] = __builtin_amdgcn_cvt_pk_u8_f32(q0, (unsigned)e, w[n]); w[2 + n] = __builtin_amdgcn_cvt_pk_u8_f32(q1, (unsigned)e, w[2 + n]); }
;                     __builtin_nontemporal_store(w, (u32x4*)(G0 + off));
;                 }
.Lxs_p1a_2:
	v_pk_add_f32 v[158:159], v[102:103], v[134:135]
	v_pk_add_f32 v[156:157], v[104:105], v[136:137]
	v_pk_add_f32 v[150:151], v[110:111], v[142:143]
	v_mul_f32_e32 v158, 0xbfb8aa3b, v158
	v_mul_f32_e32 v150, 0xbfb8aa3b, v150
	v_min_f32_e32 v150, 0x42200000, v150
	v_mul_f32_e32 v151, 0xbfb8aa3b, v151
	v_exp_f32_e32 v150, v150
	v_min_f32_e32 v151, 0x42200000, v151
	v_exp_f32_e32 v151, v151
	v_min_f32_e32 v158, 0x42200000, v158
	v_fmamk_f32 v150, v150, 0x3b808081, v194
	v_rcp_f32_e32 v150, v150
	v_mul_f32_e32 v159, 0xbfb8aa3b, v159
	v_fmamk_f32 v151, v151, 0x3b808081, v194
	v_exp_f32_e32 v158, v158
	v_min_f32_e32 v159, 0x42200000, v159
	v_rcp_f32_e32 v151, v151
	v_mul_f32_e32 v156, 0xbfb8aa3b, v156
	v_exp_f32_e32 v159, v159
	v_min_f32_e32 v156, 0x42200000, v156
	v_exp_f32_e32 v156, v156
	v_pk_add_f32 v[148:149], v[112:113], v[144:145]
	v_add_f32_e32 v150, 0.5, v150
	v_fmamk_f32 v158, v158, 0x3b808081, v194
	v_max_f32_e32 v150, 1.0, v150
	v_add_f32_e32 v151, 0.5, v151
	v_mul_f32_e32 v148, 0xbfb8aa3b, v148
	v_rcp_f32_e32 v158, v158
	v_cvt_pk_u8_f32 v150, v150, 0, 0
	v_fmamk_f32 v159, v159, 0x3b808081, v194
	v_max_f32_e32 v151, 1.0, v151
	v_min_f32_e32 v148, 0x42200000, v148
	v_mul_f32_e32 v149, 0xbfb8aa3b, v149
	v_rcp_f32_e32 v159, v159
	v_exp_f32_e32 v148, v148
	v_cvt_pk_u8_f32 v150, v151, 1, v150
	v_fmamk_f32 v151, v156, 0x3b808081, v194
	v_min_f32_e32 v149, 0x42200000, v149
	v_rcp_f32_e32 v151, v151
	v_exp_f32_e32 v149, v149
	v_add_f32_e32 v158, 0.5, v158
	v_cvt_pk_u8_f32 v158, v158, 0, 0
	v_add_f32_e32 v159, 0.5, v159
	v_fmamk_f32 v148, v148, 0x3b808081, v194
	v_pk_add_f32 v[154:155], v[106:107], v[138:139]
	v_pk_add_f32 v[198:199], v[98:99], v[130:131]
	v_rcp_f32_e32 v148, v148
	v_cvt_pk_u8_f32 v156, v159, 1, v158
	v_add_f32_e32 v151, 0.5, v151
	v_mul_f32_e32 v157, 0xbfb8aa3b, v157
	v_fmamk_f32 v149, v149, 0x3b808081, v194
	v_min_f32_e32 v157, 0x42200000, v157
	v_rcp_f32_e32 v149, v149
	v_cvt_pk_u8_f32 v151, v151, 2, v156
	v_mul_f32_e32 v154, 0xbfb8aa3b, v154
	v_mul_f32_e32 v156, 0xbfb8aa3b, v198
	v_exp_f32_e32 v157, v157
	v_min_f32_e32 v154, 0x42200000, v154
	v_min_f32_e32 v156, 0x42200000, v156
	v_exp_f32_e32 v154, v154
	v_exp_f32_e32 v156, v156
	v_add_f32_e32 v148, 0.5, v148
	v_max_f32_e32 v148, 1.0, v148
	v_add_f32_e32 v149, 0.5, v149
	v_cvt_pk_u8_f32 v148, v148, 2, v150
	v_fmamk_f32 v150, v157, 0x3b808081, v194
	v_max_f32_e32 v149, 1.0, v149
	v_rcp_f32_e32 v150, v150
	v_cvt_pk_u8_f32 v148, v149, 3, v148
	v_fmamk_f32 v149, v154, 0x3b808081, v194
	v_fmamk_f32 v154, v156, 0x3b808081, v194
	v_rcp_f32_e32 v154, v154
	v_add_f32_e32 v150, 0.5, v150
	v_cvt_pk_u8_f32 v150, v150, 3, v151
	v_pk_add_f32 v[152:153], v[108:109], v[140:141]
	v_add_f32_e32 v151, 0.5, v154
	v_mul_f32_e32 v154, 0xbfb8aa3b, v155
	v_mul_f32_e32 v155, 0xbfb8aa3b, v199
	v_min_f32_e32 v155, 0x42200000, v155
	v_exp_f32_e32 v155, v155
	v_min_f32_e32 v154, 0x42200000, v154
	v_mul_f32_e32 v152, 0xbfb8aa3b, v152
	v_exp_f32_e32 v154, v154
	v_min_f32_e32 v152, 0x42200000, v152
	v_fmamk_f32 v155, v155, 0x3b808081, v194
	v_exp_f32_e32 v152, v152
	v_rcp_f32_e32 v155, v155
	v_rcp_f32_e32 v149, v149
	v_fmamk_f32 v154, v154, 0x3b808081, v194
	v_pk_add_f32 v[160:161], v[100:101], v[132:133]
	v_rcp_f32_e32 v154, v154
	v_fmamk_f32 v152, v152, 0x3b808081, v194
	v_cvt_pk_u8_f32 v151, v151, 0, 0
	v_add_f32_e32 v155, 0.5, v155
	v_mul_f32_e32 v156, 0xbfb8aa3b, v160
	v_rcp_f32_e32 v152, v152
	v_mul_f32_e32 v153, 0xbfb8aa3b, v153
	v_min_f32_e32 v156, 0x42200000, v156
	v_cvt_pk_u8_f32 v151, v155, 1, v151
	v_min_f32_e32 v153, 0x42200000, v153
	v_mul_f32_e32 v155, 0xbfb8aa3b, v161
	v_add_f32_e32 v149, 0.5, v149
	v_exp_f32_e32 v156, v156
	v_exp_f32_e32 v153, v153
	v_min_f32_e32 v155, 0x42200000, v155
	v_max_f32_e32 v149, 1.0, v149
	v_add_f32_e32 v154, 0.5, v154
	v_exp_f32_e32 v155, v155
	v_cvt_pk_u8_f32 v149, v149, 0, 0
	v_max_f32_e32 v154, 1.0, v154
	v_add_f32_e32 v152, 0.5, v152
	v_cvt_pk_u8_f32 v149, v154, 1, v149
	v_max_f32_e32 v152, 1.0, v152
	s_or_b32 s46, s44, 1
	v_fmamk_f32 v154, v156, 0x3b808081, v194
	v_cvt_pk_u8_f32 v149, v152, 2, v149
	v_fmamk_f32 v152, v153, 0x3b808081, v194
	v_rcp_f32_e32 v154, v154
	v_rcp_f32_e32 v152, v152
	v_fmamk_f32 v153, v155, 0x3b808081, v194
	s_ashr_i32 s47, s46, 31
	v_rcp_f32_e32 v153, v153
	s_lshl_b64 s[0:1], s[46:47], 15
	s_add_u32 s0, s58, s0
	s_addc_u32 s1, s59, s1
	v_add_f32_e32 v154, 0.5, v154
	v_add_f32_e32 v152, 0.5, v152
	s_add_u32 s0, s0, s42
	v_cvt_pk_u8_f32 v151, v154, 2, v151
	v_max_f32_e32 v152, 1.0, v152
	v_add_f32_e32 v153, 0.5, v153
	s_addc_u32 s1, s1, s43
	v_cvt_pk_u8_f32 v149, v152, 3, v149
	v_cvt_pk_u8_f32 v151, v153, 3, v151
	v_lshl_add_u64 v[152:153], s[0:1], 0, v[172:173]
	v_lshl_add_u64 v[152:153], v[152:153], 0, v[146:147]
	global_store_dwordx4 v[152:153], v[148:151], off nt
	v_pk_add_f32 v[158:159], v[86:87], v[134:135]
	v_pk_add_f32 v[156:157], v[88:89], v[136:137]
	v_pk_add_f32 v[150:151], v[94:95], v[142:143]
	v_mul_f32_e32 v158, 0xbfb8aa3b, v158
	v_mul_f32_e32 v150, 0xbfb8aa3b, v150
	v_min_f32_e32 v150, 0x42200000, v150
	v_mul_f32_e32 v151, 0xbfb8aa3b, v151
	v_exp_f32_e32 v150, v150
	v_min_f32_e32 v151, 0x42200000, v151
	v_exp_f32_e32 v151, v151
	v_min_f32_e32 v158, 0x42200000, v158
	v_fmamk_f32 v150, v150, 0x3b808081, v194
	v_rcp_f32_e32 v150, v150
	v_mul_f32_e32 v159, 0xbfb8aa3b, v159
	v_fmamk_f32 v151, v151, 0x3b808081, v194
	v_exp_f32_e32 v158, v158
	v_min_f32_e32 v159, 0x42200000, v159
	v_rcp_f32_e32 v151, v151
	v_mul_f32_e32 v156, 0xbfb8aa3b, v156
	v_exp_f32_e32 v159, v159
	v_min_f32_e32 v156, 0x42200000, v156
	v_exp_f32_e32 v156, v156
	v_pk_add_f32 v[148:149], v[96:97], v[144:145]
	v_add_f32_e32 v150, 0.5, v150
;     __device__ __forceinline__ void operator()(const Acc& acc, const Unit& u, int wr, int wc, int fr, int fq) const {
;     ...
; #pragma unroll
;             for (int ai = 0; ai < 2; ++ai)
; #pragma unroll
;                 for (int m = 0; m < 4; ++m) {
;                     const int grow = row0 + ai * HALF + m * 16;
;                     const size_t off = ((size_t)(grow >> 4) * 32 + (col0 >> 5)) * 512 + (grow & 15) * 32 + (col0 & 31);
;                     f32x4 z0[2] = {acc[ai][0][m][0] + ba0, acc[ai][0][m][1] + ba1}, z1[2] = {acc[ai][1][m][0] + bb0, acc[ai][1][m][1] + bb1};
;                     u32x4 w = {0u, 0u, 0u, 0u}; const float C255 = 1.0f / 255.0f;
; #pragma unroll
;                     for (int n = 0; n < 2; ++n)
; #pragma unroll
;                         for (int e = 0; e < 4; ++e) {
;                             const float e0 = __builtin_amdgcn_exp2f(fminf(z0[n][e] * NL2E, 40.f)), e1 = __builtin_amdgcn_exp2f(fminf(z1[n][e] * NL2E, 40.f));
;                             const float q0 = fmaxf(__builtin_amdgcn_rcpf(__builtin_fmaf(e0, C255, C255)) + 0.5f, 1.0f), q1 = __builtin_amdgcn_rcpf(__builtin_fmaf(e1, C255, C255)) + 0.5f;
;                             w[n] = __builtin_amdgcn_cvt_pk_u8_f32(q0, (unsigned)e, w[n]); w[2 + n] = __builtin_amdgcn_cvt_pk_u8_f32(q1, (unsigned)e, w[2 + n]); }
;                     __builtin_nontemporal_store(w, (u32x4*)(G0 + off));
;                 }
	v_fmamk_f32 v158, v158, 0x3b808081, v194
	v_max_f32_e32 v150, 1.0, v150
	v_add_f32_e32 v151, 0.5, v151
	v_mul_f32_e32 v148, 0xbfb8aa3b, v148
	v_rcp_f32_e32 v158, v158
	v_cvt_pk_u8_f32 v150, v150, 0, 0
	v_fmamk_f32 v159, v159, 0x3b808081, v194
	v_max_f32_e32 v151, 1.0, v151
	v_min_f32_e32 v148, 0x42200000, v148
	v_mul_f32_e32 v149, 0xbfb8aa3b, v149
	v_rcp_f32_e32 v159, v159
	v_exp_f32_e32 v148, v148
	v_cvt_pk_u8_f32 v150, v151, 1, v150
	v_fmamk_f32 v151, v156, 0x3b808081, v194
	v_min_f32_e32 v149, 0x42200000, v149
	v_rcp_f32_e32 v151, v151
	v_exp_f32_e32 v149, v149
	v_add_f32_e32 v158, 0.5, v158
	v_cvt_pk_u8_f32 v158, v158, 0, 0
	v_add_f32_e32 v159, 0.5, v159
	v_fmamk_f32 v148, v148, 0x3b808081, v194
	v_pk_add_f32 v[154:155], v[90:91], v[138:139]
	v_pk_add_f32 v[198:199], v[82:83], v[130:131]
	v_rcp_f32_e32 v148, v148
	v_cvt_pk_u8_f32 v156, v159, 1, v158
	v_add_f32_e32 v151, 0.5, v151
	v_mul_f32_e32 v157, 0xbfb8aa3b, v157
	v_fmamk_f32 v149, v149, 0x3b808081, v194
	v_min_f32_e32 v157, 0x42200000, v157
	v_rcp_f32_e32 v149, v149
	v_cvt_pk_u8_f32 v151, v151, 2, v156
	v_mul_f32_e32 v154, 0xbfb8aa3b, v154
	v_mul_f32_e32 v156, 0xbfb8aa3b, v198
	v_exp_f32_e32 v157, v157
	v_min_f32_e32 v154, 0x42200000, v154
	v_min_f32_e32 v156, 0x42200000, v156
	v_exp_f32_e32 v154, v154
	v_exp_f32_e32 v156, v156
	v_add_f32_e32 v148, 0.5, v148
	v_max_f32_e32 v148, 1.0, v148
	v_add_f32_e32 v149, 0.5, v149
	v_cvt_pk_u8_f32 v148, v148, 2, v150
	v_fmamk_f32 v150, v157, 0x3b808081, v194
	v_max_f32_e32 v149, 1.0, v149
	v_rcp_f32_e32 v150, v150
	v_cvt_pk_u8_f32 v148, v149, 3, v148
	v_fmamk_f32 v149, v154, 0x3b808081, v194
	v_fmamk_f32 v154, v156, 0x3b808081, v194
	v_rcp_f32_e32 v154, v154
	v_add_f32_e32 v150, 0.5, v150
	v_cvt_pk_u8_f32 v150, v150, 3, v151
	v_pk_add_f32 v[152:153], v[92:93], v[140:141]
	v_add_f32_e32 v151, 0.5, v154
	v_mul_f32_e32 v154, 0xbfb8aa3b, v155
	v_mul_f32_e32 v155, 0xbfb8aa3b, v199
	v_min_f32_e32 v155, 0x42200000, v155
	v_exp_f32_e32 v155, v155
	v_min_f32_e32 v154, 0x42200000, v154
	v_mul_f32_e32 v152, 0xbfb8aa3b, v152
	v_exp_f32_e32 v154, v154
	v_min_f32_e32 v152, 0x42200000, v152
	v_fmamk_f32 v155, v155, 0x3b808081, v194
	v_exp_f32_e32 v152, v152
	v_rcp_f32_e32 v155, v155
	v_rcp_f32_e32 v149, v149
	v_fmamk_f32 v154, v154, 0x3b808081, v194
	v_pk_add_f32 v[160:161], v[84:85], v[132:133]
	v_rcp_f32_e32 v154, v154
	v_fmamk_f32 v152, v152, 0x3b808081, v194
	v_cvt_pk_u8_f32 v151, v151, 0, 0
	v_add_f32_e32 v155, 0.5, v155
	v_mul_f32_e32 v156, 0xbfb8aa3b, v160
	v_rcp_f32_e32 v152, v152
	v_mul_f32_e32 v153, 0xbfb8aa3b, v153
	v_min_f32_e32 v156, 0x42200000, v156
	v_cvt_pk_u8_f32 v151, v155, 1, v151
	v_min_f32_e32 v153, 0x42200000, v153
	v_mul_f32_e32 v155, 0xbfb8aa3b, v161
	v_add_f32_e32 v149, 0.5, v149
	v_exp_f32_e32 v156, v156
	v_exp_f32_e32 v153, v153
	v_min_f32_e32 v155, 0x42200000, v155
	v_max_f32_e32 v149, 1.0, v149
	v_add_f32_e32 v154, 0.5, v154
	v_exp_f32_e32 v155, v155
	v_cvt_pk_u8_f32 v149, v149, 0, 0
	v_max_f32_e32 v154, 1.0, v154
	v_add_f32_e32 v152, 0.5, v152
	v_cvt_pk_u8_f32 v149, v154, 1, v149
	v_max_f32_e32 v152, 1.0, v152
	s_or_b32 s46, s44, 2
	v_fmamk_f32 v154, v156, 0x3b808081, v194
	v_cvt_pk_u8_f32 v149, v152, 2, v149
	v_fmamk_f32 v152, v153, 0x3b808081, v194
	v_rcp_f32_e32 v154, v154
	v_rcp_f32_e32 v152, v152
	v_fmamk_f32 v153, v155, 0x3b808081, v194
	s_ashr_i32 s47, s46, 31
	v_rcp_f32_e32 v153, v153
	s_lshl_b64 s[0:1], s[46:47], 15
	s_add_u32 s0, s58, s0
	s_addc_u32 s1, s59, s1
	v_add_f32_e32 v154, 0.5, v154
	v_add_f32_e32 v152, 0.5, v152
	s_add_u32 s0, s0, s42
	v_cvt_pk_u8_f32 v151, v154, 2, v151
	v_max_f32_e32 v152, 1.0, v152
	v_add_f32_e32 v153, 0.5, v153
	s_addc_u32 s1, s1, s43
	v_cvt_pk_u8_f32 v149, v152, 3, v149
	v_cvt_pk_u8_f32 v151, v153, 3, v151
	v_lshl_add_u64 v[152:153], s[0:1], 0, v[172:173]
	v_lshl_add_u64 v[152:153], v[152:153], 0, v[146:147]
	global_store_dwordx4 v[152:153], v[148:151], off nt
	v_pk_add_f32 v[158:159], v[70:71], v[134:135]
	v_pk_add_f32 v[156:157], v[72:73], v[136:137]
	v_pk_add_f32 v[150:151], v[78:79], v[142:143]
	v_mul_f32_e32 v158, 0xbfb8aa3b, v158
	v_mul_f32_e32 v150, 0xbfb8aa3b, v150
	v_min_f32_e32 v150, 0x42200000, v150
	v_mul_f32_e32 v151, 0xbfb8aa3b, v151
	v_exp_f32_e32 v150, v150
	v_min_f32_e32 v151, 0x42200000, v151
	v_exp_f32_e32 v151, v151
	v_min_f32_e32 v158, 0x42200000, v158
	v_fmamk_f32 v150, v150, 0x3b808081, v194
	v_rcp_f32_e32 v150, v150
	v_mul_f32_e32 v159, 0xbfb8aa3b, v159
	v_fmamk_f32 v151, v151, 0x3b808081, v194
	v_exp_f32_e32 v158, v158
	v_min_f32_e32 v159, 0x42200000, v159
	v_rcp_f32_e32 v151, v151
	v_mul_f32_e32 v156, 0xbfb8aa3b, v156
	v_exp_f32_e32 v159, v159
	v_min_f32_e32 v156, 0x42200000, v156
	v_exp_f32_e32 v156, v156
	v_pk_add_f32 v[148:149], v[80:81], v[144:145]
	v_add_f32_e32 v150, 0.5, v150
	v_fmamk_f32 v158, v158, 0x3b808081, v194
	v_max_f32_e32 v150, 1.0, v150
	v_add_f32_e32 v151, 0.5, v151
	v_mul_f32_e32 v148, 0xbfb8aa3b, v148
	v_rcp_f32_e32 v158, v158
	v_cvt_pk_u8_f32 v150, v150, 0, 0
	v_fmamk_f32 v159, v159, 0x3b808081, v194
	v_max_f32_e32 v151, 1.0, v151
	v_min_f32_e32 v148, 0x42200000, v148
	v_mul_f32_e32 v149, 0xbfb8aa3b, v149
	v_rcp_f32_e32 v159, v159
	v_exp_f32_e32 v148, v148
	v_cvt_pk_u8_f32 v150, v151, 1, v150
	v_fmamk_f32 v151, v156, 0x3b808081, v194
	v_min_f32_e32 v149, 0x42200000, v149
	v_rcp_f32_e32 v151, v151
	v_exp_f32_e32 v149, v149
	v_add_f32_e32 v158, 0.5, v158
	v_cvt_pk_u8_f32 v158, v158, 0, 0
	v_add_f32_e32 v159, 0.5, v159
	v_fmamk_f32 v148, v148, 0x3b808081, v194
	v_pk_add_f32 v[154:155], v[74:75], v[138:139]
	v_pk_add_f32 v[198:199], v[66:67], v[130:131]
	v_rcp_f32_e32 v148, v148
	v_cvt_pk_u8_f32 v156, v159, 1, v158
	v_add_f32_e32 v151, 0.5, v151
;     __device__ __forceinline__ void operator()(const Acc& acc, const Unit& u, int wr, int wc, int fr, int fq) const {
;     ...
; #pragma unroll
;             for (int ai = 0; ai < 2; ++ai)
; #pragma unroll
;                 for (int m = 0; m < 4; ++m) {
;                     const int grow = row0 + ai * HALF + m * 16;
;                     const size_t off = ((size_t)(grow >> 4) * 32 + (col0 >> 5)) * 512 + (grow & 15) * 32 + (col0 & 31);
;                     f32x4 z0[2] = {acc[ai][0][m][0] + ba0, acc[ai][0][m][1] + ba1}, z1[2] = {acc[ai][1][m][0] + bb0, acc[ai][1][m][1] + bb1};
;                     u32x4 w = {0u, 0u, 0u, 0u}; const float C255 = 1.0f / 255.0f;
; #pragma unroll
;                     for (int n = 0; n < 2; ++n)
; #pragma unroll
;                         for (int e = 0; e < 4; ++e) {
;                             const float e0 = __builtin_amdgcn_exp2f(fminf(z0[n][e] * NL2E, 40.f)), e1 = __builtin_amdgcn_exp2f(fminf(z1[n][e] * NL2E, 40.f));
;                             const float q0 = fmaxf(__builtin_amdgcn_rcpf(__builtin_fmaf(e0, C255, C255)) + 0.5f, 1.0f), q1 = __builtin_amdgcn_rcpf(__builtin_fmaf(e1, C255, C255)) + 0.5f;
;                             w[n] = __builtin_amdgcn_cvt_pk_u8_f32(q0, (unsigned)e, w[n]); w[2 + n] = __builtin_amdgcn_cvt_pk_u8_f32(q1, (unsigned)e, w[2 + n]); }
;                     __builtin_nontemporal_store(w, (u32x4*)(G0 + off));
;                 }
	v_mul_f32_e32 v157, 0xbfb8aa3b, v157
	v_fmamk_f32 v149, v149, 0x3b808081, v194
	v_min_f32_e32 v157, 0x42200000, v157
	v_rcp_f32_e32 v149, v149
	v_cvt_pk_u8_f32 v151, v151, 2, v156
	v_mul_f32_e32 v154, 0xbfb8aa3b, v154
	v_mul_f32_e32 v156, 0xbfb8aa3b, v198
	v_exp_f32_e32 v157, v157
	v_min_f32_e32 v154, 0x42200000, v154
	v_min_f32_e32 v156, 0x42200000, v156
	v_exp_f32_e32 v154, v154
	v_exp_f32_e32 v156, v156
	v_add_f32_e32 v148, 0.5, v148
	v_max_f32_e32 v148, 1.0, v148
	v_add_f32_e32 v149, 0.5, v149
	v_cvt_pk_u8_f32 v148, v148, 2, v150
	v_fmamk_f32 v150, v157, 0x3b808081, v194
	v_max_f32_e32 v149, 1.0, v149
	v_rcp_f32_e32 v150, v150
	v_cvt_pk_u8_f32 v148, v149, 3, v148
	v_fmamk_f32 v149, v154, 0x3b808081, v194
	v_fmamk_f32 v154, v156, 0x3b808081, v194
	v_rcp_f32_e32 v154, v154
	v_add_f32_e32 v150, 0.5, v150
	v_cvt_pk_u8_f32 v150, v150, 3, v151
	v_pk_add_f32 v[152:153], v[76:77], v[140:141]
	v_add_f32_e32 v151, 0.5, v154
	v_mul_f32_e32 v154, 0xbfb8aa3b, v155
	v_mul_f32_e32 v155, 0xbfb8aa3b, v199
	v_min_f32_e32 v155, 0x42200000, v155
	v_exp_f32_e32 v155, v155
	v_min_f32_e32 v154, 0x42200000, v154
	v_mul_f32_e32 v152, 0xbfb8aa3b, v152
	v_exp_f32_e32 v154, v154
	v_min_f32_e32 v152, 0x42200000, v152
	v_fmamk_f32 v155, v155, 0x3b808081, v194
	v_exp_f32_e32 v152, v152
	v_rcp_f32_e32 v155, v155
	v_rcp_f32_e32 v149, v149
	v_fmamk_f32 v154, v154, 0x3b808081, v194
	v_pk_add_f32 v[160:161], v[68:69], v[132:133]
	v_rcp_f32_e32 v154, v154
	v_fmamk_f32 v152, v152, 0x3b808081, v194
	v_cvt_pk_u8_f32 v151, v151, 0, 0
	v_add_f32_e32 v155, 0.5, v155
	v_mul_f32_e32 v156, 0xbfb8aa3b, v160
	v_rcp_f32_e32 v152, v152
	v_mul_f32_e32 v153, 0xbfb8aa3b, v153
	v_min_f32_e32 v156, 0x42200000, v156
	v_cvt_pk_u8_f32 v151, v155, 1, v151
	v_min_f32_e32 v153, 0x42200000, v153
	v_mul_f32_e32 v155, 0xbfb8aa3b, v161
	v_add_f32_e32 v149, 0.5, v149
	v_exp_f32_e32 v156, v156
	v_exp_f32_e32 v153, v153
	v_min_f32_e32 v155, 0x42200000, v155
	v_max_f32_e32 v149, 1.0, v149
	v_add_f32_e32 v154, 0.5, v154
	v_exp_f32_e32 v155, v155
	v_cvt_pk_u8_f32 v149, v149, 0, 0
	v_max_f32_e32 v154, 1.0, v154
	v_add_f32_e32 v152, 0.5, v152
	v_cvt_pk_u8_f32 v149, v154, 1, v149
	v_max_f32_e32 v152, 1.0, v152
	s_or_b32 s44, s44, 3
	v_fmamk_f32 v154, v156, 0x3b808081, v194
	v_cvt_pk_u8_f32 v149, v152, 2, v149
	v_fmamk_f32 v152, v153, 0x3b808081, v194
	v_rcp_f32_e32 v154, v154
	v_rcp_f32_e32 v152, v152
	v_fmamk_f32 v153, v155, 0x3b808081, v194
	s_ashr_i32 s45, s44, 31
	v_rcp_f32_e32 v153, v153
	s_lshl_b64 s[0:1], s[44:45], 15
	s_add_u32 s0, s58, s0
	s_addc_u32 s1, s59, s1
	v_add_f32_e32 v154, 0.5, v154
	v_add_f32_e32 v152, 0.5, v152
	s_add_u32 s0, s0, s42
	v_cvt_pk_u8_f32 v151, v154, 2, v151
	v_max_f32_e32 v152, 1.0, v152
	v_add_f32_e32 v153, 0.5, v153
	s_addc_u32 s1, s1, s43
	v_cvt_pk_u8_f32 v149, v152, 3, v149
	v_cvt_pk_u8_f32 v151, v153, 3, v151
	v_lshl_add_u64 v[152:153], s[0:1], 0, v[172:173]
	v_lshl_add_u64 v[152:153], v[152:153], 0, v[146:147]
	global_store_dwordx4 v[152:153], v[148:151], off nt
	v_pk_add_f32 v[158:159], v[54:55], v[134:135]
	v_pk_add_f32 v[156:157], v[56:57], v[136:137]
	v_pk_add_f32 v[150:151], v[62:63], v[142:143]
	v_mul_f32_e32 v158, 0xbfb8aa3b, v158
	v_mul_f32_e32 v150, 0xbfb8aa3b, v150
	v_min_f32_e32 v150, 0x42200000, v150
	v_mul_f32_e32 v151, 0xbfb8aa3b, v151
	v_exp_f32_e32 v150, v150
	v_min_f32_e32 v151, 0x42200000, v151
	v_exp_f32_e32 v151, v151
	v_min_f32_e32 v158, 0x42200000, v158
	v_fmamk_f32 v150, v150, 0x3b808081, v194
	v_rcp_f32_e32 v150, v150
	v_mul_f32_e32 v159, 0xbfb8aa3b, v159
	v_fmamk_f32 v151, v151, 0x3b808081, v194
	v_exp_f32_e32 v158, v158
	v_min_f32_e32 v159, 0x42200000, v159
	v_rcp_f32_e32 v151, v151
	v_mul_f32_e32 v156, 0xbfb8aa3b, v156
	v_exp_f32_e32 v159, v159
	v_min_f32_e32 v156, 0x42200000, v156
	v_exp_f32_e32 v156, v156
	v_pk_add_f32 v[148:149], v[64:65], v[144:145]
	v_add_f32_e32 v150, 0.5, v150
	v_fmamk_f32 v158, v158, 0x3b808081, v194
	v_max_f32_e32 v150, 1.0, v150
	v_add_f32_e32 v151, 0.5, v151
	v_mul_f32_e32 v148, 0xbfb8aa3b, v148
	v_rcp_f32_e32 v158, v158
	v_cvt_pk_u8_f32 v150, v150, 0, 0
	v_fmamk_f32 v159, v159, 0x3b808081, v194
	v_max_f32_e32 v151, 1.0, v151
	v_min_f32_e32 v148, 0x42200000, v148
	v_mul_f32_e32 v149, 0xbfb8aa3b, v149
	v_rcp_f32_e32 v159, v159
	v_exp_f32_e32 v148, v148
	v_cvt_pk_u8_f32 v150, v151, 1, v150
	v_fmamk_f32 v151, v156, 0x3b808081, v194
	v_min_f32_e32 v149, 0x42200000, v149
	v_rcp_f32_e32 v151, v151
	v_exp_f32_e32 v149, v149
	v_add_f32_e32 v158, 0.5, v158
	v_cvt_pk_u8_f32 v158, v158, 0, 0
	v_add_f32_e32 v159, 0.5, v159
	v_fmamk_f32 v148, v148, 0x3b808081, v194
	v_pk_add_f32 v[154:155], v[58:59], v[138:139]
	v_pk_add_f32 v[198:199], v[50:51], v[130:131]
	v_rcp_f32_e32 v148, v148
	v_cvt_pk_u8_f32 v156, v159, 1, v158
	v_add_f32_e32 v151, 0.5, v151
	v_mul_f32_e32 v157, 0xbfb8aa3b, v157
	v_fmamk_f32 v149, v149, 0x3b808081, v194
	v_min_f32_e32 v157, 0x42200000, v157
	v_rcp_f32_e32 v149, v149
	v_cvt_pk_u8_f32 v151, v151, 2, v156
	v_mul_f32_e32 v154, 0xbfb8aa3b, v154
	v_mul_f32_e32 v156, 0xbfb8aa3b, v198
	v_exp_f32_e32 v157, v157
	v_min_f32_e32 v154, 0x42200000, v154
	v_min_f32_e32 v156, 0x42200000, v156
	v_exp_f32_e32 v154, v154
	v_exp_f32_e32 v156, v156
	v_add_f32_e32 v148, 0.5, v148
	v_max_f32_e32 v148, 1.0, v148
	v_add_f32_e32 v149, 0.5, v149
	v_cvt_pk_u8_f32 v148, v148, 2, v150
	v_fmamk_f32 v150, v157, 0x3b808081, v194
	v_max_f32_e32 v149, 1.0, v149
	v_rcp_f32_e32 v150, v150
	v_cvt_pk_u8_f32 v148, v149, 3, v148
	v_fmamk_f32 v149, v154, 0x3b808081, v194
	v_fmamk_f32 v154, v156, 0x3b808081, v194
	v_rcp_f32_e32 v154, v154
	v_add_f32_e32 v150, 0.5, v150
	v_cvt_pk_u8_f32 v150, v150, 3, v151
	v_pk_add_f32 v[152:153], v[60:61], v[140:141]
;     __device__ __forceinline__ void operator()(const Acc& acc, const Unit& u, int wr, int wc, int fr, int fq) const {
;     ...
; #pragma unroll
;             for (int ai = 0; ai < 2; ++ai)
; #pragma unroll
;                 for (int m = 0; m < 4; ++m) {
;                     const int grow = row0 + ai * HALF + m * 16;
;                     const size_t off = ((size_t)(grow >> 4) * 32 + (col0 >> 5)) * 512 + (grow & 15) * 32 + (col0 & 31);
;                     f32x4 z0[2] = {acc[ai][0][m][0] + ba0, acc[ai][0][m][1] + ba1}, z1[2] = {acc[ai][1][m][0] + bb0, acc[ai][1][m][1] + bb1};
;                     u32x4 w = {0u, 0u, 0u, 0u}; const float C255 = 1.0f / 255.0f;
; #pragma unroll
;                     for (int n = 0; n < 2; ++n)
; #pragma unroll
;                         for (int e = 0; e < 4; ++e) {
;                             const float e0 = __builtin_amdgcn_exp2f(fminf(z0[n][e] * NL2E, 40.f)), e1 = __builtin_amdgcn_exp2f(fminf(z1[n][e] * NL2E, 40.f));
;                             const float q0 = fmaxf(__builtin_amdgcn_rcpf(__builtin_fmaf(e0, C255, C255)) + 0.5f, 1.0f), q1 = __builtin_amdgcn_rcpf(__builtin_fmaf(e1, C255, C255)) + 0.5f;
;                             w[n] = __builtin_amdgcn_cvt_pk_u8_f32(q0, (unsigned)e, w[n]); w[2 + n] = __builtin_amdgcn_cvt_pk_u8_f32(q1, (unsigned)e, w[2 + n]); }
;                     __builtin_nontemporal_store(w, (u32x4*)(G0 + off));
;                 }
	v_add_f32_e32 v151, 0.5, v154
	v_mul_f32_e32 v154, 0xbfb8aa3b, v155
	v_mul_f32_e32 v155, 0xbfb8aa3b, v199
	v_min_f32_e32 v155, 0x42200000, v155
	v_exp_f32_e32 v155, v155
	v_min_f32_e32 v154, 0x42200000, v154
	v_mul_f32_e32 v152, 0xbfb8aa3b, v152
	v_exp_f32_e32 v154, v154
	v_min_f32_e32 v152, 0x42200000, v152
	v_fmamk_f32 v155, v155, 0x3b808081, v194
	v_exp_f32_e32 v152, v152
	v_rcp_f32_e32 v155, v155
	v_rcp_f32_e32 v149, v149
	v_fmamk_f32 v154, v154, 0x3b808081, v194
	v_pk_add_f32 v[160:161], v[52:53], v[132:133]
	v_rcp_f32_e32 v154, v154
	v_fmamk_f32 v152, v152, 0x3b808081, v194
	v_cvt_pk_u8_f32 v151, v151, 0, 0
	v_add_f32_e32 v155, 0.5, v155
	v_mul_f32_e32 v156, 0xbfb8aa3b, v160
	v_rcp_f32_e32 v152, v152
	v_mul_f32_e32 v153, 0xbfb8aa3b, v153
	v_min_f32_e32 v156, 0x42200000, v156
	v_cvt_pk_u8_f32 v151, v155, 1, v151
	v_min_f32_e32 v153, 0x42200000, v153
	v_mul_f32_e32 v155, 0xbfb8aa3b, v161
	v_add_f32_e32 v149, 0.5, v149
	v_exp_f32_e32 v156, v156
	v_exp_f32_e32 v153, v153
	v_min_f32_e32 v155, 0x42200000, v155
	v_max_f32_e32 v149, 1.0, v149
	v_add_f32_e32 v154, 0.5, v154
	v_exp_f32_e32 v155, v155
	v_cvt_pk_u8_f32 v149, v149, 0, 0
	v_max_f32_e32 v154, 1.0, v154
	v_add_f32_e32 v152, 0.5, v152
	s_add_i32 s0, s27, 0x80
	v_cvt_pk_u8_f32 v149, v154, 1, v149
	v_max_f32_e32 v152, 1.0, v152
	s_ashr_i32 s44, s0, 4
	v_fmamk_f32 v154, v156, 0x3b808081, v194
	v_cvt_pk_u8_f32 v149, v152, 2, v149
	v_fmamk_f32 v152, v153, 0x3b808081, v194
	v_rcp_f32_e32 v154, v154
	v_rcp_f32_e32 v152, v152
	v_fmamk_f32 v153, v155, 0x3b808081, v194
	s_ashr_i32 s45, s44, 31
	v_rcp_f32_e32 v153, v153
	s_lshl_b64 s[0:1], s[44:45], 15
	s_add_u32 s0, s58, s0
	s_addc_u32 s1, s59, s1
	v_add_f32_e32 v154, 0.5, v154
	v_add_f32_e32 v152, 0.5, v152
	s_add_u32 s0, s0, s42
	v_cvt_pk_u8_f32 v151, v154, 2, v151
	v_max_f32_e32 v152, 1.0, v152
	v_add_f32_e32 v153, 0.5, v153
	s_addc_u32 s1, s1, s43
	v_cvt_pk_u8_f32 v149, v152, 3, v149
	v_cvt_pk_u8_f32 v151, v153, 3, v151
	v_lshl_add_u64 v[152:153], s[0:1], 0, v[172:173]
	v_lshl_add_u64 v[152:153], v[152:153], 0, v[146:147]
	global_store_dwordx4 v[152:153], v[148:151], off nt
	v_pk_add_f32 v[158:159], v[42:43], v[134:135]
	v_pk_add_f32 v[156:157], v[44:45], v[136:137]
	v_pk_add_f32 v[150:151], v[38:39], v[142:143]
	v_mul_f32_e32 v158, 0xbfb8aa3b, v158
	v_mul_f32_e32 v150, 0xbfb8aa3b, v150
	v_min_f32_e32 v150, 0x42200000, v150
	v_mul_f32_e32 v151, 0xbfb8aa3b, v151
	v_exp_f32_e32 v150, v150
	v_min_f32_e32 v151, 0x42200000, v151
	v_exp_f32_e32 v151, v151
	v_min_f32_e32 v158, 0x42200000, v158
	v_fmamk_f32 v150, v150, 0x3b808081, v194
	v_rcp_f32_e32 v150, v150
	v_mul_f32_e32 v159, 0xbfb8aa3b, v159
	v_fmamk_f32 v151, v151, 0x3b808081, v194
	v_exp_f32_e32 v158, v158
	v_min_f32_e32 v159, 0x42200000, v159
	v_rcp_f32_e32 v151, v151
	v_mul_f32_e32 v156, 0xbfb8aa3b, v156
	v_exp_f32_e32 v159, v159
	v_min_f32_e32 v156, 0x42200000, v156
	v_exp_f32_e32 v156, v156
	v_pk_add_f32 v[148:149], v[40:41], v[144:145]
	v_add_f32_e32 v150, 0.5, v150
	v_fmamk_f32 v158, v158, 0x3b808081, v194
	v_max_f32_e32 v150, 1.0, v150
	v_add_f32_e32 v151, 0.5, v151
	v_mul_f32_e32 v148, 0xbfb8aa3b, v148
	v_rcp_f32_e32 v158, v158
	v_cvt_pk_u8_f32 v150, v150, 0, 0
	v_fmamk_f32 v159, v159, 0x3b808081, v194
	v_max_f32_e32 v151, 1.0, v151
	v_min_f32_e32 v148, 0x42200000, v148
	v_mul_f32_e32 v149, 0xbfb8aa3b, v149
	v_rcp_f32_e32 v159, v159
	v_exp_f32_e32 v148, v148
	v_cvt_pk_u8_f32 v150, v151, 1, v150
	v_fmamk_f32 v151, v156, 0x3b808081, v194
	v_min_f32_e32 v149, 0x42200000, v149
	v_rcp_f32_e32 v151, v151
	v_exp_f32_e32 v149, v149
	v_add_f32_e32 v158, 0.5, v158
	v_cvt_pk_u8_f32 v158, v158, 0, 0
	v_add_f32_e32 v159, 0.5, v159
	v_fmamk_f32 v148, v148, 0x3b808081, v194
	v_pk_add_f32 v[154:155], v[34:35], v[138:139]
	v_pk_add_f32 v[198:199], v[46:47], v[130:131]
	v_rcp_f32_e32 v148, v148
	v_cvt_pk_u8_f32 v156, v159, 1, v158
	v_add_f32_e32 v151, 0.5, v151
	v_mul_f32_e32 v157, 0xbfb8aa3b, v157
	v_fmamk_f32 v149, v149, 0x3b808081, v194
	v_min_f32_e32 v157, 0x42200000, v157
	v_rcp_f32_e32 v149, v149
	v_cvt_pk_u8_f32 v151, v151, 2, v156
	v_mul_f32_e32 v154, 0xbfb8aa3b, v154
	v_mul_f32_e32 v156, 0xbfb8aa3b, v198
	v_exp_f32_e32 v157, v157
	v_min_f32_e32 v154, 0x42200000, v154
	v_min_f32_e32 v156, 0x42200000, v156
	v_exp_f32_e32 v154, v154
	v_exp_f32_e32 v156, v156
	v_add_f32_e32 v148, 0.5, v148
	v_max_f32_e32 v148, 1.0, v148
	v_add_f32_e32 v149, 0.5, v149
	v_cvt_pk_u8_f32 v148, v148, 2, v150
	v_fmamk_f32 v150, v157, 0x3b808081, v194
	v_max_f32_e32 v149, 1.0, v149
	v_rcp_f32_e32 v150, v150
	v_cvt_pk_u8_f32 v148, v149, 3, v148
	v_fmamk_f32 v149, v154, 0x3b808081, v194
	v_fmamk_f32 v154, v156, 0x3b808081, v194
	v_rcp_f32_e32 v154, v154
	v_add_f32_e32 v150, 0.5, v150
	v_cvt_pk_u8_f32 v150, v150, 3, v151
	v_pk_add_f32 v[152:153], v[36:37], v[140:141]
	v_add_f32_e32 v151, 0.5, v154
	v_mul_f32_e32 v154, 0xbfb8aa3b, v155
	v_mul_f32_e32 v155, 0xbfb8aa3b, v199
	v_min_f32_e32 v155, 0x42200000, v155
	v_exp_f32_e32 v155, v155
	v_min_f32_e32 v154, 0x42200000, v154
	v_mul_f32_e32 v152, 0xbfb8aa3b, v152
	v_exp_f32_e32 v154, v154
	v_min_f32_e32 v152, 0x42200000, v152
	v_fmamk_f32 v155, v155, 0x3b808081, v194
	v_exp_f32_e32 v152, v152
	v_rcp_f32_e32 v155, v155
	v_rcp_f32_e32 v149, v149
	v_fmamk_f32 v154, v154, 0x3b808081, v194
	v_pk_add_f32 v[160:161], v[48:49], v[132:133]
	v_rcp_f32_e32 v154, v154
	v_fmamk_f32 v152, v152, 0x3b808081, v194
	v_cvt_pk_u8_f32 v151, v151, 0, 0
	v_add_f32_e32 v155, 0.5, v155
	v_mul_f32_e32 v156, 0xbfb8aa3b, v160
	v_rcp_f32_e32 v152, v152
	v_mul_f32_e32 v153, 0xbfb8aa3b, v153
	v_min_f32_e32 v156, 0x42200000, v156
	v_cvt_pk_u8_f32 v151, v155, 1, v151
	v_min_f32_e32 v153, 0x42200000, v153
;     __device__ __forceinline__ void operator()(const Acc& acc, const Unit& u, int wr, int wc, int fr, int fq) const {
;     ...
; #pragma unroll
;             for (int ai = 0; ai < 2; ++ai)
; #pragma unroll
;                 for (int m = 0; m < 4; ++m) {
;                     const int grow = row0 + ai * HALF + m * 16;
;                     const size_t off = ((size_t)(grow >> 4) * 32 + (col0 >> 5)) * 512 + (grow & 15) * 32 + (col0 & 31);
;                     f32x4 z0[2] = {acc[ai][0][m][0] + ba0, acc[ai][0][m][1] + ba1}, z1[2] = {acc[ai][1][m][0] + bb0, acc[ai][1][m][1] + bb1};
;                     u32x4 w = {0u, 0u, 0u, 0u}; const float C255 = 1.0f / 255.0f;
; #pragma unroll
;                     for (int n = 0; n < 2; ++n)
; #pragma unroll
;                         for (int e = 0; e < 4; ++e) {
;                             const float e0 = __builtin_amdgcn_exp2f(fminf(z0[n][e] * NL2E, 40.f)), e1 = __builtin_amdgcn_exp2f(fminf(z1[n][e] * NL2E, 40.f));
;                             const float q0 = fmaxf(__builtin_amdgcn_rcpf(__builtin_fmaf(e0, C255, C255)) + 0.5f, 1.0f), q1 = __builtin_amdgcn_rcpf(__builtin_fmaf(e1, C255, C255)) + 0.5f;
;                             w[n] = __builtin_amdgcn_cvt_pk_u8_f32(q0, (unsigned)e, w[n]); w[2 + n] = __builtin_amdgcn_cvt_pk_u8_f32(q1, (unsigned)e, w[2 + n]); }
;                     __builtin_nontemporal_store(w, (u32x4*)(G0 + off));
;                 }
	v_mul_f32_e32 v155, 0xbfb8aa3b, v161
	v_add_f32_e32 v149, 0.5, v149
	v_exp_f32_e32 v156, v156
	v_exp_f32_e32 v153, v153
	v_min_f32_e32 v155, 0x42200000, v155
	v_max_f32_e32 v149, 1.0, v149
	v_add_f32_e32 v154, 0.5, v154
	v_exp_f32_e32 v155, v155
	v_cvt_pk_u8_f32 v149, v149, 0, 0
	v_max_f32_e32 v154, 1.0, v154
	v_add_f32_e32 v152, 0.5, v152
	s_add_i32 s0, s27, 0x90
	v_cvt_pk_u8_f32 v149, v154, 1, v149
	v_max_f32_e32 v152, 1.0, v152
	s_ashr_i32 s44, s0, 4
	v_fmamk_f32 v154, v156, 0x3b808081, v194
	v_cvt_pk_u8_f32 v149, v152, 2, v149
	v_fmamk_f32 v152, v153, 0x3b808081, v194
	v_rcp_f32_e32 v154, v154
	v_rcp_f32_e32 v152, v152
	v_fmamk_f32 v153, v155, 0x3b808081, v194
	s_ashr_i32 s45, s44, 31
	v_rcp_f32_e32 v153, v153
	s_lshl_b64 s[0:1], s[44:45], 15
	s_add_u32 s0, s58, s0
	s_addc_u32 s1, s59, s1
	v_add_f32_e32 v154, 0.5, v154
	v_add_f32_e32 v152, 0.5, v152
	s_add_u32 s0, s0, s42
	v_cvt_pk_u8_f32 v151, v154, 2, v151
	v_max_f32_e32 v152, 1.0, v152
	v_add_f32_e32 v153, 0.5, v153
	s_addc_u32 s1, s1, s43
	v_cvt_pk_u8_f32 v149, v152, 3, v149
	v_cvt_pk_u8_f32 v151, v153, 3, v151
	v_lshl_add_u64 v[152:153], s[0:1], 0, v[172:173]
	v_lshl_add_u64 v[152:153], v[152:153], 0, v[146:147]
	global_store_dwordx4 v[152:153], v[148:151], off nt
	v_pk_add_f32 v[158:159], v[26:27], v[134:135]
	v_pk_add_f32 v[156:157], v[28:29], v[136:137]
	v_pk_add_f32 v[150:151], v[22:23], v[142:143]
	v_mul_f32_e32 v158, 0xbfb8aa3b, v158
	v_mul_f32_e32 v150, 0xbfb8aa3b, v150
	v_min_f32_e32 v150, 0x42200000, v150
	v_mul_f32_e32 v151, 0xbfb8aa3b, v151
	v_exp_f32_e32 v150, v150
	v_min_f32_e32 v151, 0x42200000, v151
	v_exp_f32_e32 v151, v151
	v_min_f32_e32 v158, 0x42200000, v158
	v_fmamk_f32 v150, v150, 0x3b808081, v194
	v_rcp_f32_e32 v150, v150
	v_mul_f32_e32 v159, 0xbfb8aa3b, v159
	v_fmamk_f32 v151, v151, 0x3b808081, v194
	v_exp_f32_e32 v158, v158
	v_min_f32_e32 v159, 0x42200000, v159
	v_rcp_f32_e32 v151, v151
	v_mul_f32_e32 v156, 0xbfb8aa3b, v156
	v_exp_f32_e32 v159, v159
	v_min_f32_e32 v156, 0x42200000, v156
	v_exp_f32_e32 v156, v156
	v_pk_add_f32 v[148:149], v[24:25], v[144:145]
	v_add_f32_e32 v150, 0.5, v150
	v_fmamk_f32 v158, v158, 0x3b808081, v194
	v_max_f32_e32 v150, 1.0, v150
	v_add_f32_e32 v151, 0.5, v151
	v_mul_f32_e32 v148, 0xbfb8aa3b, v148
	v_rcp_f32_e32 v158, v158
	v_cvt_pk_u8_f32 v150, v150, 0, 0
	v_fmamk_f32 v159, v159, 0x3b808081, v194
	v_max_f32_e32 v151, 1.0, v151
	v_min_f32_e32 v148, 0x42200000, v148
	v_mul_f32_e32 v149, 0xbfb8aa3b, v149
	v_rcp_f32_e32 v159, v159
	v_exp_f32_e32 v148, v148
	v_cvt_pk_u8_f32 v150, v151, 1, v150
	v_fmamk_f32 v151, v156, 0x3b808081, v194
	v_min_f32_e32 v149, 0x42200000, v149
	v_rcp_f32_e32 v151, v151
	v_exp_f32_e32 v149, v149
	v_add_f32_e32 v158, 0.5, v158
	v_cvt_pk_u8_f32 v158, v158, 0, 0
	v_add_f32_e32 v159, 0.5, v159
	v_fmamk_f32 v148, v148, 0x3b808081, v194
	v_pk_add_f32 v[154:155], v[18:19], v[138:139]
	v_pk_add_f32 v[198:199], v[30:31], v[130:131]
	v_rcp_f32_e32 v148, v148
	v_cvt_pk_u8_f32 v156, v159, 1, v158
	v_add_f32_e32 v151, 0.5, v151
	v_mul_f32_e32 v157, 0xbfb8aa3b, v157
	v_fmamk_f32 v149, v149, 0x3b808081, v194
	v_min_f32_e32 v157, 0x42200000, v157
	v_rcp_f32_e32 v149, v149
	v_cvt_pk_u8_f32 v151, v151, 2, v156
	v_mul_f32_e32 v154, 0xbfb8aa3b, v154
	v_mul_f32_e32 v156, 0xbfb8aa3b, v198
	v_exp_f32_e32 v157, v157
	v_min_f32_e32 v154, 0x42200000, v154
	v_min_f32_e32 v156, 0x42200000, v156
	v_exp_f32_e32 v154, v154
	v_exp_f32_e32 v156, v156
	v_add_f32_e32 v148, 0.5, v148
	v_max_f32_e32 v148, 1.0, v148
	v_add_f32_e32 v149, 0.5, v149
	v_cvt_pk_u8_f32 v148, v148, 2, v150
	v_fmamk_f32 v150, v157, 0x3b808081, v194
	v_max_f32_e32 v149, 1.0, v149
	v_rcp_f32_e32 v150, v150
	v_cvt_pk_u8_f32 v148, v149, 3, v148
	v_fmamk_f32 v149, v154, 0x3b808081, v194
	v_fmamk_f32 v154, v156, 0x3b808081, v194
	v_rcp_f32_e32 v154, v154
	v_add_f32_e32 v150, 0.5, v150
	v_cvt_pk_u8_f32 v150, v150, 3, v151
	v_pk_add_f32 v[152:153], v[20:21], v[140:141]
	v_add_f32_e32 v151, 0.5, v154
	v_mul_f32_e32 v154, 0xbfb8aa3b, v155
	v_mul_f32_e32 v155, 0xbfb8aa3b, v199
	v_min_f32_e32 v155, 0x42200000, v155
	v_exp_f32_e32 v155, v155
	v_min_f32_e32 v154, 0x42200000, v154
	v_mul_f32_e32 v152, 0xbfb8aa3b, v152
	v_exp_f32_e32 v154, v154
	v_min_f32_e32 v152, 0x42200000, v152
	v_fmamk_f32 v155, v155, 0x3b808081, v194
	v_exp_f32_e32 v152, v152
	v_rcp_f32_e32 v155, v155
	v_rcp_f32_e32 v149, v149
	v_fmamk_f32 v154, v154, 0x3b808081, v194
	v_pk_add_f32 v[160:161], v[32:33], v[132:133]
	v_rcp_f32_e32 v154, v154
	v_fmamk_f32 v152, v152, 0x3b808081, v194
	v_cvt_pk_u8_f32 v151, v151, 0, 0
	v_add_f32_e32 v155, 0.5, v155
	v_mul_f32_e32 v156, 0xbfb8aa3b, v160
	v_rcp_f32_e32 v152, v152
	v_mul_f32_e32 v153, 0xbfb8aa3b, v153
	v_min_f32_e32 v156, 0x42200000, v156
	v_cvt_pk_u8_f32 v151, v155, 1, v151
	v_min_f32_e32 v153, 0x42200000, v153
	v_mul_f32_e32 v155, 0xbfb8aa3b, v161
	v_add_f32_e32 v149, 0.5, v149
	v_exp_f32_e32 v156, v156
	v_exp_f32_e32 v153, v153
	v_min_f32_e32 v155, 0x42200000, v155
	v_max_f32_e32 v149, 1.0, v149
	v_add_f32_e32 v154, 0.5, v154
	v_exp_f32_e32 v155, v155
	v_cvt_pk_u8_f32 v149, v149, 0, 0
	v_max_f32_e32 v154, 1.0, v154
	v_add_f32_e32 v152, 0.5, v152
	s_add_i32 s0, s27, 0xa0
	v_cvt_pk_u8_f32 v149, v154, 1, v149
	v_max_f32_e32 v152, 1.0, v152
	s_ashr_i32 s44, s0, 4
	v_fmamk_f32 v154, v156, 0x3b808081, v194
	v_cvt_pk_u8_f32 v149, v152, 2, v149
	v_fmamk_f32 v152, v153, 0x3b808081, v194
	v_rcp_f32_e32 v154, v154
	v_rcp_f32_e32 v152, v152
	v_fmamk_f32 v153, v155, 0x3b808081, v194
	s_ashr_i32 s45, s44, 31
	v_rcp_f32_e32 v153, v153
	s_lshl_b64 s[0:1], s[44:45], 15
	v_pk_add_f32 v[134:135], v[10:11], v[134:135]
	s_add_u32 s0, s58, s0
	v_mul_f32_e32 v134, 0xbfb8aa3b, v134
;     __device__ __forceinline__ void operator()(const Acc& acc, const Unit& u, int wr, int wc, int fr, int fq) const {
;     ...
; #pragma unroll
;             for (int ai = 0; ai < 2; ++ai)
; #pragma unroll
;                 for (int m = 0; m < 4; ++m) {
;                     const int grow = row0 + ai * HALF + m * 16;
;                     const size_t off = ((size_t)(grow >> 4) * 32 + (col0 >> 5)) * 512 + (grow & 15) * 32 + (col0 & 31);
;                     f32x4 z0[2] = {acc[ai][0][m][0] + ba0, acc[ai][0][m][1] + ba1}, z1[2] = {acc[ai][1][m][0] + bb0, acc[ai][1][m][1] + bb1};
;                     u32x4 w = {0u, 0u, 0u, 0u}; const float C255 = 1.0f / 255.0f;
; #pragma unroll
;                     for (int n = 0; n < 2; ++n)
; #pragma unroll
;                         for (int e = 0; e < 4; ++e) {
;                             const float e0 = __builtin_amdgcn_exp2f(fminf(z0[n][e] * NL2E, 40.f)), e1 = __builtin_amdgcn_exp2f(fminf(z1[n][e] * NL2E, 40.f));
;                             const float q0 = fmaxf(__builtin_amdgcn_rcpf(__builtin_fmaf(e0, C255, C255)) + 0.5f, 1.0f), q1 = __builtin_amdgcn_rcpf(__builtin_fmaf(e1, C255, C255)) + 0.5f;
;                             w[n] = __builtin_amdgcn_cvt_pk_u8_f32(q0, (unsigned)e, w[n]); w[2 + n] = __builtin_amdgcn_cvt_pk_u8_f32(q1, (unsigned)e, w[2 + n]); }
;                     __builtin_nontemporal_store(w, (u32x4*)(G0 + off));
;                 }
	s_addc_u32 s1, s59, s1
	v_min_f32_e32 v134, 0x42200000, v134
	v_add_f32_e32 v154, 0.5, v154
	v_add_f32_e32 v152, 0.5, v152
	s_add_u32 s0, s0, s42
	v_exp_f32_e32 v134, v134
	v_cvt_pk_u8_f32 v151, v154, 2, v151
	v_max_f32_e32 v152, 1.0, v152
	v_add_f32_e32 v153, 0.5, v153
	s_addc_u32 s1, s1, s43
	v_cvt_pk_u8_f32 v149, v152, 3, v149
	v_cvt_pk_u8_f32 v151, v153, 3, v151
	v_lshl_add_u64 v[152:153], s[0:1], 0, v[172:173]
	v_pk_add_f32 v[142:143], v[6:7], v[142:143]
	v_lshl_add_u64 v[152:153], v[152:153], 0, v[146:147]
	v_mul_f32_e32 v142, 0xbfb8aa3b, v142
	global_store_dwordx4 v[152:153], v[148:151], off nt
	v_min_f32_e32 v142, 0x42200000, v142
	v_exp_f32_e32 v142, v142
	v_pk_add_f32 v[148:149], v[16:17], v[132:133]
	v_fmamk_f32 v133, v134, 0x3b808081, v194
	v_mul_f32_e32 v134, 0xbfb8aa3b, v143
	v_min_f32_e32 v134, 0x42200000, v134
	v_pk_add_f32 v[136:137], v[12:13], v[136:137]
	v_exp_f32_e32 v134, v134
	v_mul_f32_e32 v135, 0xbfb8aa3b, v135
	v_min_f32_e32 v135, 0x42200000, v135
	v_mul_f32_e32 v136, 0xbfb8aa3b, v136
	v_exp_f32_e32 v135, v135
	v_min_f32_e32 v136, 0x42200000, v136
	v_fmamk_f32 v132, v142, 0x3b808081, v194
	v_exp_f32_e32 v136, v136
	v_pk_add_f32 v[144:145], v[8:9], v[144:145]
	v_rcp_f32_e32 v132, v132
	v_fmamk_f32 v134, v134, 0x3b808081, v194
	v_rcp_f32_e32 v134, v134
	v_mul_f32_e32 v142, 0xbfb8aa3b, v144
	v_rcp_f32_e32 v133, v133
	v_fmamk_f32 v135, v135, 0x3b808081, v194
	v_min_f32_e32 v142, 0x42200000, v142
	v_rcp_f32_e32 v135, v135
	v_exp_f32_e32 v142, v142
	v_fmamk_f32 v136, v136, 0x3b808081, v194
	v_add_f32_e32 v132, 0.5, v132
	v_rcp_f32_e32 v136, v136
	v_max_f32_e32 v132, 1.0, v132
	v_add_f32_e32 v134, 0.5, v134
	v_add_f32_e32 v133, 0.5, v133
	v_cvt_pk_u8_f32 v132, v132, 0, 0
	v_max_f32_e32 v134, 1.0, v134
	v_cvt_pk_u8_f32 v133, v133, 0, 0
	v_add_f32_e32 v135, 0.5, v135
	v_cvt_pk_u8_f32 v132, v134, 1, v132
	v_fmamk_f32 v134, v142, 0x3b808081, v194
	v_rcp_f32_e32 v134, v134
	v_cvt_pk_u8_f32 v133, v135, 1, v133
	v_add_f32_e32 v135, 0.5, v136
	v_mul_f32_e32 v136, 0xbfb8aa3b, v145
	v_mul_f32_e32 v137, 0xbfb8aa3b, v137
	v_min_f32_e32 v136, 0x42200000, v136
	v_min_f32_e32 v137, 0x42200000, v137
	v_exp_f32_e32 v136, v136
	v_exp_f32_e32 v137, v137
	v_add_f32_e32 v134, 0.5, v134
	v_max_f32_e32 v134, 1.0, v134
	v_cvt_pk_u8_f32 v132, v134, 2, v132
	v_fmamk_f32 v134, v136, 0x3b808081, v194
	v_fmamk_f32 v136, v137, 0x3b808081, v194
	v_rcp_f32_e32 v136, v136
	v_pk_add_f32 v[138:139], v[2:3], v[138:139]
	v_pk_add_f32 v[130:131], v[14:15], v[130:131]
	v_rcp_f32_e32 v134, v134
	v_cvt_pk_u8_f32 v133, v135, 2, v133
	v_add_f32_e32 v135, 0.5, v136
	v_mul_f32_e32 v136, 0xbfb8aa3b, v138
	v_min_f32_e32 v136, 0x42200000, v136
	v_mul_f32_e32 v130, 0xbfb8aa3b, v130
	v_exp_f32_e32 v136, v136
	v_min_f32_e32 v130, 0x42200000, v130
	v_exp_f32_e32 v137, v130
	v_add_f32_e32 v134, 0.5, v134
	v_max_f32_e32 v134, 1.0, v134
	v_cvt_pk_u8_f32 v130, v134, 3, v132
	v_fmamk_f32 v132, v136, 0x3b808081, v194
	v_rcp_f32_e32 v134, v132
	v_fmamk_f32 v132, v137, 0x3b808081, v194
	v_rcp_f32_e32 v136, v132
	v_cvt_pk_u8_f32 v132, v135, 3, v133
	v_mul_f32_e32 v135, 0xbfb8aa3b, v139
	v_min_f32_e32 v135, 0x42200000, v135
	v_exp_f32_e32 v135, v135
	v_pk_add_f32 v[140:141], v[4:5], v[140:141]
	v_mul_f32_e32 v131, 0xbfb8aa3b, v131
	v_add_f32_e32 v133, 0.5, v134
	v_fmamk_f32 v135, v135, 0x3b808081, v194
	v_add_f32_e32 v134, 0.5, v136
	v_min_f32_e32 v131, 0x42200000, v131
	v_rcp_f32_e32 v135, v135
	v_mul_f32_e32 v136, 0xbfb8aa3b, v140
	v_mul_f32_e32 v137, 0xbfb8aa3b, v148
	v_exp_f32_e32 v131, v131
	v_min_f32_e32 v136, 0x42200000, v136
	v_min_f32_e32 v137, 0x42200000, v137
	v_exp_f32_e32 v136, v136
	v_exp_f32_e32 v137, v137
	v_max_f32_e32 v133, 1.0, v133
	v_add_f32_e32 v135, 0.5, v135
	v_cvt_pk_u8_f32 v133, v133, 0, 0
	v_fmamk_f32 v131, v131, 0x3b808081, v194
	v_max_f32_e32 v135, 1.0, v135
	v_rcp_f32_e32 v131, v131
	v_cvt_pk_u8_f32 v133, v135, 1, v133
	v_fmamk_f32 v135, v136, 0x3b808081, v194
	v_fmamk_f32 v136, v137, 0x3b808081, v194
	v_rcp_f32_e32 v135, v135
	v_rcp_f32_e32 v136, v136
	v_cvt_pk_u8_f32 v134, v134, 0, 0
	v_add_f32_e32 v131, 0.5, v131
	v_cvt_pk_u8_f32 v131, v131, 1, v134
	v_add_f32_e32 v134, 0.5, v135
	v_add_f32_e32 v135, 0.5, v136
	v_mul_f32_e32 v136, 0xbfb8aa3b, v141
	v_min_f32_e32 v136, 0x42200000, v136
	v_mul_f32_e32 v137, 0xbfb8aa3b, v149
	v_exp_f32_e32 v136, v136
	v_min_f32_e32 v137, 0x42200000, v137
	v_exp_f32_e32 v137, v137
	s_add_i32 s0, s27, 0xb0
	v_max_f32_e32 v134, 1.0, v134
	s_ashr_i32 s44, s0, 4
	v_cvt_pk_u8_f32 v133, v134, 2, v133
	v_fmamk_f32 v134, v136, 0x3b808081, v194
	v_rcp_f32_e32 v134, v134
	v_fmamk_f32 v136, v137, 0x3b808081, v194
	s_ashr_i32 s45, s44, 31
	v_rcp_f32_e32 v136, v136
	s_lshl_b64 s[0:1], s[44:45], 15
	s_add_u32 s0, s58, s0
	s_addc_u32 s1, s59, s1
	v_cvt_pk_u8_f32 v135, v135, 2, v131
	v_add_f32_e32 v131, 0.5, v134
	s_add_u32 s0, s0, s42
	v_max_f32_e32 v131, 1.0, v131
	v_add_f32_e32 v134, 0.5, v136
	s_addc_u32 s1, s1, s43
	v_cvt_pk_u8_f32 v131, v131, 3, v133
	v_cvt_pk_u8_f32 v133, v134, 3, v135
	v_lshl_add_u64 v[134:135], s[0:1], 0, v[172:173]
	v_lshl_add_u64 v[134:135], v[134:135], 0, v[146:147]
	global_store_dwordx4 v[134:135], v[130:133], off nt
	s_mov_b64 s[42:43], 0
; __device__ __forceinline__ u32x4 pack8(const f32x4 a, const f32x4 b) { u32x4 w; w.x = cvt_pk_bf16(a[0], a[1]); w.y = cvt_pk_bf16(a[2], a[3]); w.z = cvt_pk_bf16(b[0], b[1]); w.w = cvt_pk_bf16(b[2], b[3]); return w; }
;     __device__ __forceinline__ void operator()(const Acc& acc, const Unit& u, int wr, int wc, int fr, int fq) const {
;     ...
;             const int col0 = (pn - 8) * BM + wc * 32 + 8 * fq;
; #pragma unroll
;             for (int ai = 0; ai < 2; ++ai)
; #pragma unroll
;                 for (int m = 0; m < 4; ++m) { const int vrow = row0 + ai * HALF + m * 16; bf16_t* rowp = VB + ((size_t)(vrow >> 4) * 32 + (col0 >> 5)) * 512 + (vrow & 15) * 32 + (col0 & 31);
; #pragma unroll
;                     for (int bj = 0; bj < 2; ++bj) __builtin_nontemporal_store(pack8(acc[ai][bj][m][0], acc[ai][bj][m][1]), (u32x4*)(rowp + bj * (4 * 512))); }
.LBB0_237:
	s_andn2_b64 vcc, exec, s[42:43]
	s_cbranch_vccnz .LBB0_239
	s_lshl_b32 s0, s7, 8
	s_addk_i32 s0, 0xf800
	s_lshr_b32 s0, s0, 5
	s_ashr_i32 s44, s27, 4
	s_or_b32 s10, s0, s92
	s_ashr_i32 s45, s44, 31
	s_lshl_b64 s[42:43], s[10:11], 10
	s_lshl_b64 s[0:1], s[44:45], 15
	s_add_u32 s0, s74, s0
	s_addc_u32 s1, s75, s1
	s_add_u32 s0, s0, s42
	s_addc_u32 s1, s1, s43
	v_lshlrev_b32_e32 v172, 1, v176
	v_lshl_add_u64 v[130:131], s[0:1], 0, v[172:173]
	s_or_b32 s0, s44, 1
	s_ashr_i32 s1, s0, 31
	s_lshl_b64 s[0:1], s[0:1], 15
	v_lshlrev_b32_e32 v134, 1, v174
	v_mov_b32_e32 v135, v173
	s_add_u32 s0, s74, s0
	v_lshl_add_u64 v[136:137], v[130:131], 0, v[134:135]
	v_cvt_pk_bf16_f32 v130, v126, v127
	v_cvt_pk_bf16_f32 v131, v128, v129
	v_cvt_pk_bf16_f32 v132, v122, v123
	v_cvt_pk_bf16_f32 v133, v124, v125
	s_addc_u32 s1, s75, s1
	global_store_dwordx4 v[136:137], v[130:133], off nt
	v_add_co_u32_e32 v136, vcc, s65, v136
	s_add_u32 s0, s0, s42
	v_cvt_pk_bf16_f32 v130, v118, v119
	v_cvt_pk_bf16_f32 v131, v120, v121
	v_cvt_pk_bf16_f32 v132, v114, v115
	v_cvt_pk_bf16_f32 v133, v116, v117
	v_addc_co_u32_e32 v137, vcc, 0, v137, vcc
	s_addc_u32 s1, s1, s43
	global_store_dwordx4 v[136:137], v[130:133], off nt
	s_nop 1
	v_lshl_add_u64 v[130:131], s[0:1], 0, v[172:173]
	s_or_b32 s0, s44, 2
	s_ashr_i32 s1, s0, 31
	s_lshl_b64 s[0:1], s[0:1], 15
	s_add_u32 s0, s74, s0
	v_lshl_add_u64 v[136:137], v[130:131], 0, v[134:135]
	v_cvt_pk_bf16_f32 v130, v110, v111
	v_cvt_pk_bf16_f32 v131, v112, v113
	v_cvt_pk_bf16_f32 v132, v106, v107
	v_cvt_pk_bf16_f32 v133, v108, v109
	s_addc_u32 s1, s75, s1
	global_store_dwordx4 v[136:137], v[130:133], off nt
	v_add_co_u32_e32 v136, vcc, s65, v136
	s_add_u32 s0, s0, s42
	v_cvt_pk_bf16_f32 v130, v102, v103
	v_cvt_pk_bf16_f32 v131, v104, v105
	v_cvt_pk_bf16_f32 v132, v98, v99
	v_cvt_pk_bf16_f32 v133, v100, v101
	v_addc_co_u32_e32 v137, vcc, 0, v137, vcc
	s_addc_u32 s1, s1, s43
	global_store_dwordx4 v[136:137], v[130:133], off nt
	s_cmp_lg_u64 s[12:13], 0
	s_cbranch_scc0 .Lxs_p1a_1
	s_barrier
.Lxs_p1a_1:
	s_nop 1
	v_lshl_add_u64 v[130:131], s[0:1], 0, v[172:173]
	s_or_b32 s0, s44, 3
	s_ashr_i32 s1, s0, 31
	s_lshl_b64 s[0:1], s[0:1], 15
	s_add_u32 s0, s74, s0
	v_lshl_add_u64 v[136:137], v[130:131], 0, v[134:135]
	v_cvt_pk_bf16_f32 v130, v94, v95
	v_cvt_pk_bf16_f32 v131, v96, v97
	v_cvt_pk_bf16_f32 v132, v90, v91
	v_cvt_pk_bf16_f32 v133, v92, v93
	s_addc_u32 s1, s75, s1
	global_store_dwordx4 v[136:137], v[130:133], off nt
	v_add_co_u32_e32 v136, vcc, s65, v136
	s_add_u32 s0, s0, s42
	v_cvt_pk_bf16_f32 v130, v86, v87
	v_cvt_pk_bf16_f32 v131, v88, v89
	v_cvt_pk_bf16_f32 v132, v82, v83
	v_cvt_pk_bf16_f32 v133, v84, v85
	v_addc_co_u32_e32 v137, vcc, 0, v137, vcc
	s_addc_u32 s1, s1, s43
	global_store_dwordx4 v[136:137], v[130:133], off nt
	s_nop 1
	v_lshl_add_u64 v[130:131], s[0:1], 0, v[172:173]
	s_add_i32 s0, s27, 0x80
	s_ashr_i32 s0, s0, 4
	s_ashr_i32 s1, s0, 31
	s_lshl_b64 s[0:1], s[0:1], 15
	s_add_u32 s0, s74, s0
	v_lshl_add_u64 v[136:137], v[130:131], 0, v[134:135]
	v_cvt_pk_bf16_f32 v130, v78, v79
	v_cvt_pk_bf16_f32 v131, v80, v81
	v_cvt_pk_bf16_f32 v132, v74, v75
	v_cvt_pk_bf16_f32 v133, v76, v77
	s_addc_u32 s1, s75, s1
	global_store_dwordx4 v[136:137], v[130:133], off nt
	v_add_co_u32_e32 v136, vcc, s65, v136
	s_add_u32 s0, s0, s42
	v_cvt_pk_bf16_f32 v130, v70, v71
	v_cvt_pk_bf16_f32 v131, v72, v73
	v_cvt_pk_bf16_f32 v132, v66, v67
	v_cvt_pk_bf16_f32 v133, v68, v69
	v_addc_co_u32_e32 v137, vcc, 0, v137, vcc
	s_addc_u32 s1, s1, s43
	global_store_dwordx4 v[136:137], v[130:133], off nt
	s_nop 1
	v_lshl_add_u64 v[130:131], s[0:1], 0, v[172:173]
	s_add_i32 s0, s27, 0x90
	s_ashr_i32 s0, s0, 4
	s_ashr_i32 s1, s0, 31
	s_lshl_b64 s[0:1], s[0:1], 15
	s_add_u32 s0, s74, s0
	v_lshl_add_u64 v[136:137], v[130:131], 0, v[134:135]
	v_cvt_pk_bf16_f32 v130, v62, v63
	v_cvt_pk_bf16_f32 v131, v64, v65
	v_cvt_pk_bf16_f32 v132, v58, v59
	v_cvt_pk_bf16_f32 v133, v60, v61
	s_addc_u32 s1, s75, s1
	global_store_dwordx4 v[136:137], v[130:133], off nt
	v_add_co_u32_e32 v136, vcc, s65, v136
	s_add_u32 s0, s0, s42
	v_cvt_pk_bf16_f32 v130, v54, v55
	v_cvt_pk_bf16_f32 v131, v56, v57
	v_cvt_pk_bf16_f32 v132, v50, v51
	v_cvt_pk_bf16_f32 v133, v52, v53
	v_addc_co_u32_e32 v137, vcc, 0, v137, vcc
	s_addc_u32 s1, s1, s43
	global_store_dwordx4 v[136:137], v[130:133], off nt
	s_nop 1
	v_lshl_add_u64 v[130:131], s[0:1], 0, v[172:173]
	s_add_i32 s0, s27, 0xa0
	s_ashr_i32 s0, s0, 4
	s_ashr_i32 s1, s0, 31
	s_lshl_b64 s[0:1], s[0:1], 15
	s_add_u32 s0, s74, s0
	v_lshl_add_u64 v[136:137], v[130:131], 0, v[134:135]
	v_cvt_pk_bf16_f32 v130, v38, v39
	v_cvt_pk_bf16_f32 v131, v40, v41
	v_cvt_pk_bf16_f32 v132, v34, v35
	v_cvt_pk_bf16_f32 v133, v36, v37
	s_addc_u32 s1, s75, s1
	global_store_dwordx4 v[136:137], v[130:133], off nt
	v_add_co_u32_e32 v136, vcc, s65, v136
	s_add_u32 s0, s0, s42
	v_cvt_pk_bf16_f32 v130, v42, v43
	v_cvt_pk_bf16_f32 v131, v44, v45
	v_cvt_pk_bf16_f32 v132, v46, v47
	v_cvt_pk_bf16_f32 v133, v48, v49
	v_addc_co_u32_e32 v137, vcc, 0, v137, vcc
	s_addc_u32 s1, s1, s43
	global_store_dwordx4 v[136:137], v[130:133], off nt
	s_nop 1
	v_lshl_add_u64 v[130:131], s[0:1], 0, v[172:173]
	s_add_i32 s0, s27, 0xb0
	s_ashr_i32 s0, s0, 4
	s_ashr_i32 s1, s0, 31
	s_lshl_b64 s[0:1], s[0:1], 15
	s_add_u32 s0, s74, s0
	v_lshl_add_u64 v[136:137], v[130:131], 0, v[134:135]
	v_cvt_pk_bf16_f32 v130, v22, v23
	v_cvt_pk_bf16_f32 v131, v24, v25
	v_cvt_pk_bf16_f32 v132, v18, v19
	v_cvt_pk_bf16_f32 v133, v20, v21
	s_addc_u32 s1, s75, s1
	global_store_dwordx4 v[136:137], v[130:133], off nt
	v_add_co_u32_e32 v136, vcc, s65, v136
	s_add_u32 s0, s0, s42
	v_cvt_pk_bf16_f32 v130, v26, v27
	v_cvt_pk_bf16_f32 v131, v28, v29
	v_cvt_pk_bf16_f32 v132, v30, v31
	v_cvt_pk_bf16_f32 v133, v32, v33
	v_addc_co_u32_e32 v137, vcc, 0, v137, vcc
	s_addc_u32 s1, s1, s43
	global_store_dwordx4 v[136:137], v[130:133], off nt
	s_nop 1
	v_lshl_add_u64 v[130:131], s[0:1], 0, v[172:173]
	v_lshl_add_u64 v[134:135], v[130:131], 0, v[134:135]
	v_cvt_pk_bf16_f32 v130, v6, v7
	v_cvt_pk_bf16_f32 v131, v8, v9
	v_cvt_pk_bf16_f32 v132, v2, v3
	v_cvt_pk_bf16_f32 v133, v4, v5
	global_store_dwordx4 v[134:135], v[130:133], off nt
	v_add_co_u32_e32 v134, vcc, 0x1000, v134
	s_nop 0
	v_cvt_pk_bf16_f32 v130, v10, v11
	v_cvt_pk_bf16_f32 v131, v12, v13
	v_cvt_pk_bf16_f32 v132, v14, v15
	v_cvt_pk_bf16_f32 v133, v16, v17
	v_addc_co_u32_e32 v135, vcc, 0, v135, vcc
	global_store_dwordx4 v[134:135], v[130:133], off nt

; __device__ __forceinline__ u32x4 pack8(const f32x4 a, const f32x4 b) { u32x4 w; w.x = cvt_pk_bf16(a[0], a[1]); w.y = cvt_pk_bf16(a[2], a[3]); w.z = cvt_pk_bf16(b[0], b[1]); w.w = cvt_pk_bf16(b[2], b[3]); return w; }
;     __device__ __forceinline__ void operator()(const Acc& acc, const Unit& u, int wr, int wc, int fr, int fq) const {
;     ...
;             for (int ai = 0; ai < 2; ++ai) {
;                 const int sb = (row0 + ai * HALF) & (SEQ - 1);
;                 f32x4 c0 = *(const f32x4*)(ropec + sb * 32 + 8 * fq), c1 = *(const f32x4*)(ropec + sb * 32 + 8 * fq + 4);
;                 f32x4 s0 = *(const f32x4*)(ropes + sb * 32 + 8 * fq), s1 = *(const f32x4*)(ropes + sb * 32 + 8 * fq + 4);
; #pragma unroll
;                 for (int m = 0; m < 4; ++m) {
;                     const int row = row0 + ai * HALF + m * 16;
;                     if (m > 0) { const f32x4 nc0 = c0 * k0 - s0 * t0, ns0 = s0 * k0 + c0 * t0, nc1 = c1 * k1 - s1 * t1, ns1 = s1 * k1 + c1 * t1; c0 = nc0; s0 = ns0; c1 = nc1; s1 = ns1; }
;                     const f32x4 a0 = acc[ai][0][m][0], a1 = acc[ai][0][m][1], b0 = acc[ai][1][m][0], b1 = acc[ai][1][m][1];
;                     f32x4 q2 = a0 * a0 + a1 * a1 + b0 * b0 + b1 * b1; float ss = (q2[0] + q2[1]) + (q2[2] + q2[3]);
;                     ss = quad_sum(ss);
;                     const float rinv = __builtin_amdgcn_rsqf(ss * (1.0f / 64.0f) + EPS) * sc;
;                     const f32x4 y00 = a0 * rinv * gl0, y01 = a1 * rinv * gl1, y10 = b0 * rinv * gh0, y11 = b1 * rinv * gh1;
;                     const f32x4 o00 = y00 * c0 - y10 * s0, o01 = y01 * c1 - y11 * s1, o10 = y10 * c0 + y00 * s0, o11 = y11 * c1 + y01 * s1;
;                     bf16_t* rowp = (isq ? QO : KB) + ((size_t)(row >> 4) * 32 + hm * 2) * 512 + (row & 15) * 32 + 8 * fq;
;                     __builtin_nontemporal_store(pack8(o00, o01), (u32x4*)(rowp)); __builtin_nontemporal_store(pack8(o10, o11), (u32x4*)(rowp + 512));
.LBB0_240:
	v_or_b32_e32 v198, s27, v1
	v_lshlrev_b32_e32 v130, 7, v198
	v_and_b32_e32 v172, 0x3e780, v130
	v_lshl_add_u64 v[130:131], v[180:181], 0, v[172:173]
	global_load_dwordx4 v[200:203], v[130:131], off
	global_load_dwordx4 v[204:207], v[130:131], off offset:16
	v_lshl_add_u64 v[130:131], v[178:179], 0, v[172:173]
	global_load_dwordx4 v[208:211], v[130:131], off
	global_load_dwordx4 v[212:215], v[130:131], off offset:16
	v_pk_mul_f32 v[146:147], v[124:125], v[124:125]
	v_pk_mul_f32 v[148:149], v[122:123], v[122:123]
	v_pk_fma_f32 v[146:147], v[128:129], v[128:129], v[146:147]
	v_pk_fma_f32 v[148:149], v[126:127], v[126:127], v[148:149]
	v_pk_fma_f32 v[146:147], v[120:121], v[120:121], v[146:147]
	v_pk_fma_f32 v[148:149], v[118:119], v[118:119], v[148:149]
	v_pk_fma_f32 v[146:147], v[116:117], v[116:117], v[146:147]
	v_pk_fma_f32 v[148:149], v[114:115], v[114:115], v[148:149]
	v_add_f32_e32 v146, v146, v147
	v_add_f32_e32 v148, v148, v149
	v_add_f32_e32 v150, v148, v146
	s_lshl_b32 s0, s7, 2
	v_mov_b32_e32 v151, v150
	s_and_b32 s0, s0, 12
	s_nop 0
	v_permlane16_swap_b32_e32 v150, v151
	s_or_b32 s10, s0, s92
	v_add_f32_e32 v150, v150, v151
	s_cmp_lt_i32 s7, 4
	v_mov_b32_e32 v151, v150
	s_cselect_b64 vcc, -1, 0
	s_nop 0
	v_permlane32_swap_b32_e32 v150, v151
	s_and_b64 s[0:1], vcc, exec
	v_add_f32_e32 v150, v150, v151
	s_cselect_b32 s0, 0, 0x100
	v_fmamk_f32 v150, v150, 0x3c800000, v195
	v_add_u32_e32 v152, s0, v175
	v_rsq_f32_e32 v172, v150
	ds_read_b128 v[130:133], v177
	ds_read_b128 v[138:141], v177 offset:16
	ds_read_b128 v[134:137], v190
	ds_read_b128 v[142:145], v190 offset:16
	s_cselect_b32 s43, s83, s85
	s_cselect_b32 s42, s82, s84
	s_ashr_i32 s44, s27, 4
	ds_read_b128 v[154:157], v152
	ds_read_b128 v[146:149], v152 offset:16
	ds_read_b128 v[158:161], v152 offset:128
	ds_read_b128 v[150:153], v152 offset:144
	s_ashr_i32 s45, s44, 31
	v_cndmask_b32_e32 v197, 1.0, v196, vcc
	s_lshl_b64 s[0:1], s[44:45], 15
	s_add_u32 s0, s42, s0
	v_mul_f32_e32 v172, v197, v172
	v_pk_mul_f32 v[124:125], v[124:125], v[172:173] op_sel_hi:[1,0]
	v_pk_mul_f32 v[122:123], v[122:123], v[172:173] op_sel_hi:[1,0]
	v_pk_mul_f32 v[118:119], v[118:119], v[172:173] op_sel_hi:[1,0]
	v_pk_mul_f32 v[120:121], v[120:121], v[172:173] op_sel_hi:[1,0]
	v_pk_mul_f32 v[114:115], v[114:115], v[172:173] op_sel_hi:[1,0]
	v_pk_mul_f32 v[116:117], v[116:117], v[172:173] op_sel_hi:[1,0]
	s_addc_u32 s1, s43, s1
	s_lshl_b32 s10, s10, 11
	v_pk_mul_f32 v[128:129], v[128:129], v[172:173] op_sel_hi:[1,0]
	v_pk_mul_f32 v[126:127], v[126:127], v[172:173] op_sel_hi:[1,0]
	s_waitcnt lgkmcnt(0)
	v_pk_mul_f32 v[122:123], v[146:147], v[122:123]
	v_pk_mul_f32 v[124:125], v[148:149], v[124:125]
	v_pk_mul_f32 v[120:121], v[160:161], v[120:121]
	v_pk_mul_f32 v[118:119], v[158:159], v[118:119]
	v_pk_mul_f32 v[116:117], v[152:153], v[116:117]
	v_pk_mul_f32 v[114:115], v[150:151], v[114:115]
	s_add_u32 s0, s0, s10
	v_pk_mul_f32 v[126:127], v[154:155], v[126:127]
	v_pk_mul_f32 v[128:129], v[156:157], v[128:129]
	s_addc_u32 s1, s1, 0
	v_lshlrev_b32_e32 v172, 1, v176
	s_waitcnt vmcnt(0)
	s_cmp_lg_u64 s[12:13], 0
	s_cbranch_scc0 .Lxs_p1a_0
	s_barrier
.Lxs_p1a_0:
	v_pk_mul_f32 v[216:217], v[200:201], v[118:119]
	v_pk_mul_f32 v[218:219], v[202:203], v[120:121]
	v_pk_mul_f32 v[220:221], v[204:205], v[114:115]
	v_pk_mul_f32 v[222:223], v[206:207], v[116:117]
	v_pk_mul_f32 v[228:229], v[204:205], v[122:123]
	v_pk_mul_f32 v[230:231], v[206:207], v[124:125]
	v_pk_mul_f32 v[224:225], v[200:201], v[126:127]
	v_pk_mul_f32 v[226:227], v[202:203], v[128:129]
	v_pk_fma_f32 v[128:129], v[210:211], v[128:129], v[218:219] neg_lo:[0,0,1] neg_hi:[0,0,1]
	v_pk_fma_f32 v[126:127], v[208:209], v[126:127], v[216:217] neg_lo:[0,0,1] neg_hi:[0,0,1]
	v_pk_fma_f32 v[124:125], v[214:215], v[124:125], v[222:223] neg_lo:[0,0,1] neg_hi:[0,0,1]
	v_pk_fma_f32 v[122:123], v[212:213], v[122:123], v[220:221] neg_lo:[0,0,1] neg_hi:[0,0,1]
	v_pk_fma_f32 v[218:219], v[214:215], v[116:117], v[230:231]
	v_pk_fma_f32 v[220:221], v[212:213], v[114:115], v[228:229]
	v_lshl_add_u64 v[116:117], s[0:1], 0, v[172:173]
	v_lshlrev_b32_e32 v114, 1, v174
	v_mov_b32_e32 v115, v173
	v_pk_fma_f32 v[120:121], v[210:211], v[120:121], v[226:227]
	v_pk_fma_f32 v[216:217], v[208:209], v[118:119], v[224:225]
	v_lshl_add_u64 v[222:223], v[116:117], 0, v[114:115]
	v_cvt_pk_bf16_f32 v116, v126, v127
	v_cvt_pk_bf16_f32 v117, v128, v129
	v_cvt_pk_bf16_f32 v118, v122, v123
	v_cvt_pk_bf16_f32 v119, v124, v125
	global_store_dwordx4 v[222:223], v[116:119], off nt
	v_pk_mul_f32 v[122:123], v[130:131], v[200:201]
	s_or_b32 s0, s44, 1
	v_cvt_pk_bf16_f32 v116, v216, v217
	v_cvt_pk_bf16_f32 v117, v120, v121
	v_cvt_pk_bf16_f32 v118, v220, v221
	v_cvt_pk_bf16_f32 v119, v218, v219
	global_store_dwordx4 v[222:223], v[116:119], off offset:1024 nt
	v_pk_mul_f32 v[120:121], v[132:133], v[202:203]
	s_ashr_i32 s1, s0, 31
	v_pk_mul_f32 v[116:117], v[136:137], v[202:203]
	v_pk_mul_f32 v[118:119], v[134:135], v[200:201]
	v_pk_mul_f32 v[200:201], v[108:109], v[108:109]
	v_pk_mul_f32 v[202:203], v[106:107], v[106:107]
	v_pk_fma_f32 v[200:201], v[112:113], v[112:113], v[200:201]
	v_pk_fma_f32 v[202:203], v[110:111], v[110:111], v[202:203]
	v_pk_fma_f32 v[200:201], v[104:105], v[104:105], v[200:201]
	v_pk_fma_f32 v[202:203], v[102:103], v[102:103], v[202:203]
	v_pk_fma_f32 v[200:201], v[100:101], v[100:101], v[200:201]
	v_pk_fma_f32 v[202:203], v[98:99], v[98:99], v[202:203]
	v_add_f32_e32 v200, v200, v201
	v_add_f32_e32 v199, v202, v203
	v_add_f32_e32 v199, v199, v200
	v_mov_b32_e32 v200, v199
	s_nop 1
	v_permlane16_swap_b32_e32 v199, v200
	v_add_f32_e32 v199, v199, v200
; __device__ __forceinline__ u32x4 pack8(const f32x4 a, const f32x4 b) { u32x4 w; w.x = cvt_pk_bf16(a[0], a[1]); w.y = cvt_pk_bf16(a[2], a[3]); w.z = cvt_pk_bf16(b[0], b[1]); w.w = cvt_pk_bf16(b[2], b[3]); return w; }
;     __device__ __forceinline__ void operator()(const Acc& acc, const Unit& u, int wr, int wc, int fr, int fq) const {
;     ...
;                 for (int m = 0; m < 4; ++m) {
;                     const int row = row0 + ai * HALF + m * 16;
;                     if (m > 0) { const f32x4 nc0 = c0 * k0 - s0 * t0, ns0 = s0 * k0 + c0 * t0, nc1 = c1 * k1 - s1 * t1, ns1 = s1 * k1 + c1 * t1; c0 = nc0; s0 = ns0; c1 = nc1; s1 = ns1; }
;                     const f32x4 a0 = acc[ai][0][m][0], a1 = acc[ai][0][m][1], b0 = acc[ai][1][m][0], b1 = acc[ai][1][m][1];
;                     f32x4 q2 = a0 * a0 + a1 * a1 + b0 * b0 + b1 * b1; float ss = (q2[0] + q2[1]) + (q2[2] + q2[3]);
;                     ss = quad_sum(ss);
;                     const float rinv = __builtin_amdgcn_rsqf(ss * (1.0f / 64.0f) + EPS) * sc;
;                     const f32x4 y00 = a0 * rinv * gl0, y01 = a1 * rinv * gl1, y10 = b0 * rinv * gh0, y11 = b1 * rinv * gh1;
;                     const f32x4 o00 = y00 * c0 - y10 * s0, o01 = y01 * c1 - y11 * s1, o10 = y10 * c0 + y00 * s0, o11 = y11 * c1 + y01 * s1;
;                     bf16_t* rowp = (isq ? QO : KB) + ((size_t)(row >> 4) * 32 + hm * 2) * 512 + (row & 15) * 32 + 8 * fq;
;                     __builtin_nontemporal_store(pack8(o00, o01), (u32x4*)(rowp)); __builtin_nontemporal_store(pack8(o10, o11), (u32x4*)(rowp + 512));
	v_mov_b32_e32 v200, v199
	s_nop 1
	v_permlane32_swap_b32_e32 v199, v200
	v_add_f32_e32 v199, v199, v200
	v_fmamk_f32 v199, v199, 0x3c800000, v195
	v_rsq_f32_e32 v199, v199
	s_lshl_b64 s[0:1], s[0:1], 15
	v_pk_mul_f32 v[200:201], v[138:139], v[204:205]
	s_add_u32 s0, s42, s0
	v_mul_f32_e32 v202, v197, v199
	v_pk_mul_f32 v[98:99], v[98:99], v[202:203] op_sel_hi:[1,0]
	v_pk_mul_f32 v[126:127], v[142:143], v[204:205]
	v_pk_mul_f32 v[128:129], v[140:141], v[206:207]
	v_pk_fma_f32 v[200:201], v[142:143], v[212:213], v[200:201]
	v_pk_mul_f32 v[106:107], v[106:107], v[202:203] op_sel_hi:[1,0]
	v_pk_mul_f32 v[104:105], v[104:105], v[202:203] op_sel_hi:[1,0]
	v_pk_mul_f32 v[102:103], v[102:103], v[202:203] op_sel_hi:[1,0]
	v_pk_mul_f32 v[100:101], v[100:101], v[202:203] op_sel_hi:[1,0]
	v_pk_mul_f32 v[98:99], v[150:151], v[98:99]
	s_addc_u32 s1, s43, s1
	v_pk_fma_f32 v[118:119], v[130:131], v[208:209], v[118:119] neg_lo:[0,0,1] neg_hi:[0,0,1]
	v_pk_fma_f32 v[120:121], v[136:137], v[210:211], v[120:121]
	v_pk_fma_f32 v[122:123], v[134:135], v[208:209], v[122:123]
	v_pk_mul_f32 v[124:125], v[144:145], v[206:207]
	v_pk_fma_f32 v[126:127], v[138:139], v[212:213], v[126:127] neg_lo:[0,0,1] neg_hi:[0,0,1]
	v_pk_fma_f32 v[128:129], v[144:145], v[214:215], v[128:129]
	v_pk_mul_f32 v[112:113], v[112:113], v[202:203] op_sel_hi:[1,0]
	v_pk_mul_f32 v[110:111], v[110:111], v[202:203] op_sel_hi:[1,0]
	v_pk_mul_f32 v[108:109], v[108:109], v[202:203] op_sel_hi:[1,0]
	v_pk_mul_f32 v[106:107], v[146:147], v[106:107]
	v_pk_mul_f32 v[102:103], v[158:159], v[102:103]
	v_pk_mul_f32 v[104:105], v[160:161], v[104:105]
	v_pk_mul_f32 v[100:101], v[152:153], v[100:101]
	v_pk_mul_f32 v[208:209], v[200:201], v[98:99]
	s_add_u32 s0, s0, s10
	v_pk_fma_f32 v[116:117], v[132:133], v[210:211], v[116:117] neg_lo:[0,0,1] neg_hi:[0,0,1]
	v_pk_fma_f32 v[124:125], v[140:141], v[214:215], v[124:125] neg_lo:[0,0,1] neg_hi:[0,0,1]
	v_pk_mul_f32 v[110:111], v[154:155], v[110:111]
	v_pk_mul_f32 v[112:113], v[156:157], v[112:113]
	v_pk_mul_f32 v[108:109], v[148:149], v[108:109]
	v_pk_mul_f32 v[202:203], v[120:121], v[104:105]
	v_pk_mul_f32 v[204:205], v[122:123], v[102:103]
	v_pk_mul_f32 v[206:207], v[128:129], v[100:101]
	v_pk_fma_f32 v[208:209], v[126:127], v[106:107], v[208:209] neg_lo:[0,0,1] neg_hi:[0,0,1]
	v_pk_mul_f32 v[106:107], v[200:201], v[106:107]
	s_addc_u32 s1, s1, 0
	v_pk_fma_f32 v[202:203], v[116:117], v[112:113], v[202:203] neg_lo:[0,0,1] neg_hi:[0,0,1]
	v_pk_fma_f32 v[204:205], v[118:119], v[110:111], v[204:205] neg_lo:[0,0,1] neg_hi:[0,0,1]
	v_pk_fma_f32 v[206:207], v[124:125], v[108:109], v[206:207] neg_lo:[0,0,1] neg_hi:[0,0,1]
	v_pk_mul_f32 v[112:113], v[120:121], v[112:113]
	v_pk_mul_f32 v[110:111], v[122:123], v[110:111]
	v_pk_mul_f32 v[108:109], v[128:129], v[108:109]
	v_pk_fma_f32 v[106:107], v[126:127], v[98:99], v[106:107]
	v_lshl_add_u64 v[98:99], s[0:1], 0, v[172:173]
	v_pk_fma_f32 v[104:105], v[116:117], v[104:105], v[112:113]
	v_pk_fma_f32 v[102:103], v[118:119], v[102:103], v[110:111]
	v_pk_fma_f32 v[108:109], v[124:125], v[100:101], v[108:109]
	v_lshl_add_u64 v[110:111], v[98:99], 0, v[114:115]
	v_cvt_pk_bf16_f32 v98, v204, v205
	v_cvt_pk_bf16_f32 v99, v202, v203
	v_cvt_pk_bf16_f32 v100, v208, v209
	v_cvt_pk_bf16_f32 v101, v206, v207
	global_store_dwordx4 v[110:111], v[98:101], off nt
	v_pk_mul_f32 v[112:113], v[92:93], v[92:93]
	s_or_b32 s0, s44, 2
	v_cvt_pk_bf16_f32 v98, v102, v103
	v_cvt_pk_bf16_f32 v99, v104, v105
	v_cvt_pk_bf16_f32 v100, v106, v107
	v_cvt_pk_bf16_f32 v101, v108, v109
	global_store_dwordx4 v[110:111], v[98:101], off offset:1024 nt
	v_pk_mul_f32 v[102:103], v[136:137], v[116:117]
	v_pk_fma_f32 v[112:113], v[96:97], v[96:97], v[112:113]
	v_pk_mul_f32 v[98:99], v[136:137], v[120:121]
	v_pk_fma_f32 v[112:113], v[88:89], v[88:89], v[112:113]
	v_pk_fma_f32 v[98:99], v[132:133], v[116:117], v[98:99] neg_lo:[0,0,1] neg_hi:[0,0,1]
	v_pk_mul_f32 v[116:117], v[90:91], v[90:91]
	v_pk_fma_f32 v[112:113], v[84:85], v[84:85], v[112:113]
	v_pk_fma_f32 v[116:117], v[94:95], v[94:95], v[116:117]
	v_add_f32_e32 v112, v112, v113
	v_pk_fma_f32 v[116:117], v[86:87], v[86:87], v[116:117]
	s_ashr_i32 s1, s0, 31
	v_pk_fma_f32 v[116:117], v[82:83], v[82:83], v[116:117]
	s_lshl_b64 s[0:1], s[0:1], 15
	v_add_f32_e32 v116, v116, v117
	v_add_f32_e32 v112, v116, v112
	v_mov_b32_e32 v113, v112
	s_nop 1
	v_permlane16_swap_b32_e32 v112, v113
	v_add_f32_e32 v112, v112, v113
	v_mov_b32_e32 v113, v112
	s_nop 1
	v_permlane32_swap_b32_e32 v112, v113
	v_add_f32_e32 v112, v112, v113
	v_fmamk_f32 v112, v112, 0x3c800000, v195
	v_rsq_f32_e32 v116, v112
	v_pk_mul_f32 v[112:113], v[142:143], v[126:127]
	s_add_u32 s0, s42, s0
	v_pk_mul_f32 v[104:105], v[134:135], v[118:119]
	v_mul_f32_e32 v116, v197, v116
	v_pk_mul_f32 v[82:83], v[82:83], v[116:117] op_sel_hi:[1,0]
	v_pk_mul_f32 v[108:109], v[142:143], v[200:201]
	v_pk_mul_f32 v[110:111], v[144:145], v[124:125]
	v_pk_fma_f32 v[112:113], v[138:139], v[200:201], v[112:113]
	v_pk_mul_f32 v[90:91], v[90:91], v[116:117] op_sel_hi:[1,0]
	v_pk_mul_f32 v[86:87], v[86:87], v[116:117] op_sel_hi:[1,0]
	v_pk_mul_f32 v[88:89], v[88:89], v[116:117] op_sel_hi:[1,0]
	v_pk_mul_f32 v[84:85], v[84:85], v[116:117] op_sel_hi:[1,0]
	v_pk_mul_f32 v[82:83], v[150:151], v[82:83]
	s_addc_u32 s1, s43, s1
	v_pk_mul_f32 v[100:101], v[134:135], v[122:123]
	v_pk_fma_f32 v[102:103], v[132:133], v[120:121], v[102:103]
	v_pk_fma_f32 v[104:105], v[130:131], v[122:123], v[104:105]
	v_pk_mul_f32 v[106:107], v[144:145], v[128:129]
	v_pk_fma_f32 v[108:109], v[138:139], v[126:127], v[108:109] neg_lo:[0,0,1] neg_hi:[0,0,1]
	v_pk_fma_f32 v[110:111], v[140:141], v[128:129], v[110:111]
; __device__ __forceinline__ u32x4 pack8(const f32x4 a, const f32x4 b) { u32x4 w; w.x = cvt_pk_bf16(a[0], a[1]); w.y = cvt_pk_bf16(a[2], a[3]); w.z = cvt_pk_bf16(b[0], b[1]); w.w = cvt_pk_bf16(b[2], b[3]); return w; }
;     __device__ __forceinline__ void operator()(const Acc& acc, const Unit& u, int wr, int wc, int fr, int fq) const {
;     ...
;                 for (int m = 0; m < 4; ++m) {
;                     const int row = row0 + ai * HALF + m * 16;
;                     if (m > 0) { const f32x4 nc0 = c0 * k0 - s0 * t0, ns0 = s0 * k0 + c0 * t0, nc1 = c1 * k1 - s1 * t1, ns1 = s1 * k1 + c1 * t1; c0 = nc0; s0 = ns0; c1 = nc1; s1 = ns1; }
;                     const f32x4 a0 = acc[ai][0][m][0], a1 = acc[ai][0][m][1], b0 = acc[ai][1][m][0], b1 = acc[ai][1][m][1];
;                     f32x4 q2 = a0 * a0 + a1 * a1 + b0 * b0 + b1 * b1; float ss = (q2[0] + q2[1]) + (q2[2] + q2[3]);
;                     ss = quad_sum(ss);
;                     const float rinv = __builtin_amdgcn_rsqf(ss * (1.0f / 64.0f) + EPS) * sc;
;                     const f32x4 y00 = a0 * rinv * gl0, y01 = a1 * rinv * gl1, y10 = b0 * rinv * gh0, y11 = b1 * rinv * gh1;
;                     const f32x4 o00 = y00 * c0 - y10 * s0, o01 = y01 * c1 - y11 * s1, o10 = y10 * c0 + y00 * s0, o11 = y11 * c1 + y01 * s1;
;                     bf16_t* rowp = (isq ? QO : KB) + ((size_t)(row >> 4) * 32 + hm * 2) * 512 + (row & 15) * 32 + 8 * fq;
;                     __builtin_nontemporal_store(pack8(o00, o01), (u32x4*)(rowp)); __builtin_nontemporal_store(pack8(o10, o11), (u32x4*)(rowp + 512));
	v_pk_mul_f32 v[96:97], v[96:97], v[116:117] op_sel_hi:[1,0]
	v_pk_mul_f32 v[94:95], v[94:95], v[116:117] op_sel_hi:[1,0]
	v_pk_mul_f32 v[92:93], v[92:93], v[116:117] op_sel_hi:[1,0]
	v_pk_mul_f32 v[90:91], v[146:147], v[90:91]
	v_pk_mul_f32 v[88:89], v[160:161], v[88:89]
	v_pk_mul_f32 v[86:87], v[158:159], v[86:87]
	v_pk_mul_f32 v[84:85], v[152:153], v[84:85]
	v_pk_mul_f32 v[120:121], v[112:113], v[82:83]
	s_add_u32 s0, s0, s10
	v_pk_fma_f32 v[100:101], v[130:131], v[118:119], v[100:101] neg_lo:[0,0,1] neg_hi:[0,0,1]
	v_pk_fma_f32 v[106:107], v[140:141], v[124:125], v[106:107] neg_lo:[0,0,1] neg_hi:[0,0,1]
	v_pk_mul_f32 v[94:95], v[154:155], v[94:95]
	v_pk_mul_f32 v[96:97], v[156:157], v[96:97]
	v_pk_mul_f32 v[92:93], v[148:149], v[92:93]
	v_pk_mul_f32 v[116:117], v[104:105], v[86:87]
	v_pk_mul_f32 v[118:119], v[102:103], v[88:89]
	v_pk_mul_f32 v[122:123], v[110:111], v[84:85]
	v_pk_fma_f32 v[120:121], v[108:109], v[90:91], v[120:121] neg_lo:[0,0,1] neg_hi:[0,0,1]
	v_pk_mul_f32 v[90:91], v[112:113], v[90:91]
	s_addc_u32 s1, s1, 0
	v_pk_fma_f32 v[118:119], v[98:99], v[96:97], v[118:119] neg_lo:[0,0,1] neg_hi:[0,0,1]
	v_pk_fma_f32 v[116:117], v[100:101], v[94:95], v[116:117] neg_lo:[0,0,1] neg_hi:[0,0,1]
	v_pk_fma_f32 v[122:123], v[106:107], v[92:93], v[122:123] neg_lo:[0,0,1] neg_hi:[0,0,1]
	v_pk_mul_f32 v[94:95], v[104:105], v[94:95]
	v_pk_mul_f32 v[96:97], v[102:103], v[96:97]
	v_pk_mul_f32 v[92:93], v[110:111], v[92:93]
	v_pk_fma_f32 v[90:91], v[108:109], v[82:83], v[90:91]
	v_lshl_add_u64 v[82:83], s[0:1], 0, v[172:173]
	v_pk_fma_f32 v[88:89], v[98:99], v[88:89], v[96:97]
	v_pk_fma_f32 v[86:87], v[100:101], v[86:87], v[94:95]
	v_pk_fma_f32 v[92:93], v[106:107], v[84:85], v[92:93]
	v_lshl_add_u64 v[94:95], v[82:83], 0, v[114:115]
	v_cvt_pk_bf16_f32 v82, v116, v117
	v_cvt_pk_bf16_f32 v83, v118, v119
	v_cvt_pk_bf16_f32 v84, v120, v121
	v_cvt_pk_bf16_f32 v85, v122, v123
	global_store_dwordx4 v[94:95], v[82:85], off nt
	v_pk_mul_f32 v[96:97], v[76:77], v[76:77]
	s_or_b32 s0, s44, 3
	v_cvt_pk_bf16_f32 v82, v86, v87
	v_cvt_pk_bf16_f32 v83, v88, v89
	v_cvt_pk_bf16_f32 v84, v90, v91
	v_cvt_pk_bf16_f32 v85, v92, v93
	v_pk_mul_f32 v[90:91], v[136:137], v[98:99]
	global_store_dwordx4 v[94:95], v[82:85], off offset:1024 nt
	v_pk_fma_f32 v[90:91], v[132:133], v[102:103], v[90:91]
	v_pk_mul_f32 v[94:95], v[136:137], v[102:103]
	v_pk_mul_f32 v[102:103], v[74:75], v[74:75]
	v_pk_fma_f32 v[96:97], v[80:81], v[80:81], v[96:97]
	v_pk_fma_f32 v[102:103], v[78:79], v[78:79], v[102:103]
	v_pk_fma_f32 v[96:97], v[72:73], v[72:73], v[96:97]
	v_pk_fma_f32 v[102:103], v[70:71], v[70:71], v[102:103]
	v_pk_fma_f32 v[96:97], v[68:69], v[68:69], v[96:97]
	v_pk_fma_f32 v[102:103], v[66:67], v[66:67], v[102:103]
	v_add_f32_e32 v96, v96, v97
	v_add_f32_e32 v102, v102, v103
	v_add_f32_e32 v96, v102, v96
	v_mov_b32_e32 v97, v96
	s_nop 1
	v_permlane16_swap_b32_e32 v96, v97
	v_add_f32_e32 v96, v96, v97
	v_mov_b32_e32 v97, v96
	s_nop 1
	v_permlane32_swap_b32_e32 v96, v97
	v_add_f32_e32 v96, v96, v97
	v_fmamk_f32 v96, v96, 0x3c800000, v195
	v_rsq_f32_e32 v102, v96
	s_ashr_i32 s1, s0, 31
	v_pk_fma_f32 v[94:95], v[132:133], v[98:99], v[94:95] neg_lo:[0,0,1] neg_hi:[0,0,1]
	s_lshl_b64 s[0:1], s[0:1], 15
	v_mul_f32_e32 v98, v197, v102
	v_pk_mul_f32 v[84:85], v[142:143], v[108:109]
	v_pk_mul_f32 v[66:67], v[66:67], v[98:99] op_sel_hi:[1,0]
	s_add_u32 s0, s42, s0
	v_pk_mul_f32 v[82:83], v[144:145], v[106:107]
	v_pk_fma_f32 v[84:85], v[138:139], v[112:113], v[84:85]
	v_pk_mul_f32 v[88:89], v[142:143], v[112:113]
	v_pk_mul_f32 v[92:93], v[134:135], v[100:101]
	v_pk_mul_f32 v[74:75], v[74:75], v[98:99] op_sel_hi:[1,0]
	v_pk_mul_f32 v[72:73], v[72:73], v[98:99] op_sel_hi:[1,0]
	v_pk_mul_f32 v[70:71], v[70:71], v[98:99] op_sel_hi:[1,0]
	v_pk_mul_f32 v[68:69], v[68:69], v[98:99] op_sel_hi:[1,0]
	v_pk_mul_f32 v[66:67], v[150:151], v[66:67]
	s_addc_u32 s1, s43, s1
	v_pk_fma_f32 v[82:83], v[140:141], v[110:111], v[82:83]
	v_pk_mul_f32 v[86:87], v[144:145], v[110:111]
	v_pk_fma_f32 v[88:89], v[138:139], v[108:109], v[88:89] neg_lo:[0,0,1] neg_hi:[0,0,1]
	v_pk_fma_f32 v[92:93], v[130:131], v[104:105], v[92:93]
	v_pk_mul_f32 v[96:97], v[134:135], v[104:105]
	v_pk_mul_f32 v[80:81], v[80:81], v[98:99] op_sel_hi:[1,0]
	v_pk_mul_f32 v[78:79], v[78:79], v[98:99] op_sel_hi:[1,0]
	v_pk_mul_f32 v[76:77], v[76:77], v[98:99] op_sel_hi:[1,0]
	v_pk_mul_f32 v[74:75], v[146:147], v[74:75]
	v_pk_mul_f32 v[70:71], v[158:159], v[70:71]
	v_pk_mul_f32 v[72:73], v[160:161], v[72:73]
	v_pk_mul_f32 v[68:69], v[152:153], v[68:69]
	v_pk_mul_f32 v[104:105], v[84:85], v[66:67]
	s_add_u32 s0, s0, s10
	v_pk_fma_f32 v[86:87], v[140:141], v[106:107], v[86:87] neg_lo:[0,0,1] neg_hi:[0,0,1]
	v_pk_fma_f32 v[96:97], v[130:131], v[100:101], v[96:97] neg_lo:[0,0,1] neg_hi:[0,0,1]
	v_pk_mul_f32 v[78:79], v[154:155], v[78:79]
	v_pk_mul_f32 v[80:81], v[156:157], v[80:81]
	v_pk_mul_f32 v[76:77], v[148:149], v[76:77]
	v_pk_mul_f32 v[98:99], v[90:91], v[72:73]
	v_pk_mul_f32 v[100:101], v[92:93], v[70:71]
	v_pk_mul_f32 v[102:103], v[82:83], v[68:69]
	v_pk_fma_f32 v[104:105], v[88:89], v[74:75], v[104:105] neg_lo:[0,0,1] neg_hi:[0,0,1]
	v_pk_mul_f32 v[74:75], v[84:85], v[74:75]
	s_addc_u32 s1, s1, 0
	v_pk_fma_f32 v[98:99], v[94:95], v[80:81], v[98:99] neg_lo:[0,0,1] neg_hi:[0,0,1]
	v_pk_fma_f32 v[100:101], v[96:97], v[78:79], v[100:101] neg_lo:[0,0,1] neg_hi:[0,0,1]
	v_pk_fma_f32 v[102:103], v[86:87], v[76:77], v[102:103] neg_lo:[0,0,1] neg_hi:[0,0,1]
	v_pk_mul_f32 v[80:81], v[90:91], v[80:81]
	v_pk_mul_f32 v[78:79], v[92:93], v[78:79]
	v_pk_mul_f32 v[76:77], v[82:83], v[76:77]
	v_pk_fma_f32 v[74:75], v[88:89], v[66:67], v[74:75]
; __device__ __forceinline__ u32x4 pack8(const f32x4 a, const f32x4 b) { u32x4 w; w.x = cvt_pk_bf16(a[0], a[1]); w.y = cvt_pk_bf16(a[2], a[3]); w.z = cvt_pk_bf16(b[0], b[1]); w.w = cvt_pk_bf16(b[2], b[3]); return w; }
;     __device__ __forceinline__ void operator()(const Acc& acc, const Unit& u, int wr, int wc, int fr, int fq) const {
;     ...
;             for (int ai = 0; ai < 2; ++ai) {
;                 const int sb = (row0 + ai * HALF) & (SEQ - 1);
;                 f32x4 c0 = *(const f32x4*)(ropec + sb * 32 + 8 * fq), c1 = *(const f32x4*)(ropec + sb * 32 + 8 * fq + 4);
;                 f32x4 s0 = *(const f32x4*)(ropes + sb * 32 + 8 * fq), s1 = *(const f32x4*)(ropes + sb * 32 + 8 * fq + 4);
; #pragma unroll
;                 for (int m = 0; m < 4; ++m) {
;                     const int row = row0 + ai * HALF + m * 16;
;                     if (m > 0) { const f32x4 nc0 = c0 * k0 - s0 * t0, ns0 = s0 * k0 + c0 * t0, nc1 = c1 * k1 - s1 * t1, ns1 = s1 * k1 + c1 * t1; c0 = nc0; s0 = ns0; c1 = nc1; s1 = ns1; }
;                     const f32x4 a0 = acc[ai][0][m][0], a1 = acc[ai][0][m][1], b0 = acc[ai][1][m][0], b1 = acc[ai][1][m][1];
;                     f32x4 q2 = a0 * a0 + a1 * a1 + b0 * b0 + b1 * b1; float ss = (q2[0] + q2[1]) + (q2[2] + q2[3]);
;                     ss = quad_sum(ss);
;                     const float rinv = __builtin_amdgcn_rsqf(ss * (1.0f / 64.0f) + EPS) * sc;
;                     const f32x4 y00 = a0 * rinv * gl0, y01 = a1 * rinv * gl1, y10 = b0 * rinv * gh0, y11 = b1 * rinv * gh1;
;                     const f32x4 o00 = y00 * c0 - y10 * s0, o01 = y01 * c1 - y11 * s1, o10 = y10 * c0 + y00 * s0, o11 = y11 * c1 + y01 * s1;
;                     bf16_t* rowp = (isq ? QO : KB) + ((size_t)(row >> 4) * 32 + hm * 2) * 512 + (row & 15) * 32 + 8 * fq;
;                     __builtin_nontemporal_store(pack8(o00, o01), (u32x4*)(rowp)); __builtin_nontemporal_store(pack8(o10, o11), (u32x4*)(rowp + 512));
	v_lshl_add_u64 v[66:67], s[0:1], 0, v[172:173]
	v_pk_fma_f32 v[72:73], v[94:95], v[72:73], v[80:81]
	v_pk_fma_f32 v[70:71], v[96:97], v[70:71], v[78:79]
	v_pk_fma_f32 v[76:77], v[86:87], v[68:69], v[76:77]
	v_lshl_add_u64 v[78:79], v[66:67], 0, v[114:115]
	v_cvt_pk_bf16_f32 v66, v100, v101
	v_cvt_pk_bf16_f32 v67, v98, v99
	v_cvt_pk_bf16_f32 v68, v104, v105
	v_cvt_pk_bf16_f32 v69, v102, v103
	global_store_dwordx4 v[78:79], v[66:69], off nt
	v_add_u32_e32 v90, 0x80, v198
	v_pk_mul_f32 v[82:83], v[60:61], v[60:61]
	v_cvt_pk_bf16_f32 v66, v70, v71
	v_cvt_pk_bf16_f32 v67, v72, v73
	v_cvt_pk_bf16_f32 v68, v74, v75
	v_cvt_pk_bf16_f32 v69, v76, v77
	global_store_dwordx4 v[78:79], v[66:69], off offset:1024 nt
	v_mov_b32_e32 v71, v173
	v_pk_mul_f32 v[84:85], v[58:59], v[58:59]
	v_lshlrev_b32_e32 v66, 7, v90
	v_and_b32_e32 v70, 0x3e780, v66
	v_lshl_add_u64 v[74:75], v[180:181], 0, v[70:71]
	v_lshl_add_u64 v[78:79], v[178:179], 0, v[70:71]
	global_load_dwordx4 v[66:69], v[74:75], off
	global_load_dwordx4 v[70:73], v[78:79], off
	s_nop 0
	global_load_dwordx4 v[74:77], v[74:75], off offset:16
	s_nop 0
	global_load_dwordx4 v[78:81], v[78:79], off offset:16
	v_pk_fma_f32 v[82:83], v[64:65], v[64:65], v[82:83]
	v_pk_fma_f32 v[84:85], v[62:63], v[62:63], v[84:85]
	v_pk_fma_f32 v[82:83], v[56:57], v[56:57], v[82:83]
	v_pk_fma_f32 v[84:85], v[54:55], v[54:55], v[84:85]
	v_pk_fma_f32 v[82:83], v[52:53], v[52:53], v[82:83]
	v_pk_fma_f32 v[84:85], v[50:51], v[50:51], v[84:85]
	v_add_f32_e32 v82, v82, v83
	v_add_f32_e32 v84, v84, v85
	v_add_f32_e32 v82, v84, v82
	v_mov_b32_e32 v83, v82
	s_nop 1
	v_permlane16_swap_b32_e32 v82, v83
	v_add_f32_e32 v82, v82, v83
	v_mov_b32_e32 v83, v82
	s_nop 1
	v_permlane32_swap_b32_e32 v82, v83
	v_add_f32_e32 v82, v82, v83
	v_fmamk_f32 v82, v82, 0x3c800000, v195
	v_rsq_f32_e32 v82, v82
	s_add_i32 s0, s27, 0x90
	s_ashr_i32 s0, s0, 4
	s_ashr_i32 s1, s0, 31
	v_mul_f32_e32 v82, v197, v82
	v_pk_mul_f32 v[50:51], v[50:51], v[82:83] op_sel_hi:[1,0]
	v_pk_mul_f32 v[58:59], v[58:59], v[82:83] op_sel_hi:[1,0]
	v_pk_mul_f32 v[50:51], v[150:151], v[50:51]
	v_pk_mul_f32 v[58:59], v[146:147], v[58:59]
	v_pk_mul_f32 v[54:55], v[54:55], v[82:83] op_sel_hi:[1,0]
	v_pk_mul_f32 v[56:57], v[56:57], v[82:83] op_sel_hi:[1,0]
	v_pk_mul_f32 v[52:53], v[52:53], v[82:83] op_sel_hi:[1,0]
	v_pk_mul_f32 v[64:65], v[64:65], v[82:83] op_sel_hi:[1,0]
	v_pk_mul_f32 v[62:63], v[62:63], v[82:83] op_sel_hi:[1,0]
	v_pk_mul_f32 v[60:61], v[60:61], v[82:83] op_sel_hi:[1,0]
	v_pk_mul_f32 v[56:57], v[160:161], v[56:57]
	v_pk_mul_f32 v[54:55], v[158:159], v[54:55]
	v_pk_mul_f32 v[52:53], v[152:153], v[52:53]
	v_pk_mul_f32 v[62:63], v[154:155], v[62:63]
	v_pk_mul_f32 v[64:65], v[156:157], v[64:65]
	v_pk_mul_f32 v[60:61], v[148:149], v[60:61]
	s_lshl_b64 s[0:1], s[0:1], 15
	s_add_u32 s0, s42, s0
	s_addc_u32 s1, s43, s1
	s_add_u32 s0, s0, s10
	s_addc_u32 s1, s1, 0
	s_waitcnt vmcnt(1)
	v_pk_mul_f32 v[86:87], v[74:75], v[50:51]
	s_waitcnt vmcnt(0)
	v_pk_fma_f32 v[86:87], v[78:79], v[58:59], v[86:87] neg_lo:[0,0,1] neg_hi:[0,0,1]
	v_pk_mul_f32 v[58:59], v[74:75], v[58:59]
	v_pk_mul_f32 v[82:83], v[66:67], v[54:55]
	v_pk_fma_f32 v[58:59], v[78:79], v[50:51], v[58:59]
	v_ashrrev_i32_e32 v50, 4, v90
	v_ashrrev_i32_e32 v51, 31, v50
	v_lshlrev_b64 v[50:51], 15, v[50:51]
	v_lshl_add_u64 v[50:51], s[42:43], 0, v[50:51]
	v_pk_mul_f32 v[84:85], v[68:69], v[56:57]
	v_pk_mul_f32 v[88:89], v[76:77], v[52:53]
	v_lshl_add_u64 v[50:51], v[50:51], 0, s[10:11]
	v_pk_fma_f32 v[84:85], v[72:73], v[64:65], v[84:85] neg_lo:[0,0,1] neg_hi:[0,0,1]
	v_pk_fma_f32 v[82:83], v[70:71], v[62:63], v[82:83] neg_lo:[0,0,1] neg_hi:[0,0,1]
	v_pk_fma_f32 v[88:89], v[80:81], v[60:61], v[88:89] neg_lo:[0,0,1] neg_hi:[0,0,1]
	v_pk_mul_f32 v[62:63], v[66:67], v[62:63]
	v_pk_mul_f32 v[64:65], v[68:69], v[64:65]
	v_pk_mul_f32 v[60:61], v[76:77], v[60:61]
	v_lshl_add_u64 v[50:51], v[50:51], 0, v[172:173]
	v_pk_fma_f32 v[56:57], v[72:73], v[56:57], v[64:65]
	v_pk_fma_f32 v[54:55], v[70:71], v[54:55], v[62:63]
	v_pk_fma_f32 v[60:61], v[80:81], v[52:53], v[60:61]
	v_lshl_add_u64 v[62:63], v[50:51], 0, v[114:115]
	v_cvt_pk_bf16_f32 v50, v82, v83
	v_cvt_pk_bf16_f32 v51, v84, v85
	v_cvt_pk_bf16_f32 v52, v86, v87
	v_cvt_pk_bf16_f32 v53, v88, v89
	global_store_dwordx4 v[62:63], v[50:53], off nt
	v_pk_mul_f32 v[64:65], v[36:37], v[36:37]
	s_nop 0
	v_cvt_pk_bf16_f32 v50, v54, v55
	v_cvt_pk_bf16_f32 v51, v56, v57
	v_cvt_pk_bf16_f32 v52, v58, v59
	v_cvt_pk_bf16_f32 v53, v60, v61
	global_store_dwordx4 v[62:63], v[50:53], off offset:1024 nt
	v_pk_mul_f32 v[56:57], v[130:131], v[66:67]
	v_pk_fma_f32 v[64:65], v[40:41], v[40:41], v[64:65]
	v_pk_mul_f32 v[52:53], v[134:135], v[66:67]
	v_pk_mul_f32 v[66:67], v[34:35], v[34:35]
	v_pk_fma_f32 v[64:65], v[44:45], v[44:45], v[64:65]
	v_pk_fma_f32 v[66:67], v[38:39], v[38:39], v[66:67]
	v_pk_fma_f32 v[64:65], v[48:49], v[48:49], v[64:65]
	v_pk_fma_f32 v[66:67], v[42:43], v[42:43], v[66:67]
	v_add_f32_e32 v64, v64, v65
	v_pk_fma_f32 v[66:67], v[46:47], v[46:47], v[66:67]
	v_pk_mul_f32 v[54:55], v[132:133], v[68:69]
	v_add_f32_e32 v66, v66, v67
	v_add_f32_e32 v64, v66, v64
	v_mov_b32_e32 v65, v64
	s_nop 1
	v_permlane16_swap_b32_e32 v64, v65
	v_add_f32_e32 v64, v64, v65
	v_mov_b32_e32 v65, v64
	s_nop 1
	v_permlane32_swap_b32_e32 v64, v65
	v_add_f32_e32 v64, v64, v65
	v_fmamk_f32 v64, v64, 0x3c800000, v195
	v_rsq_f32_e32 v66, v64
	v_pk_mul_f32 v[64:65], v[138:139], v[74:75]
	v_pk_mul_f32 v[50:51], v[136:137], v[68:69]
	v_pk_fma_f32 v[54:55], v[136:137], v[72:73], v[54:55]
	v_mul_f32_e32 v66, v197, v66
	v_pk_mul_f32 v[44:45], v[44:45], v[66:67] op_sel_hi:[1,0]
	v_pk_mul_f32 v[46:47], v[46:47], v[66:67] op_sel_hi:[1,0]
; __device__ __forceinline__ u32x4 pack8(const f32x4 a, const f32x4 b) { u32x4 w; w.x = cvt_pk_bf16(a[0], a[1]); w.y = cvt_pk_bf16(a[2], a[3]); w.z = cvt_pk_bf16(b[0], b[1]); w.w = cvt_pk_bf16(b[2], b[3]); return w; }
;     __device__ __forceinline__ void operator()(const Acc& acc, const Unit& u, int wr, int wc, int fr, int fq) const {
;     ...
;                 for (int m = 0; m < 4; ++m) {
;                     const int row = row0 + ai * HALF + m * 16;
;                     if (m > 0) { const f32x4 nc0 = c0 * k0 - s0 * t0, ns0 = s0 * k0 + c0 * t0, nc1 = c1 * k1 - s1 * t1, ns1 = s1 * k1 + c1 * t1; c0 = nc0; s0 = ns0; c1 = nc1; s1 = ns1; }
;                     const f32x4 a0 = acc[ai][0][m][0], a1 = acc[ai][0][m][1], b0 = acc[ai][1][m][0], b1 = acc[ai][1][m][1];
;                     f32x4 q2 = a0 * a0 + a1 * a1 + b0 * b0 + b1 * b1; float ss = (q2[0] + q2[1]) + (q2[2] + q2[3]);
;                     ss = quad_sum(ss);
;                     const float rinv = __builtin_amdgcn_rsqf(ss * (1.0f / 64.0f) + EPS) * sc;
;                     const f32x4 y00 = a0 * rinv * gl0, y01 = a1 * rinv * gl1, y10 = b0 * rinv * gh0, y11 = b1 * rinv * gh1;
;                     const f32x4 o00 = y00 * c0 - y10 * s0, o01 = y01 * c1 - y11 * s1, o10 = y10 * c0 + y00 * s0, o11 = y11 * c1 + y01 * s1;
;                     bf16_t* rowp = (isq ? QO : KB) + ((size_t)(row >> 4) * 32 + hm * 2) * 512 + (row & 15) * 32 + 8 * fq;
;                     __builtin_nontemporal_store(pack8(o00, o01), (u32x4*)(rowp)); __builtin_nontemporal_store(pack8(o10, o11), (u32x4*)(rowp + 512));
	v_pk_mul_f32 v[60:61], v[142:143], v[74:75]
	v_pk_mul_f32 v[62:63], v[140:141], v[76:77]
	v_pk_fma_f32 v[64:65], v[142:143], v[78:79], v[64:65]
	v_pk_mul_f32 v[40:41], v[40:41], v[66:67] op_sel_hi:[1,0]
	v_pk_mul_f32 v[34:35], v[34:35], v[66:67] op_sel_hi:[1,0]
	v_pk_mul_f32 v[42:43], v[42:43], v[66:67] op_sel_hi:[1,0]
	v_pk_mul_f32 v[44:45], v[160:161], v[44:45]
	v_pk_mul_f32 v[48:49], v[48:49], v[66:67] op_sel_hi:[1,0]
	v_pk_mul_f32 v[46:47], v[150:151], v[46:47]
	v_pk_fma_f32 v[50:51], v[132:133], v[72:73], v[50:51] neg_lo:[0,0,1] neg_hi:[0,0,1]
	v_pk_fma_f32 v[56:57], v[134:135], v[70:71], v[56:57]
	v_pk_mul_f32 v[58:59], v[144:145], v[76:77]
	v_pk_fma_f32 v[60:61], v[138:139], v[78:79], v[60:61] neg_lo:[0,0,1] neg_hi:[0,0,1]
	v_pk_fma_f32 v[62:63], v[144:145], v[80:81], v[62:63]
	v_pk_mul_f32 v[38:39], v[38:39], v[66:67] op_sel_hi:[1,0]
	v_pk_mul_f32 v[40:41], v[156:157], v[40:41]
	v_pk_mul_f32 v[36:37], v[36:37], v[66:67] op_sel_hi:[1,0]
	v_pk_mul_f32 v[34:35], v[146:147], v[34:35]
	v_pk_mul_f32 v[42:43], v[158:159], v[42:43]
	v_pk_mul_f32 v[48:49], v[152:153], v[48:49]
	v_pk_mul_f32 v[66:67], v[54:55], v[44:45]
	v_pk_mul_f32 v[72:73], v[64:65], v[46:47]
	v_pk_fma_f32 v[52:53], v[130:131], v[70:71], v[52:53] neg_lo:[0,0,1] neg_hi:[0,0,1]
	v_pk_fma_f32 v[58:59], v[140:141], v[80:81], v[58:59] neg_lo:[0,0,1] neg_hi:[0,0,1]
	v_pk_mul_f32 v[38:39], v[154:155], v[38:39]
	v_pk_mul_f32 v[36:37], v[148:149], v[36:37]
	v_pk_mul_f32 v[68:69], v[56:57], v[42:43]
	v_pk_fma_f32 v[66:67], v[50:51], v[40:41], v[66:67] neg_lo:[0,0,1] neg_hi:[0,0,1]
	v_pk_mul_f32 v[70:71], v[62:63], v[48:49]
	v_pk_fma_f32 v[72:73], v[60:61], v[34:35], v[72:73] neg_lo:[0,0,1] neg_hi:[0,0,1]
	v_pk_mul_f32 v[40:41], v[54:55], v[40:41]
	v_pk_mul_f32 v[34:35], v[64:65], v[34:35]
	v_pk_fma_f32 v[68:69], v[52:53], v[38:39], v[68:69] neg_lo:[0,0,1] neg_hi:[0,0,1]
	v_pk_fma_f32 v[70:71], v[58:59], v[36:37], v[70:71] neg_lo:[0,0,1] neg_hi:[0,0,1]
	v_pk_mul_f32 v[38:39], v[56:57], v[38:39]
	v_pk_fma_f32 v[40:41], v[50:51], v[44:45], v[40:41]
	v_pk_mul_f32 v[36:37], v[62:63], v[36:37]
	v_pk_fma_f32 v[44:45], v[60:61], v[46:47], v[34:35]
	v_lshl_add_u64 v[34:35], s[0:1], 0, v[172:173]
	v_pk_fma_f32 v[38:39], v[52:53], v[42:43], v[38:39]
	v_pk_fma_f32 v[42:43], v[58:59], v[48:49], v[36:37]
	v_lshl_add_u64 v[46:47], v[34:35], 0, v[114:115]
	v_cvt_pk_bf16_f32 v34, v68, v69
	v_cvt_pk_bf16_f32 v35, v66, v67
	v_cvt_pk_bf16_f32 v36, v72, v73
	v_cvt_pk_bf16_f32 v37, v70, v71
	global_store_dwordx4 v[46:47], v[34:37], off nt
	v_pk_mul_f32 v[48:49], v[20:21], v[20:21]
	s_add_i32 s0, s27, 0xa0
	v_cvt_pk_bf16_f32 v34, v38, v39
	v_cvt_pk_bf16_f32 v35, v40, v41
	v_cvt_pk_bf16_f32 v36, v44, v45
	v_cvt_pk_bf16_f32 v37, v42, v43
	global_store_dwordx4 v[46:47], v[34:37], off offset:1024 nt
	v_pk_mul_f32 v[38:39], v[136:137], v[50:51]
	v_pk_fma_f32 v[48:49], v[24:25], v[24:25], v[48:49]
	v_pk_mul_f32 v[34:35], v[136:137], v[54:55]
	v_pk_fma_f32 v[48:49], v[28:29], v[28:29], v[48:49]
	v_pk_fma_f32 v[34:35], v[132:133], v[50:51], v[34:35] neg_lo:[0,0,1] neg_hi:[0,0,1]
	v_pk_mul_f32 v[50:51], v[18:19], v[18:19]
	v_pk_fma_f32 v[48:49], v[32:33], v[32:33], v[48:49]
	v_pk_fma_f32 v[50:51], v[22:23], v[22:23], v[50:51]
	v_add_f32_e32 v48, v48, v49
	v_pk_fma_f32 v[50:51], v[26:27], v[26:27], v[50:51]
	s_ashr_i32 s0, s0, 4
	v_pk_fma_f32 v[50:51], v[30:31], v[30:31], v[50:51]
	s_ashr_i32 s1, s0, 31
	v_add_f32_e32 v50, v50, v51
	v_add_f32_e32 v48, v50, v48
	v_mov_b32_e32 v49, v48
	s_nop 1
	v_permlane16_swap_b32_e32 v48, v49
	v_add_f32_e32 v48, v48, v49
	v_mov_b32_e32 v49, v48
	s_nop 1
	v_permlane32_swap_b32_e32 v48, v49
	v_add_f32_e32 v48, v48, v49
	v_fmamk_f32 v48, v48, 0x3c800000, v195
	v_rsq_f32_e32 v50, v48
	s_lshl_b64 s[0:1], s[0:1], 15
	v_pk_mul_f32 v[48:49], v[142:143], v[60:61]
	s_add_u32 s0, s42, s0
	v_mul_f32_e32 v50, v197, v50
	v_pk_mul_f32 v[28:29], v[28:29], v[50:51] op_sel_hi:[1,0]
	v_pk_mul_f32 v[30:31], v[30:31], v[50:51] op_sel_hi:[1,0]
	v_pk_mul_f32 v[36:37], v[134:135], v[56:57]
	v_pk_mul_f32 v[40:41], v[134:135], v[52:53]
	v_pk_fma_f32 v[38:39], v[132:133], v[54:55], v[38:39]
	v_pk_mul_f32 v[44:45], v[142:143], v[64:65]
	v_pk_mul_f32 v[46:47], v[144:145], v[58:59]
	v_pk_fma_f32 v[48:49], v[138:139], v[64:65], v[48:49]
	v_pk_mul_f32 v[24:25], v[24:25], v[50:51] op_sel_hi:[1,0]
	v_pk_mul_f32 v[18:19], v[18:19], v[50:51] op_sel_hi:[1,0]
	v_pk_mul_f32 v[26:27], v[26:27], v[50:51] op_sel_hi:[1,0]
	v_pk_mul_f32 v[28:29], v[160:161], v[28:29]
	v_pk_mul_f32 v[32:33], v[32:33], v[50:51] op_sel_hi:[1,0]
	v_pk_mul_f32 v[30:31], v[150:151], v[30:31]
	s_addc_u32 s1, s43, s1
	v_pk_fma_f32 v[36:37], v[130:131], v[52:53], v[36:37] neg_lo:[0,0,1] neg_hi:[0,0,1]
	v_pk_fma_f32 v[40:41], v[130:131], v[56:57], v[40:41]
	v_pk_mul_f32 v[42:43], v[144:145], v[62:63]
	v_pk_fma_f32 v[44:45], v[138:139], v[60:61], v[44:45] neg_lo:[0,0,1] neg_hi:[0,0,1]
	v_pk_fma_f32 v[46:47], v[140:141], v[62:63], v[46:47]
	v_pk_mul_f32 v[22:23], v[22:23], v[50:51] op_sel_hi:[1,0]
	v_pk_mul_f32 v[24:25], v[156:157], v[24:25]
	v_pk_mul_f32 v[20:21], v[20:21], v[50:51] op_sel_hi:[1,0]
	v_pk_mul_f32 v[18:19], v[146:147], v[18:19]
	v_pk_mul_f32 v[26:27], v[158:159], v[26:27]
	v_pk_mul_f32 v[32:33], v[152:153], v[32:33]
	v_pk_mul_f32 v[52:53], v[38:39], v[28:29]
	v_pk_mul_f32 v[54:55], v[48:49], v[30:31]
	s_add_u32 s0, s0, s10
	v_pk_fma_f32 v[42:43], v[140:141], v[58:59], v[42:43] neg_lo:[0,0,1] neg_hi:[0,0,1]
	v_pk_mul_f32 v[22:23], v[154:155], v[22:23]
	v_pk_mul_f32 v[20:21], v[148:149], v[20:21]
; __device__ __forceinline__ u32x4 pack8(const f32x4 a, const f32x4 b) { u32x4 w; w.x = cvt_pk_bf16(a[0], a[1]); w.y = cvt_pk_bf16(a[2], a[3]); w.z = cvt_pk_bf16(b[0], b[1]); w.w = cvt_pk_bf16(b[2], b[3]); return w; }
; #define PG8_BAR __builtin_amdgcn_s_barrier()
; template <class Epi, bool ALIGN_EPI, bool SPLITA>
; __device__ __forceinline__ void gemm_phase(LAS unsigned char* lds, const Gemm g, const StaticOrder& S, const Epi& E) {
;     ...
;         if (!has_next) break;
; #pragma unroll
;         for (int a = 0; a < 2; ++a)
; #pragma unroll
;             for (int b = 0; b < 2; ++b)
; #pragma unroll
;                 for (int m = 0; m < 4; ++m)
; #pragma unroll
;                     for (int n = 0; n < 2; ++n) acc[a][b][m][n] = (f32x4){0.f, 0.f, 0.f, 0.f};
;         cur = nxt; cA = nA; cB = nB; mirC = mirN; if constexpr (SPLITA) cA2 = (const char*)g.A2 + (size_t)cur.pm * tstepA; ++ui;
;         if constexpr (ALIGN_EPI) { if (wr == 1) PG8_BAR; }
;     __device__ __forceinline__ void operator()(const Acc& acc, const Unit& u, int wr, int wc, int fr, int fq) const {
;     ...
;                 for (int m = 0; m < 4; ++m) {
;                     const int row = row0 + ai * HALF + m * 16;
;                     if (m > 0) { const f32x4 nc0 = c0 * k0 - s0 * t0, ns0 = s0 * k0 + c0 * t0, nc1 = c1 * k1 - s1 * t1, ns1 = s1 * k1 + c1 * t1; c0 = nc0; s0 = ns0; c1 = nc1; s1 = ns1; }
;                     const f32x4 a0 = acc[ai][0][m][0], a1 = acc[ai][0][m][1], b0 = acc[ai][1][m][0], b1 = acc[ai][1][m][1];
;                     f32x4 q2 = a0 * a0 + a1 * a1 + b0 * b0 + b1 * b1; float ss = (q2[0] + q2[1]) + (q2[2] + q2[3]);
;                     ss = quad_sum(ss);
;                     const float rinv = __builtin_amdgcn_rsqf(ss * (1.0f / 64.0f) + EPS) * sc;
;                     const f32x4 y00 = a0 * rinv * gl0, y01 = a1 * rinv * gl1, y10 = b0 * rinv * gh0, y11 = b1 * rinv * gh1;
;                     const f32x4 o00 = y00 * c0 - y10 * s0, o01 = y01 * c1 - y11 * s1, o10 = y10 * c0 + y00 * s0, o11 = y11 * c1 + y01 * s1;
;                     bf16_t* rowp = (isq ? QO : KB) + ((size_t)(row >> 4) * 32 + hm * 2) * 512 + (row & 15) * 32 + 8 * fq;
;                     __builtin_nontemporal_store(pack8(o00, o01), (u32x4*)(rowp)); __builtin_nontemporal_store(pack8(o10, o11), (u32x4*)(rowp + 512));
	v_pk_mul_f32 v[50:51], v[40:41], v[26:27]
	v_pk_fma_f32 v[52:53], v[34:35], v[24:25], v[52:53] neg_lo:[0,0,1] neg_hi:[0,0,1]
	v_pk_mul_f32 v[56:57], v[46:47], v[32:33]
	v_pk_fma_f32 v[54:55], v[44:45], v[18:19], v[54:55] neg_lo:[0,0,1] neg_hi:[0,0,1]
	v_pk_mul_f32 v[24:25], v[38:39], v[24:25]
	v_pk_mul_f32 v[18:19], v[48:49], v[18:19]
	s_addc_u32 s1, s1, 0
	v_pk_fma_f32 v[50:51], v[36:37], v[22:23], v[50:51] neg_lo:[0,0,1] neg_hi:[0,0,1]
	v_pk_fma_f32 v[56:57], v[42:43], v[20:21], v[56:57] neg_lo:[0,0,1] neg_hi:[0,0,1]
	v_pk_mul_f32 v[22:23], v[40:41], v[22:23]
	v_pk_fma_f32 v[24:25], v[34:35], v[28:29], v[24:25]
	v_pk_mul_f32 v[20:21], v[46:47], v[20:21]
	v_pk_fma_f32 v[28:29], v[44:45], v[30:31], v[18:19]
	v_lshl_add_u64 v[18:19], s[0:1], 0, v[172:173]
	v_pk_fma_f32 v[22:23], v[36:37], v[26:27], v[22:23]
	v_pk_fma_f32 v[26:27], v[42:43], v[32:33], v[20:21]
	v_lshl_add_u64 v[30:31], v[18:19], 0, v[114:115]
	v_cvt_pk_bf16_f32 v18, v50, v51
	v_cvt_pk_bf16_f32 v19, v52, v53
	v_cvt_pk_bf16_f32 v20, v54, v55
	v_cvt_pk_bf16_f32 v21, v56, v57
	global_store_dwordx4 v[30:31], v[18:21], off nt
	v_pk_mul_f32 v[32:33], v[4:5], v[4:5]
	s_addk_i32 s27, 0xb0
	v_cvt_pk_bf16_f32 v18, v22, v23
	v_cvt_pk_bf16_f32 v19, v24, v25
	v_cvt_pk_bf16_f32 v20, v28, v29
	v_cvt_pk_bf16_f32 v21, v26, v27
	v_pk_mul_f32 v[26:27], v[136:137], v[34:35]
	global_store_dwordx4 v[30:31], v[18:21], off offset:1024 nt
	v_pk_fma_f32 v[26:27], v[132:133], v[38:39], v[26:27]
	v_pk_mul_f32 v[30:31], v[136:137], v[38:39]
	v_pk_mul_f32 v[38:39], v[2:3], v[2:3]
	v_pk_fma_f32 v[32:33], v[8:9], v[8:9], v[32:33]
	v_pk_fma_f32 v[38:39], v[6:7], v[6:7], v[38:39]
	v_pk_fma_f32 v[32:33], v[12:13], v[12:13], v[32:33]
	v_pk_fma_f32 v[38:39], v[10:11], v[10:11], v[38:39]
	v_pk_fma_f32 v[32:33], v[16:17], v[16:17], v[32:33]
	v_pk_fma_f32 v[38:39], v[14:15], v[14:15], v[38:39]
	v_add_f32_e32 v32, v32, v33
	v_add_f32_e32 v38, v38, v39
	v_add_f32_e32 v32, v38, v32
	v_mov_b32_e32 v33, v32
	s_nop 1
	v_permlane16_swap_b32_e32 v32, v33
	v_add_f32_e32 v32, v32, v33
	v_mov_b32_e32 v33, v32
	s_nop 1
	v_permlane32_swap_b32_e32 v32, v33
	v_add_f32_e32 v32, v32, v33
	v_fmamk_f32 v32, v32, 0x3c800000, v195
	v_rsq_f32_e32 v38, v32
	s_ashr_i32 s0, s27, 4
	s_ashr_i32 s1, s0, 31
	v_pk_fma_f32 v[30:31], v[132:133], v[34:35], v[30:31] neg_lo:[0,0,1] neg_hi:[0,0,1]
	v_mul_f32_e32 v34, v197, v38
	s_lshl_b64 s[0:1], s[0:1], 15
	v_pk_mul_f32 v[20:21], v[142:143], v[44:45]
	v_pk_mul_f32 v[12:13], v[12:13], v[34:35] op_sel_hi:[1,0]
	v_pk_mul_f32 v[14:15], v[14:15], v[34:35] op_sel_hi:[1,0]
	s_add_u32 s0, s42, s0
	v_pk_mul_f32 v[18:19], v[144:145], v[42:43]
	v_pk_fma_f32 v[20:21], v[138:139], v[48:49], v[20:21]
	v_pk_mul_f32 v[24:25], v[142:143], v[48:49]
	v_pk_mul_f32 v[28:29], v[134:135], v[36:37]
	v_pk_mul_f32 v[8:9], v[8:9], v[34:35] op_sel_hi:[1,0]
	v_pk_mul_f32 v[2:3], v[2:3], v[34:35] op_sel_hi:[1,0]
	v_pk_mul_f32 v[10:11], v[10:11], v[34:35] op_sel_hi:[1,0]
	v_pk_mul_f32 v[12:13], v[160:161], v[12:13]
	v_pk_mul_f32 v[16:17], v[16:17], v[34:35] op_sel_hi:[1,0]
	v_pk_mul_f32 v[14:15], v[150:151], v[14:15]
	s_addc_u32 s1, s43, s1
	v_pk_fma_f32 v[18:19], v[140:141], v[46:47], v[18:19]
	v_pk_mul_f32 v[22:23], v[144:145], v[46:47]
	v_pk_fma_f32 v[24:25], v[138:139], v[44:45], v[24:25] neg_lo:[0,0,1] neg_hi:[0,0,1]
	v_pk_fma_f32 v[28:29], v[130:131], v[40:41], v[28:29]
	v_pk_mul_f32 v[32:33], v[134:135], v[40:41]
	v_pk_mul_f32 v[6:7], v[6:7], v[34:35] op_sel_hi:[1,0]
	v_pk_mul_f32 v[8:9], v[156:157], v[8:9]
	v_pk_mul_f32 v[4:5], v[4:5], v[34:35] op_sel_hi:[1,0]
	v_pk_mul_f32 v[2:3], v[146:147], v[2:3]
	v_pk_mul_f32 v[10:11], v[158:159], v[10:11]
	v_pk_mul_f32 v[16:17], v[152:153], v[16:17]
	v_pk_mul_f32 v[34:35], v[26:27], v[12:13]
	v_pk_mul_f32 v[40:41], v[20:21], v[14:15]
	s_add_u32 s0, s0, s10
	v_pk_fma_f32 v[22:23], v[140:141], v[42:43], v[22:23] neg_lo:[0,0,1] neg_hi:[0,0,1]
	v_pk_fma_f32 v[32:33], v[130:131], v[36:37], v[32:33] neg_lo:[0,0,1] neg_hi:[0,0,1]
	v_pk_mul_f32 v[6:7], v[154:155], v[6:7]
	v_pk_mul_f32 v[4:5], v[148:149], v[4:5]
	v_pk_mul_f32 v[36:37], v[28:29], v[10:11]
	v_pk_fma_f32 v[34:35], v[30:31], v[8:9], v[34:35] neg_lo:[0,0,1] neg_hi:[0,0,1]
	v_pk_mul_f32 v[38:39], v[18:19], v[16:17]
	v_pk_fma_f32 v[40:41], v[24:25], v[2:3], v[40:41] neg_lo:[0,0,1] neg_hi:[0,0,1]
	v_pk_mul_f32 v[8:9], v[26:27], v[8:9]
	v_pk_mul_f32 v[2:3], v[20:21], v[2:3]
	s_addc_u32 s1, s1, 0
	v_pk_fma_f32 v[36:37], v[32:33], v[6:7], v[36:37] neg_lo:[0,0,1] neg_hi:[0,0,1]
	v_pk_fma_f32 v[38:39], v[22:23], v[4:5], v[38:39] neg_lo:[0,0,1] neg_hi:[0,0,1]
	v_pk_mul_f32 v[6:7], v[28:29], v[6:7]
	v_pk_fma_f32 v[8:9], v[30:31], v[12:13], v[8:9]
	v_pk_mul_f32 v[4:5], v[18:19], v[4:5]
	v_pk_fma_f32 v[12:13], v[24:25], v[14:15], v[2:3]
	v_lshl_add_u64 v[2:3], s[0:1], 0, v[172:173]
	v_pk_fma_f32 v[6:7], v[32:33], v[10:11], v[6:7]
	v_pk_fma_f32 v[10:11], v[22:23], v[16:17], v[4:5]
	v_lshl_add_u64 v[14:15], v[2:3], 0, v[114:115]
	v_cvt_pk_bf16_f32 v2, v36, v37
	v_cvt_pk_bf16_f32 v3, v34, v35
	v_cvt_pk_bf16_f32 v4, v40, v41
	v_cvt_pk_bf16_f32 v5, v38, v39
	global_store_dwordx4 v[14:15], v[2:5], off nt
	s_nop 1
	v_cvt_pk_bf16_f32 v2, v6, v7
	v_cvt_pk_bf16_f32 v3, v8, v9
	v_cvt_pk_bf16_f32 v4, v12, v13
	v_cvt_pk_bf16_f32 v5, v10, v11
	global_store_dwordx4 v[14:15], v[2:5], off offset:1024 nt
	s_andn2_b64 vcc, exec, s[2:3]
	s_mov_b64 s[2:3], -1
	s_cbranch_vccnz .LBB0_225
.LBB0_241:
	s_mov_b32 s99, 0
	s_andn2_b64 vcc, exec, s[4:5]
	s_cbranch_vccnz .LBB0_224
	s_mov_b32 s99, 1
	s_branch .LBB0_224

; #define PG8_STAGE(bufoff, gbase, voff) do { _Pragma("unroll") for (int _i = 0; _i < 2; ++_i) \
;         __builtin_amdgcn_global_load_lds((const unsigned*)((const char*)(gbase) + (voff)[_i]), (LAS unsigned*)(lds + (bufoff) + ldsw + _i * 8192), 16, 0, 0); } while (0)
; #define PG8_WAIT_V(n) asm volatile("s_waitcnt vmcnt(" #n ")" ::: "memory")
; #define PG8_BAR __builtin_amdgcn_s_barrier()
; template <class Epi, bool ALIGN_EPI, bool SPLITA>
; __device__ __forceinline__ void gemm_phase(LAS unsigned char* lds, const Gemm g, const StaticOrder& S, const Epi& E) {
;     ...
;     const char* cA = baseA1(cur); const char* cB = baseB(cur);
;     const char* cA2 = SPLITA ? (const char*)g.A2 + (size_t)cur.pm * tstepA : cA;
;     bool mirC = mirrored(cur);
;     { const unsigned vo[2] = {mirC ? voffAm[0] : voffA[0], mirC ? voffAm[1] : voffA[1]}; const char* cAh = mirC ? cA - hstepA : cA + hstepA;
;       PG8_STAGE(PG8_SB(0, 0), cB, voffB); PG8_STAGE(PG8_SB(0, 1), cB + hstepB, voffB); PG8_STAGE(PG8_SA(0, 0), cA, vo); PG8_STAGE(PG8_SA(0, 1), cAh, vo);
;       if (wr == 1) PG8_BAR;
;       PG8_WAIT_V(2); PG8_BAR;
;       PG8_STAGE(PG8_SB(1, 0), cB + kstepB, voffB); PG8_STAGE(PG8_SA(1, 0), cA + kofs(1), vo); PG8_STAGE(PG8_SB(1, 1), cB + hstepB + kstepB, voffB); }
;     PG8_WAIT_V(6); PG8_BAR;
.LBB0_257:
	s_lshl_b32 s8, s8, 5
	s_and_b32 s26, s8, 0x60
	s_mov_b64 s[8:9], 0x80
	s_add_i32 m0, s43, 0x18000
	v_lshl_add_u64 v[8:9], v[8:9], 0, s[8:9]
	s_lshl_b32 s1, s10, 13
	s_lshl_b32 s11, s26, 7
	s_waitcnt vmcnt(2)
	s_barrier
	global_load_lds_dwordx4 v[8:9], off
	v_lshl_add_u64 v[6:7], v[6:7], 0, s[8:9]
	s_add_i32 m0, s43, 0x1a000
	s_add_i32 s72, s43, 0x8000
	s_add_i32 s73, s43, 0xa000
	global_load_lds_dwordx4 v[6:7], off
	v_lshl_add_u64 v[2:3], v[2:3], 0, s[8:9]
	s_mov_b32 m0, s72
	s_add_u32 s12, s44, 0x200080
	global_load_lds_dwordx4 v[2:3], off
	v_lshl_add_u64 v[2:3], v[4:5], 0, s[8:9]
	s_mov_b32 m0, s73
	s_addc_u32 s13, s45, 0
	global_load_lds_dwordx4 v[2:3], off
	s_add_i32 m0, s43, 0x1c000
	v_lshl_add_u64 v[2:3], s[12:13], 0, v[134:135]
	global_load_lds_dwordx4 v[2:3], off
	v_lshl_add_u64 v[2:3], s[12:13], 0, v[130:131]
	s_add_i32 m0, s43, 0x1e000
	s_cmpk_lt_u32 s3, 0x100
	global_load_lds_dwordx4 v[2:3], off
	v_lshrrev_b32_e32 v3, 1, v11
	v_and_b32_e32 v3, 24, v3
	v_and_b32_e32 v2, 15, v11
	v_lshlrev_b32_e32 v4, 1, v3
	v_lshl_or_b32 v1, s10, 6, v2
	v_lshl_or_b32 v2, v2, 6, v4
	v_lshlrev_b32_e32 v4, 2, v11
	v_and_b32_e32 v4, 32, v4
	v_bitop3_b32 v5, v2, s1, v4 bitop3:0xde
	v_bitop3_b32 v150, v2, s11, v4 bitop3:0xde
	v_lshlrev_b32_e32 v2, 14, v15
	v_and_b32_e32 v2, 0xffff8000, v2
	v_or_b32_e32 v151, s26, v3
	v_lshl_add_u32 v2, v14, 11, v2
	v_and_b32_e32 v3, 1, v15
	v_lshl_or_b32 v2, v3, 6, v2
	v_lshl_add_u32 v138, v16, 1, v2
	v_lshlrev_b32_e32 v2, 14, v10
	v_and_b32_e32 v2, 0xffff8000, v2
	s_waitcnt vmcnt(6)
	v_lshl_add_u32 v2, v12, 11, v2
	v_and_b32_e32 v3, 1, v10
	s_cselect_b64 s[10:11], -1, 0
	v_lshl_or_b32 v2, v3, 6, v2
	s_add_i32 s79, 0, 0x10000
	s_add_i32 s80, 0, 0x14000
	s_sext_i32_i8 s87, s2
	s_sext_i32_i8 s88, s0
	s_mov_b32 s78, 0x18000
	v_mov_b32_e32 v139, v135
	v_lshl_add_u32 v140, v13, 1, v2
	v_mov_b32_e32 v141, v135
	v_mov_b64_e32 v[142:143], 0x180
	v_mov_b64_e32 v[144:145], 0x17f
	v_add_u32_e32 v152, s79, v150
	v_add_u32_e32 v153, s80, v150
	v_add_u32_e32 v154, 0, v5
	s_mov_b32 s81, 0xc000
	s_barrier
	s_mov_b32 s99, 0
	s_branch .LBB0_260

; #define PG8_LDA(dst, b, h) do { _Pragma("unroll") for (int m = 0; m < 4; ++m) _Pragma("unroll") for (int k = 0; k < 2; ++k) dst[m][k] = *(const LAS bf16x8*)(lds + PG8_SA(b, h) + aoff + m * 2048 + k * 1024); } while (0)
; template <class Epi, bool ALIGN_EPI, bool SPLITA>
; __device__ __forceinline__ void gemm_phase(LAS unsigned char* lds, const Gemm g, const StaticOrder& S, const Epi& E) {
;     ...
;         const bool has_next = S.next(ui + 1, nxt);
;         const char* nA = has_next ? baseA1(nxt) : cA;
;         const char* nB = has_next ? baseB(nxt) : cB;
;         const bool mirN = has_next ? mirrored(nxt) : mirC;
;         for (int t = 0; t < nt; t += 2) {
;             const bool last = (t == nt - 2);
;             if constexpr (Epi::MIDK) { if (t == g.ksplit) E.mid(acc, cur, wr, wc, fr, fq); }
;             const char *a1, *a2;
;             if constexpr (SPLITA) {
;                 a1 = (t + 1 < g.ksplit) ? cA + (size_t)(t + 1) * kstep : cA2 + (size_t)(t + 1 - g.ksplit) * 2048;
;                 a2 = last ? nA : ((t + 2 < g.ksplit) ? cA + (size_t)(t + 2) * kstep : cA2 + (size_t)(t + 2 - g.ksplit) * 2048);
;             } else { a1 = cA + kofs(t + 1); a2 = last ? nA : cA + kofs(t + 2); }
;             const char* b2 = last ? nB : cB + (size_t)(t + 2) * kstepB;
;             const bool s2a = SPLITA && (t + 1 >= g.ksplit), s2b = SPLITA && !last && (t + 2 >= g.ksplit);
;             const char* a3 = a2 + ((Epi::KSUB || s2b) ? (size_t)2048 : kstep); const char* b3 = b2 + kstepB;
;             const bool m1 = SPLITA && mirC && (t + 1 < g.ksplit), m2 = SPLITA && (last ? mirN : (mirC && (t + 2 < g.ksplit)));
;             const unsigned vo1[2] = {s2a ? voffA2[0] : m1 ? voffAm[0] : voffA[0], s2a ? voffA2[1] : m1 ? voffAm[1] : voffA[1]}, vo2[2] = {s2b ? voffA2[0] : m2 ? voffAm[0] : voffA[0], s2b ? voffA2[1] : m2 ? voffAm[1] : voffA[1]};
;             const char* a1h = m1 ? a1 - hstepA : a1 + hstepA; const char* a2h = m2 ? a2 - hstepA : a2 + hstepA;
;             PG8_LDB(B0, 0, 0); PG8_LDB(B1, 0, 1); PG8_SCHED; PG8_LDA(At, 0, 0); PG8_STAGE(PG8_SA(1, 1), a1h, vo1);
;             PG8_WAIT_V(8); PG8_WAIT_L(0); PG8_BAR; PG8_MMA(0, 0, At, B0); PG8_MMA(0, 1, At, B1); PG8_BAR; PG8_SCHED;
;             PG8_LDA(At, 0, 1); PG8_STAGE(PG8_SB(0, 0), b2, voffB); PG8_STAGE(PG8_SB(0, 1), b2 + hstepB, voffB); PG8_STAGE(PG8_SA(0, 0), a2, vo2);
.LBB0_264:
	s_ashr_i32 s29, s28, 31
	s_lshl_b64 s[40:41], s[28:29], 19
	s_add_u32 s40, s6, s40
	s_addc_u32 s41, s7, s41
	s_and_b64 s[0:1], s[0:1], exec
	s_cselect_b32 s13, s41, s47
	s_cselect_b32 s27, s40, s46
	s_add_u32 s0, s46, 0x40080
	s_addc_u32 s1, s47, 0
	s_add_u32 s29, s44, 0x100
	s_addc_u32 s90, s45, 0
	s_mov_b32 s91, -2
	s_cmp_lg_u32 s99, 0
	s_cbranch_scc0 .Lyd_p1b
	s_barrier
	s_mov_b32 s99, 0
.Lyd_p1b:
	ds_read_b128 v[146:149], v152
	ds_read_b128 v[156:159], v152 offset:1024
	ds_read_b128 v[164:167], v152 offset:2048
	ds_read_b128 v[168:171], v152 offset:3072
	ds_read_b128 v[172:175], v153
	ds_read_b128 v[176:179], v153 offset:1024
	ds_read_b128 v[180:183], v153 offset:2048
	ds_read_b128 v[184:187], v153 offset:3072
	s_add_u32 s44, s0, 0xfffc0080
	s_addc_u32 s45, s1, -1
	s_cmp_eq_u32 s91, 12
	s_cselect_b32 s47, s13, s45
	s_cselect_b32 s46, s27, s44
	s_cselect_b32 s45, s39, s90
	s_cselect_b32 s44, s38, s29
	s_add_i32 m0, s43, 0xc000
	ds_read_b128 v[188:191], v154
	ds_read_b128 v[192:195], v154 offset:1024
	ds_read_b128 v[196:199], v154 offset:2048
	ds_read_b128 v[200:203], v154 offset:3072
	ds_read_b128 v[204:207], v154 offset:4096
	ds_read_b128 v[208:211], v154 offset:5120
	ds_read_b128 v[212:215], v154 offset:6144
	ds_read_b128 v[216:219], v154 offset:7168
	global_load_lds_dwordx4 v138, s[0:1]
	s_add_i32 m0, s43, 0xe000
	s_nop 0
	global_load_lds_dwordx4 v140, s[0:1]
	s_waitcnt vmcnt(8)
	s_waitcnt lgkmcnt(0)
	s_barrier
	s_setprio 1
	s_waitcnt lgkmcnt(0)
	v_mfma_f32_16x16x32_bf16 v[126:129], v[146:149], v[188:191], 0
	v_mfma_f32_16x16x32_bf16 v[122:125], v[164:167], v[188:191], 0
	v_mfma_f32_16x16x32_bf16 v[110:113], v[146:149], v[196:199], 0
	v_mfma_f32_16x16x32_bf16 v[106:109], v[164:167], v[196:199], 0
	v_mfma_f32_16x16x32_bf16 v[94:97], v[146:149], v[204:207], 0
	v_mfma_f32_16x16x32_bf16 v[90:93], v[164:167], v[204:207], 0
	v_mfma_f32_16x16x32_bf16 v[78:81], v[146:149], v[212:215], 0
	v_mfma_f32_16x16x32_bf16 v[74:77], v[164:167], v[212:215], 0
	v_mfma_f32_16x16x32_bf16 v[126:129], v[156:159], v[192:195], v[126:129]
	v_mfma_f32_16x16x32_bf16 v[122:125], v[168:171], v[192:195], v[122:125]
	v_mfma_f32_16x16x32_bf16 v[110:113], v[156:159], v[200:203], v[110:113]
	v_mfma_f32_16x16x32_bf16 v[106:109], v[168:171], v[200:203], v[106:109]
	v_mfma_f32_16x16x32_bf16 v[94:97], v[156:159], v[208:211], v[94:97]
	v_mfma_f32_16x16x32_bf16 v[90:93], v[168:171], v[208:211], v[90:93]
	v_mfma_f32_16x16x32_bf16 v[78:81], v[156:159], v[216:219], v[78:81]
	v_mfma_f32_16x16x32_bf16 v[74:77], v[168:171], v[216:219], v[74:77]
	s_setprio 0
	s_setprio 1
	v_mfma_f32_16x16x32_bf16 v[118:121], v[172:175], v[188:191], 0
	v_mfma_f32_16x16x32_bf16 v[114:117], v[180:183], v[188:191], 0
	v_mfma_f32_16x16x32_bf16 v[102:105], v[172:175], v[196:199], 0
	v_mfma_f32_16x16x32_bf16 v[98:101], v[180:183], v[196:199], 0
	v_mfma_f32_16x16x32_bf16 v[86:89], v[172:175], v[204:207], 0
	v_mfma_f32_16x16x32_bf16 v[82:85], v[180:183], v[204:207], 0
	v_mfma_f32_16x16x32_bf16 v[70:73], v[172:175], v[212:215], 0
	v_mfma_f32_16x16x32_bf16 v[66:69], v[180:183], v[212:215], 0
	v_mfma_f32_16x16x32_bf16 v[118:121], v[176:179], v[192:195], v[118:121]
	v_mfma_f32_16x16x32_bf16 v[114:117], v[184:187], v[192:195], v[114:117]
	v_mfma_f32_16x16x32_bf16 v[102:105], v[176:179], v[200:203], v[102:105]
	v_mfma_f32_16x16x32_bf16 v[98:101], v[184:187], v[200:203], v[98:101]
	v_mfma_f32_16x16x32_bf16 v[86:89], v[176:179], v[208:211], v[86:89]
	v_mfma_f32_16x16x32_bf16 v[82:85], v[184:187], v[208:211], v[82:85]
	v_mfma_f32_16x16x32_bf16 v[70:73], v[176:179], v[216:219], v[70:73]
	v_mfma_f32_16x16x32_bf16 v[66:69], v[184:187], v[216:219], v[66:69]
	s_setprio 0
	s_barrier
	s_add_u32 s98, s44, s8
	s_addc_u32 s99, s45, s9
	s_add_u32 s100, s46, s8
	s_addc_u32 s101, s47, s9
	s_add_i32 s89, s79, s33
	s_mov_b32 m0, s89
	ds_read_b128 v[188:191], v154 offset:16384
	ds_read_b128 v[192:195], v154 offset:17408
	ds_read_b128 v[196:199], v154 offset:18432
	ds_read_b128 v[200:203], v154 offset:19456
	ds_read_b128 v[204:207], v154 offset:20480
	ds_read_b128 v[208:211], v154 offset:21504
	ds_read_b128 v[212:215], v154 offset:22528
	ds_read_b128 v[216:219], v154 offset:23552
	global_load_lds_dwordx4 v134, s[44:45]
	s_add_i32 m0, s89, 0x2000
	s_add_u32 s92, s44, 0x200000
	s_addc_u32 s93, s45, 0
	s_add_i32 s89, s80, s33
	global_load_lds_dwordx4 v130, s[44:45]
	s_mov_b32 m0, s89
	s_nop 0
	global_load_lds_dwordx4 v134, s[92:93]
	s_add_i32 m0, s89, 0x2000
	s_nop 0
	global_load_lds_dwordx4 v130, s[92:93]
	s_mov_b32 m0, s43
	s_nop 0
	global_load_lds_dwordx4 v136, s[46:47]
	s_mov_b32 m0, s60
	s_nop 0
	global_load_lds_dwordx4 v132, s[46:47]
	s_waitcnt vmcnt(8)
	s_waitcnt lgkmcnt(0)
	s_barrier
; #define PG8_STAGE(bufoff, gbase, voff) do { _Pragma("unroll") for (int _i = 0; _i < 2; ++_i) \
;         __builtin_amdgcn_global_load_lds((const unsigned*)((const char*)(gbase) + (voff)[_i]), (LAS unsigned*)(lds + (bufoff) + ldsw + _i * 8192), 16, 0, 0); } while (0)
; #define PG8_LDA(dst, b, h) do { _Pragma("unroll") for (int m = 0; m < 4; ++m) _Pragma("unroll") for (int k = 0; k < 2; ++k) dst[m][k] = *(const LAS bf16x8*)(lds + PG8_SA(b, h) + aoff + m * 2048 + k * 1024); } while (0)
; #define PG8_LDB(dst, b, h) do { _Pragma("unroll") for (int n = 0; n < 2; ++n) _Pragma("unroll") for (int k = 0; k < 2; ++k) dst[n][k] = *(const LAS bf16x8*)(lds + PG8_SB(b, h) + boff + n * 2048 + k * 1024); } while (0)
; #define PG8_MMA(ai, bj, At, Bt) do { __builtin_amdgcn_s_setprio(1); _Pragma("unroll") for (int m = 0; m < 4; ++m) _Pragma("unroll") for (int n = 0; n < 2; ++n) _Pragma("unroll") for (int k = 0; k < 2; ++k) \
;         acc[ai][bj][m][n] = __builtin_amdgcn_mfma_f32_16x16x32_bf16(Bt[n][k], At[m][k], acc[ai][bj][m][n], 0, 0, 0); __builtin_amdgcn_s_setprio(0); } while (0)
; #define PG8_WAIT_V(n) asm volatile("s_waitcnt vmcnt(" #n ")" ::: "memory")
; #define PG8_WAIT_L(n) asm volatile("s_waitcnt lgkmcnt(" #n ")" ::: "memory")
; #define PG8_BAR __builtin_amdgcn_s_barrier()
; #define PG8_SCHED __builtin_amdgcn_sched_barrier(0)
; template <class Epi, bool ALIGN_EPI, bool SPLITA>
; __device__ __forceinline__ void gemm_phase(LAS unsigned char* lds, const Gemm g, const StaticOrder& S, const Epi& E) {
;     ...
;             PG8_WAIT_V(8); PG8_WAIT_L(0); PG8_BAR; PG8_MMA(1, 0, At, B0); PG8_MMA(1, 1, At, B1); PG8_BAR; PG8_SCHED;
;             PG8_LDB(B0, 1, 0); PG8_LDB(B1, 1, 1); PG8_SCHED; PG8_LDA(At, 1, 0); PG8_STAGE(PG8_SA(0, 1), a2h, vo2);
;             PG8_WAIT_V(8); PG8_WAIT_L(0); PG8_BAR; PG8_MMA(0, 0, At, B0); PG8_MMA(0, 1, At, B1); PG8_BAR; PG8_SCHED;
	s_setprio 1
	s_waitcnt lgkmcnt(0)
	v_mfma_f32_16x16x32_bf16 v[54:57], v[146:149], v[188:191], 0
	v_mfma_f32_16x16x32_bf16 v[50:53], v[164:167], v[188:191], 0
	v_mfma_f32_16x16x32_bf16 v[22:25], v[146:149], v[196:199], 0
	v_mfma_f32_16x16x32_bf16 v[18:21], v[164:167], v[196:199], 0
	v_mfma_f32_16x16x32_bf16 v[14:17], v[146:149], v[204:207], 0
	v_mfma_f32_16x16x32_bf16 v[10:13], v[164:167], v[204:207], 0
	v_mfma_f32_16x16x32_bf16 v[6:9], v[146:149], v[212:215], 0
	v_mfma_f32_16x16x32_bf16 v[2:5], v[164:167], v[212:215], 0
	v_mfma_f32_16x16x32_bf16 v[54:57], v[156:159], v[192:195], v[54:57]
	v_mfma_f32_16x16x32_bf16 v[50:53], v[168:171], v[192:195], v[50:53]
	v_mfma_f32_16x16x32_bf16 v[22:25], v[156:159], v[200:203], v[22:25]
	v_mfma_f32_16x16x32_bf16 v[18:21], v[168:171], v[200:203], v[18:21]
	v_mfma_f32_16x16x32_bf16 v[14:17], v[156:159], v[208:211], v[14:17]
	v_mfma_f32_16x16x32_bf16 v[10:13], v[168:171], v[208:211], v[10:13]
	v_mfma_f32_16x16x32_bf16 v[6:9], v[156:159], v[216:219], v[6:9]
	v_mfma_f32_16x16x32_bf16 v[2:5], v[168:171], v[216:219], v[2:5]
	s_setprio 0
	s_setprio 1
	v_mfma_f32_16x16x32_bf16 v[38:41], v[172:175], v[188:191], 0
	v_mfma_f32_16x16x32_bf16 v[34:37], v[180:183], v[188:191], 0
	v_mfma_f32_16x16x32_bf16 v[58:61], v[172:175], v[196:199], 0
	v_mfma_f32_16x16x32_bf16 v[62:65], v[180:183], v[196:199], 0
	v_mfma_f32_16x16x32_bf16 v[42:45], v[172:175], v[204:207], 0
	v_mfma_f32_16x16x32_bf16 v[46:49], v[180:183], v[204:207], 0
	v_mfma_f32_16x16x32_bf16 v[26:29], v[172:175], v[212:215], 0
	v_mfma_f32_16x16x32_bf16 v[30:33], v[180:183], v[212:215], 0
	v_mfma_f32_16x16x32_bf16 v[38:41], v[176:179], v[192:195], v[38:41]
	v_mfma_f32_16x16x32_bf16 v[34:37], v[184:187], v[192:195], v[34:37]
	v_mfma_f32_16x16x32_bf16 v[58:61], v[176:179], v[200:203], v[58:61]
	v_mfma_f32_16x16x32_bf16 v[62:65], v[184:187], v[200:203], v[62:65]
	v_mfma_f32_16x16x32_bf16 v[42:45], v[176:179], v[208:211], v[42:45]
	v_mfma_f32_16x16x32_bf16 v[46:49], v[184:187], v[208:211], v[46:49]
	v_mfma_f32_16x16x32_bf16 v[26:29], v[176:179], v[216:219], v[26:29]
	v_mfma_f32_16x16x32_bf16 v[30:33], v[184:187], v[216:219], v[30:33]
	s_setprio 0
	s_barrier
	s_add_i32 s89, 0, 0x18000
	v_add_u32_e32 v155, s89, v150
	s_add_i32 s92, 0, 0x1c000
	ds_read_b128 v[146:149], v155
	ds_read_b128 v[156:159], v155 offset:1024
	ds_read_b128 v[164:167], v155 offset:2048
	ds_read_b128 v[168:171], v155 offset:3072
	v_add_u32_e32 v155, s92, v150
	ds_read_b128 v[172:175], v155
	ds_read_b128 v[176:179], v155 offset:1024
	ds_read_b128 v[180:183], v155 offset:2048
	ds_read_b128 v[184:187], v155 offset:3072
	s_add_u32 s46, s46, 0x40000
	s_addc_u32 s47, s47, 0
	s_mov_b32 m0, s61
	ds_read_b128 v[188:191], v154 offset:32768
	ds_read_b128 v[192:195], v154 offset:33792
	ds_read_b128 v[196:199], v154 offset:34816
	ds_read_b128 v[200:203], v154 offset:35840
	ds_read_b128 v[204:207], v154 offset:36864
	ds_read_b128 v[208:211], v154 offset:37888
	ds_read_b128 v[212:215], v154 offset:38912
	ds_read_b128 v[216:219], v154 offset:39936
	global_load_lds_dwordx4 v136, s[46:47]
	s_mov_b32 m0, s64
	s_nop 0
	global_load_lds_dwordx4 v132, s[46:47]
	s_waitcnt vmcnt(8)
	s_waitcnt lgkmcnt(0)
	s_barrier
	s_setprio 1
	s_waitcnt lgkmcnt(0)
	v_mfma_f32_16x16x32_bf16 v[126:129], v[146:149], v[188:191], v[126:129]
	v_mfma_f32_16x16x32_bf16 v[122:125], v[164:167], v[188:191], v[122:125]
	v_mfma_f32_16x16x32_bf16 v[110:113], v[146:149], v[196:199], v[110:113]
	v_mfma_f32_16x16x32_bf16 v[106:109], v[164:167], v[196:199], v[106:109]
	v_mfma_f32_16x16x32_bf16 v[94:97], v[146:149], v[204:207], v[94:97]
	v_mfma_f32_16x16x32_bf16 v[90:93], v[164:167], v[204:207], v[90:93]
	v_mfma_f32_16x16x32_bf16 v[78:81], v[146:149], v[212:215], v[78:81]
	v_mfma_f32_16x16x32_bf16 v[74:77], v[164:167], v[212:215], v[74:77]
	v_mfma_f32_16x16x32_bf16 v[126:129], v[156:159], v[192:195], v[126:129]
	v_mfma_f32_16x16x32_bf16 v[122:125], v[168:171], v[192:195], v[122:125]
	v_mfma_f32_16x16x32_bf16 v[110:113], v[156:159], v[200:203], v[110:113]
	v_mfma_f32_16x16x32_bf16 v[106:109], v[168:171], v[200:203], v[106:109]
	v_mfma_f32_16x16x32_bf16 v[94:97], v[156:159], v[208:211], v[94:97]
	v_mfma_f32_16x16x32_bf16 v[90:93], v[168:171], v[208:211], v[90:93]
	v_mfma_f32_16x16x32_bf16 v[78:81], v[156:159], v[216:219], v[78:81]
	v_mfma_f32_16x16x32_bf16 v[74:77], v[168:171], v[216:219], v[74:77]
	s_setprio 0
	s_setprio 1
	v_mfma_f32_16x16x32_bf16 v[118:121], v[172:175], v[188:191], v[118:121]
	v_mfma_f32_16x16x32_bf16 v[114:117], v[180:183], v[188:191], v[114:117]
	v_mfma_f32_16x16x32_bf16 v[102:105], v[172:175], v[196:199], v[102:105]
	v_mfma_f32_16x16x32_bf16 v[98:101], v[180:183], v[196:199], v[98:101]
	v_mfma_f32_16x16x32_bf16 v[86:89], v[172:175], v[204:207], v[86:89]
	v_mfma_f32_16x16x32_bf16 v[82:85], v[180:183], v[204:207], v[82:85]
	v_mfma_f32_16x16x32_bf16 v[70:73], v[172:175], v[212:215], v[70:73]
	v_mfma_f32_16x16x32_bf16 v[66:69], v[180:183], v[212:215], v[66:69]
	v_mfma_f32_16x16x32_bf16 v[118:121], v[176:179], v[192:195], v[118:121]
	v_mfma_f32_16x16x32_bf16 v[114:117], v[184:187], v[192:195], v[114:117]
	v_mfma_f32_16x16x32_bf16 v[102:105], v[176:179], v[200:203], v[102:105]
	v_mfma_f32_16x16x32_bf16 v[98:101], v[184:187], v[200:203], v[98:101]
	v_mfma_f32_16x16x32_bf16 v[86:89], v[176:179], v[208:211], v[86:89]
	v_mfma_f32_16x16x32_bf16 v[82:85], v[184:187], v[208:211], v[82:85]
	v_mfma_f32_16x16x32_bf16 v[70:73], v[176:179], v[216:219], v[70:73]
	v_mfma_f32_16x16x32_bf16 v[66:69], v[184:187], v[216:219], v[66:69]
	s_setprio 0
	s_barrier
; #define PG8_STAGE(bufoff, gbase, voff) do { _Pragma("unroll") for (int _i = 0; _i < 2; ++_i) \
;         __builtin_amdgcn_global_load_lds((const unsigned*)((const char*)(gbase) + (voff)[_i]), (LAS unsigned*)(lds + (bufoff) + ldsw + _i * 8192), 16, 0, 0); } while (0)
; #define PG8_LDA(dst, b, h) do { _Pragma("unroll") for (int m = 0; m < 4; ++m) _Pragma("unroll") for (int k = 0; k < 2; ++k) dst[m][k] = *(const LAS bf16x8*)(lds + PG8_SA(b, h) + aoff + m * 2048 + k * 1024); } while (0)
; #define PG8_MMA(ai, bj, At, Bt) do { __builtin_amdgcn_s_setprio(1); _Pragma("unroll") for (int m = 0; m < 4; ++m) _Pragma("unroll") for (int n = 0; n < 2; ++n) _Pragma("unroll") for (int k = 0; k < 2; ++k) \
;         acc[ai][bj][m][n] = __builtin_amdgcn_mfma_f32_16x16x32_bf16(Bt[n][k], At[m][k], acc[ai][bj][m][n], 0, 0, 0); __builtin_amdgcn_s_setprio(0); } while (0)
; #define PG8_WAIT_V(n) asm volatile("s_waitcnt vmcnt(" #n ")" ::: "memory")
; #define PG8_WAIT_L(n) asm volatile("s_waitcnt lgkmcnt(" #n ")" ::: "memory")
; #define PG8_BAR __builtin_amdgcn_s_barrier()
; #define PG8_SCHED __builtin_amdgcn_sched_barrier(0)
; template <class Epi, bool ALIGN_EPI, bool SPLITA>
; __device__ __forceinline__ void gemm_phase(LAS unsigned char* lds, const Gemm g, const StaticOrder& S, const Epi& E) {
;     ...
;             PG8_LDA(At, 1, 1); PG8_STAGE(PG8_SB(1, 0), b3, voffB); PG8_STAGE(PG8_SB(1, 1), b3 + hstepB, voffB); PG8_STAGE(PG8_SA(1, 0), a3, vo2);
;             PG8_WAIT_V(8); PG8_WAIT_L(0); PG8_BAR; PG8_MMA(1, 0, At, B0); PG8_MMA(1, 1, At, B1); PG8_BAR; PG8_SCHED;
	s_add_i32 s46, s89, s33
	s_mov_b32 m0, s46
	ds_read_b128 v[188:191], v154 offset:49152
	ds_read_b128 v[192:195], v154 offset:50176
	ds_read_b128 v[196:199], v154 offset:51200
	ds_read_b128 v[200:203], v154 offset:52224
	ds_read_b128 v[204:207], v154 offset:53248
	ds_read_b128 v[208:211], v154 offset:54272
	ds_read_b128 v[212:215], v154 offset:55296
	ds_read_b128 v[216:219], v154 offset:56320
	global_load_lds_dwordx4 v134, s[98:99]
	s_add_i32 m0, s46, 0x2000
	s_add_u32 s44, s44, 0x200080
	s_addc_u32 s45, s45, 0
	s_add_i32 s46, s92, s33
	global_load_lds_dwordx4 v130, s[98:99]
	s_mov_b32 m0, s46
	s_nop 0
	global_load_lds_dwordx4 v134, s[44:45]
	s_add_i32 m0, s46, 0x2000
	s_nop 0
	global_load_lds_dwordx4 v130, s[44:45]
	s_mov_b32 m0, s72
	s_nop 0
	global_load_lds_dwordx4 v136, s[100:101]
	s_mov_b32 m0, s73
	s_nop 0
	global_load_lds_dwordx4 v132, s[100:101]
	s_waitcnt vmcnt(8)
	s_waitcnt lgkmcnt(0)
	s_barrier
	s_setprio 1
	s_waitcnt lgkmcnt(0)
	v_mfma_f32_16x16x32_bf16 v[54:57], v[146:149], v[188:191], v[54:57]
	v_mfma_f32_16x16x32_bf16 v[50:53], v[164:167], v[188:191], v[50:53]
	v_mfma_f32_16x16x32_bf16 v[22:25], v[146:149], v[196:199], v[22:25]
	v_mfma_f32_16x16x32_bf16 v[18:21], v[164:167], v[196:199], v[18:21]
	v_mfma_f32_16x16x32_bf16 v[14:17], v[146:149], v[204:207], v[14:17]
	v_mfma_f32_16x16x32_bf16 v[10:13], v[164:167], v[204:207], v[10:13]
	v_mfma_f32_16x16x32_bf16 v[6:9], v[146:149], v[212:215], v[6:9]
	v_mfma_f32_16x16x32_bf16 v[2:5], v[164:167], v[212:215], v[2:5]
	v_mfma_f32_16x16x32_bf16 v[54:57], v[156:159], v[192:195], v[54:57]
	v_mfma_f32_16x16x32_bf16 v[50:53], v[168:171], v[192:195], v[50:53]
	v_mfma_f32_16x16x32_bf16 v[22:25], v[156:159], v[200:203], v[22:25]
	v_mfma_f32_16x16x32_bf16 v[18:21], v[168:171], v[200:203], v[18:21]
	v_mfma_f32_16x16x32_bf16 v[14:17], v[156:159], v[208:211], v[14:17]
	v_mfma_f32_16x16x32_bf16 v[10:13], v[168:171], v[208:211], v[10:13]
	v_mfma_f32_16x16x32_bf16 v[6:9], v[156:159], v[216:219], v[6:9]
	v_mfma_f32_16x16x32_bf16 v[2:5], v[168:171], v[216:219], v[2:5]
	s_setprio 0
	s_setprio 1
	v_mfma_f32_16x16x32_bf16 v[38:41], v[172:175], v[188:191], v[38:41]
	v_mfma_f32_16x16x32_bf16 v[34:37], v[180:183], v[188:191], v[34:37]
	v_mfma_f32_16x16x32_bf16 v[58:61], v[172:175], v[196:199], v[58:61]
	v_mfma_f32_16x16x32_bf16 v[62:65], v[180:183], v[196:199], v[62:65]
	v_mfma_f32_16x16x32_bf16 v[42:45], v[172:175], v[204:207], v[42:45]
	v_mfma_f32_16x16x32_bf16 v[46:49], v[180:183], v[204:207], v[46:49]
	v_mfma_f32_16x16x32_bf16 v[26:29], v[172:175], v[212:215], v[26:29]
	v_mfma_f32_16x16x32_bf16 v[30:33], v[180:183], v[212:215], v[30:33]
	v_mfma_f32_16x16x32_bf16 v[38:41], v[176:179], v[192:195], v[38:41]
	v_mfma_f32_16x16x32_bf16 v[34:37], v[184:187], v[192:195], v[34:37]
	v_mfma_f32_16x16x32_bf16 v[58:61], v[176:179], v[200:203], v[58:61]
	v_mfma_f32_16x16x32_bf16 v[62:65], v[184:187], v[200:203], v[62:65]
	v_mfma_f32_16x16x32_bf16 v[42:45], v[176:179], v[208:211], v[42:45]
	v_mfma_f32_16x16x32_bf16 v[46:49], v[184:187], v[208:211], v[46:49]
	v_mfma_f32_16x16x32_bf16 v[26:29], v[176:179], v[216:219], v[26:29]
	v_mfma_f32_16x16x32_bf16 v[30:33], v[184:187], v[216:219], v[30:33]
	s_setprio 0
	s_barrier
	s_add_i32 s91, s91, 2
	s_add_u32 s0, s0, 0x100
	s_addc_u32 s1, s1, 0
	s_add_u32 s29, s29, 0x100
	s_addc_u32 s90, s90, 0

; __device__ __forceinline__ u32x4 pack8(const f32x4 a, const f32x4 b) { u32x4 w; w.x = cvt_pk_bf16(a[0], a[1]); w.y = cvt_pk_bf16(a[2], a[3]); w.z = cvt_pk_bf16(b[0], b[1]); w.w = cvt_pk_bf16(b[2], b[3]); return w; }
; #define PG8_BAR __builtin_amdgcn_s_barrier()
; template <class Epi, bool ALIGN_EPI, bool SPLITA>
; __device__ __forceinline__ void gemm_phase(LAS unsigned char* lds, const Gemm g, const StaticOrder& S, const Epi& E) {
;     ...
;         if constexpr (ALIGN_EPI) { if (wr == 0) PG8_BAR; }
;     __device__ __forceinline__ void operator()(const Acc& acc, const Unit& u, int wr, int wc, int fr, int fq) const {
;         const int row0 = u.pm * BM + wr * 64 + fr, col0 = u.pb * 1024 + u.pn * 128 + wc * 32 + 8 * fq;
; #pragma unroll
;         for (int ai = 0; ai < 2; ++ai)
; #pragma unroll
;             for (int m = 0; m < 4; ++m) { bf16_t* rowp = O + (size_t)(row0 + ai * HALF + m * 16) * M + col0;
;                 *(u32x4*)(rowp) = pack8(acc[ai][0][m][0] + acc[ai][1][m][0], acc[ai][0][m][1] + acc[ai][1][m][1]);
;                 *(u32x4*)(rowp + NBATCH * 1024) = pack8(acc[ai][0][m][0] - acc[ai][1][m][0], acc[ai][0][m][1] - acc[ai][1][m][1]); }
.LBB0_268:
	s_lshl_b32 s0, s42, 10
	s_lshl_b32 s1, s88, 7
	s_add_i32 s1, s1, s0
	v_or_b32_e32 v148, s1, v151
	v_lshl_add_u32 v155, s87, 8, v1
	v_ashrrev_i32_e32 v149, 31, v148
	v_mov_b64_e32 v[146:147], s[36:37]
	v_mad_i64_i32 v[156:157], s[0:1], v155, s78, v[146:147]
	v_lshlrev_b64 v[148:149], 1, v[148:149]
	v_lshl_add_u64 v[160:161], v[156:157], 0, v[148:149]
	v_pk_add_f32 v[156:157], v[126:127], v[118:119]
	v_sub_f32_e32 v119, v127, v119
	v_sub_f32_e32 v118, v126, v118
	v_pk_add_f32 v[158:159], v[128:129], v[120:121]
	v_pk_add_f32 v[164:165], v[124:125], v[116:117]
	v_pk_add_f32 v[166:167], v[122:123], v[114:115]
	v_sub_f32_e32 v121, v129, v121
	v_sub_f32_e32 v120, v128, v120
	v_sub_f32_e32 v117, v125, v117
	v_sub_f32_e32 v124, v124, v116
	v_sub_f32_e32 v116, v123, v115
	v_sub_f32_e32 v122, v122, v114
	v_cvt_pk_bf16_f32 v114, v118, v119
	v_add_co_u32_e32 v118, vcc, s81, v160
	v_cvt_pk_bf16_f32 v115, v120, v121
	v_cvt_pk_bf16_f32 v116, v122, v116
	v_cvt_pk_bf16_f32 v117, v124, v117
	v_addc_co_u32_e32 v119, vcc, 0, v161, vcc
	global_store_dwordx4 v[118:119], v[114:117], off
	v_pk_add_f32 v[120:121], v[108:109], v[100:101]
	v_pk_add_f32 v[122:123], v[106:107], v[98:99]
	v_or_b32_e32 v114, 16, v155
	v_mad_i64_i32 v[114:115], s[0:1], v114, s78, v[146:147]
	v_lshl_add_u64 v[118:119], v[114:115], 0, v[148:149]
	v_pk_add_f32 v[114:115], v[110:111], v[102:103]
	v_sub_f32_e32 v103, v111, v103
	v_sub_f32_e32 v102, v110, v102
	v_pk_add_f32 v[116:117], v[112:113], v[104:105]
	v_sub_f32_e32 v105, v113, v105
	v_sub_f32_e32 v104, v112, v104
	v_sub_f32_e32 v101, v109, v101
	v_sub_f32_e32 v108, v108, v100
	v_sub_f32_e32 v100, v107, v99
	v_sub_f32_e32 v106, v106, v98
	v_cvt_pk_bf16_f32 v98, v102, v103
	v_add_co_u32_e32 v102, vcc, s81, v118
	v_cvt_pk_bf16_f32 v99, v104, v105
	v_cvt_pk_bf16_f32 v100, v106, v100
	v_cvt_pk_bf16_f32 v101, v108, v101
	v_addc_co_u32_e32 v103, vcc, 0, v119, vcc
	global_store_dwordx4 v[102:103], v[98:101], off
	v_pk_add_f32 v[104:105], v[92:93], v[84:85]
	v_pk_add_f32 v[106:107], v[90:91], v[82:83]
	v_or_b32_e32 v98, 32, v155
	v_mad_i64_i32 v[98:99], s[0:1], v98, s78, v[146:147]
	v_lshl_add_u64 v[102:103], v[98:99], 0, v[148:149]
	v_pk_add_f32 v[98:99], v[94:95], v[86:87]
	v_sub_f32_e32 v87, v95, v87
	v_sub_f32_e32 v86, v94, v86
	v_pk_add_f32 v[100:101], v[96:97], v[88:89]
	v_sub_f32_e32 v89, v97, v89
	v_sub_f32_e32 v88, v96, v88
	v_sub_f32_e32 v85, v93, v85
	v_sub_f32_e32 v92, v92, v84
	v_sub_f32_e32 v84, v91, v83
	v_sub_f32_e32 v90, v90, v82
	v_cvt_pk_bf16_f32 v82, v86, v87
	v_add_co_u32_e32 v86, vcc, s81, v102
	v_cvt_pk_bf16_f32 v83, v88, v89
	v_cvt_pk_bf16_f32 v84, v90, v84
	v_cvt_pk_bf16_f32 v85, v92, v85
	v_addc_co_u32_e32 v87, vcc, 0, v103, vcc
	global_store_dwordx4 v[86:87], v[82:85], off
	v_pk_add_f32 v[88:89], v[76:77], v[68:69]
	v_pk_add_f32 v[90:91], v[74:75], v[66:67]
	v_or_b32_e32 v82, 48, v155
	v_mad_i64_i32 v[82:83], s[0:1], v82, s78, v[146:147]
	v_lshl_add_u64 v[86:87], v[82:83], 0, v[148:149]
	v_pk_add_f32 v[82:83], v[78:79], v[70:71]
	v_sub_f32_e32 v71, v79, v71
	v_sub_f32_e32 v70, v78, v70
	v_pk_add_f32 v[84:85], v[80:81], v[72:73]
	v_sub_f32_e32 v73, v81, v73
	v_sub_f32_e32 v72, v80, v72
	v_sub_f32_e32 v69, v77, v69
	v_sub_f32_e32 v76, v76, v68
	v_sub_f32_e32 v68, v75, v67
	v_sub_f32_e32 v74, v74, v66
	v_cvt_pk_bf16_f32 v66, v70, v71
	v_add_co_u32_e32 v70, vcc, s81, v86
	v_cvt_pk_bf16_f32 v67, v72, v73
	v_cvt_pk_bf16_f32 v68, v74, v68
	v_cvt_pk_bf16_f32 v69, v76, v69
	v_addc_co_u32_e32 v71, vcc, 0, v87, vcc
	global_store_dwordx4 v[70:71], v[66:69], off
	s_cmp_lg_u64 s[10:11], 0
	s_cbranch_scc0 .Lxs_p1b_0
	s_barrier
; __device__ __forceinline__ u32x4 pack8(const f32x4 a, const f32x4 b) { u32x4 w; w.x = cvt_pk_bf16(a[0], a[1]); w.y = cvt_pk_bf16(a[2], a[3]); w.z = cvt_pk_bf16(b[0], b[1]); w.w = cvt_pk_bf16(b[2], b[3]); return w; }
; #define PG8_BAR __builtin_amdgcn_s_barrier()
; template <class Epi, bool ALIGN_EPI, bool SPLITA>
; __device__ __forceinline__ void gemm_phase(LAS unsigned char* lds, const Gemm g, const StaticOrder& S, const Epi& E) {
;     ...
;         if (!has_next) break;
; #pragma unroll
;         for (int a = 0; a < 2; ++a)
; #pragma unroll
;             for (int b = 0; b < 2; ++b)
; #pragma unroll
;                 for (int m = 0; m < 4; ++m)
; #pragma unroll
;                     for (int n = 0; n < 2; ++n) acc[a][b][m][n] = (f32x4){0.f, 0.f, 0.f, 0.f};
;         cur = nxt; cA = nA; cB = nB; mirC = mirN; if constexpr (SPLITA) cA2 = (const char*)g.A2 + (size_t)cur.pm * tstepA; ++ui;
;         if constexpr (ALIGN_EPI) { if (wr == 1) PG8_BAR; }
;     __device__ __forceinline__ void operator()(const Acc& acc, const Unit& u, int wr, int wc, int fr, int fq) const {
;         const int row0 = u.pm * BM + wr * 64 + fr, col0 = u.pb * 1024 + u.pn * 128 + wc * 32 + 8 * fq;
; #pragma unroll
;         for (int ai = 0; ai < 2; ++ai)
; #pragma unroll
;             for (int m = 0; m < 4; ++m) { bf16_t* rowp = O + (size_t)(row0 + ai * HALF + m * 16) * M + col0;
;                 *(u32x4*)(rowp) = pack8(acc[ai][0][m][0] + acc[ai][1][m][0], acc[ai][0][m][1] + acc[ai][1][m][1]);
;                 *(u32x4*)(rowp + NBATCH * 1024) = pack8(acc[ai][0][m][0] - acc[ai][1][m][0], acc[ai][0][m][1] - acc[ai][1][m][1]); }
.Lxs_p1b_0:
	v_pk_add_f32 v[72:73], v[52:53], v[36:37]
	v_pk_add_f32 v[74:75], v[50:51], v[34:35]
	v_add_u32_e32 v66, 0x80, v155
	v_mad_i64_i32 v[66:67], s[0:1], v66, s78, v[146:147]
	v_lshl_add_u64 v[70:71], v[66:67], 0, v[148:149]
	v_pk_add_f32 v[66:67], v[54:55], v[38:39]
	v_sub_f32_e32 v39, v55, v39
	v_sub_f32_e32 v38, v54, v38
	v_pk_add_f32 v[68:69], v[56:57], v[40:41]
	v_sub_f32_e32 v41, v57, v41
	v_sub_f32_e32 v40, v56, v40
	v_sub_f32_e32 v37, v53, v37
	v_sub_f32_e32 v52, v52, v36
	v_sub_f32_e32 v36, v51, v35
	v_sub_f32_e32 v50, v50, v34
	v_cvt_pk_bf16_f32 v34, v38, v39
	v_add_co_u32_e32 v38, vcc, s81, v70
	v_cvt_pk_bf16_f32 v35, v40, v41
	v_cvt_pk_bf16_f32 v36, v50, v36
	v_cvt_pk_bf16_f32 v37, v52, v37
	v_addc_co_u32_e32 v39, vcc, 0, v71, vcc
	global_store_dwordx4 v[38:39], v[34:37], off
	v_pk_add_f32 v[40:41], v[20:21], v[64:65]
	v_pk_add_f32 v[50:51], v[18:19], v[62:63]
	v_add_u32_e32 v34, 0x90, v155
	v_mad_i64_i32 v[34:35], s[0:1], v34, s78, v[146:147]
	v_lshl_add_u64 v[38:39], v[34:35], 0, v[148:149]
	v_pk_add_f32 v[36:37], v[24:25], v[60:61]
	v_pk_add_f32 v[34:35], v[22:23], v[58:59]
	v_sub_f32_e32 v23, v23, v59
	v_cvt_pk_bf16_f32 v34, v34, v35
	v_cvt_pk_bf16_f32 v35, v36, v37
	v_cvt_pk_bf16_f32 v36, v50, v51
	v_cvt_pk_bf16_f32 v37, v40, v41
	v_sub_f32_e32 v22, v22, v58
	global_store_dwordx4 v[38:39], v[34:37], off
	v_sub_f32_e32 v25, v25, v61
	v_sub_f32_e32 v24, v24, v60
	v_sub_f32_e32 v21, v21, v65
	v_sub_f32_e32 v34, v20, v64
	v_sub_f32_e32 v20, v19, v63
	v_sub_f32_e32 v35, v18, v62
	v_cvt_pk_bf16_f32 v18, v22, v23
	v_add_co_u32_e32 v22, vcc, s81, v38
	v_cvt_pk_bf16_f32 v19, v24, v25
	v_cvt_pk_bf16_f32 v20, v35, v20
	v_cvt_pk_bf16_f32 v21, v34, v21
	v_addc_co_u32_e32 v23, vcc, 0, v39, vcc
	global_store_dwordx4 v[22:23], v[18:21], off
	v_pk_add_f32 v[24:25], v[12:13], v[48:49]
	v_pk_add_f32 v[34:35], v[10:11], v[46:47]
	v_add_u32_e32 v18, 0xa0, v155
	v_mad_i64_i32 v[18:19], s[0:1], v18, s78, v[146:147]
	v_lshl_add_u64 v[22:23], v[18:19], 0, v[148:149]
	v_pk_add_f32 v[20:21], v[16:17], v[44:45]
	v_pk_add_f32 v[18:19], v[14:15], v[42:43]
	v_sub_f32_e32 v15, v15, v43
	v_cvt_pk_bf16_f32 v18, v18, v19
	v_cvt_pk_bf16_f32 v19, v20, v21
	v_cvt_pk_bf16_f32 v20, v34, v35
	v_cvt_pk_bf16_f32 v21, v24, v25
	v_sub_f32_e32 v14, v14, v42
	global_store_dwordx4 v[22:23], v[18:21], off
	v_sub_f32_e32 v17, v17, v45
	v_sub_f32_e32 v16, v16, v44
	v_sub_f32_e32 v13, v13, v49
	v_sub_f32_e32 v18, v12, v48
	v_sub_f32_e32 v12, v11, v47
	v_sub_f32_e32 v19, v10, v46
	v_cvt_pk_bf16_f32 v10, v14, v15
	v_add_co_u32_e32 v14, vcc, s81, v22
	v_cvt_pk_bf16_f32 v11, v16, v17
	v_cvt_pk_bf16_f32 v12, v19, v12
	v_cvt_pk_bf16_f32 v13, v18, v13
	v_addc_co_u32_e32 v15, vcc, 0, v23, vcc
	global_store_dwordx4 v[14:15], v[10:13], off
	v_pk_add_f32 v[16:17], v[4:5], v[32:33]
	v_pk_add_f32 v[18:19], v[2:3], v[30:31]
	v_add_u32_e32 v10, 0xb0, v155
	v_mad_i64_i32 v[10:11], s[0:1], v10, s78, v[146:147]
	v_lshl_add_u64 v[14:15], v[10:11], 0, v[148:149]
	v_pk_add_f32 v[12:13], v[8:9], v[28:29]
	v_pk_add_f32 v[10:11], v[6:7], v[26:27]
	v_sub_f32_e32 v7, v7, v27
	v_cvt_pk_bf16_f32 v10, v10, v11
	v_cvt_pk_bf16_f32 v11, v12, v13
	v_cvt_pk_bf16_f32 v12, v18, v19
	v_cvt_pk_bf16_f32 v13, v16, v17
	v_sub_f32_e32 v6, v6, v26
	global_store_dwordx4 v[14:15], v[10:13], off
	v_sub_f32_e32 v9, v9, v29
	v_sub_f32_e32 v8, v8, v28
	v_sub_f32_e32 v11, v2, v30
	v_cvt_pk_bf16_f32 v2, v6, v7
	v_add_co_u32_e32 v6, vcc, 0xc000, v14
	v_sub_f32_e32 v5, v5, v33
	v_sub_f32_e32 v10, v4, v32
	v_sub_f32_e32 v4, v3, v31
	v_addc_co_u32_e32 v7, vcc, 0, v15, vcc
	v_cvt_pk_bf16_f32 v156, v156, v157
	v_cvt_pk_bf16_f32 v157, v158, v159
	v_cvt_pk_bf16_f32 v158, v166, v167
	v_cvt_pk_bf16_f32 v159, v164, v165
	v_cvt_pk_bf16_f32 v114, v114, v115
	v_cvt_pk_bf16_f32 v115, v116, v117
	v_cvt_pk_bf16_f32 v116, v122, v123
	v_cvt_pk_bf16_f32 v117, v120, v121
	v_cvt_pk_bf16_f32 v98, v98, v99
	v_cvt_pk_bf16_f32 v99, v100, v101
	v_cvt_pk_bf16_f32 v100, v106, v107
	v_cvt_pk_bf16_f32 v101, v104, v105
	v_cvt_pk_bf16_f32 v82, v82, v83
	v_cvt_pk_bf16_f32 v83, v84, v85
	v_cvt_pk_bf16_f32 v84, v90, v91
	v_cvt_pk_bf16_f32 v85, v88, v89
	v_cvt_pk_bf16_f32 v66, v66, v67
	v_cvt_pk_bf16_f32 v67, v68, v69
	v_cvt_pk_bf16_f32 v68, v74, v75
	v_cvt_pk_bf16_f32 v69, v72, v73
	v_cvt_pk_bf16_f32 v3, v8, v9
	v_cvt_pk_bf16_f32 v4, v11, v4
	v_cvt_pk_bf16_f32 v5, v10, v5
	s_and_b64 vcc, exec, s[2:3]
	s_mov_b64 s[0:1], -1
	global_store_dwordx4 v[160:161], v[156:159], off
	global_store_dwordx4 v[118:119], v[114:117], off
	global_store_dwordx4 v[102:103], v[98:101], off
	global_store_dwordx4 v[86:87], v[82:85], off
	global_store_dwordx4 v[70:71], v[66:69], off
	global_store_dwordx4 v[6:7], v[2:5], off
	s_cbranch_vccnz .LBB0_259
	s_mov_b32 s99, 0
	s_andn2_b64 vcc, exec, s[4:5]
	s_cbranch_vccnz .LBB0_258
	s_mov_b32 s99, 1
	s_branch .LBB0_258

; #define PG8_STAGE(bufoff, gbase, voff) do { _Pragma("unroll") for (int _i = 0; _i < 2; ++_i) \
;         __builtin_amdgcn_global_load_lds((const unsigned*)((const char*)(gbase) + (voff)[_i]), (LAS unsigned*)(lds + (bufoff) + ldsw + _i * 8192), 16, 0, 0); } while (0)
; #define PG8_WAIT_V(n) asm volatile("s_waitcnt vmcnt(" #n ")" ::: "memory")
; #define PG8_BAR __builtin_amdgcn_s_barrier()
; template <class Epi, bool ALIGN_EPI, bool SPLITA>
; __device__ __forceinline__ void gemm_phase(LAS unsigned char* lds, const Gemm g, const StaticOrder& S, const Epi& E) {
;     ...
;     const char* cA = baseA1(cur); const char* cB = baseB(cur);
;     const char* cA2 = SPLITA ? (const char*)g.A2 + (size_t)cur.pm * tstepA : cA;
;     bool mirC = mirrored(cur);
;     { const unsigned vo[2] = {mirC ? voffAm[0] : voffA[0], mirC ? voffAm[1] : voffA[1]}; const char* cAh = mirC ? cA - hstepA : cA + hstepA;
;       PG8_STAGE(PG8_SB(0, 0), cB, voffB); PG8_STAGE(PG8_SB(0, 1), cB + hstepB, voffB); PG8_STAGE(PG8_SA(0, 0), cA, vo); PG8_STAGE(PG8_SA(0, 1), cAh, vo);
;       if (wr == 1) PG8_BAR;
;       PG8_WAIT_V(2); PG8_BAR;
;       PG8_STAGE(PG8_SB(1, 0), cB + kstepB, voffB); PG8_STAGE(PG8_SA(1, 0), cA + kofs(1), vo); PG8_STAGE(PG8_SB(1, 1), cB + hstepB + kstepB, voffB); }
;     PG8_WAIT_V(6); PG8_BAR;
.LBB0_405:
	s_lshl_b32 s0, s0, 5
	s_mov_b64 s[18:19], 0x80
	s_and_b32 s0, s0, 0x60
	s_add_i32 m0, s54, 0x18000
	v_lshl_add_u64 v[8:9], v[8:9], 0, s[18:19]
	s_ashr_i32 s60, s15, 31
	s_lshl_b32 s3, s1, 13
	s_lshl_b32 s5, s0, 7
	s_waitcnt vmcnt(2)
	s_barrier
	global_load_lds_dwordx4 v[8:9], off
	v_lshl_add_u64 v[6:7], v[6:7], 0, s[18:19]
	s_add_i32 m0, s54, 0x1a000
	s_add_i32 s61, s54, 0x8000
	s_add_i32 s64, s54, 0xa000
	global_load_lds_dwordx4 v[6:7], off
	v_lshl_add_u64 v[2:3], v[2:3], 0, s[18:19]
	s_mov_b32 m0, s61
	s_add_u32 s20, s50, 0xc00080
	global_load_lds_dwordx4 v[2:3], off
	v_lshl_add_u64 v[2:3], v[4:5], 0, s[18:19]
	s_mov_b32 m0, s64
	s_addc_u32 s21, s51, 0
	global_load_lds_dwordx4 v[2:3], off
	s_add_i32 m0, s54, 0x1c000
	v_lshl_add_u64 v[2:3], s[20:21], 0, v[132:133]
	global_load_lds_dwordx4 v[2:3], off
	v_lshl_add_u64 v[2:3], s[20:21], 0, v[136:137]
	s_add_i32 m0, s54, 0x1e000
	s_cmpk_lt_u32 s2, 0x100
	global_load_lds_dwordx4 v[2:3], off
	v_lshrrev_b32_e32 v3, 1, v10
	v_and_b32_e32 v3, 24, v3
	v_and_b32_e32 v2, 15, v10
	v_lshlrev_b32_e32 v4, 1, v3
	v_lshl_or_b32 v1, s1, 6, v2
	v_lshl_or_b32 v2, v2, 6, v4
	v_lshlrev_b32_e32 v4, 2, v10
	v_and_b32_e32 v4, 32, v4
	v_bitop3_b32 v5, v2, s3, v4 bitop3:0xde
	v_bitop3_b32 v154, v2, s5, v4 bitop3:0xde
	v_lshlrev_b32_e32 v2, 14, v11
	v_and_b32_e32 v2, 0xffff8000, v2
	v_or_b32_e32 v155, s0, v3
	v_lshl_add_u32 v2, v12, 11, v2
	v_and_b32_e32 v3, 1, v11
	v_lshl_or_b32 v2, v3, 6, v2
	v_lshl_add_u32 v138, v13, 1, v2
	v_lshlrev_b32_e32 v2, 14, v14
	v_and_b32_e32 v2, 0xffff8000, v2
	s_waitcnt vmcnt(6)
	v_lshl_add_u32 v2, v15, 11, v2
	v_and_b32_e32 v3, 1, v14
	s_cselect_b64 s[20:21], -1, 0
	v_lshl_or_b32 v2, v3, 6, v2
	s_add_i32 s65, 0, 0x10000
	s_add_i32 s72, 0, 0x14000
	v_mov_b32_e32 v139, v133
	v_lshl_add_u32 v140, v16, 1, v2
	v_mov_b32_e32 v141, v133
	v_mov_b64_e32 v[142:143], 0x180
	v_mov_b64_e32 v[144:145], 0x17f
	v_add_u32_e32 v156, s65, v154
	v_add_u32_e32 v157, s72, v154
	v_add_u32_e32 v158, 0, v5
	s_movk_i32 s73, 0x1ff
	s_mov_b64 s[22:23], 0x1ffc00
	s_mov_b64 s[24:25], 0x200000
	s_mov_b32 s74, 0
	s_barrier
	s_mov_b32 s99, 0
	s_branch .LBB0_408

; #define PG8_STAGE(bufoff, gbase, voff) do { _Pragma("unroll") for (int _i = 0; _i < 2; ++_i) \
;         __builtin_amdgcn_global_load_lds((const unsigned*)((const char*)(gbase) + (voff)[_i]), (LAS unsigned*)(lds + (bufoff) + ldsw + _i * 8192), 16, 0, 0); } while (0)
; #define PG8_LDA(dst, b, h) do { _Pragma("unroll") for (int m = 0; m < 4; ++m) _Pragma("unroll") for (int k = 0; k < 2; ++k) dst[m][k] = *(const LAS bf16x8*)(lds + PG8_SA(b, h) + aoff + m * 2048 + k * 1024); } while (0)
; #define PG8_LDB(dst, b, h) do { _Pragma("unroll") for (int n = 0; n < 2; ++n) _Pragma("unroll") for (int k = 0; k < 2; ++k) dst[n][k] = *(const LAS bf16x8*)(lds + PG8_SB(b, h) + boff + n * 2048 + k * 1024); } while (0)
; #define PG8_WAIT_V(n) asm volatile("s_waitcnt vmcnt(" #n ")" ::: "memory")
; #define PG8_WAIT_L(n) asm volatile("s_waitcnt lgkmcnt(" #n ")" ::: "memory")
; #define PG8_BAR __builtin_amdgcn_s_barrier()
; #define PG8_SCHED __builtin_amdgcn_sched_barrier(0)
; template <class Epi, bool ALIGN_EPI, bool SPLITA>
; __device__ __forceinline__ void gemm_phase(LAS unsigned char* lds, const Gemm g, const StaticOrder& S, const Epi& E) {
;     ...
;             const char* b2 = last ? nB : cB + (size_t)(t + 2) * kstepB;
;             const bool s2a = SPLITA && (t + 1 >= g.ksplit), s2b = SPLITA && !last && (t + 2 >= g.ksplit);
;             const char* a3 = a2 + ((Epi::KSUB || s2b) ? (size_t)2048 : kstep); const char* b3 = b2 + kstepB;
;             const bool m1 = SPLITA && mirC && (t + 1 < g.ksplit), m2 = SPLITA && (last ? mirN : (mirC && (t + 2 < g.ksplit)));
;             const unsigned vo1[2] = {s2a ? voffA2[0] : m1 ? voffAm[0] : voffA[0], s2a ? voffA2[1] : m1 ? voffAm[1] : voffA[1]}, vo2[2] = {s2b ? voffA2[0] : m2 ? voffAm[0] : voffA[0], s2b ? voffA2[1] : m2 ? voffAm[1] : voffA[1]};
;             const char* a1h = m1 ? a1 - hstepA : a1 + hstepA; const char* a2h = m2 ? a2 - hstepA : a2 + hstepA;
;             PG8_LDB(B0, 0, 0); PG8_LDB(B1, 0, 1); PG8_SCHED; PG8_LDA(At, 0, 0); PG8_STAGE(PG8_SA(1, 1), a1h, vo1);
;             PG8_WAIT_V(8); PG8_WAIT_L(0); PG8_BAR; PG8_MMA(0, 0, At, B0); PG8_MMA(0, 1, At, B1); PG8_BAR; PG8_SCHED;
;             PG8_LDA(At, 0, 1); PG8_STAGE(PG8_SB(0, 0), b2, voffB); PG8_STAGE(PG8_SB(0, 1), b2 + hstepB, voffB); PG8_STAGE(PG8_SA(0, 0), a2, vo2);
.LBB0_414:
	s_add_u32 s48, s48, 0x40080
	s_addc_u32 s49, s49, 0
	s_add_u32 s5, s50, 0x100
	s_addc_u32 s11, s51, 0
	s_mov_b32 s31, -2
	s_cmp_lg_u32 s99, 0
	s_cbranch_scc0 .Lyd_dft
	s_barrier
	s_mov_b32 s99, 0
.Lyd_dft:
	ds_read_b128 v[146:149], v156
	ds_read_b128 v[150:153], v156 offset:1024
	ds_read_b128 v[160:163], v156 offset:2048
	ds_read_b128 v[164:167], v156 offset:3072
	ds_read_b128 v[168:171], v157
	ds_read_b128 v[172:175], v157 offset:1024
	ds_read_b128 v[176:179], v157 offset:2048
	ds_read_b128 v[180:183], v157 offset:3072
	s_add_u32 s12, s48, 0xfffc0080
	s_addc_u32 s13, s49, -1
	s_cmp_eq_u32 s31, 12
	s_cselect_b32 s53, s1, s13
	s_cselect_b32 s52, s0, s12
	s_cselect_b32 s51, s47, s11
	s_cselect_b32 s50, s46, s5
	s_add_i32 m0, s54, 0xc000
	ds_read_b128 v[184:187], v158
	ds_read_b128 v[188:191], v158 offset:1024
	ds_read_b128 v[192:195], v158 offset:2048
	ds_read_b128 v[196:199], v158 offset:3072
	ds_read_b128 v[200:203], v158 offset:4096
	ds_read_b128 v[204:207], v158 offset:5120
	ds_read_b128 v[208:211], v158 offset:6144
	ds_read_b128 v[212:215], v158 offset:7168
	global_load_lds_dwordx4 v138, s[48:49]
	s_add_i32 m0, s54, 0xe000
	s_nop 0
	global_load_lds_dwordx4 v140, s[48:49]
	s_waitcnt vmcnt(8)
	s_waitcnt lgkmcnt(0)
	s_barrier
	s_setprio 1
	s_waitcnt lgkmcnt(0)
	v_mfma_f32_16x16x32_bf16 v[126:129], v[146:149], v[184:187], 0
	v_mfma_f32_16x16x32_bf16 v[122:125], v[160:163], v[184:187], 0
	v_mfma_f32_16x16x32_bf16 v[110:113], v[146:149], v[192:195], 0
	v_mfma_f32_16x16x32_bf16 v[106:109], v[160:163], v[192:195], 0
	v_mfma_f32_16x16x32_bf16 v[94:97], v[146:149], v[200:203], 0
	v_mfma_f32_16x16x32_bf16 v[90:93], v[160:163], v[200:203], 0
	v_mfma_f32_16x16x32_bf16 v[78:81], v[146:149], v[208:211], 0
	v_mfma_f32_16x16x32_bf16 v[74:77], v[160:163], v[208:211], 0
	v_mfma_f32_16x16x32_bf16 v[126:129], v[150:153], v[188:191], v[126:129]
	v_mfma_f32_16x16x32_bf16 v[122:125], v[164:167], v[188:191], v[122:125]
	v_mfma_f32_16x16x32_bf16 v[110:113], v[150:153], v[196:199], v[110:113]
	v_mfma_f32_16x16x32_bf16 v[106:109], v[164:167], v[196:199], v[106:109]
	v_mfma_f32_16x16x32_bf16 v[94:97], v[150:153], v[204:207], v[94:97]
	v_mfma_f32_16x16x32_bf16 v[90:93], v[164:167], v[204:207], v[90:93]
	v_mfma_f32_16x16x32_bf16 v[78:81], v[150:153], v[212:215], v[78:81]
	v_mfma_f32_16x16x32_bf16 v[74:77], v[164:167], v[212:215], v[74:77]
	s_setprio 0
	s_setprio 1
	v_mfma_f32_16x16x32_bf16 v[118:121], v[168:171], v[184:187], 0
	v_mfma_f32_16x16x32_bf16 v[114:117], v[176:179], v[184:187], 0
	v_mfma_f32_16x16x32_bf16 v[102:105], v[168:171], v[192:195], 0
	v_mfma_f32_16x16x32_bf16 v[98:101], v[176:179], v[192:195], 0
	v_mfma_f32_16x16x32_bf16 v[86:89], v[168:171], v[200:203], 0
	v_mfma_f32_16x16x32_bf16 v[82:85], v[176:179], v[200:203], 0
	v_mfma_f32_16x16x32_bf16 v[70:73], v[168:171], v[208:211], 0
	v_mfma_f32_16x16x32_bf16 v[66:69], v[176:179], v[208:211], 0
	v_mfma_f32_16x16x32_bf16 v[118:121], v[172:175], v[188:191], v[118:121]
	v_mfma_f32_16x16x32_bf16 v[114:117], v[180:183], v[188:191], v[114:117]
	v_mfma_f32_16x16x32_bf16 v[102:105], v[172:175], v[196:199], v[102:105]
	v_mfma_f32_16x16x32_bf16 v[98:101], v[180:183], v[196:199], v[98:101]
	v_mfma_f32_16x16x32_bf16 v[86:89], v[172:175], v[204:207], v[86:89]
	v_mfma_f32_16x16x32_bf16 v[82:85], v[180:183], v[204:207], v[82:85]
	v_mfma_f32_16x16x32_bf16 v[70:73], v[172:175], v[212:215], v[70:73]
	v_mfma_f32_16x16x32_bf16 v[66:69], v[180:183], v[212:215], v[66:69]
	s_setprio 0
	s_barrier
	s_add_u32 s98, s50, s18
	s_addc_u32 s99, s51, s19
	s_add_u32 s100, s52, s18
	s_addc_u32 s101, s53, s19
	s_add_i32 s12, s65, s33
	s_mov_b32 m0, s12
	ds_read_b128 v[184:187], v158 offset:16384
	ds_read_b128 v[188:191], v158 offset:17408
	ds_read_b128 v[192:195], v158 offset:18432
	ds_read_b128 v[196:199], v158 offset:19456
	ds_read_b128 v[200:203], v158 offset:20480
	ds_read_b128 v[204:207], v158 offset:21504
	ds_read_b128 v[208:211], v158 offset:22528
	ds_read_b128 v[212:215], v158 offset:23552
	global_load_lds_dwordx4 v132, s[50:51]
	s_add_i32 m0, s12, 0x2000
	s_add_u32 s76, s50, 0xc00000
	s_addc_u32 s77, s51, 0
	s_add_i32 s12, s72, s33
	global_load_lds_dwordx4 v136, s[50:51]
	s_mov_b32 m0, s12
	s_nop 0
	global_load_lds_dwordx4 v132, s[76:77]
	s_add_i32 m0, s12, 0x2000
	s_nop 0
	global_load_lds_dwordx4 v136, s[76:77]
	s_mov_b32 m0, s54
	s_nop 0
	global_load_lds_dwordx4 v130, s[52:53]
	s_mov_b32 m0, s55
	s_nop 0
	global_load_lds_dwordx4 v134, s[52:53]
	s_waitcnt vmcnt(8)
	s_waitcnt lgkmcnt(0)
	s_barrier
	s_setprio 1
	s_waitcnt lgkmcnt(0)
	v_mfma_f32_16x16x32_bf16 v[62:65], v[146:149], v[184:187], 0
	v_mfma_f32_16x16x32_bf16 v[58:61], v[160:163], v[184:187], 0
	v_mfma_f32_16x16x32_bf16 v[38:41], v[146:149], v[192:195], 0
	v_mfma_f32_16x16x32_bf16 v[34:37], v[160:163], v[192:195], 0
	v_mfma_f32_16x16x32_bf16 v[22:25], v[146:149], v[200:203], 0
	v_mfma_f32_16x16x32_bf16 v[18:21], v[160:163], v[200:203], 0
	v_mfma_f32_16x16x32_bf16 v[6:9], v[146:149], v[208:211], 0
	v_mfma_f32_16x16x32_bf16 v[2:5], v[160:163], v[208:211], 0
	v_mfma_f32_16x16x32_bf16 v[62:65], v[150:153], v[188:191], v[62:65]
	v_mfma_f32_16x16x32_bf16 v[58:61], v[164:167], v[188:191], v[58:61]
	v_mfma_f32_16x16x32_bf16 v[38:41], v[150:153], v[196:199], v[38:41]
	v_mfma_f32_16x16x32_bf16 v[34:37], v[164:167], v[196:199], v[34:37]
	v_mfma_f32_16x16x32_bf16 v[22:25], v[150:153], v[204:207], v[22:25]
	v_mfma_f32_16x16x32_bf16 v[18:21], v[164:167], v[204:207], v[18:21]
	v_mfma_f32_16x16x32_bf16 v[6:9], v[150:153], v[212:215], v[6:9]
	v_mfma_f32_16x16x32_bf16 v[2:5], v[164:167], v[212:215], v[2:5]
	s_setprio 0
	s_setprio 1
	v_mfma_f32_16x16x32_bf16 v[54:57], v[168:171], v[184:187], 0
	v_mfma_f32_16x16x32_bf16 v[50:53], v[176:179], v[184:187], 0
	v_mfma_f32_16x16x32_bf16 v[42:45], v[168:171], v[192:195], 0
	v_mfma_f32_16x16x32_bf16 v[46:49], v[176:179], v[192:195], 0
	v_mfma_f32_16x16x32_bf16 v[26:29], v[168:171], v[200:203], 0
	v_mfma_f32_16x16x32_bf16 v[30:33], v[176:179], v[200:203], 0
	v_mfma_f32_16x16x32_bf16 v[10:13], v[168:171], v[208:211], 0
	v_mfma_f32_16x16x32_bf16 v[14:17], v[176:179], v[208:211], 0
	v_mfma_f32_16x16x32_bf16 v[54:57], v[172:175], v[188:191], v[54:57]
	v_mfma_f32_16x16x32_bf16 v[50:53], v[180:183], v[188:191], v[50:53]
	v_mfma_f32_16x16x32_bf16 v[42:45], v[172:175], v[196:199], v[42:45]
	v_mfma_f32_16x16x32_bf16 v[46:49], v[180:183], v[196:199], v[46:49]
	v_mfma_f32_16x16x32_bf16 v[26:29], v[172:175], v[204:207], v[26:29]
	v_mfma_f32_16x16x32_bf16 v[30:33], v[180:183], v[204:207], v[30:33]
	v_mfma_f32_16x16x32_bf16 v[10:13], v[172:175], v[212:215], v[10:13]
	v_mfma_f32_16x16x32_bf16 v[14:17], v[180:183], v[212:215], v[14:17]
	s_setprio 0
	s_barrier
; #define PG8_STAGE(bufoff, gbase, voff) do { _Pragma("unroll") for (int _i = 0; _i < 2; ++_i) \
;         __builtin_amdgcn_global_load_lds((const unsigned*)((const char*)(gbase) + (voff)[_i]), (LAS unsigned*)(lds + (bufoff) + ldsw + _i * 8192), 16, 0, 0); } while (0)
; #define PG8_LDA(dst, b, h) do { _Pragma("unroll") for (int m = 0; m < 4; ++m) _Pragma("unroll") for (int k = 0; k < 2; ++k) dst[m][k] = *(const LAS bf16x8*)(lds + PG8_SA(b, h) + aoff + m * 2048 + k * 1024); } while (0)
; #define PG8_LDB(dst, b, h) do { _Pragma("unroll") for (int n = 0; n < 2; ++n) _Pragma("unroll") for (int k = 0; k < 2; ++k) dst[n][k] = *(const LAS bf16x8*)(lds + PG8_SB(b, h) + boff + n * 2048 + k * 1024); } while (0)
; #define PG8_MMA(ai, bj, At, Bt) do { __builtin_amdgcn_s_setprio(1); _Pragma("unroll") for (int m = 0; m < 4; ++m) _Pragma("unroll") for (int n = 0; n < 2; ++n) _Pragma("unroll") for (int k = 0; k < 2; ++k) \
;         acc[ai][bj][m][n] = __builtin_amdgcn_mfma_f32_16x16x32_bf16(Bt[n][k], At[m][k], acc[ai][bj][m][n], 0, 0, 0); __builtin_amdgcn_s_setprio(0); } while (0)
; #define PG8_WAIT_V(n) asm volatile("s_waitcnt vmcnt(" #n ")" ::: "memory")
; #define PG8_WAIT_L(n) asm volatile("s_waitcnt lgkmcnt(" #n ")" ::: "memory")
; #define PG8_BAR __builtin_amdgcn_s_barrier()
; #define PG8_SCHED __builtin_amdgcn_sched_barrier(0)
; template <class Epi, bool ALIGN_EPI, bool SPLITA>
; __device__ __forceinline__ void gemm_phase(LAS unsigned char* lds, const Gemm g, const StaticOrder& S, const Epi& E) {
;     ...
;             PG8_WAIT_V(8); PG8_WAIT_L(0); PG8_BAR; PG8_MMA(1, 0, At, B0); PG8_MMA(1, 1, At, B1); PG8_BAR; PG8_SCHED;
;             PG8_LDB(B0, 1, 0); PG8_LDB(B1, 1, 1); PG8_SCHED; PG8_LDA(At, 1, 0); PG8_STAGE(PG8_SA(0, 1), a2h, vo2);
;             PG8_WAIT_V(8); PG8_WAIT_L(0); PG8_BAR; PG8_MMA(0, 0, At, B0); PG8_MMA(0, 1, At, B1); PG8_BAR; PG8_SCHED;
;             PG8_LDA(At, 1, 1); PG8_STAGE(PG8_SB(1, 0), b3, voffB); PG8_STAGE(PG8_SB(1, 1), b3 + hstepB, voffB); PG8_STAGE(PG8_SA(1, 0), a3, vo2);
;             PG8_WAIT_V(8); PG8_WAIT_L(0); PG8_BAR; PG8_MMA(1, 0, At, B0); PG8_MMA(1, 1, At, B1); PG8_BAR; PG8_SCHED;
	s_add_i32 s12, 0, 0x18000
	v_add_u32_e32 v159, s12, v154
	s_add_i32 s13, 0, 0x1c000
	ds_read_b128 v[146:149], v159
	ds_read_b128 v[150:153], v159 offset:1024
	ds_read_b128 v[160:163], v159 offset:2048
	ds_read_b128 v[164:167], v159 offset:3072
	v_add_u32_e32 v159, s13, v154
	ds_read_b128 v[168:171], v159
	ds_read_b128 v[172:175], v159 offset:1024
	ds_read_b128 v[176:179], v159 offset:2048
	ds_read_b128 v[180:183], v159 offset:3072
	s_add_u32 s52, s52, 0x40000
	s_addc_u32 s53, s53, 0
	s_mov_b32 m0, s56
	ds_read_b128 v[184:187], v158 offset:32768
	ds_read_b128 v[188:191], v158 offset:33792
	ds_read_b128 v[192:195], v158 offset:34816
	ds_read_b128 v[196:199], v158 offset:35840
	ds_read_b128 v[200:203], v158 offset:36864
	ds_read_b128 v[204:207], v158 offset:37888
	ds_read_b128 v[208:211], v158 offset:38912
	ds_read_b128 v[212:215], v158 offset:39936
	global_load_lds_dwordx4 v130, s[52:53]
	s_mov_b32 m0, s57
	s_nop 0
	global_load_lds_dwordx4 v134, s[52:53]
	s_waitcnt vmcnt(8)
	s_waitcnt lgkmcnt(0)
	s_barrier
	s_setprio 1
	s_waitcnt lgkmcnt(0)
	v_mfma_f32_16x16x32_bf16 v[126:129], v[146:149], v[184:187], v[126:129]
	v_mfma_f32_16x16x32_bf16 v[122:125], v[160:163], v[184:187], v[122:125]
	v_mfma_f32_16x16x32_bf16 v[110:113], v[146:149], v[192:195], v[110:113]
	v_mfma_f32_16x16x32_bf16 v[106:109], v[160:163], v[192:195], v[106:109]
	v_mfma_f32_16x16x32_bf16 v[94:97], v[146:149], v[200:203], v[94:97]
	v_mfma_f32_16x16x32_bf16 v[90:93], v[160:163], v[200:203], v[90:93]
	v_mfma_f32_16x16x32_bf16 v[78:81], v[146:149], v[208:211], v[78:81]
	v_mfma_f32_16x16x32_bf16 v[74:77], v[160:163], v[208:211], v[74:77]
	v_mfma_f32_16x16x32_bf16 v[126:129], v[150:153], v[188:191], v[126:129]
	v_mfma_f32_16x16x32_bf16 v[122:125], v[164:167], v[188:191], v[122:125]
	v_mfma_f32_16x16x32_bf16 v[110:113], v[150:153], v[196:199], v[110:113]
	v_mfma_f32_16x16x32_bf16 v[106:109], v[164:167], v[196:199], v[106:109]
	v_mfma_f32_16x16x32_bf16 v[94:97], v[150:153], v[204:207], v[94:97]
	v_mfma_f32_16x16x32_bf16 v[90:93], v[164:167], v[204:207], v[90:93]
	v_mfma_f32_16x16x32_bf16 v[78:81], v[150:153], v[212:215], v[78:81]
	v_mfma_f32_16x16x32_bf16 v[74:77], v[164:167], v[212:215], v[74:77]
	s_setprio 0
	s_setprio 1
	v_mfma_f32_16x16x32_bf16 v[118:121], v[168:171], v[184:187], v[118:121]
	v_mfma_f32_16x16x32_bf16 v[114:117], v[176:179], v[184:187], v[114:117]
	v_mfma_f32_16x16x32_bf16 v[102:105], v[168:171], v[192:195], v[102:105]
	v_mfma_f32_16x16x32_bf16 v[98:101], v[176:179], v[192:195], v[98:101]
	v_mfma_f32_16x16x32_bf16 v[86:89], v[168:171], v[200:203], v[86:89]
	v_mfma_f32_16x16x32_bf16 v[82:85], v[176:179], v[200:203], v[82:85]
	v_mfma_f32_16x16x32_bf16 v[70:73], v[168:171], v[208:211], v[70:73]
	v_mfma_f32_16x16x32_bf16 v[66:69], v[176:179], v[208:211], v[66:69]
	v_mfma_f32_16x16x32_bf16 v[118:121], v[172:175], v[188:191], v[118:121]
	v_mfma_f32_16x16x32_bf16 v[114:117], v[180:183], v[188:191], v[114:117]
	v_mfma_f32_16x16x32_bf16 v[102:105], v[172:175], v[196:199], v[102:105]
	v_mfma_f32_16x16x32_bf16 v[98:101], v[180:183], v[196:199], v[98:101]
	v_mfma_f32_16x16x32_bf16 v[86:89], v[172:175], v[204:207], v[86:89]
	v_mfma_f32_16x16x32_bf16 v[82:85], v[180:183], v[204:207], v[82:85]
	v_mfma_f32_16x16x32_bf16 v[70:73], v[172:175], v[212:215], v[70:73]
	v_mfma_f32_16x16x32_bf16 v[66:69], v[180:183], v[212:215], v[66:69]
	s_setprio 0
	s_barrier
	s_add_i32 s12, s12, s33
	s_mov_b32 m0, s12
	ds_read_b128 v[184:187], v158 offset:49152
	ds_read_b128 v[188:191], v158 offset:50176
	ds_read_b128 v[192:195], v158 offset:51200
	ds_read_b128 v[196:199], v158 offset:52224
	ds_read_b128 v[200:203], v158 offset:53248
	ds_read_b128 v[204:207], v158 offset:54272
	ds_read_b128 v[208:211], v158 offset:55296
	ds_read_b128 v[212:215], v158 offset:56320
	global_load_lds_dwordx4 v132, s[98:99]
	s_add_i32 m0, s12, 0x2000
	s_add_u32 s50, s50, 0xc00080
	s_addc_u32 s51, s51, 0
	s_add_i32 s12, s13, s33
	global_load_lds_dwordx4 v136, s[98:99]
	s_mov_b32 m0, s12
	s_nop 0
	global_load_lds_dwordx4 v132, s[50:51]
	s_add_i32 m0, s12, 0x2000
	s_nop 0
	global_load_lds_dwordx4 v136, s[50:51]
	s_mov_b32 m0, s61
	s_nop 0
	global_load_lds_dwordx4 v130, s[100:101]
	s_mov_b32 m0, s64
	s_nop 0
	global_load_lds_dwordx4 v134, s[100:101]
	s_waitcnt vmcnt(8)
	s_waitcnt lgkmcnt(0)
	s_barrier
	s_setprio 1
	s_waitcnt lgkmcnt(0)
	v_mfma_f32_16x16x32_bf16 v[62:65], v[146:149], v[184:187], v[62:65]
	v_mfma_f32_16x16x32_bf16 v[58:61], v[160:163], v[184:187], v[58:61]
	v_mfma_f32_16x16x32_bf16 v[38:41], v[146:149], v[192:195], v[38:41]
	v_mfma_f32_16x16x32_bf16 v[34:37], v[160:163], v[192:195], v[34:37]
	v_mfma_f32_16x16x32_bf16 v[22:25], v[146:149], v[200:203], v[22:25]
	v_mfma_f32_16x16x32_bf16 v[18:21], v[160:163], v[200:203], v[18:21]
	v_mfma_f32_16x16x32_bf16 v[6:9], v[146:149], v[208:211], v[6:9]
	v_mfma_f32_16x16x32_bf16 v[2:5], v[160:163], v[208:211], v[2:5]
	v_mfma_f32_16x16x32_bf16 v[62:65], v[150:153], v[188:191], v[62:65]
	v_mfma_f32_16x16x32_bf16 v[58:61], v[164:167], v[188:191], v[58:61]
	v_mfma_f32_16x16x32_bf16 v[38:41], v[150:153], v[196:199], v[38:41]
	v_mfma_f32_16x16x32_bf16 v[34:37], v[164:167], v[196:199], v[34:37]
	v_mfma_f32_16x16x32_bf16 v[22:25], v[150:153], v[204:207], v[22:25]
	v_mfma_f32_16x16x32_bf16 v[18:21], v[164:167], v[204:207], v[18:21]
	v_mfma_f32_16x16x32_bf16 v[6:9], v[150:153], v[212:215], v[6:9]
	v_mfma_f32_16x16x32_bf16 v[2:5], v[164:167], v[212:215], v[2:5]
	s_setprio 0
	s_setprio 1
	v_mfma_f32_16x16x32_bf16 v[54:57], v[168:171], v[184:187], v[54:57]
	v_mfma_f32_16x16x32_bf16 v[50:53], v[176:179], v[184:187], v[50:53]
	v_mfma_f32_16x16x32_bf16 v[42:45], v[168:171], v[192:195], v[42:45]
	v_mfma_f32_16x16x32_bf16 v[46:49], v[176:179], v[192:195], v[46:49]
	v_mfma_f32_16x16x32_bf16 v[26:29], v[168:171], v[200:203], v[26:29]
	v_mfma_f32_16x16x32_bf16 v[30:33], v[176:179], v[200:203], v[30:33]
	v_mfma_f32_16x16x32_bf16 v[10:13], v[168:171], v[208:211], v[10:13]
	v_mfma_f32_16x16x32_bf16 v[14:17], v[176:179], v[208:211], v[14:17]
	v_mfma_f32_16x16x32_bf16 v[54:57], v[172:175], v[188:191], v[54:57]
	v_mfma_f32_16x16x32_bf16 v[50:53], v[180:183], v[188:191], v[50:53]
	v_mfma_f32_16x16x32_bf16 v[42:45], v[172:175], v[196:199], v[42:45]
	v_mfma_f32_16x16x32_bf16 v[46:49], v[180:183], v[196:199], v[46:49]
	v_mfma_f32_16x16x32_bf16 v[26:29], v[172:175], v[204:207], v[26:29]
	v_mfma_f32_16x16x32_bf16 v[30:33], v[180:183], v[204:207], v[30:33]
	v_mfma_f32_16x16x32_bf16 v[10:13], v[172:175], v[212:215], v[10:13]
	v_mfma_f32_16x16x32_bf16 v[14:17], v[180:183], v[212:215], v[14:17]
	s_setprio 0
	s_barrier
	s_add_i32 s31, s31, 2
	s_add_u32 s48, s48, 0x100
	s_addc_u32 s49, s49, 0
	s_add_u32 s5, s5, 0x100
	s_addc_u32 s11, s11, 0

; #define PG8_BAR __builtin_amdgcn_s_barrier()
; template <class Epi, bool ALIGN_EPI, bool SPLITA>
; __device__ __forceinline__ void gemm_phase(LAS unsigned char* lds, const Gemm g, const StaticOrder& S, const Epi& E) {
;     ...
;         if (!has_next) break;
; #pragma unroll
;         for (int a = 0; a < 2; ++a)
; #pragma unroll
;             for (int b = 0; b < 2; ++b)
; #pragma unroll
;                 for (int m = 0; m < 4; ++m)
; #pragma unroll
;                     for (int n = 0; n < 2; ++n) acc[a][b][m][n] = (f32x4){0.f, 0.f, 0.f, 0.f};
;         cur = nxt; cA = nA; cB = nB; mirC = mirN; if constexpr (SPLITA) cA2 = (const char*)g.A2 + (size_t)cur.pm * tstepA; ++ui;
;         if constexpr (ALIGN_EPI) { if (wr == 1) PG8_BAR; }
.LBB0_547:
	s_mov_b32 s99, 0
	s_andn2_b64 vcc, exec, s[16:17]
	s_cbranch_vccnz .LBB0_406
	s_mov_b32 s99, 1
	s_branch .LBB0_406

; #define PG8_STAGE(bufoff, gbase, voff) do { _Pragma("unroll") for (int _i = 0; _i < 2; ++_i) \
;         __builtin_amdgcn_global_load_lds((const unsigned*)((const char*)(gbase) + (voff)[_i]), (LAS unsigned*)(lds + (bufoff) + ldsw + _i * 8192), 16, 0, 0); } while (0)
; #define PG8_WAIT_V(n) asm volatile("s_waitcnt vmcnt(" #n ")" ::: "memory")
; #define PG8_BAR __builtin_amdgcn_s_barrier()
; template <class Epi, bool ALIGN_EPI, bool SPLITA>
; __device__ __forceinline__ void gemm_phase(LAS unsigned char* lds, const Gemm g, const StaticOrder& S, const Epi& E) {
;     ...
;     const char* cA = baseA1(cur); const char* cB = baseB(cur);
;     const char* cA2 = SPLITA ? (const char*)g.A2 + (size_t)cur.pm * tstepA : cA;
;     bool mirC = mirrored(cur);
;     { const unsigned vo[2] = {mirC ? voffAm[0] : voffA[0], mirC ? voffAm[1] : voffA[1]}; const char* cAh = mirC ? cA - hstepA : cA + hstepA;
;       PG8_STAGE(PG8_SB(0, 0), cB, voffB); PG8_STAGE(PG8_SB(0, 1), cB + hstepB, voffB); PG8_STAGE(PG8_SA(0, 0), cA, vo); PG8_STAGE(PG8_SA(0, 1), cAh, vo);
;       if (wr == 1) PG8_BAR;
;       PG8_WAIT_V(2); PG8_BAR;
;       PG8_STAGE(PG8_SB(1, 0), cB + kstepB, voffB); PG8_STAGE(PG8_SA(1, 0), cA + kofs(1), vo); PG8_STAGE(PG8_SB(1, 1), cB + hstepB + kstepB, voffB); }
;     PG8_WAIT_V(6); PG8_BAR;
.LBB0_703:
	s_lshl_b32 s3, s3, 5
	s_mov_b64 s[16:17], 0x80
	s_and_b32 s8, s3, 0x60
	s_add_i32 m0, s7, 0x18000
	v_lshl_add_u64 v[8:9], v[8:9], 0, s[16:17]
	s_lshl_b32 s5, s2, 13
	s_lshl_b32 s3, s8, 7
	s_waitcnt vmcnt(2)
	s_barrier
	global_load_lds_dwordx4 v[8:9], off
	v_lshl_add_u64 v[6:7], v[6:7], 0, s[16:17]
	s_add_i32 m0, s7, 0x1a000
	s_mov_b64 s[18:19], 0x800
	s_add_i32 s49, s7, 0x8000
	s_add_i32 s50, s7, 0xa000
	global_load_lds_dwordx4 v[6:7], off
	v_lshl_add_u64 v[2:3], v[2:3], 0, s[18:19]
	s_mov_b32 m0, s49
	s_add_u32 s12, s44, 0x40080
	global_load_lds_dwordx4 v[2:3], off
	v_lshl_add_u64 v[2:3], v[4:5], 0, s[18:19]
	s_mov_b32 m0, s50
	s_addc_u32 s13, s45, 0
	global_load_lds_dwordx4 v[2:3], off
	s_add_i32 m0, s7, 0x1c000
	v_lshl_add_u64 v[2:3], s[12:13], 0, v[156:157]
	global_load_lds_dwordx4 v[2:3], off
	v_lshl_add_u64 v[2:3], s[12:13], 0, v[160:161]
	s_add_i32 m0, s7, 0x1e000
	s_cmpk_lt_u32 s4, 0x100
	global_load_lds_dwordx4 v[2:3], off
	v_bfe_u32 v2, v10, 4, 2
	v_and_b32_e32 v3, 15, v10
	v_lshlrev_b32_e32 v4, 4, v2
	v_lshl_or_b32 v1, s2, 6, v3
	v_lshl_or_b32 v3, v3, 6, v4
	v_lshlrev_b32_e32 v4, 2, v10
	v_and_b32_e32 v4, 32, v4
	s_waitcnt vmcnt(6)
	v_bitop3_b32 v5, v3, s5, v4 bitop3:0xde
	v_bitop3_b32 v177, v3, s3, v4 bitop3:0xde
	s_cselect_b64 s[20:21], -1, 0
	s_add_i32 s54, 0, 0x10000
	s_add_i32 s55, 0, 0x14000
	v_cmp_eq_u32_e64 s[2:3], 0, v2
	s_ashr_i32 s51, s15, 31
	s_ashr_i32 s52, s14, 31
	v_lshl_or_b32 v183, v2, 3, s8
	v_mov_b64_e32 v[162:163], 0x300
	v_mov_b64_e32 v[164:165], 0x2ff
	s_movk_i32 s53, 0x61
	v_add_u32_e32 v189, s54, v177
	v_add_u32_e32 v192, s55, v177
	v_add_u32_e32 v193, 0, v5
	s_mov_b32 s56, 0
	s_barrier
	s_mov_b32 s99, 0
	s_branch .LBB0_706

; #define PG8_LDA(dst, b, h) do { _Pragma("unroll") for (int m = 0; m < 4; ++m) _Pragma("unroll") for (int k = 0; k < 2; ++k) dst[m][k] = *(const LAS bf16x8*)(lds + PG8_SA(b, h) + aoff + m * 2048 + k * 1024); } while (0)
; template <class Epi, bool ALIGN_EPI, bool SPLITA>
; __device__ __forceinline__ void gemm_phase(LAS unsigned char* lds, const Gemm g, const StaticOrder& S, const Epi& E) {
;     ...
;         const bool has_next = S.next(ui + 1, nxt);
;         const char* nA = has_next ? baseA1(nxt) : cA;
;         const char* nB = has_next ? baseB(nxt) : cB;
;         const bool mirN = has_next ? mirrored(nxt) : mirC;
;         for (int t = 0; t < nt; t += 2) {
;             const bool last = (t == nt - 2);
;             if constexpr (Epi::MIDK) { if (t == g.ksplit) E.mid(acc, cur, wr, wc, fr, fq); }
;             const char *a1, *a2;
;             if constexpr (SPLITA) {
;                 a1 = (t + 1 < g.ksplit) ? cA + (size_t)(t + 1) * kstep : cA2 + (size_t)(t + 1 - g.ksplit) * 2048;
;                 a2 = last ? nA : ((t + 2 < g.ksplit) ? cA + (size_t)(t + 2) * kstep : cA2 + (size_t)(t + 2 - g.ksplit) * 2048);
;             } else { a1 = cA + kofs(t + 1); a2 = last ? nA : cA + kofs(t + 2); }
;             const char* b2 = last ? nB : cB + (size_t)(t + 2) * kstepB;
;             const bool s2a = SPLITA && (t + 1 >= g.ksplit), s2b = SPLITA && !last && (t + 2 >= g.ksplit);
;             const char* a3 = a2 + ((Epi::KSUB || s2b) ? (size_t)2048 : kstep); const char* b3 = b2 + kstepB;
;             const bool m1 = SPLITA && mirC && (t + 1 < g.ksplit), m2 = SPLITA && (last ? mirN : (mirC && (t + 2 < g.ksplit)));
;             const unsigned vo1[2] = {s2a ? voffA2[0] : m1 ? voffAm[0] : voffA[0], s2a ? voffA2[1] : m1 ? voffAm[1] : voffA[1]}, vo2[2] = {s2b ? voffA2[0] : m2 ? voffAm[0] : voffA[0], s2b ? voffA2[1] : m2 ? voffAm[1] : voffA[1]};
;             const char* a1h = m1 ? a1 - hstepA : a1 + hstepA; const char* a2h = m2 ? a2 - hstepA : a2 + hstepA;
;             PG8_LDB(B0, 0, 0); PG8_LDB(B1, 0, 1); PG8_SCHED; PG8_LDA(At, 0, 0); PG8_STAGE(PG8_SA(1, 1), a1h, vo1);
;             PG8_WAIT_V(8); PG8_WAIT_L(0); PG8_BAR; PG8_MMA(0, 0, At, B0); PG8_MMA(0, 1, At, B1); PG8_BAR; PG8_SCHED;
;             PG8_LDA(At, 0, 1); PG8_STAGE(PG8_SB(0, 0), b2, voffB); PG8_STAGE(PG8_SB(0, 1), b2 + hstepB, voffB); PG8_STAGE(PG8_SA(0, 0), a2, vo2);
.LBB0_708:
	s_ashr_i32 s23, s22, 31
	s_lshl_b64 s[12:13], s[22:23], 19
	s_add_u32 s30, s84, s12
	s_addc_u32 s31, s85, s13
	s_and_b64 s[12:13], s[4:5], exec
	s_cselect_b32 s23, s31, s43
	s_cselect_b32 s39, s30, s42
	s_ashr_i32 s25, s24, 31
	s_lshl_b64 s[12:13], s[24:25], 19
	s_add_u32 s36, s28, s12
	s_addc_u32 s37, s29, s13
	s_and_b64 s[12:13], s[4:5], exec
	s_cselect_b32 s25, s37, s45
	s_cselect_b32 s57, s36, s44
	s_add_u32 s60, s44, 0x100
	s_addc_u32 s61, s45, 0
	s_mov_b32 s44, -2
	s_movk_i32 s64, 0x1000
	s_cmp_lg_u32 s99, 0
	s_cbranch_scc0 .Lyd_p4
	s_barrier
	s_mov_b32 s99, 0
.Lyd_p4:
	s_add_i32 s65, s44, 2
	s_lshr_b32 s8, s65, 2
	s_lshl_b64 s[12:13], s[8:9], 17
	s_add_i32 s8, s64, 0xfffff000
	s_and_b32 s8, s8, 0x1000
	s_add_u32 s12, s42, s12
	s_addc_u32 s13, s43, s13
	s_add_u32 s45, s12, s8
	s_addc_u32 s46, s13, 0
	s_add_i32 s8, s44, 4
	ds_read_b128 v[130:133], v189
	ds_read_b128 v[134:137], v189 offset:1024
	ds_read_b128 v[138:141], v189 offset:2048
	ds_read_b128 v[142:145], v189 offset:3072
	ds_read_b128 v[146:149], v192
	ds_read_b128 v[150:153], v192 offset:1024
	ds_read_b128 v[166:169], v192 offset:2048
	ds_read_b128 v[170:173], v192 offset:3072
	s_lshr_b32 s8, s8, 2
	s_lshl_b64 s[12:13], s[8:9], 17
	s_and_b32 s8, s64, 0x1000
	s_add_u32 s12, s42, s12
	s_addc_u32 s13, s43, s13
	s_add_u32 s8, s12, s8
	s_addc_u32 s47, s13, 0
	s_add_u32 s12, s45, 0x10800
	s_addc_u32 s13, s46, 0
	s_cmp_eq_u32 s44, 12
	s_cselect_b32 s44, s57, s60
	s_cselect_b32 s47, s23, s47
	s_cselect_b32 s46, s39, s8
	s_cselect_b32 s45, s25, s61
	s_add_i32 m0, s7, 0xc000
	ds_read_b128 v[178:181], v193
	ds_read_b128 v[184:187], v193 offset:1024
	ds_read_b128 v[194:197], v193 offset:2048
	ds_read_b128 v[198:201], v193 offset:3072
	ds_read_b128 v[202:205], v193 offset:4096
	ds_read_b128 v[206:209], v193 offset:5120
	ds_read_b128 v[210:213], v193 offset:6144
	ds_read_b128 v[214:217], v193 offset:7168
	global_load_lds_dwordx4 v154, s[12:13]
	s_add_i32 m0, s7, 0xe000
	s_nop 0
	global_load_lds_dwordx4 v158, s[12:13]
	s_waitcnt vmcnt(8)
	s_waitcnt lgkmcnt(0)
	s_barrier
	s_setprio 1
	s_waitcnt lgkmcnt(0)
	v_mfma_f32_16x16x32_bf16 v[126:129], v[130:133], v[178:181], 0
	v_mfma_f32_16x16x32_bf16 v[122:125], v[138:141], v[178:181], 0
	v_mfma_f32_16x16x32_bf16 v[110:113], v[130:133], v[194:197], 0
	v_mfma_f32_16x16x32_bf16 v[106:109], v[138:141], v[194:197], 0
	v_mfma_f32_16x16x32_bf16 v[94:97], v[130:133], v[202:205], 0
	v_mfma_f32_16x16x32_bf16 v[90:93], v[138:141], v[202:205], 0
	v_mfma_f32_16x16x32_bf16 v[78:81], v[130:133], v[210:213], 0
	v_mfma_f32_16x16x32_bf16 v[74:77], v[138:141], v[210:213], 0
	v_mfma_f32_16x16x32_bf16 v[126:129], v[134:137], v[184:187], v[126:129]
	v_mfma_f32_16x16x32_bf16 v[122:125], v[142:145], v[184:187], v[122:125]
	v_mfma_f32_16x16x32_bf16 v[110:113], v[134:137], v[198:201], v[110:113]
	v_mfma_f32_16x16x32_bf16 v[106:109], v[142:145], v[198:201], v[106:109]
	v_mfma_f32_16x16x32_bf16 v[94:97], v[134:137], v[206:209], v[94:97]
	v_mfma_f32_16x16x32_bf16 v[90:93], v[142:145], v[206:209], v[90:93]
	v_mfma_f32_16x16x32_bf16 v[78:81], v[134:137], v[214:217], v[78:81]
	v_mfma_f32_16x16x32_bf16 v[74:77], v[142:145], v[214:217], v[74:77]
	s_setprio 0
	s_setprio 1
	v_mfma_f32_16x16x32_bf16 v[118:121], v[146:149], v[178:181], 0
	v_mfma_f32_16x16x32_bf16 v[114:117], v[166:169], v[178:181], 0
	v_mfma_f32_16x16x32_bf16 v[102:105], v[146:149], v[194:197], 0
	v_mfma_f32_16x16x32_bf16 v[98:101], v[166:169], v[194:197], 0
	v_mfma_f32_16x16x32_bf16 v[86:89], v[146:149], v[202:205], 0
	v_mfma_f32_16x16x32_bf16 v[82:85], v[166:169], v[202:205], 0
	v_mfma_f32_16x16x32_bf16 v[70:73], v[146:149], v[210:213], 0
	v_mfma_f32_16x16x32_bf16 v[66:69], v[166:169], v[210:213], 0
	v_mfma_f32_16x16x32_bf16 v[118:121], v[150:153], v[184:187], v[118:121]
	v_mfma_f32_16x16x32_bf16 v[114:117], v[170:173], v[184:187], v[114:117]
	v_mfma_f32_16x16x32_bf16 v[102:105], v[150:153], v[198:201], v[102:105]
	v_mfma_f32_16x16x32_bf16 v[98:101], v[170:173], v[198:201], v[98:101]
	v_mfma_f32_16x16x32_bf16 v[86:89], v[150:153], v[206:209], v[86:89]
	v_mfma_f32_16x16x32_bf16 v[82:85], v[170:173], v[206:209], v[82:85]
	v_mfma_f32_16x16x32_bf16 v[70:73], v[150:153], v[214:217], v[70:73]
	v_mfma_f32_16x16x32_bf16 v[66:69], v[170:173], v[214:217], v[66:69]
	s_setprio 0
	s_barrier
	s_add_u32 s98, s44, s16
	s_addc_u32 s99, s45, s17
	s_add_u32 s100, s46, s18
	s_addc_u32 s101, s47, s19
	s_add_i32 s8, s54, s6
	s_mov_b32 m0, s8
	ds_read_b128 v[178:181], v193 offset:16384
	ds_read_b128 v[184:187], v193 offset:17408
	ds_read_b128 v[194:197], v193 offset:18432
	ds_read_b128 v[198:201], v193 offset:19456
	ds_read_b128 v[202:205], v193 offset:20480
	ds_read_b128 v[206:209], v193 offset:21504
	ds_read_b128 v[210:213], v193 offset:22528
	ds_read_b128 v[214:217], v193 offset:23552
	global_load_lds_dwordx4 v156, s[44:45]
	s_add_i32 m0, s8, 0x2000
	s_add_u32 s12, s44, 0x40000
	s_addc_u32 s13, s45, 0
	s_add_i32 s8, s55, s6
	global_load_lds_dwordx4 v160, s[44:45]
	s_mov_b32 m0, s8
	s_nop 0
	global_load_lds_dwordx4 v156, s[12:13]
	s_add_i32 m0, s8, 0x2000
	s_nop 0
	global_load_lds_dwordx4 v160, s[12:13]
	s_mov_b32 m0, s7
	s_nop 0
	global_load_lds_dwordx4 v154, s[46:47]
	s_mov_b32 m0, s33
	s_nop 0
	global_load_lds_dwordx4 v158, s[46:47]
	s_waitcnt vmcnt(8)
	s_waitcnt lgkmcnt(0)
	s_barrier
; #define PG8_STAGE(bufoff, gbase, voff) do { _Pragma("unroll") for (int _i = 0; _i < 2; ++_i) \
;         __builtin_amdgcn_global_load_lds((const unsigned*)((const char*)(gbase) + (voff)[_i]), (LAS unsigned*)(lds + (bufoff) + ldsw + _i * 8192), 16, 0, 0); } while (0)
; #define PG8_LDA(dst, b, h) do { _Pragma("unroll") for (int m = 0; m < 4; ++m) _Pragma("unroll") for (int k = 0; k < 2; ++k) dst[m][k] = *(const LAS bf16x8*)(lds + PG8_SA(b, h) + aoff + m * 2048 + k * 1024); } while (0)
; #define PG8_LDB(dst, b, h) do { _Pragma("unroll") for (int n = 0; n < 2; ++n) _Pragma("unroll") for (int k = 0; k < 2; ++k) dst[n][k] = *(const LAS bf16x8*)(lds + PG8_SB(b, h) + boff + n * 2048 + k * 1024); } while (0)
; #define PG8_MMA(ai, bj, At, Bt) do { __builtin_amdgcn_s_setprio(1); _Pragma("unroll") for (int m = 0; m < 4; ++m) _Pragma("unroll") for (int n = 0; n < 2; ++n) _Pragma("unroll") for (int k = 0; k < 2; ++k) \
;         acc[ai][bj][m][n] = __builtin_amdgcn_mfma_f32_16x16x32_bf16(Bt[n][k], At[m][k], acc[ai][bj][m][n], 0, 0, 0); __builtin_amdgcn_s_setprio(0); } while (0)
; #define PG8_WAIT_V(n) asm volatile("s_waitcnt vmcnt(" #n ")" ::: "memory")
; #define PG8_WAIT_L(n) asm volatile("s_waitcnt lgkmcnt(" #n ")" ::: "memory")
; #define PG8_BAR __builtin_amdgcn_s_barrier()
; #define PG8_SCHED __builtin_amdgcn_sched_barrier(0)
; template <class Epi, bool ALIGN_EPI, bool SPLITA>
; __device__ __forceinline__ void gemm_phase(LAS unsigned char* lds, const Gemm g, const StaticOrder& S, const Epi& E) {
;     ...
;             PG8_WAIT_V(8); PG8_WAIT_L(0); PG8_BAR; PG8_MMA(1, 0, At, B0); PG8_MMA(1, 1, At, B1); PG8_BAR; PG8_SCHED;
;             PG8_LDB(B0, 1, 0); PG8_LDB(B1, 1, 1); PG8_SCHED; PG8_LDA(At, 1, 0); PG8_STAGE(PG8_SA(0, 1), a2h, vo2);
;             PG8_WAIT_V(8); PG8_WAIT_L(0); PG8_BAR; PG8_MMA(0, 0, At, B0); PG8_MMA(0, 1, At, B1); PG8_BAR; PG8_SCHED;
	s_setprio 1
	s_waitcnt lgkmcnt(0)
	v_mfma_f32_16x16x32_bf16 v[62:65], v[130:133], v[178:181], 0
	v_mfma_f32_16x16x32_bf16 v[58:61], v[138:141], v[178:181], 0
	v_mfma_f32_16x16x32_bf16 v[38:41], v[130:133], v[194:197], 0
	v_mfma_f32_16x16x32_bf16 v[34:37], v[138:141], v[194:197], 0
	v_mfma_f32_16x16x32_bf16 v[22:25], v[130:133], v[202:205], 0
	v_mfma_f32_16x16x32_bf16 v[18:21], v[138:141], v[202:205], 0
	v_mfma_f32_16x16x32_bf16 v[6:9], v[130:133], v[210:213], 0
	v_mfma_f32_16x16x32_bf16 v[2:5], v[138:141], v[210:213], 0
	v_mfma_f32_16x16x32_bf16 v[62:65], v[134:137], v[184:187], v[62:65]
	v_mfma_f32_16x16x32_bf16 v[58:61], v[142:145], v[184:187], v[58:61]
	v_mfma_f32_16x16x32_bf16 v[38:41], v[134:137], v[198:201], v[38:41]
	v_mfma_f32_16x16x32_bf16 v[34:37], v[142:145], v[198:201], v[34:37]
	v_mfma_f32_16x16x32_bf16 v[22:25], v[134:137], v[206:209], v[22:25]
	v_mfma_f32_16x16x32_bf16 v[18:21], v[142:145], v[206:209], v[18:21]
	v_mfma_f32_16x16x32_bf16 v[6:9], v[134:137], v[214:217], v[6:9]
	v_mfma_f32_16x16x32_bf16 v[2:5], v[142:145], v[214:217], v[2:5]
	s_setprio 0
	s_setprio 1
	v_mfma_f32_16x16x32_bf16 v[54:57], v[146:149], v[178:181], 0
	v_mfma_f32_16x16x32_bf16 v[46:49], v[166:169], v[178:181], 0
	v_mfma_f32_16x16x32_bf16 v[50:53], v[146:149], v[194:197], 0
	v_mfma_f32_16x16x32_bf16 v[42:45], v[166:169], v[194:197], 0
	v_mfma_f32_16x16x32_bf16 v[30:33], v[146:149], v[202:205], 0
	v_mfma_f32_16x16x32_bf16 v[26:29], v[166:169], v[202:205], 0
	v_mfma_f32_16x16x32_bf16 v[14:17], v[146:149], v[210:213], 0
	v_mfma_f32_16x16x32_bf16 v[10:13], v[166:169], v[210:213], 0
	v_mfma_f32_16x16x32_bf16 v[54:57], v[150:153], v[184:187], v[54:57]
	v_mfma_f32_16x16x32_bf16 v[46:49], v[170:173], v[184:187], v[46:49]
	v_mfma_f32_16x16x32_bf16 v[50:53], v[150:153], v[198:201], v[50:53]
	v_mfma_f32_16x16x32_bf16 v[42:45], v[170:173], v[198:201], v[42:45]
	v_mfma_f32_16x16x32_bf16 v[30:33], v[150:153], v[206:209], v[30:33]
	v_mfma_f32_16x16x32_bf16 v[26:29], v[170:173], v[206:209], v[26:29]
	v_mfma_f32_16x16x32_bf16 v[14:17], v[150:153], v[214:217], v[14:17]
	v_mfma_f32_16x16x32_bf16 v[10:13], v[170:173], v[214:217], v[10:13]
	s_setprio 0
	s_barrier
	s_add_i32 s8, 0, 0x18000
	s_add_i32 s70, 0, 0x1c000
	v_add_u32_e32 v142, s8, v177
	v_add_u32_e32 v170, s70, v177
	ds_read_b128 v[130:133], v142
	ds_read_b128 v[134:137], v142 offset:1024
	ds_read_b128 v[138:141], v142 offset:2048
	ds_read_b128 v[142:145], v142 offset:3072
	ds_read_b128 v[146:149], v170
	ds_read_b128 v[150:153], v170 offset:1024
	ds_read_b128 v[166:169], v170 offset:2048
	ds_read_b128 v[170:173], v170 offset:3072
	s_add_u32 s12, s46, 0x10000
	s_addc_u32 s13, s47, 0
	s_mov_b32 m0, s41
	ds_read_b128 v[178:181], v193 offset:32768
	ds_read_b128 v[184:187], v193 offset:33792
	ds_read_b128 v[194:197], v193 offset:34816
	ds_read_b128 v[198:201], v193 offset:35840
	ds_read_b128 v[202:205], v193 offset:36864
	ds_read_b128 v[206:209], v193 offset:37888
	ds_read_b128 v[210:213], v193 offset:38912
	ds_read_b128 v[214:217], v193 offset:39936
	global_load_lds_dwordx4 v154, s[12:13]
	s_mov_b32 m0, s48
	s_nop 0
	global_load_lds_dwordx4 v158, s[12:13]
	s_waitcnt vmcnt(8)
	s_waitcnt lgkmcnt(0)
	s_barrier
	s_setprio 1
	s_waitcnt lgkmcnt(0)
	v_mfma_f32_16x16x32_bf16 v[126:129], v[130:133], v[178:181], v[126:129]
	v_mfma_f32_16x16x32_bf16 v[122:125], v[138:141], v[178:181], v[122:125]
	v_mfma_f32_16x16x32_bf16 v[110:113], v[130:133], v[194:197], v[110:113]
	v_mfma_f32_16x16x32_bf16 v[106:109], v[138:141], v[194:197], v[106:109]
	v_mfma_f32_16x16x32_bf16 v[94:97], v[130:133], v[202:205], v[94:97]
	v_mfma_f32_16x16x32_bf16 v[90:93], v[138:141], v[202:205], v[90:93]
	v_mfma_f32_16x16x32_bf16 v[78:81], v[130:133], v[210:213], v[78:81]
	v_mfma_f32_16x16x32_bf16 v[74:77], v[138:141], v[210:213], v[74:77]
	v_mfma_f32_16x16x32_bf16 v[126:129], v[134:137], v[184:187], v[126:129]
	v_mfma_f32_16x16x32_bf16 v[122:125], v[142:145], v[184:187], v[122:125]
	v_mfma_f32_16x16x32_bf16 v[110:113], v[134:137], v[198:201], v[110:113]
	v_mfma_f32_16x16x32_bf16 v[106:109], v[142:145], v[198:201], v[106:109]
	v_mfma_f32_16x16x32_bf16 v[94:97], v[134:137], v[206:209], v[94:97]
	v_mfma_f32_16x16x32_bf16 v[90:93], v[142:145], v[206:209], v[90:93]
	v_mfma_f32_16x16x32_bf16 v[78:81], v[134:137], v[214:217], v[78:81]
	v_mfma_f32_16x16x32_bf16 v[74:77], v[142:145], v[214:217], v[74:77]
	s_setprio 0
	s_setprio 1
	v_mfma_f32_16x16x32_bf16 v[118:121], v[146:149], v[178:181], v[118:121]
	v_mfma_f32_16x16x32_bf16 v[114:117], v[166:169], v[178:181], v[114:117]
	v_mfma_f32_16x16x32_bf16 v[102:105], v[146:149], v[194:197], v[102:105]
	v_mfma_f32_16x16x32_bf16 v[98:101], v[166:169], v[194:197], v[98:101]
	v_mfma_f32_16x16x32_bf16 v[86:89], v[146:149], v[202:205], v[86:89]
	v_mfma_f32_16x16x32_bf16 v[82:85], v[166:169], v[202:205], v[82:85]
	v_mfma_f32_16x16x32_bf16 v[70:73], v[146:149], v[210:213], v[70:73]
	v_mfma_f32_16x16x32_bf16 v[66:69], v[166:169], v[210:213], v[66:69]
	v_mfma_f32_16x16x32_bf16 v[118:121], v[150:153], v[184:187], v[118:121]
	v_mfma_f32_16x16x32_bf16 v[114:117], v[170:173], v[184:187], v[114:117]
	v_mfma_f32_16x16x32_bf16 v[102:105], v[150:153], v[198:201], v[102:105]
	v_mfma_f32_16x16x32_bf16 v[98:101], v[170:173], v[198:201], v[98:101]
	v_mfma_f32_16x16x32_bf16 v[86:89], v[150:153], v[206:209], v[86:89]
	v_mfma_f32_16x16x32_bf16 v[82:85], v[170:173], v[206:209], v[82:85]
	v_mfma_f32_16x16x32_bf16 v[70:73], v[150:153], v[214:217], v[70:73]
	v_mfma_f32_16x16x32_bf16 v[66:69], v[170:173], v[214:217], v[66:69]
	s_setprio 0
	s_barrier
; #define PG8_STAGE(bufoff, gbase, voff) do { _Pragma("unroll") for (int _i = 0; _i < 2; ++_i) \
;         __builtin_amdgcn_global_load_lds((const unsigned*)((const char*)(gbase) + (voff)[_i]), (LAS unsigned*)(lds + (bufoff) + ldsw + _i * 8192), 16, 0, 0); } while (0)
; #define PG8_LDA(dst, b, h) do { _Pragma("unroll") for (int m = 0; m < 4; ++m) _Pragma("unroll") for (int k = 0; k < 2; ++k) dst[m][k] = *(const LAS bf16x8*)(lds + PG8_SA(b, h) + aoff + m * 2048 + k * 1024); } while (0)
; #define PG8_MMA(ai, bj, At, Bt) do { __builtin_amdgcn_s_setprio(1); _Pragma("unroll") for (int m = 0; m < 4; ++m) _Pragma("unroll") for (int n = 0; n < 2; ++n) _Pragma("unroll") for (int k = 0; k < 2; ++k) \
;         acc[ai][bj][m][n] = __builtin_amdgcn_mfma_f32_16x16x32_bf16(Bt[n][k], At[m][k], acc[ai][bj][m][n], 0, 0, 0); __builtin_amdgcn_s_setprio(0); } while (0)
; #define PG8_WAIT_V(n) asm volatile("s_waitcnt vmcnt(" #n ")" ::: "memory")
; #define PG8_WAIT_L(n) asm volatile("s_waitcnt lgkmcnt(" #n ")" ::: "memory")
; #define PG8_BAR __builtin_amdgcn_s_barrier()
; #define PG8_SCHED __builtin_amdgcn_sched_barrier(0)
; template <class Epi, bool ALIGN_EPI, bool SPLITA>
; __device__ __forceinline__ void gemm_phase(LAS unsigned char* lds, const Gemm g, const StaticOrder& S, const Epi& E) {
;     ...
;             PG8_LDA(At, 1, 1); PG8_STAGE(PG8_SB(1, 0), b3, voffB); PG8_STAGE(PG8_SB(1, 1), b3 + hstepB, voffB); PG8_STAGE(PG8_SA(1, 0), a3, vo2);
;             PG8_WAIT_V(8); PG8_WAIT_L(0); PG8_BAR; PG8_MMA(1, 0, At, B0); PG8_MMA(1, 1, At, B1); PG8_BAR; PG8_SCHED;
	s_add_i32 s8, s8, s6
	s_mov_b32 m0, s8
	ds_read_b128 v[178:181], v193 offset:49152
	ds_read_b128 v[184:187], v193 offset:50176
	ds_read_b128 v[194:197], v193 offset:51200
	ds_read_b128 v[198:201], v193 offset:52224
	ds_read_b128 v[202:205], v193 offset:53248
	ds_read_b128 v[206:209], v193 offset:54272
	ds_read_b128 v[210:213], v193 offset:55296
	ds_read_b128 v[214:217], v193 offset:56320
	global_load_lds_dwordx4 v156, s[98:99]
	s_add_i32 m0, s8, 0x2000
	s_add_u32 s12, s44, 0x40080
	s_addc_u32 s13, s45, 0
	s_add_i32 s8, s70, s6
	global_load_lds_dwordx4 v160, s[98:99]
	s_mov_b32 m0, s8
	s_nop 0
	global_load_lds_dwordx4 v156, s[12:13]
	s_add_i32 m0, s8, 0x2000
	s_nop 0
	global_load_lds_dwordx4 v160, s[12:13]
	s_mov_b32 m0, s49
	s_nop 0
	global_load_lds_dwordx4 v154, s[100:101]
	s_mov_b32 m0, s50
	s_nop 0
	global_load_lds_dwordx4 v158, s[100:101]
	s_waitcnt vmcnt(8)
	s_waitcnt lgkmcnt(0)
	s_barrier
	s_setprio 1
	s_waitcnt lgkmcnt(0)
	v_mfma_f32_16x16x32_bf16 v[62:65], v[130:133], v[178:181], v[62:65]
	v_mfma_f32_16x16x32_bf16 v[58:61], v[138:141], v[178:181], v[58:61]
	v_mfma_f32_16x16x32_bf16 v[38:41], v[130:133], v[194:197], v[38:41]
	v_mfma_f32_16x16x32_bf16 v[34:37], v[138:141], v[194:197], v[34:37]
	v_mfma_f32_16x16x32_bf16 v[22:25], v[130:133], v[202:205], v[22:25]
	v_mfma_f32_16x16x32_bf16 v[18:21], v[138:141], v[202:205], v[18:21]
	v_mfma_f32_16x16x32_bf16 v[6:9], v[130:133], v[210:213], v[6:9]
	v_mfma_f32_16x16x32_bf16 v[2:5], v[138:141], v[210:213], v[2:5]
	v_mfma_f32_16x16x32_bf16 v[62:65], v[134:137], v[184:187], v[62:65]
	v_mfma_f32_16x16x32_bf16 v[58:61], v[142:145], v[184:187], v[58:61]
	v_mfma_f32_16x16x32_bf16 v[38:41], v[134:137], v[198:201], v[38:41]
	v_mfma_f32_16x16x32_bf16 v[34:37], v[142:145], v[198:201], v[34:37]
	v_mfma_f32_16x16x32_bf16 v[22:25], v[134:137], v[206:209], v[22:25]
	v_mfma_f32_16x16x32_bf16 v[18:21], v[142:145], v[206:209], v[18:21]
	v_mfma_f32_16x16x32_bf16 v[6:9], v[134:137], v[214:217], v[6:9]
	v_mfma_f32_16x16x32_bf16 v[2:5], v[142:145], v[214:217], v[2:5]
	s_setprio 0
	s_setprio 1
	v_mfma_f32_16x16x32_bf16 v[54:57], v[146:149], v[178:181], v[54:57]
	v_mfma_f32_16x16x32_bf16 v[46:49], v[166:169], v[178:181], v[46:49]
	v_mfma_f32_16x16x32_bf16 v[50:53], v[146:149], v[194:197], v[50:53]
	v_mfma_f32_16x16x32_bf16 v[42:45], v[166:169], v[194:197], v[42:45]
	v_mfma_f32_16x16x32_bf16 v[30:33], v[146:149], v[202:205], v[30:33]
	v_mfma_f32_16x16x32_bf16 v[26:29], v[166:169], v[202:205], v[26:29]
	v_mfma_f32_16x16x32_bf16 v[14:17], v[146:149], v[210:213], v[14:17]
	v_mfma_f32_16x16x32_bf16 v[10:13], v[166:169], v[210:213], v[10:13]
	v_mfma_f32_16x16x32_bf16 v[54:57], v[150:153], v[184:187], v[54:57]
	v_mfma_f32_16x16x32_bf16 v[46:49], v[170:173], v[184:187], v[46:49]
	v_mfma_f32_16x16x32_bf16 v[50:53], v[150:153], v[198:201], v[50:53]
	v_mfma_f32_16x16x32_bf16 v[42:45], v[170:173], v[198:201], v[42:45]
	v_mfma_f32_16x16x32_bf16 v[30:33], v[150:153], v[206:209], v[30:33]
	v_mfma_f32_16x16x32_bf16 v[26:29], v[170:173], v[206:209], v[26:29]
	v_mfma_f32_16x16x32_bf16 v[14:17], v[150:153], v[214:217], v[14:17]
	v_mfma_f32_16x16x32_bf16 v[10:13], v[170:173], v[214:217], v[10:13]
	s_setprio 0
	s_barrier
	s_add_u32 s60, s60, 0x100
	s_addc_u32 s61, s61, 0
	s_addk_i32 s64, 0x1000
	s_mov_b32 s44, s65

; __device__ __forceinline__ u32x4 pack8(const f32x4 a, const f32x4 b) { u32x4 w; w.x = cvt_pk_bf16(a[0], a[1]); w.y = cvt_pk_bf16(a[2], a[3]); w.z = cvt_pk_bf16(b[0], b[1]); w.w = cvt_pk_bf16(b[2], b[3]); return w; }
; #define PG8_BAR __builtin_amdgcn_s_barrier()
; template <class Epi, bool ALIGN_EPI, bool SPLITA>
; __device__ __forceinline__ void gemm_phase(LAS unsigned char* lds, const Gemm g, const StaticOrder& S, const Epi& E) {
;     ...
;         if constexpr (ALIGN_EPI) { if (wr == 0) PG8_BAR; }
;     __device__ __forceinline__ void operator()(const Acc& acc, const Unit& u, int wr, int wc, int fr, int fq) const {
;         const int row0 = u.pm * BM + wr * 64 + fr, col0 = u.pn * BM + wc * 32 + 8 * fq;
; #pragma unroll
;         for (int ai = 0; ai < 2; ++ai) {
;             u32x4 xw[4][2]; float nr[4];
; #pragma unroll
;             for (int m = 0; m < 4; ++m) { nr[m] = xn[row0 + ai * HALF + m * 16];
; #pragma unroll
;                 for (int bj = 0; bj < 2; ++bj) xw[m][bj] = *(const u32x4*)(X1B + (size_t)(row0 + ai * HALF + m * 16) * DM + col0 + bj * HALF); }
; #pragma unroll
;             for (int m = 0; m < 4; ++m) {
;                 const int row = row0 + ai * HALF + m * 16; const size_t off = (size_t)row * DM + col0; float ss = 0.f;
; #pragma unroll
;                 for (int bj = 0; bj < 2; ++bj) {
;                     f32x4 xa, xb2; unpack8(xw[m][bj], xa, xb2);
;                     const f32x4 v0 = xa * nr[m] + acc[ai][bj][m][0], v1 = xb2 * nr[m] + acc[ai][bj][m][1];
;                     *(u32x4*)(X1B + off + bj * HALF) = pack8(v0, v1);
;                     const f32x4 q = v0 * v0 + v1 * v1; ss += (q[0] + q[1]) + (q[2] + q[3]); }
;                 ss = quad_sum(ss);
;                 if (fq == 0) atomicAdd(ssq + row, ss);
.LBB0_712:
	v_lshl_or_b32 v166, s38, 8, v183
	v_lshl_add_u32 v170, s40, 8, v1
	v_ashrrev_i32_e32 v167, 31, v166
	v_lshlrev_b64 v[202:203], 1, v[166:167]
	v_ashrrev_i32_e32 v171, 31, v170
	v_lshl_add_u64 v[168:169], s[34:35], 0, v[202:203]
	v_lshlrev_b64 v[204:205], 11, v[170:171]
	v_lshl_add_u64 v[130:131], v[168:169], 0, v[204:205]
	global_load_dwordx4 v[194:197], v[130:131], off
	global_load_dwordx4 v[198:201], v[130:131], off offset:256
	v_lshl_add_u64 v[172:173], v[170:171], 2, s[68:69]
	global_load_dword v206, v[172:173], off
	v_or_b32_e32 v186, 16, v170
	v_or_b32_e32 v180, 32, v170
	v_or_b32_e32 v174, 48, v170
	v_ashrrev_i32_e32 v187, 31, v186
	v_ashrrev_i32_e32 v181, 31, v180
	v_ashrrev_i32_e32 v175, 31, v174
	v_lshlrev_b64 v[190:191], 11, v[186:187]
	v_lshlrev_b64 v[184:185], 11, v[180:181]
	v_lshl_add_u64 v[130:131], v[186:187], 2, s[68:69]
	v_lshl_add_u64 v[132:133], v[180:181], 2, s[68:69]
	v_lshl_add_u64 v[134:135], v[174:175], 2, s[68:69]
	v_lshlrev_b64 v[178:179], 11, v[174:175]
	v_lshl_add_u64 v[136:137], v[168:169], 0, v[190:191]
	v_lshl_add_u64 v[138:139], v[168:169], 0, v[184:185]
	v_lshl_add_u64 v[208:209], v[168:169], 0, v[178:179]
	global_load_dword v188, v[130:131], off
	global_load_dwordx4 v[150:153], v[136:137], off
	global_load_dwordx4 v[146:149], v[136:137], off offset:256
	global_load_dword v182, v[132:133], off
	global_load_dwordx4 v[142:145], v[138:139], off
	s_nop 0
	global_load_dwordx4 v[138:141], v[138:139], off offset:256
	s_nop 0
	global_load_dword v176, v[134:135], off
	s_nop 0
	global_load_dwordx4 v[134:137], v[208:209], off
	global_load_dwordx4 v[130:133], v[208:209], off offset:256
	v_lshl_add_u64 v[204:205], s[34:35], 0, v[204:205]
	v_lshl_add_u64 v[202:203], v[204:205], 0, v[202:203]
	s_waitcnt vmcnt(0)
	s_cmp_lg_u64 s[20:21], 0
	s_cbranch_scc0 .Lxs_p4_0
	s_barrier
.Lxs_p4_0:
	v_lshlrev_b32_e32 v204, 16, v194
	v_and_b32_e32 v205, 0xffff0000, v194
	v_lshlrev_b32_e32 v194, 16, v195
	v_and_b32_e32 v195, 0xffff0000, v195
	v_lshlrev_b32_e32 v208, 16, v196
	v_and_b32_e32 v209, 0xffff0000, v196
	v_lshlrev_b32_e32 v196, 16, v197
	v_and_b32_e32 v197, 0xffff0000, v197
	v_lshlrev_b32_e32 v210, 16, v198
	v_and_b32_e32 v211, 0xffff0000, v198
	v_lshlrev_b32_e32 v198, 16, v199
	v_and_b32_e32 v199, 0xffff0000, v199
	v_lshlrev_b32_e32 v212, 16, v200
	v_and_b32_e32 v213, 0xffff0000, v200
	v_lshlrev_b32_e32 v200, 16, v201
	v_and_b32_e32 v201, 0xffff0000, v201
	v_pk_fma_f32 v[128:129], v[206:207], v[194:195], v[128:129] op_sel_hi:[0,1,1]
	v_pk_fma_f32 v[126:127], v[206:207], v[204:205], v[126:127] op_sel_hi:[0,1,1]
	v_pk_fma_f32 v[124:125], v[206:207], v[196:197], v[124:125] op_sel_hi:[0,1,1]
	v_pk_fma_f32 v[122:123], v[206:207], v[208:209], v[122:123] op_sel_hi:[0,1,1]
	v_pk_fma_f32 v[194:195], v[206:207], v[198:199], v[120:121] op_sel_hi:[0,1,1]
	v_pk_fma_f32 v[196:197], v[206:207], v[210:211], v[118:119] op_sel_hi:[0,1,1]
	v_pk_fma_f32 v[198:199], v[206:207], v[200:201], v[116:117] op_sel_hi:[0,1,1]
	v_pk_fma_f32 v[200:201], v[206:207], v[212:213], v[114:115] op_sel_hi:[0,1,1]
	v_cvt_pk_bf16_f32 v114, v126, v127
	v_cvt_pk_bf16_f32 v115, v128, v129
	v_cvt_pk_bf16_f32 v116, v122, v123
	v_cvt_pk_bf16_f32 v117, v124, v125
	v_pk_mul_f32 v[122:123], v[122:123], v[122:123]
	v_pk_mul_f32 v[124:125], v[124:125], v[124:125]
	v_cvt_pk_bf16_f32 v118, v196, v197
	v_cvt_pk_bf16_f32 v119, v194, v195
	v_cvt_pk_bf16_f32 v120, v200, v201
	v_cvt_pk_bf16_f32 v121, v198, v199
	v_pk_mul_f32 v[200:201], v[200:201], v[200:201]
	v_pk_mul_f32 v[198:199], v[198:199], v[198:199]
	global_store_dwordx4 v[202:203], v[114:117], off
	global_store_dwordx4 v[202:203], v[118:121], off offset:256
	s_nop 0
	v_pk_fma_f32 v[114:115], v[128:129], v[128:129], v[124:125]
	v_pk_fma_f32 v[116:117], v[126:127], v[126:127], v[122:123]
	v_pk_fma_f32 v[118:119], v[194:195], v[194:195], v[198:199]
	v_pk_fma_f32 v[120:121], v[196:197], v[196:197], v[200:201]
	v_add_f32_e32 v116, v116, v117
	v_add_f32_e32 v114, v114, v115
	v_add_f32_e32 v115, v120, v121
	v_add_f32_e32 v117, v118, v119
	v_add_f32_e32 v114, v116, v114
	v_add_f32_e32 v115, v115, v117
	v_add_f32_e32 v114, v114, v115
	v_mov_b32_e32 v115, v114
	s_nop 1
	v_permlane16_swap_b32_e32 v114, v115
	v_add_f32_e32 v114, v114, v115
	v_mov_b32_e32 v115, v114
	s_nop 1
	v_permlane32_swap_b32_e32 v114, v115
	s_and_saveexec_b64 s[38:39], s[2:3]
	s_cbranch_execz .LBB0_714
	v_lshl_add_u64 v[116:117], v[170:171], 2, s[66:67]
	v_add_f32_e32 v114, v114, v115
	global_atomic_add_f32 v[116:117], v114, off

; #define PG8_BAR __builtin_amdgcn_s_barrier()
; template <class Epi, bool ALIGN_EPI, bool SPLITA>
; __device__ __forceinline__ void gemm_phase(LAS unsigned char* lds, const Gemm g, const StaticOrder& S, const Epi& E) {
;     ...
;         if (!has_next) break;
; #pragma unroll
;         for (int a = 0; a < 2; ++a)
; #pragma unroll
;             for (int b = 0; b < 2; ++b)
; #pragma unroll
;                 for (int m = 0; m < 4; ++m)
; #pragma unroll
;                     for (int n = 0; n < 2; ++n) acc[a][b][m][n] = (f32x4){0.f, 0.f, 0.f, 0.f};
;         cur = nxt; cA = nA; cB = nB; mirC = mirN; if constexpr (SPLITA) cA2 = (const char*)g.A2 + (size_t)cur.pm * tstepA; ++ui;
;         if constexpr (ALIGN_EPI) { if (wr == 1) PG8_BAR; }
.LBB0_728:
	s_or_b64 exec, exec, s[38:39]
	s_andn2_b64 vcc, exec, s[4:5]
	s_mov_b64 s[4:5], -1
	s_cbranch_vccnz .LBB0_705
	s_mov_b32 s99, 0
	s_andn2_b64 vcc, exec, s[10:11]
	s_cbranch_vccnz .LBB0_704
	s_mov_b32 s99, 1
	s_branch .LBB0_704

; #define PG8_STAGE(bufoff, gbase, voff) do { _Pragma("unroll") for (int _i = 0; _i < 2; ++_i) \
;         __builtin_amdgcn_global_load_lds((const unsigned*)((const char*)(gbase) + (voff)[_i]), (LAS unsigned*)(lds + (bufoff) + ldsw + _i * 8192), 16, 0, 0); } while (0)
; #define PG8_WAIT_V(n) asm volatile("s_waitcnt vmcnt(" #n ")" ::: "memory")
; #define PG8_BAR __builtin_amdgcn_s_barrier()
; template <class Epi, bool ALIGN_EPI, bool SPLITA>
; __device__ __forceinline__ void gemm_phase(LAS unsigned char* lds, const Gemm g, const StaticOrder& S, const Epi& E) {
;     ...
;     const char* cA = baseA1(cur); const char* cB = baseB(cur);
;     const char* cA2 = SPLITA ? (const char*)g.A2 + (size_t)cur.pm * tstepA : cA;
;     bool mirC = mirrored(cur);
;     { const unsigned vo[2] = {mirC ? voffAm[0] : voffA[0], mirC ? voffAm[1] : voffA[1]}; const char* cAh = mirC ? cA - hstepA : cA + hstepA;
;       PG8_STAGE(PG8_SB(0, 0), cB, voffB); PG8_STAGE(PG8_SB(0, 1), cB + hstepB, voffB); PG8_STAGE(PG8_SA(0, 0), cA, vo); PG8_STAGE(PG8_SA(0, 1), cAh, vo);
;       if (wr == 1) PG8_BAR;
;       PG8_WAIT_V(2); PG8_BAR;
;       PG8_STAGE(PG8_SB(1, 0), cB + kstepB, voffB); PG8_STAGE(PG8_SA(1, 0), cA + kofs(1), vo); PG8_STAGE(PG8_SB(1, 1), cB + hstepB + kstepB, voffB); }
;     PG8_WAIT_V(6); PG8_BAR;
.LBB0_790:
	s_and_b32 s48, s8, 3
	s_mov_b64 s[8:9], 0x800
	s_add_i32 m0, s42, 0x18000
	v_lshl_add_u64 v[8:9], v[8:9], 0, s[8:9]
	s_ashr_i32 s47, s15, 31
	s_lshl_b32 s17, s3, 13
	s_lshl_b32 s18, s48, 12
	s_waitcnt vmcnt(2)
	s_barrier
	global_load_lds_dwordx4 v[8:9], off
	v_lshl_add_u64 v[6:7], v[6:7], 0, s[8:9]
	s_add_i32 m0, s42, 0x1a000
	s_mov_b64 s[10:11], 0x80
	s_add_i32 s49, s42, 0x8000
	s_add_i32 s50, s42, 0xa000
	global_load_lds_dwordx4 v[6:7], off
	v_lshl_add_u64 v[2:3], v[2:3], 0, s[10:11]
	s_mov_b32 m0, s49
	s_add_u32 s12, s36, 0x40800
	global_load_lds_dwordx4 v[2:3], off
	v_lshl_add_u64 v[2:3], v[4:5], 0, s[10:11]
	s_mov_b32 m0, s50
	s_addc_u32 s13, s37, 0
	global_load_lds_dwordx4 v[2:3], off
	s_add_i32 m0, s42, 0x1c000
	v_lshl_add_u64 v[2:3], s[12:13], 0, v[134:135]
	global_load_lds_dwordx4 v[2:3], off
	v_lshl_add_u64 v[2:3], s[12:13], 0, v[130:131]
	s_add_i32 m0, s42, 0x1e000
	v_lshlrev_b32_e32 v5, 2, v12
	global_load_lds_dwordx4 v[2:3], off
	v_lshrrev_b32_e32 v2, 1, v12
	v_and_b32_e32 v2, 24, v2
	v_and_b32_e32 v3, 15, v12
	v_lshlrev_b32_e32 v4, 1, v2
	v_lshl_or_b32 v4, v3, 6, v4
	v_and_b32_e32 v5, 32, v5
	v_lshl_or_b32 v1, s3, 6, v3
	v_bitop3_b32 v6, v4, s17, v5 bitop3:0xde
	v_bitop3_b32 v154, v4, s18, v5 bitop3:0xde
	v_lshlrev_b32_e32 v4, 5, v3
	v_lshlrev_b32_e32 v3, 14, v15
	v_and_b32_e32 v3, 0xffff8000, v3
	v_lshl_add_u32 v3, v14, 11, v3
	v_and_b32_e32 v5, 1, v15
	s_cmpk_lt_u32 s16, 0x100
	v_lshl_or_b32 v3, v5, 6, v3
	s_sext_i32_i8 s30, s2
	s_cselect_b64 s[16:17], -1, 0
	s_lshl_b32 s2, s3, 5
	v_lshl_add_u32 v140, v16, 1, v3
	v_lshlrev_b32_e32 v3, 14, v10
	s_and_b32 s2, s2, 0x60
	v_and_b32_e32 v3, 0xffff8000, v3
	s_waitcnt vmcnt(6)
	s_or_b32 s2, s2, s48
	v_lshl_add_u32 v3, v11, 11, v3
	v_and_b32_e32 v5, 1, v10
	s_lshl_b32 s2, s2, 9
	v_lshl_or_b32 v3, v5, 6, v3
	s_add_i32 s51, 0, 0x10000
	s_add_i32 s52, 0, 0x14000
	v_mov_b32_e32 v141, v139
	v_lshl_add_u32 v142, v13, 1, v3
	v_mov_b32_e32 v143, v139
	v_mov_b64_e32 v[144:145], 0xc00
	v_mov_b64_e32 v[146:147], 0xbff
	v_add_u32_e32 v155, s51, v154
	v_add_u32_e32 v156, s52, v154
	v_add_u32_e32 v157, 0, v6
	v_mov_b32_e32 v158, 0x358637bd
	s_lshl_b32 s53, s2, 1
	v_lshlrev_b32_e32 v138, 1, v4
	v_lshlrev_b32_e32 v148, 1, v2
	s_movk_i32 s54, 0x1000
	s_barrier
	s_mov_b32 s99, 0
	s_branch .LBB0_793

; #define PG8_LDA(dst, b, h) do { _Pragma("unroll") for (int m = 0; m < 4; ++m) _Pragma("unroll") for (int k = 0; k < 2; ++k) dst[m][k] = *(const LAS bf16x8*)(lds + PG8_SA(b, h) + aoff + m * 2048 + k * 1024); } while (0)
; template <class Epi, bool ALIGN_EPI, bool SPLITA>
; __device__ __forceinline__ void gemm_phase(LAS unsigned char* lds, const Gemm g, const StaticOrder& S, const Epi& E) {
;     ...
;         const bool has_next = S.next(ui + 1, nxt);
;         const char* nA = has_next ? baseA1(nxt) : cA;
;         const char* nB = has_next ? baseB(nxt) : cB;
;         const bool mirN = has_next ? mirrored(nxt) : mirC;
;         for (int t = 0; t < nt; t += 2) {
;             const bool last = (t == nt - 2);
;             if constexpr (Epi::MIDK) { if (t == g.ksplit) E.mid(acc, cur, wr, wc, fr, fq); }
;             const char *a1, *a2;
;             if constexpr (SPLITA) {
;                 a1 = (t + 1 < g.ksplit) ? cA + (size_t)(t + 1) * kstep : cA2 + (size_t)(t + 1 - g.ksplit) * 2048;
;                 a2 = last ? nA : ((t + 2 < g.ksplit) ? cA + (size_t)(t + 2) * kstep : cA2 + (size_t)(t + 2 - g.ksplit) * 2048);
;             } else { a1 = cA + kofs(t + 1); a2 = last ? nA : cA + kofs(t + 2); }
;             const char* b2 = last ? nB : cB + (size_t)(t + 2) * kstepB;
;             const bool s2a = SPLITA && (t + 1 >= g.ksplit), s2b = SPLITA && !last && (t + 2 >= g.ksplit);
;             const char* a3 = a2 + ((Epi::KSUB || s2b) ? (size_t)2048 : kstep); const char* b3 = b2 + kstepB;
;             const bool m1 = SPLITA && mirC && (t + 1 < g.ksplit), m2 = SPLITA && (last ? mirN : (mirC && (t + 2 < g.ksplit)));
;             const unsigned vo1[2] = {s2a ? voffA2[0] : m1 ? voffAm[0] : voffA[0], s2a ? voffA2[1] : m1 ? voffAm[1] : voffA[1]}, vo2[2] = {s2b ? voffA2[0] : m2 ? voffAm[0] : voffA[0], s2b ? voffA2[1] : m2 ? voffAm[1] : voffA[1]};
;             const char* a1h = m1 ? a1 - hstepA : a1 + hstepA; const char* a2h = m2 ? a2 - hstepA : a2 + hstepA;
;             PG8_LDB(B0, 0, 0); PG8_LDB(B1, 0, 1); PG8_SCHED; PG8_LDA(At, 0, 0); PG8_STAGE(PG8_SA(1, 1), a1h, vo1);
;             PG8_WAIT_V(8); PG8_WAIT_L(0); PG8_BAR; PG8_MMA(0, 0, At, B0); PG8_MMA(0, 1, At, B1); PG8_BAR; PG8_SCHED;
;             PG8_LDA(At, 0, 1); PG8_STAGE(PG8_SB(0, 0), b2, voffB); PG8_STAGE(PG8_SB(0, 1), b2 + hstepB, voffB); PG8_STAGE(PG8_SA(0, 0), a2, vo2);
.LBB0_795:
	s_ashr_i32 s19, s18, 31
	s_lshl_b64 s[12:13], s[18:19], 19
	s_add_u32 s22, s34, s12
	s_addc_u32 s23, s35, s13
	s_and_b64 s[12:13], s[2:3], exec
	s_cselect_b32 s19, s23, s39
	s_cselect_b32 s29, s22, s38
	s_ashr_i32 s21, s20, 31
	s_lshl_b64 s[12:13], s[20:21], 19
	s_add_u32 s24, s26, s12
	s_addc_u32 s25, s27, s13
	s_and_b64 s[12:13], s[2:3], exec
	s_cselect_b32 s21, s25, s37
	s_cselect_b32 s31, s24, s36
	s_add_u32 s55, s36, 0x1000
	s_addc_u32 s56, s37, 0
	s_add_u32 s36, s38, 0x40080
	s_addc_u32 s37, s39, 0
	s_mov_b32 s57, -2
	s_cmp_lg_u32 s99, 0
	s_cbranch_scc0 .Lyd_p5
	s_barrier
	s_mov_b32 s99, 0
.Lyd_p5:
	ds_read_b128 v[150:153], v155
	ds_read_b128 v[160:163], v155 offset:1024
	ds_read_b128 v[164:167], v155 offset:2048
	ds_read_b128 v[168:171], v155 offset:3072
	ds_read_b128 v[172:175], v156
	ds_read_b128 v[176:179], v156 offset:1024
	ds_read_b128 v[180:183], v156 offset:2048
	ds_read_b128 v[184:187], v156 offset:3072
	s_add_u32 s12, s36, 0xfffc0080
	s_addc_u32 s13, s37, -1
	s_cmp_eq_u32 s57, 12
	s_cselect_b32 s41, s19, s13
	s_cselect_b32 s40, s29, s12
	s_cselect_b32 s39, s21, s56
	s_cselect_b32 s38, s31, s55
	s_add_i32 m0, s42, 0xc000
	ds_read_b128 v[188:191], v157
	ds_read_b128 v[192:195], v157 offset:1024
	ds_read_b128 v[196:199], v157 offset:2048
	ds_read_b128 v[200:203], v157 offset:3072
	ds_read_b128 v[204:207], v157 offset:4096
	ds_read_b128 v[208:211], v157 offset:5120
	ds_read_b128 v[212:215], v157 offset:6144
	ds_read_b128 v[216:219], v157 offset:7168
	global_load_lds_dwordx4 v140, s[36:37]
	s_add_i32 m0, s42, 0xe000
	s_nop 0
	global_load_lds_dwordx4 v142, s[36:37]
	s_waitcnt vmcnt(8)
	s_waitcnt lgkmcnt(0)
	s_barrier
	s_setprio 1
	s_waitcnt lgkmcnt(0)
	v_mfma_f32_16x16x32_bf16 v[126:129], v[150:153], v[188:191], 0
	v_mfma_f32_16x16x32_bf16 v[122:125], v[164:167], v[188:191], 0
	v_mfma_f32_16x16x32_bf16 v[110:113], v[150:153], v[196:199], 0
	v_mfma_f32_16x16x32_bf16 v[106:109], v[164:167], v[196:199], 0
	v_mfma_f32_16x16x32_bf16 v[94:97], v[150:153], v[204:207], 0
	v_mfma_f32_16x16x32_bf16 v[90:93], v[164:167], v[204:207], 0
	v_mfma_f32_16x16x32_bf16 v[78:81], v[150:153], v[212:215], 0
	v_mfma_f32_16x16x32_bf16 v[74:77], v[164:167], v[212:215], 0
	v_mfma_f32_16x16x32_bf16 v[126:129], v[160:163], v[192:195], v[126:129]
	v_mfma_f32_16x16x32_bf16 v[122:125], v[168:171], v[192:195], v[122:125]
	v_mfma_f32_16x16x32_bf16 v[110:113], v[160:163], v[200:203], v[110:113]
	v_mfma_f32_16x16x32_bf16 v[106:109], v[168:171], v[200:203], v[106:109]
	v_mfma_f32_16x16x32_bf16 v[94:97], v[160:163], v[208:211], v[94:97]
	v_mfma_f32_16x16x32_bf16 v[90:93], v[168:171], v[208:211], v[90:93]
	v_mfma_f32_16x16x32_bf16 v[78:81], v[160:163], v[216:219], v[78:81]
	v_mfma_f32_16x16x32_bf16 v[74:77], v[168:171], v[216:219], v[74:77]
	s_setprio 0
	s_setprio 1
	v_mfma_f32_16x16x32_bf16 v[118:121], v[172:175], v[188:191], 0
	v_mfma_f32_16x16x32_bf16 v[114:117], v[180:183], v[188:191], 0
	v_mfma_f32_16x16x32_bf16 v[102:105], v[172:175], v[196:199], 0
	v_mfma_f32_16x16x32_bf16 v[98:101], v[180:183], v[196:199], 0
	v_mfma_f32_16x16x32_bf16 v[86:89], v[172:175], v[204:207], 0
	v_mfma_f32_16x16x32_bf16 v[82:85], v[180:183], v[204:207], 0
	v_mfma_f32_16x16x32_bf16 v[70:73], v[172:175], v[212:215], 0
	v_mfma_f32_16x16x32_bf16 v[66:69], v[180:183], v[212:215], 0
	v_mfma_f32_16x16x32_bf16 v[118:121], v[176:179], v[192:195], v[118:121]
	v_mfma_f32_16x16x32_bf16 v[114:117], v[184:187], v[192:195], v[114:117]
	v_mfma_f32_16x16x32_bf16 v[102:105], v[176:179], v[200:203], v[102:105]
	v_mfma_f32_16x16x32_bf16 v[98:101], v[184:187], v[200:203], v[98:101]
	v_mfma_f32_16x16x32_bf16 v[86:89], v[176:179], v[208:211], v[86:89]
	v_mfma_f32_16x16x32_bf16 v[82:85], v[184:187], v[208:211], v[82:85]
	v_mfma_f32_16x16x32_bf16 v[70:73], v[176:179], v[216:219], v[70:73]
	v_mfma_f32_16x16x32_bf16 v[66:69], v[184:187], v[216:219], v[66:69]
	s_setprio 0
	s_barrier
	s_add_u32 s98, s38, s8
	s_addc_u32 s99, s39, s9
	s_add_u32 s100, s40, s10
	s_addc_u32 s101, s41, s11
	s_add_i32 s12, s51, s6
	s_mov_b32 m0, s12
	ds_read_b128 v[188:191], v157 offset:16384
	ds_read_b128 v[192:195], v157 offset:17408
	ds_read_b128 v[196:199], v157 offset:18432
	ds_read_b128 v[200:203], v157 offset:19456
	ds_read_b128 v[204:207], v157 offset:20480
	ds_read_b128 v[208:211], v157 offset:21504
	ds_read_b128 v[212:215], v157 offset:22528
	ds_read_b128 v[216:219], v157 offset:23552
	global_load_lds_dwordx4 v134, s[38:39]
	s_add_i32 m0, s12, 0x2000
	s_add_u32 s12, s38, 0x40000
	s_addc_u32 s13, s39, 0
	s_add_i32 s60, s52, s6
	global_load_lds_dwordx4 v130, s[38:39]
	s_mov_b32 m0, s60
	s_nop 0
	global_load_lds_dwordx4 v134, s[12:13]
	s_add_i32 m0, s60, 0x2000
	s_nop 0
	global_load_lds_dwordx4 v130, s[12:13]
	s_mov_b32 m0, s42
	s_nop 0
	global_load_lds_dwordx4 v136, s[40:41]
	s_mov_b32 m0, s43
	s_nop 0
	global_load_lds_dwordx4 v132, s[40:41]
	s_waitcnt vmcnt(8)
	s_waitcnt lgkmcnt(0)
	s_barrier
; #define PG8_STAGE(bufoff, gbase, voff) do { _Pragma("unroll") for (int _i = 0; _i < 2; ++_i) \
;         __builtin_amdgcn_global_load_lds((const unsigned*)((const char*)(gbase) + (voff)[_i]), (LAS unsigned*)(lds + (bufoff) + ldsw + _i * 8192), 16, 0, 0); } while (0)
; #define PG8_LDA(dst, b, h) do { _Pragma("unroll") for (int m = 0; m < 4; ++m) _Pragma("unroll") for (int k = 0; k < 2; ++k) dst[m][k] = *(const LAS bf16x8*)(lds + PG8_SA(b, h) + aoff + m * 2048 + k * 1024); } while (0)
; #define PG8_LDB(dst, b, h) do { _Pragma("unroll") for (int n = 0; n < 2; ++n) _Pragma("unroll") for (int k = 0; k < 2; ++k) dst[n][k] = *(const LAS bf16x8*)(lds + PG8_SB(b, h) + boff + n * 2048 + k * 1024); } while (0)
; #define PG8_MMA(ai, bj, At, Bt) do { __builtin_amdgcn_s_setprio(1); _Pragma("unroll") for (int m = 0; m < 4; ++m) _Pragma("unroll") for (int n = 0; n < 2; ++n) _Pragma("unroll") for (int k = 0; k < 2; ++k) \
;         acc[ai][bj][m][n] = __builtin_amdgcn_mfma_f32_16x16x32_bf16(Bt[n][k], At[m][k], acc[ai][bj][m][n], 0, 0, 0); __builtin_amdgcn_s_setprio(0); } while (0)
; #define PG8_WAIT_V(n) asm volatile("s_waitcnt vmcnt(" #n ")" ::: "memory")
; #define PG8_WAIT_L(n) asm volatile("s_waitcnt lgkmcnt(" #n ")" ::: "memory")
; #define PG8_BAR __builtin_amdgcn_s_barrier()
; #define PG8_SCHED __builtin_amdgcn_sched_barrier(0)
; template <class Epi, bool ALIGN_EPI, bool SPLITA>
; __device__ __forceinline__ void gemm_phase(LAS unsigned char* lds, const Gemm g, const StaticOrder& S, const Epi& E) {
;     ...
;             PG8_WAIT_V(8); PG8_WAIT_L(0); PG8_BAR; PG8_MMA(1, 0, At, B0); PG8_MMA(1, 1, At, B1); PG8_BAR; PG8_SCHED;
;             PG8_LDB(B0, 1, 0); PG8_LDB(B1, 1, 1); PG8_SCHED; PG8_LDA(At, 1, 0); PG8_STAGE(PG8_SA(0, 1), a2h, vo2);
;             PG8_WAIT_V(8); PG8_WAIT_L(0); PG8_BAR; PG8_MMA(0, 0, At, B0); PG8_MMA(0, 1, At, B1); PG8_BAR; PG8_SCHED;
	s_setprio 1
	s_waitcnt lgkmcnt(0)
	v_mfma_f32_16x16x32_bf16 v[62:65], v[150:153], v[188:191], 0
	v_mfma_f32_16x16x32_bf16 v[58:61], v[164:167], v[188:191], 0
	v_mfma_f32_16x16x32_bf16 v[38:41], v[150:153], v[196:199], 0
	v_mfma_f32_16x16x32_bf16 v[34:37], v[164:167], v[196:199], 0
	v_mfma_f32_16x16x32_bf16 v[22:25], v[150:153], v[204:207], 0
	v_mfma_f32_16x16x32_bf16 v[18:21], v[164:167], v[204:207], 0
	v_mfma_f32_16x16x32_bf16 v[6:9], v[150:153], v[212:215], 0
	v_mfma_f32_16x16x32_bf16 v[2:5], v[164:167], v[212:215], 0
	v_mfma_f32_16x16x32_bf16 v[62:65], v[160:163], v[192:195], v[62:65]
	v_mfma_f32_16x16x32_bf16 v[58:61], v[168:171], v[192:195], v[58:61]
	v_mfma_f32_16x16x32_bf16 v[38:41], v[160:163], v[200:203], v[38:41]
	v_mfma_f32_16x16x32_bf16 v[34:37], v[168:171], v[200:203], v[34:37]
	v_mfma_f32_16x16x32_bf16 v[22:25], v[160:163], v[208:211], v[22:25]
	v_mfma_f32_16x16x32_bf16 v[18:21], v[168:171], v[208:211], v[18:21]
	v_mfma_f32_16x16x32_bf16 v[6:9], v[160:163], v[216:219], v[6:9]
	v_mfma_f32_16x16x32_bf16 v[2:5], v[168:171], v[216:219], v[2:5]
	s_setprio 0
	s_setprio 1
	v_mfma_f32_16x16x32_bf16 v[54:57], v[172:175], v[188:191], 0
	v_mfma_f32_16x16x32_bf16 v[50:53], v[180:183], v[188:191], 0
	v_mfma_f32_16x16x32_bf16 v[42:45], v[172:175], v[196:199], 0
	v_mfma_f32_16x16x32_bf16 v[46:49], v[180:183], v[196:199], 0
	v_mfma_f32_16x16x32_bf16 v[26:29], v[172:175], v[204:207], 0
	v_mfma_f32_16x16x32_bf16 v[30:33], v[180:183], v[204:207], 0
	v_mfma_f32_16x16x32_bf16 v[10:13], v[172:175], v[212:215], 0
	v_mfma_f32_16x16x32_bf16 v[14:17], v[180:183], v[212:215], 0
	v_mfma_f32_16x16x32_bf16 v[54:57], v[176:179], v[192:195], v[54:57]
	v_mfma_f32_16x16x32_bf16 v[50:53], v[184:187], v[192:195], v[50:53]
	v_mfma_f32_16x16x32_bf16 v[42:45], v[176:179], v[200:203], v[42:45]
	v_mfma_f32_16x16x32_bf16 v[46:49], v[184:187], v[200:203], v[46:49]
	v_mfma_f32_16x16x32_bf16 v[26:29], v[176:179], v[208:211], v[26:29]
	v_mfma_f32_16x16x32_bf16 v[30:33], v[184:187], v[208:211], v[30:33]
	v_mfma_f32_16x16x32_bf16 v[10:13], v[176:179], v[216:219], v[10:13]
	v_mfma_f32_16x16x32_bf16 v[14:17], v[184:187], v[216:219], v[14:17]
	s_setprio 0
	s_barrier
	s_add_i32 s60, 0, 0x18000
	v_add_u32_e32 v149, s60, v154
	s_add_i32 s61, 0, 0x1c000
	ds_read_b128 v[150:153], v149
	ds_read_b128 v[160:163], v149 offset:1024
	ds_read_b128 v[164:167], v149 offset:2048
	ds_read_b128 v[168:171], v149 offset:3072
	v_add_u32_e32 v149, s61, v154
	ds_read_b128 v[172:175], v149
	ds_read_b128 v[176:179], v149 offset:1024
	ds_read_b128 v[180:183], v149 offset:2048
	ds_read_b128 v[184:187], v149 offset:3072
	s_add_u32 s12, s40, 0x40000
	s_addc_u32 s13, s41, 0
	s_mov_b32 m0, s44
	ds_read_b128 v[188:191], v157 offset:32768
	ds_read_b128 v[192:195], v157 offset:33792
	ds_read_b128 v[196:199], v157 offset:34816
	ds_read_b128 v[200:203], v157 offset:35840
	ds_read_b128 v[204:207], v157 offset:36864
	ds_read_b128 v[208:211], v157 offset:37888
	ds_read_b128 v[212:215], v157 offset:38912
	ds_read_b128 v[216:219], v157 offset:39936
	global_load_lds_dwordx4 v136, s[12:13]
	s_mov_b32 m0, s45
	s_nop 0
	global_load_lds_dwordx4 v132, s[12:13]
	s_waitcnt vmcnt(8)
	s_waitcnt lgkmcnt(0)
	s_barrier
	s_setprio 1
	s_waitcnt lgkmcnt(0)
	v_mfma_f32_16x16x32_bf16 v[126:129], v[150:153], v[188:191], v[126:129]
	v_mfma_f32_16x16x32_bf16 v[122:125], v[164:167], v[188:191], v[122:125]
	v_mfma_f32_16x16x32_bf16 v[110:113], v[150:153], v[196:199], v[110:113]
	v_mfma_f32_16x16x32_bf16 v[106:109], v[164:167], v[196:199], v[106:109]
	v_mfma_f32_16x16x32_bf16 v[94:97], v[150:153], v[204:207], v[94:97]
	v_mfma_f32_16x16x32_bf16 v[90:93], v[164:167], v[204:207], v[90:93]
	v_mfma_f32_16x16x32_bf16 v[78:81], v[150:153], v[212:215], v[78:81]
	v_mfma_f32_16x16x32_bf16 v[74:77], v[164:167], v[212:215], v[74:77]
	v_mfma_f32_16x16x32_bf16 v[126:129], v[160:163], v[192:195], v[126:129]
	v_mfma_f32_16x16x32_bf16 v[122:125], v[168:171], v[192:195], v[122:125]
	v_mfma_f32_16x16x32_bf16 v[110:113], v[160:163], v[200:203], v[110:113]
	v_mfma_f32_16x16x32_bf16 v[106:109], v[168:171], v[200:203], v[106:109]
	v_mfma_f32_16x16x32_bf16 v[94:97], v[160:163], v[208:211], v[94:97]
	v_mfma_f32_16x16x32_bf16 v[90:93], v[168:171], v[208:211], v[90:93]
	v_mfma_f32_16x16x32_bf16 v[78:81], v[160:163], v[216:219], v[78:81]
	v_mfma_f32_16x16x32_bf16 v[74:77], v[168:171], v[216:219], v[74:77]
	s_setprio 0
	s_setprio 1
	v_mfma_f32_16x16x32_bf16 v[118:121], v[172:175], v[188:191], v[118:121]
	v_mfma_f32_16x16x32_bf16 v[114:117], v[180:183], v[188:191], v[114:117]
	v_mfma_f32_16x16x32_bf16 v[102:105], v[172:175], v[196:199], v[102:105]
	v_mfma_f32_16x16x32_bf16 v[98:101], v[180:183], v[196:199], v[98:101]
	v_mfma_f32_16x16x32_bf16 v[86:89], v[172:175], v[204:207], v[86:89]
	v_mfma_f32_16x16x32_bf16 v[82:85], v[180:183], v[204:207], v[82:85]
	v_mfma_f32_16x16x32_bf16 v[70:73], v[172:175], v[212:215], v[70:73]
	v_mfma_f32_16x16x32_bf16 v[66:69], v[180:183], v[212:215], v[66:69]
	v_mfma_f32_16x16x32_bf16 v[118:121], v[176:179], v[192:195], v[118:121]
	v_mfma_f32_16x16x32_bf16 v[114:117], v[184:187], v[192:195], v[114:117]
	v_mfma_f32_16x16x32_bf16 v[102:105], v[176:179], v[200:203], v[102:105]
	v_mfma_f32_16x16x32_bf16 v[98:101], v[184:187], v[200:203], v[98:101]
	v_mfma_f32_16x16x32_bf16 v[86:89], v[176:179], v[208:211], v[86:89]
	v_mfma_f32_16x16x32_bf16 v[82:85], v[184:187], v[208:211], v[82:85]
	v_mfma_f32_16x16x32_bf16 v[70:73], v[176:179], v[216:219], v[70:73]
	v_mfma_f32_16x16x32_bf16 v[66:69], v[184:187], v[216:219], v[66:69]
	s_setprio 0
	s_barrier
; #define PG8_STAGE(bufoff, gbase, voff) do { _Pragma("unroll") for (int _i = 0; _i < 2; ++_i) \
;         __builtin_amdgcn_global_load_lds((const unsigned*)((const char*)(gbase) + (voff)[_i]), (LAS unsigned*)(lds + (bufoff) + ldsw + _i * 8192), 16, 0, 0); } while (0)
; #define PG8_LDA(dst, b, h) do { _Pragma("unroll") for (int m = 0; m < 4; ++m) _Pragma("unroll") for (int k = 0; k < 2; ++k) dst[m][k] = *(const LAS bf16x8*)(lds + PG8_SA(b, h) + aoff + m * 2048 + k * 1024); } while (0)
; #define PG8_MMA(ai, bj, At, Bt) do { __builtin_amdgcn_s_setprio(1); _Pragma("unroll") for (int m = 0; m < 4; ++m) _Pragma("unroll") for (int n = 0; n < 2; ++n) _Pragma("unroll") for (int k = 0; k < 2; ++k) \
;         acc[ai][bj][m][n] = __builtin_amdgcn_mfma_f32_16x16x32_bf16(Bt[n][k], At[m][k], acc[ai][bj][m][n], 0, 0, 0); __builtin_amdgcn_s_setprio(0); } while (0)
; #define PG8_WAIT_V(n) asm volatile("s_waitcnt vmcnt(" #n ")" ::: "memory")
; #define PG8_WAIT_L(n) asm volatile("s_waitcnt lgkmcnt(" #n ")" ::: "memory")
; #define PG8_BAR __builtin_amdgcn_s_barrier()
; #define PG8_SCHED __builtin_amdgcn_sched_barrier(0)
; template <class Epi, bool ALIGN_EPI, bool SPLITA>
; __device__ __forceinline__ void gemm_phase(LAS unsigned char* lds, const Gemm g, const StaticOrder& S, const Epi& E) {
;     ...
;             PG8_LDA(At, 1, 1); PG8_STAGE(PG8_SB(1, 0), b3, voffB); PG8_STAGE(PG8_SB(1, 1), b3 + hstepB, voffB); PG8_STAGE(PG8_SA(1, 0), a3, vo2);
;             PG8_WAIT_V(8); PG8_WAIT_L(0); PG8_BAR; PG8_MMA(1, 0, At, B0); PG8_MMA(1, 1, At, B1); PG8_BAR; PG8_SCHED;
	s_add_i32 s12, s60, s6
	s_mov_b32 m0, s12
	ds_read_b128 v[188:191], v157 offset:49152
	ds_read_b128 v[192:195], v157 offset:50176
	ds_read_b128 v[196:199], v157 offset:51200
	ds_read_b128 v[200:203], v157 offset:52224
	ds_read_b128 v[204:207], v157 offset:53248
	ds_read_b128 v[208:211], v157 offset:54272
	ds_read_b128 v[212:215], v157 offset:55296
	ds_read_b128 v[216:219], v157 offset:56320
	global_load_lds_dwordx4 v134, s[98:99]
	s_add_i32 m0, s12, 0x2000
	s_add_u32 s12, s38, 0x40800
	s_addc_u32 s13, s39, 0
	s_add_i32 s38, s61, s6
	global_load_lds_dwordx4 v130, s[98:99]
	s_mov_b32 m0, s38
	s_nop 0
	global_load_lds_dwordx4 v134, s[12:13]
	s_add_i32 m0, s38, 0x2000
	s_nop 0
	global_load_lds_dwordx4 v130, s[12:13]
	s_mov_b32 m0, s49
	s_nop 0
	global_load_lds_dwordx4 v136, s[100:101]
	s_mov_b32 m0, s50
	s_nop 0
	global_load_lds_dwordx4 v132, s[100:101]
	s_waitcnt vmcnt(8)
	s_waitcnt lgkmcnt(0)
	s_barrier
	s_setprio 1
	s_waitcnt lgkmcnt(0)
	v_mfma_f32_16x16x32_bf16 v[62:65], v[150:153], v[188:191], v[62:65]
	v_mfma_f32_16x16x32_bf16 v[58:61], v[164:167], v[188:191], v[58:61]
	v_mfma_f32_16x16x32_bf16 v[38:41], v[150:153], v[196:199], v[38:41]
	v_mfma_f32_16x16x32_bf16 v[34:37], v[164:167], v[196:199], v[34:37]
	v_mfma_f32_16x16x32_bf16 v[22:25], v[150:153], v[204:207], v[22:25]
	v_mfma_f32_16x16x32_bf16 v[18:21], v[164:167], v[204:207], v[18:21]
	v_mfma_f32_16x16x32_bf16 v[6:9], v[150:153], v[212:215], v[6:9]
	v_mfma_f32_16x16x32_bf16 v[2:5], v[164:167], v[212:215], v[2:5]
	v_mfma_f32_16x16x32_bf16 v[62:65], v[160:163], v[192:195], v[62:65]
	v_mfma_f32_16x16x32_bf16 v[58:61], v[168:171], v[192:195], v[58:61]
	v_mfma_f32_16x16x32_bf16 v[38:41], v[160:163], v[200:203], v[38:41]
	v_mfma_f32_16x16x32_bf16 v[34:37], v[168:171], v[200:203], v[34:37]
	v_mfma_f32_16x16x32_bf16 v[22:25], v[160:163], v[208:211], v[22:25]
	v_mfma_f32_16x16x32_bf16 v[18:21], v[168:171], v[208:211], v[18:21]
	v_mfma_f32_16x16x32_bf16 v[6:9], v[160:163], v[216:219], v[6:9]
	v_mfma_f32_16x16x32_bf16 v[2:5], v[168:171], v[216:219], v[2:5]
	s_setprio 0
	s_setprio 1
	v_mfma_f32_16x16x32_bf16 v[54:57], v[172:175], v[188:191], v[54:57]
	v_mfma_f32_16x16x32_bf16 v[50:53], v[180:183], v[188:191], v[50:53]
	v_mfma_f32_16x16x32_bf16 v[42:45], v[172:175], v[196:199], v[42:45]
	v_mfma_f32_16x16x32_bf16 v[46:49], v[180:183], v[196:199], v[46:49]
	v_mfma_f32_16x16x32_bf16 v[26:29], v[172:175], v[204:207], v[26:29]
	v_mfma_f32_16x16x32_bf16 v[30:33], v[180:183], v[204:207], v[30:33]
	v_mfma_f32_16x16x32_bf16 v[10:13], v[172:175], v[212:215], v[10:13]
	v_mfma_f32_16x16x32_bf16 v[14:17], v[180:183], v[212:215], v[14:17]
	v_mfma_f32_16x16x32_bf16 v[54:57], v[176:179], v[192:195], v[54:57]
	v_mfma_f32_16x16x32_bf16 v[50:53], v[184:187], v[192:195], v[50:53]
	v_mfma_f32_16x16x32_bf16 v[42:45], v[176:179], v[200:203], v[42:45]
	v_mfma_f32_16x16x32_bf16 v[46:49], v[184:187], v[200:203], v[46:49]
	v_mfma_f32_16x16x32_bf16 v[26:29], v[176:179], v[208:211], v[26:29]
	v_mfma_f32_16x16x32_bf16 v[30:33], v[184:187], v[208:211], v[30:33]
	v_mfma_f32_16x16x32_bf16 v[10:13], v[176:179], v[216:219], v[10:13]
	v_mfma_f32_16x16x32_bf16 v[14:17], v[184:187], v[216:219], v[14:17]
	s_setprio 0
	s_barrier
	s_add_i32 s57, s57, 2
	s_add_u32 s55, s55, 0x1000
	s_addc_u32 s56, s56, 0
	s_add_u32 s36, s36, 0x100
	s_addc_u32 s37, s37, 0

; __device__ __forceinline__ u32x4 pack8(const f32x4 a, const f32x4 b) { u32x4 w; w.x = cvt_pk_bf16(a[0], a[1]); w.y = cvt_pk_bf16(a[2], a[3]); w.z = cvt_pk_bf16(b[0], b[1]); w.w = cvt_pk_bf16(b[2], b[3]); return w; }
; #define PG8_BAR __builtin_amdgcn_s_barrier()
; template <class Epi, bool ALIGN_EPI, bool SPLITA>
; __device__ __forceinline__ void gemm_phase(LAS unsigned char* lds, const Gemm g, const StaticOrder& S, const Epi& E) {
;     ...
;         if constexpr (ALIGN_EPI) { if (wr == 0) PG8_BAR; }
;     __device__ __forceinline__ void operator()(const Acc& acc, const Unit& u, int wr, int wc, int fr, int fq) const {
;         const int row0 = u.pm * BM + wr * 64 + fr, col0 = u.pn * BM + wc * 32 + 8 * fq;
; #pragma unroll
;         for (int ai = 0; ai < 2; ++ai)
; #pragma unroll
;             for (int m = 0; m < 4; ++m) {
;                 const int row = row0 + ai * HALF + m * 16; const float rinv = __builtin_amdgcn_rsqf(ssq[row] * (1.0f / DM) + EPS);
;                 bf16_t* rowp = U + (size_t)u.pm * (BM * FF) + (size_t)u.pn * (BM * BM) + (size_t)(((row & (BM - 1)) >> 4) * 8 + wc) * 512 + fr * 32 + 8 * fq;
; #pragma unroll
;                 for (int bj = 0; bj < 2; ++bj) { f32x4 v0 = acc[ai][bj][m][0] * rinv, v1 = acc[ai][bj][m][1] * rinv;
; #pragma unroll
;                     for (int e = 0; e < 4; ++e) { const float a = fmaxf(v0[e], 0.f), b = fmaxf(v1[e], 0.f); v0[e] = a * a; v1[e] = b * b; }
;                     __builtin_nontemporal_store(pack8(v0, v1), (u32x4*)(rowp + bj * (4 * 512))); }
.LBB0_799:
	v_lshl_add_u32 v150, s28, 8, v1
	v_ashrrev_i32_e32 v151, 31, v150
	v_lshl_add_u64 v[152:153], v[150:151], 2, s[66:67]
	global_load_dword v151, v[152:153], off
	s_ashr_i32 s29, s28, 31
	s_ashr_i32 s31, s30, 31
	s_lshl_b64 s[12:13], s[28:29], 21
	s_lshl_b64 s[28:29], s[30:31], 17
	s_add_u32 s12, s82, s12
	s_addc_u32 s13, s83, s13
	s_add_u32 s28, s12, s28
	s_addc_u32 s29, s13, s29
	s_add_u32 s12, s28, s53
	s_addc_u32 s13, s29, 0
	v_mov_b32_e32 v149, v139
	v_lshl_add_u64 v[164:165], s[12:13], 0, v[138:139]
	v_or_b32_e32 v160, 16, v150
	v_lshl_add_u64 v[164:165], v[164:165], 0, v[148:149]
	v_ashrrev_i32_e32 v161, 31, v160
	v_add_co_u32_e32 v168, vcc, s54, v164
	v_lshl_add_u64 v[162:163], v[160:161], 2, s[66:67]
	s_nop 0
	v_addc_co_u32_e32 v169, vcc, 0, v165, vcc
	s_waitcnt vmcnt(0)
	v_fmamk_f32 v151, v151, 0x3a800000, v158
	v_rsq_f32_e32 v166, v151
	s_nop 0
	v_pk_mul_f32 v[128:129], v[128:129], v[166:167] op_sel_hi:[1,0]
	v_pk_mul_f32 v[126:127], v[126:127], v[166:167] op_sel_hi:[1,0]
	v_pk_mul_f32 v[124:125], v[124:125], v[166:167] op_sel_hi:[1,0]
	v_pk_mul_f32 v[122:123], v[122:123], v[166:167] op_sel_hi:[1,0]
	v_pk_mul_f32 v[120:121], v[120:121], v[166:167] op_sel_hi:[1,0]
	v_pk_mul_f32 v[118:119], v[118:119], v[166:167] op_sel_hi:[1,0]
	v_pk_mul_f32 v[116:117], v[116:117], v[166:167] op_sel_hi:[1,0]
	v_pk_mul_f32 v[114:115], v[114:115], v[166:167] op_sel_hi:[1,0]
	v_max_f32_e32 v126, 0, v126
	v_max_f32_e32 v122, 0, v122
	v_max_f32_e32 v127, 0, v127
	v_max_f32_e32 v123, 0, v123
	v_max_f32_e32 v128, 0, v128
	v_max_f32_e32 v124, 0, v124
	v_max_f32_e32 v129, 0, v129
	v_max_f32_e32 v125, 0, v125
	v_max_f32_e32 v118, 0, v118
	v_max_f32_e32 v114, 0, v114
	v_max_f32_e32 v119, 0, v119
	v_max_f32_e32 v115, 0, v115
	v_max_f32_e32 v120, 0, v120
	v_max_f32_e32 v116, 0, v116
	v_max_f32_e32 v121, 0, v121
	v_max_f32_e32 v117, 0, v117
	v_pk_mul_f32 v[126:127], v[126:127], v[126:127]
	v_pk_mul_f32 v[122:123], v[122:123], v[122:123]
	v_pk_mul_f32 v[128:129], v[128:129], v[128:129]
	v_pk_mul_f32 v[124:125], v[124:125], v[124:125]
	v_pk_mul_f32 v[118:119], v[118:119], v[118:119]
	v_pk_mul_f32 v[166:167], v[114:115], v[114:115]
	v_pk_mul_f32 v[120:121], v[120:121], v[120:121]
	v_pk_mul_f32 v[170:171], v[116:117], v[116:117]
	v_cvt_pk_bf16_f32 v114, v126, v127
	v_cvt_pk_bf16_f32 v115, v128, v129
	v_cvt_pk_bf16_f32 v116, v122, v123
	v_cvt_pk_bf16_f32 v117, v124, v125
	v_cvt_pk_bf16_f32 v118, v118, v119
	v_cvt_pk_bf16_f32 v119, v120, v121
	v_cvt_pk_bf16_f32 v120, v166, v167
	v_cvt_pk_bf16_f32 v121, v170, v171
	global_store_dwordx4 v[164:165], v[114:117], off nt
	global_store_dwordx4 v[168:169], v[118:121], off nt
	global_load_dword v120, v[162:163], off
	v_or_b32_e32 v116, 32, v150
	v_ashrrev_i32_e32 v117, 31, v116
	v_lshl_add_u64 v[118:119], v[116:117], 2, s[66:67]
	v_lshrrev_b32_e32 v114, 1, v160
	v_and_b32_e32 v114, 0x68, v114
	v_or_b32_e32 v114, s48, v114
	v_mov_b32_e32 v115, v139
	v_lshlrev_b32_e32 v114, 10, v114
	v_lshl_add_u64 v[114:115], s[28:29], 0, v[114:115]
	v_lshl_add_u64 v[114:115], v[114:115], 0, v[138:139]
	v_lshl_add_u64 v[114:115], v[114:115], 0, v[148:149]
	v_add_co_u32_e32 v122, vcc, s54, v114
	s_waitcnt vmcnt(0)
	v_fmamk_f32 v117, v120, 0x3a800000, v158
	v_rsq_f32_e32 v120, v117
	v_addc_co_u32_e32 v123, vcc, 0, v115, vcc
	v_pk_mul_f32 v[112:113], v[112:113], v[120:121] op_sel_hi:[1,0]
	v_pk_mul_f32 v[110:111], v[110:111], v[120:121] op_sel_hi:[1,0]
	v_pk_mul_f32 v[108:109], v[108:109], v[120:121] op_sel_hi:[1,0]
	v_pk_mul_f32 v[106:107], v[106:107], v[120:121] op_sel_hi:[1,0]
	v_pk_mul_f32 v[104:105], v[104:105], v[120:121] op_sel_hi:[1,0]
	v_pk_mul_f32 v[102:103], v[102:103], v[120:121] op_sel_hi:[1,0]
	v_pk_mul_f32 v[100:101], v[100:101], v[120:121] op_sel_hi:[1,0]
	v_pk_mul_f32 v[98:99], v[98:99], v[120:121] op_sel_hi:[1,0]
	v_max_f32_e32 v110, 0, v110
	v_max_f32_e32 v106, 0, v106
	v_max_f32_e32 v111, 0, v111
	v_max_f32_e32 v107, 0, v107
	v_max_f32_e32 v112, 0, v112
	v_max_f32_e32 v108, 0, v108
	v_max_f32_e32 v113, 0, v113
	v_max_f32_e32 v109, 0, v109
	v_max_f32_e32 v102, 0, v102
	v_max_f32_e32 v98, 0, v98
	v_max_f32_e32 v103, 0, v103
	v_max_f32_e32 v99, 0, v99
	v_max_f32_e32 v104, 0, v104
	v_max_f32_e32 v100, 0, v100
	v_max_f32_e32 v105, 0, v105
	v_max_f32_e32 v101, 0, v101
	v_pk_mul_f32 v[110:111], v[110:111], v[110:111]
	v_pk_mul_f32 v[106:107], v[106:107], v[106:107]
	v_pk_mul_f32 v[112:113], v[112:113], v[112:113]
	v_pk_mul_f32 v[108:109], v[108:109], v[108:109]
	v_pk_mul_f32 v[102:103], v[102:103], v[102:103]
	v_pk_mul_f32 v[120:121], v[98:99], v[98:99]
	v_pk_mul_f32 v[104:105], v[104:105], v[104:105]
	v_pk_mul_f32 v[124:125], v[100:101], v[100:101]
	v_cvt_pk_bf16_f32 v98, v110, v111
	v_cvt_pk_bf16_f32 v99, v112, v113
	v_cvt_pk_bf16_f32 v100, v106, v107
	v_cvt_pk_bf16_f32 v101, v108, v109
	v_cvt_pk_bf16_f32 v102, v102, v103
	v_cvt_pk_bf16_f32 v103, v104, v105
	v_cvt_pk_bf16_f32 v104, v120, v121
	v_cvt_pk_bf16_f32 v105, v124, v125
	global_store_dwordx4 v[114:115], v[98:101], off nt
	global_store_dwordx4 v[122:123], v[102:105], off nt
	s_cmp_lg_u64 s[16:17], 0
	s_cbranch_scc0 .Lxs_p5_0
	s_barrier
; __device__ __forceinline__ u32x4 pack8(const f32x4 a, const f32x4 b) { u32x4 w; w.x = cvt_pk_bf16(a[0], a[1]); w.y = cvt_pk_bf16(a[2], a[3]); w.z = cvt_pk_bf16(b[0], b[1]); w.w = cvt_pk_bf16(b[2], b[3]); return w; }
;     __device__ __forceinline__ void operator()(const Acc& acc, const Unit& u, int wr, int wc, int fr, int fq) const {
;         const int row0 = u.pm * BM + wr * 64 + fr, col0 = u.pn * BM + wc * 32 + 8 * fq;
; #pragma unroll
;         for (int ai = 0; ai < 2; ++ai)
; #pragma unroll
;             for (int m = 0; m < 4; ++m) {
;                 const int row = row0 + ai * HALF + m * 16; const float rinv = __builtin_amdgcn_rsqf(ssq[row] * (1.0f / DM) + EPS);
;                 bf16_t* rowp = U + (size_t)u.pm * (BM * FF) + (size_t)u.pn * (BM * BM) + (size_t)(((row & (BM - 1)) >> 4) * 8 + wc) * 512 + fr * 32 + 8 * fq;
; #pragma unroll
;                 for (int bj = 0; bj < 2; ++bj) { f32x4 v0 = acc[ai][bj][m][0] * rinv, v1 = acc[ai][bj][m][1] * rinv;
; #pragma unroll
;                     for (int e = 0; e < 4; ++e) { const float a = fmaxf(v0[e], 0.f), b = fmaxf(v1[e], 0.f); v0[e] = a * a; v1[e] = b * b; }
;                     __builtin_nontemporal_store(pack8(v0, v1), (u32x4*)(rowp + bj * (4 * 512))); }
;             }
.Lxs_p5_0:
	global_load_dword v104, v[118:119], off
	v_or_b32_e32 v100, 48, v150
	v_ashrrev_i32_e32 v101, 31, v100
	v_lshl_add_u64 v[102:103], v[100:101], 2, s[66:67]
	v_lshrrev_b32_e32 v98, 1, v116
	v_and_b32_e32 v98, 0x70, v98
	v_or_b32_e32 v98, s48, v98
	v_mov_b32_e32 v99, v139
	v_lshlrev_b32_e32 v98, 10, v98
	v_lshl_add_u64 v[98:99], s[28:29], 0, v[98:99]
	v_lshl_add_u64 v[98:99], v[98:99], 0, v[138:139]
	v_lshl_add_u64 v[98:99], v[98:99], 0, v[148:149]
	v_add_co_u32_e32 v106, vcc, s54, v98
	s_waitcnt vmcnt(0)
	v_fmamk_f32 v101, v104, 0x3a800000, v158
	v_rsq_f32_e32 v104, v101
	v_addc_co_u32_e32 v107, vcc, 0, v99, vcc
	v_pk_mul_f32 v[96:97], v[96:97], v[104:105] op_sel_hi:[1,0]
	v_pk_mul_f32 v[94:95], v[94:95], v[104:105] op_sel_hi:[1,0]
	v_pk_mul_f32 v[92:93], v[92:93], v[104:105] op_sel_hi:[1,0]
	v_pk_mul_f32 v[90:91], v[90:91], v[104:105] op_sel_hi:[1,0]
	v_pk_mul_f32 v[88:89], v[88:89], v[104:105] op_sel_hi:[1,0]
	v_pk_mul_f32 v[86:87], v[86:87], v[104:105] op_sel_hi:[1,0]
	v_pk_mul_f32 v[84:85], v[84:85], v[104:105] op_sel_hi:[1,0]
	v_pk_mul_f32 v[82:83], v[82:83], v[104:105] op_sel_hi:[1,0]
	v_max_f32_e32 v94, 0, v94
	v_max_f32_e32 v90, 0, v90
	v_max_f32_e32 v95, 0, v95
	v_max_f32_e32 v91, 0, v91
	v_max_f32_e32 v96, 0, v96
	v_max_f32_e32 v92, 0, v92
	v_max_f32_e32 v97, 0, v97
	v_max_f32_e32 v93, 0, v93
	v_max_f32_e32 v86, 0, v86
	v_max_f32_e32 v82, 0, v82
	v_max_f32_e32 v87, 0, v87
	v_max_f32_e32 v83, 0, v83
	v_max_f32_e32 v88, 0, v88
	v_max_f32_e32 v84, 0, v84
	v_max_f32_e32 v89, 0, v89
	v_max_f32_e32 v85, 0, v85
	v_pk_mul_f32 v[94:95], v[94:95], v[94:95]
	v_pk_mul_f32 v[90:91], v[90:91], v[90:91]
	v_pk_mul_f32 v[96:97], v[96:97], v[96:97]
	v_pk_mul_f32 v[92:93], v[92:93], v[92:93]
	v_pk_mul_f32 v[86:87], v[86:87], v[86:87]
	v_pk_mul_f32 v[104:105], v[82:83], v[82:83]
	v_pk_mul_f32 v[88:89], v[88:89], v[88:89]
	v_pk_mul_f32 v[108:109], v[84:85], v[84:85]
	v_cvt_pk_bf16_f32 v82, v94, v95
	v_cvt_pk_bf16_f32 v83, v96, v97
	v_cvt_pk_bf16_f32 v84, v90, v91
	v_cvt_pk_bf16_f32 v85, v92, v93
	v_cvt_pk_bf16_f32 v86, v86, v87
	v_cvt_pk_bf16_f32 v87, v88, v89
	v_cvt_pk_bf16_f32 v88, v104, v105
	v_cvt_pk_bf16_f32 v89, v108, v109
	global_store_dwordx4 v[98:99], v[82:85], off nt
	global_store_dwordx4 v[106:107], v[86:89], off nt
	global_load_dword v84, v[102:103], off
	v_lshrrev_b32_e32 v82, 1, v100
	v_and_b32_e32 v82, 0x78, v82
	v_or_b32_e32 v82, s48, v82
	v_mov_b32_e32 v83, v139
	v_lshlrev_b32_e32 v82, 10, v82
	v_lshl_add_u64 v[82:83], s[28:29], 0, v[82:83]
	v_lshl_add_u64 v[82:83], v[82:83], 0, v[138:139]
	v_lshl_add_u64 v[82:83], v[82:83], 0, v[148:149]
	v_add_co_u32_e32 v86, vcc, s54, v82
	s_waitcnt vmcnt(0)
	v_fmamk_f32 v84, v84, 0x3a800000, v158
	v_rsq_f32_e32 v84, v84
	v_addc_co_u32_e32 v87, vcc, 0, v83, vcc
	v_pk_mul_f32 v[80:81], v[80:81], v[84:85] op_sel_hi:[1,0]
	v_pk_mul_f32 v[78:79], v[78:79], v[84:85] op_sel_hi:[1,0]
	v_pk_mul_f32 v[76:77], v[76:77], v[84:85] op_sel_hi:[1,0]
	v_pk_mul_f32 v[74:75], v[74:75], v[84:85] op_sel_hi:[1,0]
	v_pk_mul_f32 v[72:73], v[72:73], v[84:85] op_sel_hi:[1,0]
	v_pk_mul_f32 v[70:71], v[70:71], v[84:85] op_sel_hi:[1,0]
	v_pk_mul_f32 v[68:69], v[68:69], v[84:85] op_sel_hi:[1,0]
	v_pk_mul_f32 v[66:67], v[66:67], v[84:85] op_sel_hi:[1,0]
	v_max_f32_e32 v78, 0, v78
	v_max_f32_e32 v74, 0, v74
	v_max_f32_e32 v79, 0, v79
	v_max_f32_e32 v75, 0, v75
	v_max_f32_e32 v80, 0, v80
	v_max_f32_e32 v76, 0, v76
	v_max_f32_e32 v81, 0, v81
	v_max_f32_e32 v77, 0, v77
	v_max_f32_e32 v70, 0, v70
	v_max_f32_e32 v66, 0, v66
	v_max_f32_e32 v71, 0, v71
	v_max_f32_e32 v67, 0, v67
	v_max_f32_e32 v72, 0, v72
	v_max_f32_e32 v68, 0, v68
	v_max_f32_e32 v73, 0, v73
	v_max_f32_e32 v69, 0, v69
	v_pk_mul_f32 v[78:79], v[78:79], v[78:79]
	v_pk_mul_f32 v[74:75], v[74:75], v[74:75]
	v_pk_mul_f32 v[80:81], v[80:81], v[80:81]
	v_pk_mul_f32 v[76:77], v[76:77], v[76:77]
	v_pk_mul_f32 v[70:71], v[70:71], v[70:71]
	v_pk_mul_f32 v[84:85], v[66:67], v[66:67]
	v_pk_mul_f32 v[72:73], v[72:73], v[72:73]
	v_pk_mul_f32 v[88:89], v[68:69], v[68:69]
	v_cvt_pk_bf16_f32 v66, v78, v79
	v_cvt_pk_bf16_f32 v67, v80, v81
	v_cvt_pk_bf16_f32 v68, v74, v75
	v_cvt_pk_bf16_f32 v69, v76, v77
	v_cvt_pk_bf16_f32 v70, v70, v71
	v_cvt_pk_bf16_f32 v71, v72, v73
	v_cvt_pk_bf16_f32 v72, v84, v85
	v_cvt_pk_bf16_f32 v73, v88, v89
	global_store_dwordx4 v[82:83], v[66:69], off nt
	global_store_dwordx4 v[86:87], v[70:73], off nt
	global_load_dword v68, v[152:153], off offset:512
	v_add_u32_e32 v66, 0x80, v150
	v_lshrrev_b32_e32 v66, 1, v66
	v_and_b32_e32 v66, 0x60, v66
	v_or_b32_e32 v66, s48, v66
	v_mov_b32_e32 v67, v139
	v_lshlrev_b32_e32 v66, 10, v66
	v_lshl_add_u64 v[66:67], s[28:29], 0, v[66:67]
	v_lshl_add_u64 v[66:67], v[66:67], 0, v[138:139]
	v_lshl_add_u64 v[66:67], v[66:67], 0, v[148:149]
	v_add_co_u32_e32 v70, vcc, s54, v66
	s_waitcnt vmcnt(0)
; __device__ __forceinline__ u32x4 pack8(const f32x4 a, const f32x4 b) { u32x4 w; w.x = cvt_pk_bf16(a[0], a[1]); w.y = cvt_pk_bf16(a[2], a[3]); w.z = cvt_pk_bf16(b[0], b[1]); w.w = cvt_pk_bf16(b[2], b[3]); return w; }
;     __device__ __forceinline__ void operator()(const Acc& acc, const Unit& u, int wr, int wc, int fr, int fq) const {
;     ...
;         for (int ai = 0; ai < 2; ++ai)
; #pragma unroll
;             for (int m = 0; m < 4; ++m) {
;                 const int row = row0 + ai * HALF + m * 16; const float rinv = __builtin_amdgcn_rsqf(ssq[row] * (1.0f / DM) + EPS);
;                 bf16_t* rowp = U + (size_t)u.pm * (BM * FF) + (size_t)u.pn * (BM * BM) + (size_t)(((row & (BM - 1)) >> 4) * 8 + wc) * 512 + fr * 32 + 8 * fq;
; #pragma unroll
;                 for (int bj = 0; bj < 2; ++bj) { f32x4 v0 = acc[ai][bj][m][0] * rinv, v1 = acc[ai][bj][m][1] * rinv;
; #pragma unroll
;                     for (int e = 0; e < 4; ++e) { const float a = fmaxf(v0[e], 0.f), b = fmaxf(v1[e], 0.f); v0[e] = a * a; v1[e] = b * b; }
;                     __builtin_nontemporal_store(pack8(v0, v1), (u32x4*)(rowp + bj * (4 * 512))); }
;             }
	v_fmamk_f32 v68, v68, 0x3a800000, v158
	v_rsq_f32_e32 v68, v68
	v_addc_co_u32_e32 v71, vcc, 0, v67, vcc
	v_pk_mul_f32 v[64:65], v[64:65], v[68:69] op_sel_hi:[1,0]
	v_pk_mul_f32 v[62:63], v[62:63], v[68:69] op_sel_hi:[1,0]
	v_pk_mul_f32 v[60:61], v[60:61], v[68:69] op_sel_hi:[1,0]
	v_pk_mul_f32 v[58:59], v[58:59], v[68:69] op_sel_hi:[1,0]
	v_pk_mul_f32 v[56:57], v[56:57], v[68:69] op_sel_hi:[1,0]
	v_pk_mul_f32 v[54:55], v[54:55], v[68:69] op_sel_hi:[1,0]
	v_pk_mul_f32 v[52:53], v[52:53], v[68:69] op_sel_hi:[1,0]
	v_pk_mul_f32 v[50:51], v[50:51], v[68:69] op_sel_hi:[1,0]
	v_max_f32_e32 v62, 0, v62
	v_max_f32_e32 v58, 0, v58
	v_max_f32_e32 v63, 0, v63
	v_max_f32_e32 v59, 0, v59
	v_max_f32_e32 v64, 0, v64
	v_max_f32_e32 v60, 0, v60
	v_max_f32_e32 v65, 0, v65
	v_max_f32_e32 v61, 0, v61
	v_max_f32_e32 v54, 0, v54
	v_max_f32_e32 v50, 0, v50
	v_max_f32_e32 v55, 0, v55
	v_max_f32_e32 v51, 0, v51
	v_max_f32_e32 v56, 0, v56
	v_max_f32_e32 v52, 0, v52
	v_max_f32_e32 v57, 0, v57
	v_max_f32_e32 v53, 0, v53
	v_pk_mul_f32 v[62:63], v[62:63], v[62:63]
	v_pk_mul_f32 v[58:59], v[58:59], v[58:59]
	v_pk_mul_f32 v[64:65], v[64:65], v[64:65]
	v_pk_mul_f32 v[60:61], v[60:61], v[60:61]
	v_pk_mul_f32 v[54:55], v[54:55], v[54:55]
	v_pk_mul_f32 v[68:69], v[50:51], v[50:51]
	v_pk_mul_f32 v[56:57], v[56:57], v[56:57]
	v_pk_mul_f32 v[72:73], v[52:53], v[52:53]
	v_cvt_pk_bf16_f32 v50, v62, v63
	v_cvt_pk_bf16_f32 v51, v64, v65
	v_cvt_pk_bf16_f32 v52, v58, v59
	v_cvt_pk_bf16_f32 v53, v60, v61
	v_cvt_pk_bf16_f32 v54, v54, v55
	v_cvt_pk_bf16_f32 v55, v56, v57
	v_cvt_pk_bf16_f32 v56, v68, v69
	v_cvt_pk_bf16_f32 v57, v72, v73
	global_store_dwordx4 v[66:67], v[50:53], off nt
	global_store_dwordx4 v[70:71], v[54:57], off nt
	global_load_dword v52, v[152:153], off offset:576
	v_add_u32_e32 v50, 0x90, v150
	v_lshrrev_b32_e32 v50, 1, v50
	v_and_b32_e32 v50, 0x68, v50
	v_or_b32_e32 v50, s48, v50
	v_mov_b32_e32 v51, v139
	v_lshlrev_b32_e32 v50, 10, v50
	v_lshl_add_u64 v[50:51], s[28:29], 0, v[50:51]
	v_lshl_add_u64 v[50:51], v[50:51], 0, v[138:139]
	v_lshl_add_u64 v[50:51], v[50:51], 0, v[148:149]
	v_add_co_u32_e32 v54, vcc, s54, v50
	s_waitcnt vmcnt(0)
	v_fmamk_f32 v52, v52, 0x3a800000, v158
	v_rsq_f32_e32 v52, v52
	v_addc_co_u32_e32 v55, vcc, 0, v51, vcc
	v_pk_mul_f32 v[40:41], v[40:41], v[52:53] op_sel_hi:[1,0]
	v_pk_mul_f32 v[38:39], v[38:39], v[52:53] op_sel_hi:[1,0]
	v_pk_mul_f32 v[36:37], v[36:37], v[52:53] op_sel_hi:[1,0]
	v_pk_mul_f32 v[34:35], v[34:35], v[52:53] op_sel_hi:[1,0]
	v_pk_mul_f32 v[44:45], v[44:45], v[52:53] op_sel_hi:[1,0]
	v_pk_mul_f32 v[42:43], v[42:43], v[52:53] op_sel_hi:[1,0]
	v_pk_mul_f32 v[48:49], v[48:49], v[52:53] op_sel_hi:[1,0]
	v_pk_mul_f32 v[46:47], v[46:47], v[52:53] op_sel_hi:[1,0]
	v_max_f32_e32 v38, 0, v38
	v_max_f32_e32 v34, 0, v34
	v_max_f32_e32 v39, 0, v39
	v_max_f32_e32 v35, 0, v35
	v_max_f32_e32 v40, 0, v40
	v_max_f32_e32 v36, 0, v36
	v_max_f32_e32 v41, 0, v41
	v_max_f32_e32 v37, 0, v37
	v_max_f32_e32 v42, 0, v42
	v_max_f32_e32 v46, 0, v46
	v_max_f32_e32 v43, 0, v43
	v_max_f32_e32 v47, 0, v47
	v_max_f32_e32 v44, 0, v44
	v_max_f32_e32 v48, 0, v48
	v_max_f32_e32 v45, 0, v45
	v_max_f32_e32 v49, 0, v49
	v_pk_mul_f32 v[38:39], v[38:39], v[38:39]
	v_pk_mul_f32 v[52:53], v[34:35], v[34:35]
	v_pk_mul_f32 v[40:41], v[40:41], v[40:41]
	v_pk_mul_f32 v[56:57], v[36:37], v[36:37]
	v_pk_mul_f32 v[42:43], v[42:43], v[42:43]
	v_pk_mul_f32 v[46:47], v[46:47], v[46:47]
	v_pk_mul_f32 v[44:45], v[44:45], v[44:45]
	v_pk_mul_f32 v[48:49], v[48:49], v[48:49]
	v_cvt_pk_bf16_f32 v34, v38, v39
	v_cvt_pk_bf16_f32 v35, v40, v41
	v_cvt_pk_bf16_f32 v36, v52, v53
	v_cvt_pk_bf16_f32 v37, v56, v57
	v_cvt_pk_bf16_f32 v38, v42, v43
	v_cvt_pk_bf16_f32 v39, v44, v45
	v_cvt_pk_bf16_f32 v40, v46, v47
	v_cvt_pk_bf16_f32 v41, v48, v49
	global_store_dwordx4 v[50:51], v[34:37], off nt
	global_store_dwordx4 v[54:55], v[38:41], off nt
	global_load_dword v36, v[152:153], off offset:640
	v_add_u32_e32 v34, 0xa0, v150
	v_lshrrev_b32_e32 v34, 1, v34
	v_and_b32_e32 v34, 0x70, v34
	v_or_b32_e32 v34, s48, v34
	v_mov_b32_e32 v35, v139
	v_lshlrev_b32_e32 v34, 10, v34
	v_lshl_add_u64 v[34:35], s[28:29], 0, v[34:35]
	v_lshl_add_u64 v[34:35], v[34:35], 0, v[138:139]
	v_lshl_add_u64 v[34:35], v[34:35], 0, v[148:149]
	v_add_co_u32_e32 v38, vcc, s54, v34
	s_waitcnt vmcnt(0)
; __device__ __forceinline__ u32x4 pack8(const f32x4 a, const f32x4 b) { u32x4 w; w.x = cvt_pk_bf16(a[0], a[1]); w.y = cvt_pk_bf16(a[2], a[3]); w.z = cvt_pk_bf16(b[0], b[1]); w.w = cvt_pk_bf16(b[2], b[3]); return w; }
; #define PG8_BAR __builtin_amdgcn_s_barrier()
; template <class Epi, bool ALIGN_EPI, bool SPLITA>
; __device__ __forceinline__ void gemm_phase(LAS unsigned char* lds, const Gemm g, const StaticOrder& S, const Epi& E) {
;     ...
;         if (!has_next) break;
; #pragma unroll
;         for (int a = 0; a < 2; ++a)
; #pragma unroll
;             for (int b = 0; b < 2; ++b)
; #pragma unroll
;                 for (int m = 0; m < 4; ++m)
; #pragma unroll
;                     for (int n = 0; n < 2; ++n) acc[a][b][m][n] = (f32x4){0.f, 0.f, 0.f, 0.f};
;         cur = nxt; cA = nA; cB = nB; mirC = mirN; if constexpr (SPLITA) cA2 = (const char*)g.A2 + (size_t)cur.pm * tstepA; ++ui;
;         if constexpr (ALIGN_EPI) { if (wr == 1) PG8_BAR; }
;     __device__ __forceinline__ void operator()(const Acc& acc, const Unit& u, int wr, int wc, int fr, int fq) const {
;     ...
;         for (int ai = 0; ai < 2; ++ai)
; #pragma unroll
;             for (int m = 0; m < 4; ++m) {
;                 const int row = row0 + ai * HALF + m * 16; const float rinv = __builtin_amdgcn_rsqf(ssq[row] * (1.0f / DM) + EPS);
;                 bf16_t* rowp = U + (size_t)u.pm * (BM * FF) + (size_t)u.pn * (BM * BM) + (size_t)(((row & (BM - 1)) >> 4) * 8 + wc) * 512 + fr * 32 + 8 * fq;
; #pragma unroll
;                 for (int bj = 0; bj < 2; ++bj) { f32x4 v0 = acc[ai][bj][m][0] * rinv, v1 = acc[ai][bj][m][1] * rinv;
; #pragma unroll
;                     for (int e = 0; e < 4; ++e) { const float a = fmaxf(v0[e], 0.f), b = fmaxf(v1[e], 0.f); v0[e] = a * a; v1[e] = b * b; }
;                     __builtin_nontemporal_store(pack8(v0, v1), (u32x4*)(rowp + bj * (4 * 512))); }
;             }
	v_fmamk_f32 v36, v36, 0x3a800000, v158
	v_rsq_f32_e32 v36, v36
	v_addc_co_u32_e32 v39, vcc, 0, v35, vcc
	v_pk_mul_f32 v[24:25], v[24:25], v[36:37] op_sel_hi:[1,0]
	v_pk_mul_f32 v[22:23], v[22:23], v[36:37] op_sel_hi:[1,0]
	v_pk_mul_f32 v[20:21], v[20:21], v[36:37] op_sel_hi:[1,0]
	v_pk_mul_f32 v[18:19], v[18:19], v[36:37] op_sel_hi:[1,0]
	v_pk_mul_f32 v[28:29], v[28:29], v[36:37] op_sel_hi:[1,0]
	v_pk_mul_f32 v[26:27], v[26:27], v[36:37] op_sel_hi:[1,0]
	v_pk_mul_f32 v[32:33], v[32:33], v[36:37] op_sel_hi:[1,0]
	v_pk_mul_f32 v[30:31], v[30:31], v[36:37] op_sel_hi:[1,0]
	v_max_f32_e32 v22, 0, v22
	v_max_f32_e32 v18, 0, v18
	v_max_f32_e32 v23, 0, v23
	v_max_f32_e32 v19, 0, v19
	v_max_f32_e32 v24, 0, v24
	v_max_f32_e32 v20, 0, v20
	v_max_f32_e32 v25, 0, v25
	v_max_f32_e32 v21, 0, v21
	v_max_f32_e32 v26, 0, v26
	v_max_f32_e32 v30, 0, v30
	v_max_f32_e32 v27, 0, v27
	v_max_f32_e32 v31, 0, v31
	v_max_f32_e32 v28, 0, v28
	v_max_f32_e32 v32, 0, v32
	v_max_f32_e32 v29, 0, v29
	v_max_f32_e32 v33, 0, v33
	v_pk_mul_f32 v[22:23], v[22:23], v[22:23]
	v_pk_mul_f32 v[36:37], v[18:19], v[18:19]
	v_pk_mul_f32 v[24:25], v[24:25], v[24:25]
	v_pk_mul_f32 v[40:41], v[20:21], v[20:21]
	v_pk_mul_f32 v[26:27], v[26:27], v[26:27]
	v_pk_mul_f32 v[30:31], v[30:31], v[30:31]
	v_pk_mul_f32 v[28:29], v[28:29], v[28:29]
	v_pk_mul_f32 v[32:33], v[32:33], v[32:33]
	v_cvt_pk_bf16_f32 v18, v22, v23
	v_cvt_pk_bf16_f32 v19, v24, v25
	v_cvt_pk_bf16_f32 v20, v36, v37
	v_cvt_pk_bf16_f32 v21, v40, v41
	v_cvt_pk_bf16_f32 v22, v26, v27
	v_cvt_pk_bf16_f32 v23, v28, v29
	v_cvt_pk_bf16_f32 v24, v30, v31
	v_cvt_pk_bf16_f32 v25, v32, v33
	global_store_dwordx4 v[34:35], v[18:21], off nt
	global_store_dwordx4 v[38:39], v[22:25], off nt
	global_load_dword v21, v[152:153], off offset:704
	v_add_u32_e32 v18, 0xb0, v150
	v_lshrrev_b32_e32 v18, 1, v18
	v_and_b32_e32 v18, 0x78, v18
	v_or_b32_e32 v18, s48, v18
	v_mov_b32_e32 v19, v139
	v_lshlrev_b32_e32 v18, 10, v18
	v_lshl_add_u64 v[18:19], s[28:29], 0, v[18:19]
	v_lshl_add_u64 v[18:19], v[18:19], 0, v[138:139]
	v_lshl_add_u64 v[18:19], v[18:19], 0, v[148:149]
	v_add_co_u32_e32 v20, vcc, 0x1000, v18
	s_waitcnt vmcnt(0)
	v_fmamk_f32 v21, v21, 0x3a800000, v158
	v_rsq_f32_e32 v22, v21
	v_addc_co_u32_e32 v21, vcc, 0, v19, vcc
	s_andn2_b64 vcc, exec, s[2:3]
	v_pk_mul_f32 v[8:9], v[8:9], v[22:23] op_sel_hi:[1,0]
	v_pk_mul_f32 v[6:7], v[6:7], v[22:23] op_sel_hi:[1,0]
	v_pk_mul_f32 v[4:5], v[4:5], v[22:23] op_sel_hi:[1,0]
	v_pk_mul_f32 v[2:3], v[2:3], v[22:23] op_sel_hi:[1,0]
	v_pk_mul_f32 v[12:13], v[12:13], v[22:23] op_sel_hi:[1,0]
	v_pk_mul_f32 v[10:11], v[10:11], v[22:23] op_sel_hi:[1,0]
	v_pk_mul_f32 v[16:17], v[16:17], v[22:23] op_sel_hi:[1,0]
	v_pk_mul_f32 v[14:15], v[14:15], v[22:23] op_sel_hi:[1,0]
	v_max_f32_e32 v6, 0, v6
	v_max_f32_e32 v2, 0, v2
	v_max_f32_e32 v7, 0, v7
	v_max_f32_e32 v3, 0, v3
	v_max_f32_e32 v8, 0, v8
	v_max_f32_e32 v4, 0, v4
	v_max_f32_e32 v9, 0, v9
	v_max_f32_e32 v5, 0, v5
	v_max_f32_e32 v10, 0, v10
	v_max_f32_e32 v14, 0, v14
	v_max_f32_e32 v11, 0, v11
	v_max_f32_e32 v15, 0, v15
	v_max_f32_e32 v12, 0, v12
	v_max_f32_e32 v16, 0, v16
	v_max_f32_e32 v13, 0, v13
	v_max_f32_e32 v17, 0, v17
	v_pk_mul_f32 v[6:7], v[6:7], v[6:7]
	v_pk_mul_f32 v[22:23], v[2:3], v[2:3]
	v_pk_mul_f32 v[8:9], v[8:9], v[8:9]
	v_pk_mul_f32 v[24:25], v[4:5], v[4:5]
	v_pk_mul_f32 v[10:11], v[10:11], v[10:11]
	v_pk_mul_f32 v[14:15], v[14:15], v[14:15]
	v_pk_mul_f32 v[12:13], v[12:13], v[12:13]
	v_pk_mul_f32 v[16:17], v[16:17], v[16:17]
	v_cvt_pk_bf16_f32 v2, v6, v7
	v_cvt_pk_bf16_f32 v3, v8, v9
	v_cvt_pk_bf16_f32 v4, v22, v23
	v_cvt_pk_bf16_f32 v5, v24, v25
	s_mov_b64 s[2:3], -1
	v_cvt_pk_bf16_f32 v6, v10, v11
	v_cvt_pk_bf16_f32 v7, v12, v13
	v_cvt_pk_bf16_f32 v8, v14, v15
	v_cvt_pk_bf16_f32 v9, v16, v17
	global_store_dwordx4 v[18:19], v[2:5], off nt
	global_store_dwordx4 v[20:21], v[6:9], off nt
	s_cbranch_vccnz .LBB0_792
	s_mov_b32 s99, 0
	s_andn2_b64 vcc, exec, s[4:5]
	s_cbranch_vccnz .LBB0_791
	s_mov_b32 s99, 1
	s_branch .LBB0_791

; #define PG8_STAGE(bufoff, gbase, voff) do { _Pragma("unroll") for (int _i = 0; _i < 2; ++_i) \
;         __builtin_amdgcn_global_load_lds((const unsigned*)((const char*)(gbase) + (voff)[_i]), (LAS unsigned*)(lds + (bufoff) + ldsw + _i * 8192), 16, 0, 0); } while (0)
; #define PG8_WAIT_V(n) asm volatile("s_waitcnt vmcnt(" #n ")" ::: "memory")
; #define PG8_BAR __builtin_amdgcn_s_barrier()
; template <class Epi, bool ALIGN_EPI, bool SPLITA>
; __device__ __forceinline__ void gemm_phase(LAS unsigned char* lds, const Gemm g, const StaticOrder& S, const Epi& E) {
;     ...
;     const unsigned ldsw = (unsigned)wid * 1024u;
;     const int aoff = lds_byte(wr * 64 + fr, fq * 8), boff = lds_byte(wc * 32 + fr, fq * 8);
;     ...
;     { const unsigned vo[2] = {mirC ? voffAm[0] : voffA[0], mirC ? voffAm[1] : voffA[1]}; const char* cAh = mirC ? cA - hstepA : cA + hstepA;
;       PG8_STAGE(PG8_SB(0, 0), cB, voffB); PG8_STAGE(PG8_SB(0, 1), cB + hstepB, voffB); PG8_STAGE(PG8_SA(0, 0), cA, vo); PG8_STAGE(PG8_SA(0, 1), cAh, vo);
;       if (wr == 1) PG8_BAR;
;       PG8_WAIT_V(2); PG8_BAR;
;       PG8_STAGE(PG8_SB(1, 0), cB + kstepB, voffB); PG8_STAGE(PG8_SA(1, 0), cA + kofs(1), vo); PG8_STAGE(PG8_SB(1, 1), cB + hstepB + kstepB, voffB); }
;     PG8_WAIT_V(6); PG8_BAR;
.LBB0_861:
	s_lshl_b32 s6, s6, 5
	s_and_b32 s13, s6, 0x60
	s_mov_b64 s[6:7], 0x80
	s_add_i32 m0, s25, 0x18000
	v_lshl_add_u64 v[8:9], v[8:9], 0, s[6:7]
	s_lshl_b32 s12, s2, 13
	s_lshl_b32 s16, s13, 7
	s_waitcnt vmcnt(2)
	s_barrier
	global_load_lds_dwordx4 v[8:9], off
	v_lshl_add_u64 v[6:7], v[6:7], 0, s[6:7]
	s_add_i32 m0, s25, 0x1a000
	s_mov_b64 s[8:9], 0x800
	s_add_i32 s41, s25, 0x8000
	s_add_i32 s42, s25, 0xa000
	global_load_lds_dwordx4 v[6:7], off
	v_lshl_add_u64 v[2:3], v[2:3], 0, s[8:9]
	s_mov_b32 m0, s41
	s_add_u32 s10, s28, 0x100080
	global_load_lds_dwordx4 v[2:3], off
	v_lshl_add_u64 v[2:3], v[4:5], 0, s[8:9]
	s_mov_b32 m0, s42
	s_addc_u32 s11, s29, 0
	global_load_lds_dwordx4 v[2:3], off
	s_add_i32 m0, s25, 0x1c000
	v_lshl_add_u64 v[2:3], s[10:11], 0, v[132:133]
	global_load_lds_dwordx4 v[2:3], off
	v_lshl_add_u64 v[2:3], s[10:11], 0, v[128:129]
	s_add_i32 m0, s25, 0x1e000
	v_and_b32_e32 v1, 15, v0
	global_load_lds_dwordx4 v[2:3], off
	v_lshrrev_b32_e32 v2, 1, v0
	v_and_b32_e32 v2, 24, v2
	v_lshlrev_b32_e32 v3, 1, v2
	v_lshlrev_b32_e32 v0, 2, v0
	v_lshl_or_b32 v148, s2, 6, v1
	v_lshl_or_b32 v1, v1, 6, v3
	v_and_b32_e32 v0, 32, v0
	s_waitcnt vmcnt(6)
	s_cmpk_lt_u32 s1, 0x100
	v_bitop3_b32 v3, v1, s12, v0 bitop3:0xde
	v_bitop3_b32 v149, v1, s16, v0 bitop3:0xde
	s_cselect_b64 s[10:11], -1, 0
	s_add_i32 s44, 0, 0x10000
	s_add_i32 s45, 0, 0x14000
	s_sext_i32_i8 s47, s0
	s_ashr_i32 s43, s15, 31
	v_or_b32_e32 v150, s13, v2
	v_mov_b64_e32 v[136:137], 0x300
	v_mov_b64_e32 v[138:139], 0x2ff
	v_add_u32_e32 v151, s44, v149
	v_add_u32_e32 v152, s45, v149
	v_add_u32_e32 v153, 0, v3
	s_mov_b32 s46, 0
	s_barrier
	s_mov_b32 s99, 0
	s_branch .LBB0_864

; #define PG8_WAIT_V(n) asm volatile("s_waitcnt vmcnt(" #n ")" ::: "memory")
; #define PG8_BAR __builtin_amdgcn_s_barrier()
; template <class Epi, bool ALIGN_EPI, bool SPLITA>
; __device__ __forceinline__ void gemm_phase(LAS unsigned char* lds, const Gemm g, const StaticOrder& S, const Epi& E) {
;     ...
;         const bool has_next = S.next(ui + 1, nxt);
;         const char* nA = has_next ? baseA1(nxt) : cA;
;         const char* nB = has_next ? baseB(nxt) : cB;
;         const bool mirN = has_next ? mirrored(nxt) : mirC;
;         for (int t = 0; t < nt; t += 2) {
;             const bool last = (t == nt - 2);
;             if constexpr (Epi::MIDK) { if (t == g.ksplit) E.mid(acc, cur, wr, wc, fr, fq); }
;             const char *a1, *a2;
;             if constexpr (SPLITA) {
;                 a1 = (t + 1 < g.ksplit) ? cA + (size_t)(t + 1) * kstep : cA2 + (size_t)(t + 1 - g.ksplit) * 2048;
;                 a2 = last ? nA : ((t + 2 < g.ksplit) ? cA + (size_t)(t + 2) * kstep : cA2 + (size_t)(t + 2 - g.ksplit) * 2048);
;             } else { a1 = cA + kofs(t + 1); a2 = last ? nA : cA + kofs(t + 2); }
;             const char* b2 = last ? nB : cB + (size_t)(t + 2) * kstepB;
;             const bool s2a = SPLITA && (t + 1 >= g.ksplit), s2b = SPLITA && !last && (t + 2 >= g.ksplit);
;             const char* a3 = a2 + ((Epi::KSUB || s2b) ? (size_t)2048 : kstep); const char* b3 = b2 + kstepB;
;             const bool m1 = SPLITA && mirC && (t + 1 < g.ksplit), m2 = SPLITA && (last ? mirN : (mirC && (t + 2 < g.ksplit)));
;             const unsigned vo1[2] = {s2a ? voffA2[0] : m1 ? voffAm[0] : voffA[0], s2a ? voffA2[1] : m1 ? voffAm[1] : voffA[1]}, vo2[2] = {s2b ? voffA2[0] : m2 ? voffAm[0] : voffA[0], s2b ? voffA2[1] : m2 ? voffAm[1] : voffA[1]};
;             const char* a1h = m1 ? a1 - hstepA : a1 + hstepA; const char* a2h = m2 ? a2 - hstepA : a2 + hstepA;
;             PG8_LDB(B0, 0, 0); PG8_LDB(B1, 0, 1); PG8_SCHED; PG8_LDA(At, 0, 0); PG8_STAGE(PG8_SA(1, 1), a1h, vo1);
;             PG8_WAIT_V(8); PG8_WAIT_L(0); PG8_BAR; PG8_MMA(0, 0, At, B0); PG8_MMA(0, 1, At, B1); PG8_BAR; PG8_SCHED;
;             PG8_LDA(At, 0, 1); PG8_STAGE(PG8_SB(0, 0), b2, voffB); PG8_STAGE(PG8_SB(0, 1), b2 + hstepB, voffB); PG8_STAGE(PG8_SA(0, 0), a2, vo2);
;             PG8_WAIT_V(8); PG8_WAIT_L(0); PG8_BAR; PG8_MMA(1, 0, At, B0); PG8_MMA(1, 1, At, B1); PG8_BAR; PG8_SCHED;
.LBB0_866:
	s_ashr_i32 s17, s16, 31
	s_lshl_b64 s[12:13], s[16:17], 21
	s_add_u32 s20, s82, s12
	s_addc_u32 s21, s83, s13
	s_and_b64 s[12:13], s[0:1], exec
	s_cselect_b32 s17, s21, s27
	s_cselect_b32 s48, s20, s26
	s_ashr_i32 s19, s18, 31
	s_lshl_b64 s[12:13], s[18:19], 21
	s_add_u32 s22, s78, s12
	s_addc_u32 s23, s79, s13
	s_and_b64 s[12:13], s[0:1], exec
	s_cselect_b32 s19, s23, s29
	s_cselect_b32 s49, s22, s28
	s_add_u32 s50, s28, 0x100
	s_addc_u32 s51, s29, 0
	s_mov_b32 s28, -2
	s_movk_i32 s52, 0x1000
	s_cmp_lg_u32 s99, 0
	s_cbranch_scc0 .Lyd_p6
	s_barrier
	s_mov_b32 s99, 0
.Lyd_p6:
	s_add_i32 s53, s28, 2
	s_lshr_b32 s2, s53, 2
	s_lshl_b64 s[12:13], s[2:3], 17
	s_add_i32 s2, s52, 0xfffff000
	s_and_b32 s2, s2, 0x1000
	s_add_u32 s12, s26, s12
	s_addc_u32 s13, s27, s13
	s_add_u32 s29, s12, s2
	s_addc_u32 s30, s13, 0
	s_add_i32 s2, s28, 4
	ds_read_b128 v[140:143], v151
	ds_read_b128 v[144:147], v151 offset:1024
	ds_read_b128 v[154:157], v151 offset:2048
	ds_read_b128 v[158:161], v151 offset:3072
	ds_read_b128 v[162:165], v152
	ds_read_b128 v[166:169], v152 offset:1024
	ds_read_b128 v[170:173], v152 offset:2048
	ds_read_b128 v[174:177], v152 offset:3072
	s_lshr_b32 s2, s2, 2
	s_lshl_b64 s[12:13], s[2:3], 17
	s_and_b32 s2, s52, 0x1000
	s_add_u32 s12, s26, s12
	s_addc_u32 s13, s27, s13
	s_add_u32 s2, s12, s2
	s_addc_u32 s31, s13, 0
	s_add_u32 s12, s29, 0x10800
	s_addc_u32 s13, s30, 0
	s_cmp_eq_u32 s28, 60
	s_cselect_b32 s28, s49, s50
	s_cselect_b32 s31, s17, s31
	s_cselect_b32 s30, s48, s2
	s_cselect_b32 s29, s19, s51
	s_add_i32 m0, s25, 0xc000
	ds_read_b128 v[178:181], v153
	ds_read_b128 v[182:185], v153 offset:1024
	ds_read_b128 v[186:189], v153 offset:2048
	ds_read_b128 v[190:193], v153 offset:3072
	ds_read_b128 v[194:197], v153 offset:4096
	ds_read_b128 v[198:201], v153 offset:5120
	ds_read_b128 v[202:205], v153 offset:6144
	ds_read_b128 v[206:209], v153 offset:7168
	global_load_lds_dwordx4 v134, s[12:13]
	s_add_i32 m0, s25, 0xe000
	s_nop 0
	global_load_lds_dwordx4 v130, s[12:13]
	s_waitcnt vmcnt(8)
	s_waitcnt lgkmcnt(0)
	s_barrier
	s_setprio 1
	s_waitcnt lgkmcnt(0)
	v_mfma_f32_16x16x32_bf16 v[124:127], v[140:143], v[178:181], 0
	v_mfma_f32_16x16x32_bf16 v[120:123], v[154:157], v[178:181], 0
	v_mfma_f32_16x16x32_bf16 v[108:111], v[140:143], v[186:189], 0
	v_mfma_f32_16x16x32_bf16 v[104:107], v[154:157], v[186:189], 0
	v_mfma_f32_16x16x32_bf16 v[96:99], v[140:143], v[194:197], 0
	v_mfma_f32_16x16x32_bf16 v[88:91], v[154:157], v[194:197], 0
	v_mfma_f32_16x16x32_bf16 v[80:83], v[140:143], v[202:205], 0
	v_mfma_f32_16x16x32_bf16 v[72:75], v[154:157], v[202:205], 0
	v_mfma_f32_16x16x32_bf16 v[124:127], v[144:147], v[182:185], v[124:127]
	v_mfma_f32_16x16x32_bf16 v[120:123], v[158:161], v[182:185], v[120:123]
	v_mfma_f32_16x16x32_bf16 v[108:111], v[144:147], v[190:193], v[108:111]
	v_mfma_f32_16x16x32_bf16 v[104:107], v[158:161], v[190:193], v[104:107]
	v_mfma_f32_16x16x32_bf16 v[96:99], v[144:147], v[198:201], v[96:99]
	v_mfma_f32_16x16x32_bf16 v[88:91], v[158:161], v[198:201], v[88:91]
	v_mfma_f32_16x16x32_bf16 v[80:83], v[144:147], v[206:209], v[80:83]
	v_mfma_f32_16x16x32_bf16 v[72:75], v[158:161], v[206:209], v[72:75]
	s_setprio 0
	s_setprio 1
	v_mfma_f32_16x16x32_bf16 v[116:119], v[162:165], v[178:181], 0
	v_mfma_f32_16x16x32_bf16 v[112:115], v[170:173], v[178:181], 0
	v_mfma_f32_16x16x32_bf16 v[100:103], v[162:165], v[186:189], 0
	v_mfma_f32_16x16x32_bf16 v[92:95], v[170:173], v[186:189], 0
	v_mfma_f32_16x16x32_bf16 v[84:87], v[162:165], v[194:197], 0
	v_mfma_f32_16x16x32_bf16 v[76:79], v[170:173], v[194:197], 0
	v_mfma_f32_16x16x32_bf16 v[68:71], v[162:165], v[202:205], 0
	v_mfma_f32_16x16x32_bf16 v[64:67], v[170:173], v[202:205], 0
	v_mfma_f32_16x16x32_bf16 v[116:119], v[166:169], v[182:185], v[116:119]
	v_mfma_f32_16x16x32_bf16 v[112:115], v[174:177], v[182:185], v[112:115]
	v_mfma_f32_16x16x32_bf16 v[100:103], v[166:169], v[190:193], v[100:103]
	v_mfma_f32_16x16x32_bf16 v[92:95], v[174:177], v[190:193], v[92:95]
	v_mfma_f32_16x16x32_bf16 v[84:87], v[166:169], v[198:201], v[84:87]
	v_mfma_f32_16x16x32_bf16 v[76:79], v[174:177], v[198:201], v[76:79]
	v_mfma_f32_16x16x32_bf16 v[68:71], v[166:169], v[206:209], v[68:71]
	v_mfma_f32_16x16x32_bf16 v[64:67], v[174:177], v[206:209], v[64:67]
	s_setprio 0
	s_barrier
	s_add_u32 s98, s28, s6
	s_addc_u32 s99, s29, s7
	s_add_u32 s100, s30, s8
	s_addc_u32 s101, s31, s9
	s_add_i32 s2, s44, s33
	s_mov_b32 m0, s2
	ds_read_b128 v[178:181], v153 offset:16384
	ds_read_b128 v[182:185], v153 offset:17408
	ds_read_b128 v[186:189], v153 offset:18432
	ds_read_b128 v[190:193], v153 offset:19456
	ds_read_b128 v[194:197], v153 offset:20480
	ds_read_b128 v[198:201], v153 offset:21504
	ds_read_b128 v[202:205], v153 offset:22528
	ds_read_b128 v[206:209], v153 offset:23552
	global_load_lds_dwordx4 v132, s[28:29]
	s_add_i32 m0, s2, 0x2000
	s_add_u32 s12, s28, 0x100000
	s_addc_u32 s13, s29, 0
	s_add_i32 s2, s45, s33
	global_load_lds_dwordx4 v128, s[28:29]
	s_mov_b32 m0, s2
	s_nop 0
	global_load_lds_dwordx4 v132, s[12:13]
	s_add_i32 m0, s2, 0x2000
	s_nop 0
	global_load_lds_dwordx4 v128, s[12:13]
	s_mov_b32 m0, s25
	s_nop 0
	global_load_lds_dwordx4 v134, s[30:31]
	s_mov_b32 m0, s38
	s_nop 0
	global_load_lds_dwordx4 v130, s[30:31]
	s_waitcnt vmcnt(8)
	s_waitcnt lgkmcnt(0)
	s_barrier
; #define PG8_STAGE(bufoff, gbase, voff) do { _Pragma("unroll") for (int _i = 0; _i < 2; ++_i) \
;         __builtin_amdgcn_global_load_lds((const unsigned*)((const char*)(gbase) + (voff)[_i]), (LAS unsigned*)(lds + (bufoff) + ldsw + _i * 8192), 16, 0, 0); } while (0)
; #define PG8_LDA(dst, b, h) do { _Pragma("unroll") for (int m = 0; m < 4; ++m) _Pragma("unroll") for (int k = 0; k < 2; ++k) dst[m][k] = *(const LAS bf16x8*)(lds + PG8_SA(b, h) + aoff + m * 2048 + k * 1024); } while (0)
; #define PG8_LDB(dst, b, h) do { _Pragma("unroll") for (int n = 0; n < 2; ++n) _Pragma("unroll") for (int k = 0; k < 2; ++k) dst[n][k] = *(const LAS bf16x8*)(lds + PG8_SB(b, h) + boff + n * 2048 + k * 1024); } while (0)
; #define PG8_MMA(ai, bj, At, Bt) do { __builtin_amdgcn_s_setprio(1); _Pragma("unroll") for (int m = 0; m < 4; ++m) _Pragma("unroll") for (int n = 0; n < 2; ++n) _Pragma("unroll") for (int k = 0; k < 2; ++k) \
;         acc[ai][bj][m][n] = __builtin_amdgcn_mfma_f32_16x16x32_bf16(Bt[n][k], At[m][k], acc[ai][bj][m][n], 0, 0, 0); __builtin_amdgcn_s_setprio(0); } while (0)
; #define PG8_WAIT_V(n) asm volatile("s_waitcnt vmcnt(" #n ")" ::: "memory")
; #define PG8_WAIT_L(n) asm volatile("s_waitcnt lgkmcnt(" #n ")" ::: "memory")
; #define PG8_BAR __builtin_amdgcn_s_barrier()
; #define PG8_SCHED __builtin_amdgcn_sched_barrier(0)
; template <class Epi, bool ALIGN_EPI, bool SPLITA>
; __device__ __forceinline__ void gemm_phase(LAS unsigned char* lds, const Gemm g, const StaticOrder& S, const Epi& E) {
;     ...
;             PG8_WAIT_V(8); PG8_WAIT_L(0); PG8_BAR; PG8_MMA(1, 0, At, B0); PG8_MMA(1, 1, At, B1); PG8_BAR; PG8_SCHED;
;             PG8_LDB(B0, 1, 0); PG8_LDB(B1, 1, 1); PG8_SCHED; PG8_LDA(At, 1, 0); PG8_STAGE(PG8_SA(0, 1), a2h, vo2);
;             PG8_WAIT_V(8); PG8_WAIT_L(0); PG8_BAR; PG8_MMA(0, 0, At, B0); PG8_MMA(0, 1, At, B1); PG8_BAR; PG8_SCHED;
	s_setprio 1
	s_waitcnt lgkmcnt(0)
	v_mfma_f32_16x16x32_bf16 v[60:63], v[140:143], v[178:181], 0
	v_mfma_f32_16x16x32_bf16 v[56:59], v[154:157], v[178:181], 0
	v_mfma_f32_16x16x32_bf16 v[40:43], v[140:143], v[186:189], 0
	v_mfma_f32_16x16x32_bf16 v[32:35], v[154:157], v[186:189], 0
	v_mfma_f32_16x16x32_bf16 v[20:23], v[140:143], v[194:197], 0
	v_mfma_f32_16x16x32_bf16 v[8:11], v[154:157], v[194:197], 0
	v_mfma_f32_16x16x32_bf16 v[4:7], v[140:143], v[202:205], 0
	v_mfma_f32_16x16x32_bf16 v[0:3], v[154:157], v[202:205], 0
	v_mfma_f32_16x16x32_bf16 v[60:63], v[144:147], v[182:185], v[60:63]
	v_mfma_f32_16x16x32_bf16 v[56:59], v[158:161], v[182:185], v[56:59]
	v_mfma_f32_16x16x32_bf16 v[40:43], v[144:147], v[190:193], v[40:43]
	v_mfma_f32_16x16x32_bf16 v[32:35], v[158:161], v[190:193], v[32:35]
	v_mfma_f32_16x16x32_bf16 v[20:23], v[144:147], v[198:201], v[20:23]
	v_mfma_f32_16x16x32_bf16 v[8:11], v[158:161], v[198:201], v[8:11]
	v_mfma_f32_16x16x32_bf16 v[4:7], v[144:147], v[206:209], v[4:7]
	v_mfma_f32_16x16x32_bf16 v[0:3], v[158:161], v[206:209], v[0:3]
	s_setprio 0
	s_setprio 1
	v_mfma_f32_16x16x32_bf16 v[44:47], v[162:165], v[178:181], 0
	v_mfma_f32_16x16x32_bf16 v[36:39], v[170:173], v[178:181], 0
	v_mfma_f32_16x16x32_bf16 v[52:55], v[162:165], v[186:189], 0
	v_mfma_f32_16x16x32_bf16 v[48:51], v[170:173], v[186:189], 0
	v_mfma_f32_16x16x32_bf16 v[28:31], v[162:165], v[194:197], 0
	v_mfma_f32_16x16x32_bf16 v[24:27], v[170:173], v[194:197], 0
	v_mfma_f32_16x16x32_bf16 v[16:19], v[162:165], v[202:205], 0
	v_mfma_f32_16x16x32_bf16 v[12:15], v[170:173], v[202:205], 0
	v_mfma_f32_16x16x32_bf16 v[44:47], v[166:169], v[182:185], v[44:47]
	v_mfma_f32_16x16x32_bf16 v[36:39], v[174:177], v[182:185], v[36:39]
	v_mfma_f32_16x16x32_bf16 v[52:55], v[166:169], v[190:193], v[52:55]
	v_mfma_f32_16x16x32_bf16 v[48:51], v[174:177], v[190:193], v[48:51]
	v_mfma_f32_16x16x32_bf16 v[28:31], v[166:169], v[198:201], v[28:31]
	v_mfma_f32_16x16x32_bf16 v[24:27], v[174:177], v[198:201], v[24:27]
	v_mfma_f32_16x16x32_bf16 v[16:19], v[166:169], v[206:209], v[16:19]
	v_mfma_f32_16x16x32_bf16 v[12:15], v[174:177], v[206:209], v[12:15]
	s_setprio 0
	s_barrier
	s_add_i32 s2, 0, 0x18000
	s_add_i32 s54, 0, 0x1c000
	v_add_u32_e32 v158, s2, v149
	v_add_u32_e32 v174, s54, v149
	ds_read_b128 v[140:143], v158
	ds_read_b128 v[144:147], v158 offset:1024
	ds_read_b128 v[154:157], v158 offset:2048
	ds_read_b128 v[158:161], v158 offset:3072
	ds_read_b128 v[162:165], v174
	ds_read_b128 v[166:169], v174 offset:1024
	ds_read_b128 v[170:173], v174 offset:2048
	ds_read_b128 v[174:177], v174 offset:3072
	s_add_u32 s12, s30, 0x10000
	s_addc_u32 s13, s31, 0
	s_mov_b32 m0, s39
	ds_read_b128 v[178:181], v153 offset:32768
	ds_read_b128 v[182:185], v153 offset:33792
	ds_read_b128 v[186:189], v153 offset:34816
	ds_read_b128 v[190:193], v153 offset:35840
	ds_read_b128 v[194:197], v153 offset:36864
	ds_read_b128 v[198:201], v153 offset:37888
	ds_read_b128 v[202:205], v153 offset:38912
	ds_read_b128 v[206:209], v153 offset:39936
	global_load_lds_dwordx4 v134, s[12:13]
	s_mov_b32 m0, s40
	s_nop 0
	global_load_lds_dwordx4 v130, s[12:13]
	s_waitcnt vmcnt(8)
	s_waitcnt lgkmcnt(0)
	s_barrier
	s_setprio 1
	s_waitcnt lgkmcnt(0)
	v_mfma_f32_16x16x32_bf16 v[124:127], v[140:143], v[178:181], v[124:127]
	v_mfma_f32_16x16x32_bf16 v[120:123], v[154:157], v[178:181], v[120:123]
	v_mfma_f32_16x16x32_bf16 v[108:111], v[140:143], v[186:189], v[108:111]
	v_mfma_f32_16x16x32_bf16 v[104:107], v[154:157], v[186:189], v[104:107]
	v_mfma_f32_16x16x32_bf16 v[96:99], v[140:143], v[194:197], v[96:99]
	v_mfma_f32_16x16x32_bf16 v[88:91], v[154:157], v[194:197], v[88:91]
	v_mfma_f32_16x16x32_bf16 v[80:83], v[140:143], v[202:205], v[80:83]
	v_mfma_f32_16x16x32_bf16 v[72:75], v[154:157], v[202:205], v[72:75]
	v_mfma_f32_16x16x32_bf16 v[124:127], v[144:147], v[182:185], v[124:127]
	v_mfma_f32_16x16x32_bf16 v[120:123], v[158:161], v[182:185], v[120:123]
	v_mfma_f32_16x16x32_bf16 v[108:111], v[144:147], v[190:193], v[108:111]
	v_mfma_f32_16x16x32_bf16 v[104:107], v[158:161], v[190:193], v[104:107]
	v_mfma_f32_16x16x32_bf16 v[96:99], v[144:147], v[198:201], v[96:99]
	v_mfma_f32_16x16x32_bf16 v[88:91], v[158:161], v[198:201], v[88:91]
	v_mfma_f32_16x16x32_bf16 v[80:83], v[144:147], v[206:209], v[80:83]
	v_mfma_f32_16x16x32_bf16 v[72:75], v[158:161], v[206:209], v[72:75]
	s_setprio 0
	s_setprio 1
	v_mfma_f32_16x16x32_bf16 v[116:119], v[162:165], v[178:181], v[116:119]
	v_mfma_f32_16x16x32_bf16 v[112:115], v[170:173], v[178:181], v[112:115]
	v_mfma_f32_16x16x32_bf16 v[100:103], v[162:165], v[186:189], v[100:103]
	v_mfma_f32_16x16x32_bf16 v[92:95], v[170:173], v[186:189], v[92:95]
	v_mfma_f32_16x16x32_bf16 v[84:87], v[162:165], v[194:197], v[84:87]
	v_mfma_f32_16x16x32_bf16 v[76:79], v[170:173], v[194:197], v[76:79]
	v_mfma_f32_16x16x32_bf16 v[68:71], v[162:165], v[202:205], v[68:71]
	v_mfma_f32_16x16x32_bf16 v[64:67], v[170:173], v[202:205], v[64:67]
	v_mfma_f32_16x16x32_bf16 v[116:119], v[166:169], v[182:185], v[116:119]
	v_mfma_f32_16x16x32_bf16 v[112:115], v[174:177], v[182:185], v[112:115]
	v_mfma_f32_16x16x32_bf16 v[100:103], v[166:169], v[190:193], v[100:103]
	v_mfma_f32_16x16x32_bf16 v[92:95], v[174:177], v[190:193], v[92:95]
	v_mfma_f32_16x16x32_bf16 v[84:87], v[166:169], v[198:201], v[84:87]
	v_mfma_f32_16x16x32_bf16 v[76:79], v[174:177], v[198:201], v[76:79]
	v_mfma_f32_16x16x32_bf16 v[68:71], v[166:169], v[206:209], v[68:71]
	v_mfma_f32_16x16x32_bf16 v[64:67], v[174:177], v[206:209], v[64:67]
	s_setprio 0
	s_barrier
; #define PG8_STAGE(bufoff, gbase, voff) do { _Pragma("unroll") for (int _i = 0; _i < 2; ++_i) \
;         __builtin_amdgcn_global_load_lds((const unsigned*)((const char*)(gbase) + (voff)[_i]), (LAS unsigned*)(lds + (bufoff) + ldsw + _i * 8192), 16, 0, 0); } while (0)
; #define PG8_LDA(dst, b, h) do { _Pragma("unroll") for (int m = 0; m < 4; ++m) _Pragma("unroll") for (int k = 0; k < 2; ++k) dst[m][k] = *(const LAS bf16x8*)(lds + PG8_SA(b, h) + aoff + m * 2048 + k * 1024); } while (0)
; #define PG8_MMA(ai, bj, At, Bt) do { __builtin_amdgcn_s_setprio(1); _Pragma("unroll") for (int m = 0; m < 4; ++m) _Pragma("unroll") for (int n = 0; n < 2; ++n) _Pragma("unroll") for (int k = 0; k < 2; ++k) \
;         acc[ai][bj][m][n] = __builtin_amdgcn_mfma_f32_16x16x32_bf16(Bt[n][k], At[m][k], acc[ai][bj][m][n], 0, 0, 0); __builtin_amdgcn_s_setprio(0); } while (0)
; #define PG8_WAIT_V(n) asm volatile("s_waitcnt vmcnt(" #n ")" ::: "memory")
; #define PG8_WAIT_L(n) asm volatile("s_waitcnt lgkmcnt(" #n ")" ::: "memory")
; #define PG8_BAR __builtin_amdgcn_s_barrier()
; #define PG8_SCHED __builtin_amdgcn_sched_barrier(0)
; template <class Epi, bool ALIGN_EPI, bool SPLITA>
; __device__ __forceinline__ void gemm_phase(LAS unsigned char* lds, const Gemm g, const StaticOrder& S, const Epi& E) {
;     ...
;             PG8_LDA(At, 1, 1); PG8_STAGE(PG8_SB(1, 0), b3, voffB); PG8_STAGE(PG8_SB(1, 1), b3 + hstepB, voffB); PG8_STAGE(PG8_SA(1, 0), a3, vo2);
;             PG8_WAIT_V(8); PG8_WAIT_L(0); PG8_BAR; PG8_MMA(1, 0, At, B0); PG8_MMA(1, 1, At, B1); PG8_BAR; PG8_SCHED;
	s_add_i32 s2, s2, s33
	s_mov_b32 m0, s2
	ds_read_b128 v[178:181], v153 offset:49152
	ds_read_b128 v[182:185], v153 offset:50176
	ds_read_b128 v[186:189], v153 offset:51200
	ds_read_b128 v[190:193], v153 offset:52224
	ds_read_b128 v[194:197], v153 offset:53248
	ds_read_b128 v[198:201], v153 offset:54272
	ds_read_b128 v[202:205], v153 offset:55296
	ds_read_b128 v[206:209], v153 offset:56320
	global_load_lds_dwordx4 v132, s[98:99]
	s_add_i32 m0, s2, 0x2000
	s_add_u32 s12, s28, 0x100080
	s_addc_u32 s13, s29, 0
	s_add_i32 s2, s54, s33
	global_load_lds_dwordx4 v128, s[98:99]
	s_mov_b32 m0, s2
	s_nop 0
	global_load_lds_dwordx4 v132, s[12:13]
	s_add_i32 m0, s2, 0x2000
	s_nop 0
	global_load_lds_dwordx4 v128, s[12:13]
	s_mov_b32 m0, s41
	s_nop 0
	global_load_lds_dwordx4 v134, s[100:101]
	s_mov_b32 m0, s42
	s_nop 0
	global_load_lds_dwordx4 v130, s[100:101]
	s_waitcnt vmcnt(8)
	s_waitcnt lgkmcnt(0)
	s_barrier
	s_setprio 1
	s_waitcnt lgkmcnt(0)
	v_mfma_f32_16x16x32_bf16 v[60:63], v[140:143], v[178:181], v[60:63]
	v_mfma_f32_16x16x32_bf16 v[56:59], v[154:157], v[178:181], v[56:59]
	v_mfma_f32_16x16x32_bf16 v[40:43], v[140:143], v[186:189], v[40:43]
	v_mfma_f32_16x16x32_bf16 v[32:35], v[154:157], v[186:189], v[32:35]
	v_mfma_f32_16x16x32_bf16 v[20:23], v[140:143], v[194:197], v[20:23]
	v_mfma_f32_16x16x32_bf16 v[8:11], v[154:157], v[194:197], v[8:11]
	v_mfma_f32_16x16x32_bf16 v[4:7], v[140:143], v[202:205], v[4:7]
	v_mfma_f32_16x16x32_bf16 v[0:3], v[154:157], v[202:205], v[0:3]
	v_mfma_f32_16x16x32_bf16 v[60:63], v[144:147], v[182:185], v[60:63]
	v_mfma_f32_16x16x32_bf16 v[56:59], v[158:161], v[182:185], v[56:59]
	v_mfma_f32_16x16x32_bf16 v[40:43], v[144:147], v[190:193], v[40:43]
	v_mfma_f32_16x16x32_bf16 v[32:35], v[158:161], v[190:193], v[32:35]
	v_mfma_f32_16x16x32_bf16 v[20:23], v[144:147], v[198:201], v[20:23]
	v_mfma_f32_16x16x32_bf16 v[8:11], v[158:161], v[198:201], v[8:11]
	v_mfma_f32_16x16x32_bf16 v[4:7], v[144:147], v[206:209], v[4:7]
	v_mfma_f32_16x16x32_bf16 v[0:3], v[158:161], v[206:209], v[0:3]
	s_setprio 0
	s_setprio 1
	v_mfma_f32_16x16x32_bf16 v[44:47], v[162:165], v[178:181], v[44:47]
	v_mfma_f32_16x16x32_bf16 v[36:39], v[170:173], v[178:181], v[36:39]
	v_mfma_f32_16x16x32_bf16 v[52:55], v[162:165], v[186:189], v[52:55]
	v_mfma_f32_16x16x32_bf16 v[48:51], v[170:173], v[186:189], v[48:51]
	v_mfma_f32_16x16x32_bf16 v[28:31], v[162:165], v[194:197], v[28:31]
	v_mfma_f32_16x16x32_bf16 v[24:27], v[170:173], v[194:197], v[24:27]
	v_mfma_f32_16x16x32_bf16 v[16:19], v[162:165], v[202:205], v[16:19]
	v_mfma_f32_16x16x32_bf16 v[12:15], v[170:173], v[202:205], v[12:15]
	v_mfma_f32_16x16x32_bf16 v[44:47], v[166:169], v[182:185], v[44:47]
	v_mfma_f32_16x16x32_bf16 v[36:39], v[174:177], v[182:185], v[36:39]
	v_mfma_f32_16x16x32_bf16 v[52:55], v[166:169], v[190:193], v[52:55]
	v_mfma_f32_16x16x32_bf16 v[48:51], v[174:177], v[190:193], v[48:51]
	v_mfma_f32_16x16x32_bf16 v[28:31], v[166:169], v[198:201], v[28:31]
	v_mfma_f32_16x16x32_bf16 v[24:27], v[174:177], v[198:201], v[24:27]
	v_mfma_f32_16x16x32_bf16 v[16:19], v[166:169], v[206:209], v[16:19]
	v_mfma_f32_16x16x32_bf16 v[12:15], v[174:177], v[206:209], v[12:15]
	s_setprio 0
	s_barrier
	s_add_u32 s50, s50, 0x100
	s_addc_u32 s51, s51, 0
	s_addk_i32 s52, 0x1000
	s_mov_b32 s28, s53

; #define PG8_BAR __builtin_amdgcn_s_barrier()
; template <class Epi, bool ALIGN_EPI, bool SPLITA>
; __device__ __forceinline__ void gemm_phase(LAS unsigned char* lds, const Gemm g, const StaticOrder& S, const Epi& E) {
;     ...
;         if constexpr (ALIGN_EPI) { if (wr == 0) PG8_BAR; }
;     __device__ __forceinline__ void operator()(const Acc& acc, const Unit& u, int wr, int wc, int fr, int fq) const {
;         const int row0 = u.pm * BM + wr * 64 + fr, col0 = u.pn * BM + wc * 32 + 8 * fq;
; #pragma unroll
;         for (int ai = 0; ai < 2; ++ai) {
;             u32x4 xv[4][2];
; #pragma unroll
;             for (int m = 0; m < 4; ++m)
; #pragma unroll
;                 for (int bj = 0; bj < 2; ++bj) xv[m][bj] = *(const u32x4*)(X1B + (size_t)(row0 + ai * HALF + m * 16) * DM + col0 + bj * HALF);
; #pragma unroll
;             for (int m = 0; m < 4; ++m)
; #pragma unroll
;                 for (int bj = 0; bj < 2; ++bj) { float* rowp = out + (size_t)(row0 + ai * HALF + m * 16) * DM + col0 + bj * HALF; f32x4 a, b; unpack8(xv[m][bj], a, b);
;                     __builtin_nontemporal_store(a + acc[ai][bj][m][0], (f32x4*)(rowp)); __builtin_nontemporal_store(b + acc[ai][bj][m][1], (f32x4*)(rowp + 4)); }
;             asm volatile("" ::: "memory");
;         }
.LBB0_870:
	v_lshl_add_u32 v144, s24, 8, v148
	v_lshl_or_b32 v140, s47, 8, v150
	v_ashrrev_i32_e32 v141, 31, v140
	v_ashrrev_i32_e32 v145, 31, v144
	v_lshl_add_u64 v[142:143], v[140:141], 1, s[34:35]
	v_lshlrev_b64 v[146:147], 11, v[144:145]
	v_or_b32_e32 v174, 16, v144
	v_lshl_add_u64 v[146:147], v[142:143], 0, v[146:147]
	v_ashrrev_i32_e32 v175, 31, v174
	global_load_dwordx4 v[154:157], v[146:147], off
	global_load_dwordx4 v[158:161], v[146:147], off offset:256
	v_lshlrev_b64 v[146:147], 11, v[174:175]
	v_lshl_add_u64 v[146:147], v[142:143], 0, v[146:147]
	global_load_dwordx4 v[162:165], v[146:147], off
	global_load_dwordx4 v[166:169], v[146:147], off offset:256
	v_or_b32_e32 v186, 32, v144
	v_ashrrev_i32_e32 v187, 31, v186
	v_lshlrev_b64 v[146:147], 11, v[186:187]
	v_lshl_add_u64 v[176:177], v[142:143], 0, v[146:147]
	global_load_dwordx4 v[170:173], v[176:177], off
	v_lshlrev_b64 v[182:183], 12, v[174:175]
	global_load_dwordx4 v[174:177], v[176:177], off offset:256
	v_or_b32_e32 v146, 48, v144
	v_ashrrev_i32_e32 v147, 31, v146
	v_lshlrev_b64 v[178:179], 12, v[144:145]
	v_lshlrev_b64 v[180:181], 11, v[146:147]
	v_lshlrev_b64 v[140:141], 2, v[140:141]
	v_lshl_add_u64 v[178:179], s[58:59], 0, v[178:179]
	v_lshl_add_u64 v[184:185], v[142:143], 0, v[180:181]
	v_lshl_add_u64 v[188:189], v[178:179], 0, v[140:141]
	v_lshl_add_u64 v[190:191], s[58:59], 0, v[182:183]
	global_load_dwordx4 v[178:181], v[184:185], off
	s_nop 0
	global_load_dwordx4 v[182:185], v[184:185], off offset:256
	v_lshl_add_u64 v[190:191], v[190:191], 0, v[140:141]
	s_andn2_b64 vcc, exec, s[0:1]
	s_mov_b64 s[0:1], -1
	s_waitcnt vmcnt(0)
	s_cmp_lg_u64 s[10:11], 0
	s_cbranch_scc0 .Lxs_p6_0
	s_barrier
.Lxs_p6_0:
	v_lshlrev_b32_e32 v192, 16, v154
	v_and_b32_e32 v193, 0xffff0000, v154
	v_lshlrev_b32_e32 v154, 16, v155
	v_and_b32_e32 v155, 0xffff0000, v155
	v_lshlrev_b32_e32 v194, 16, v156
	v_and_b32_e32 v195, 0xffff0000, v156
	v_lshlrev_b32_e32 v156, 16, v157
	v_and_b32_e32 v157, 0xffff0000, v157
	v_lshlrev_b32_e32 v196, 16, v158
	v_and_b32_e32 v197, 0xffff0000, v158
	v_lshlrev_b32_e32 v158, 16, v159
	v_and_b32_e32 v159, 0xffff0000, v159
	v_lshlrev_b32_e32 v198, 16, v160
	v_and_b32_e32 v199, 0xffff0000, v160
	v_lshlrev_b32_e32 v160, 16, v161
	v_and_b32_e32 v161, 0xffff0000, v161
	v_pk_add_f32 v[126:127], v[126:127], v[154:155]
	v_pk_add_f32 v[122:123], v[122:123], v[156:157]
	v_pk_add_f32 v[118:119], v[118:119], v[158:159]
	v_pk_add_f32 v[114:115], v[114:115], v[160:161]
	v_lshlrev_b32_e32 v154, 16, v162
	v_and_b32_e32 v155, 0xffff0000, v162
	v_lshlrev_b32_e32 v156, 16, v163
	v_and_b32_e32 v157, 0xffff0000, v163
	v_lshlrev_b32_e32 v158, 16, v164
	v_and_b32_e32 v159, 0xffff0000, v164
	v_lshlrev_b32_e32 v160, 16, v165
	v_and_b32_e32 v161, 0xffff0000, v165
	v_lshlrev_b32_e32 v162, 16, v166
	v_and_b32_e32 v163, 0xffff0000, v166
	v_lshlrev_b32_e32 v164, 16, v167
	v_and_b32_e32 v165, 0xffff0000, v167
	v_lshlrev_b32_e32 v166, 16, v168
	v_and_b32_e32 v167, 0xffff0000, v168
	v_lshlrev_b32_e32 v168, 16, v169
	v_and_b32_e32 v169, 0xffff0000, v169
	v_pk_add_f32 v[124:125], v[124:125], v[192:193]
	v_pk_add_f32 v[110:111], v[110:111], v[156:157]
	v_pk_add_f32 v[108:109], v[108:109], v[154:155]
	v_pk_add_f32 v[94:95], v[94:95], v[168:169]
	v_pk_add_f32 v[92:93], v[92:93], v[166:167]
	v_pk_add_f32 v[120:121], v[120:121], v[194:195]
	v_pk_add_f32 v[116:117], v[116:117], v[196:197]
	v_pk_add_f32 v[112:113], v[112:113], v[198:199]
	global_store_dwordx4 v[188:189], v[124:127], off nt
	global_store_dwordx4 v[188:189], v[120:123], off offset:16 nt
	global_store_dwordx4 v[188:189], v[116:119], off offset:512 nt
	global_store_dwordx4 v[188:189], v[112:115], off offset:528 nt
	v_pk_add_f32 v[106:107], v[106:107], v[160:161]
	v_pk_add_f32 v[104:105], v[104:105], v[158:159]
	v_pk_add_f32 v[102:103], v[102:103], v[164:165]
	v_pk_add_f32 v[100:101], v[100:101], v[162:163]
	global_store_dwordx4 v[190:191], v[108:111], off nt
	global_store_dwordx4 v[190:191], v[104:107], off offset:16 nt
	global_store_dwordx4 v[190:191], v[100:103], off offset:512 nt
	global_store_dwordx4 v[190:191], v[92:95], off offset:528 nt
	v_lshlrev_b32_e32 v104, 16, v173
	v_lshlrev_b32_e32 v102, 16, v172
	v_lshlrev_b64 v[92:93], 12, v[186:187]
	v_lshl_add_u64 v[92:93], s[58:59], 0, v[92:93]
	v_lshl_add_u64 v[100:101], v[92:93], 0, v[140:141]
	v_lshlrev_b32_e32 v92, 16, v170
	v_and_b32_e32 v93, 0xffff0000, v170
	v_lshlrev_b32_e32 v94, 16, v171
	v_and_b32_e32 v95, 0xffff0000, v171
	v_pk_add_f32 v[94:95], v[98:99], v[94:95]
	v_pk_add_f32 v[92:93], v[96:97], v[92:93]
	v_and_b32_e32 v103, 0xffff0000, v172
	v_and_b32_e32 v105, 0xffff0000, v173
	global_store_dwordx4 v[100:101], v[92:95], off nt
	v_pk_add_f32 v[90:91], v[90:91], v[104:105]
	v_pk_add_f32 v[88:89], v[88:89], v[102:103]
	v_lshlrev_b32_e32 v92, 16, v176
	v_and_b32_e32 v93, 0xffff0000, v176
	v_lshlrev_b32_e32 v94, 16, v177
	v_and_b32_e32 v95, 0xffff0000, v177
	v_pk_add_f32 v[78:79], v[78:79], v[94:95]
	v_pk_add_f32 v[76:77], v[76:77], v[92:93]
	global_store_dwordx4 v[100:101], v[88:91], off offset:16 nt
	global_store_dwordx4 v[100:101], v[76:79], off offset:528 nt
	v_add_u32_e32 v96, 0x80, v144
	v_lshlrev_b32_e32 v88, 16, v174
	v_and_b32_e32 v89, 0xffff0000, v174
	v_lshlrev_b32_e32 v90, 16, v175
	v_and_b32_e32 v91, 0xffff0000, v175
	v_lshlrev_b64 v[76:77], 12, v[146:147]
	v_pk_add_f32 v[86:87], v[86:87], v[90:91]
	v_pk_add_f32 v[84:85], v[84:85], v[88:89]
	v_lshl_add_u64 v[76:77], s[58:59], 0, v[76:77]
	global_store_dwordx4 v[100:101], v[84:87], off offset:512 nt
	v_lshlrev_b32_e32 v78, 16, v179
	v_and_b32_e32 v79, 0xffff0000, v179
	v_lshl_add_u64 v[84:85], v[76:77], 0, v[140:141]
;     __device__ __forceinline__ void operator()(const Acc& acc, const Unit& u, int wr, int wc, int fr, int fq) const {
;     ...
;             for (int m = 0; m < 4; ++m)
; #pragma unroll
;                 for (int bj = 0; bj < 2; ++bj) xv[m][bj] = *(const u32x4*)(X1B + (size_t)(row0 + ai * HALF + m * 16) * DM + col0 + bj * HALF);
; #pragma unroll
;             for (int m = 0; m < 4; ++m)
; #pragma unroll
;                 for (int bj = 0; bj < 2; ++bj) { float* rowp = out + (size_t)(row0 + ai * HALF + m * 16) * DM + col0 + bj * HALF; f32x4 a, b; unpack8(xv[m][bj], a, b);
;                     __builtin_nontemporal_store(a + acc[ai][bj][m][0], (f32x4*)(rowp)); __builtin_nontemporal_store(b + acc[ai][bj][m][1], (f32x4*)(rowp + 4)); }
	v_lshlrev_b32_e32 v76, 16, v178
	v_and_b32_e32 v77, 0xffff0000, v178
	v_lshlrev_b32_e32 v86, 16, v180
	v_and_b32_e32 v87, 0xffff0000, v180
	v_lshlrev_b32_e32 v88, 16, v181
	v_and_b32_e32 v89, 0xffff0000, v181
	v_pk_add_f32 v[78:79], v[82:83], v[78:79]
	v_pk_add_f32 v[76:77], v[80:81], v[76:77]
	v_pk_add_f32 v[74:75], v[74:75], v[88:89]
	v_pk_add_f32 v[72:73], v[72:73], v[86:87]
	global_store_dwordx4 v[84:85], v[76:79], off nt
	global_store_dwordx4 v[84:85], v[72:75], off offset:16 nt
	v_ashrrev_i32_e32 v97, 31, v96
	v_lshlrev_b32_e32 v76, 16, v184
	v_lshlrev_b32_e32 v72, 16, v182
	v_and_b32_e32 v73, 0xffff0000, v182
	v_lshlrev_b32_e32 v74, 16, v183
	v_and_b32_e32 v75, 0xffff0000, v183
	v_and_b32_e32 v77, 0xffff0000, v184
	v_lshlrev_b32_e32 v78, 16, v185
	v_and_b32_e32 v79, 0xffff0000, v185
	v_pk_add_f32 v[70:71], v[70:71], v[74:75]
	v_pk_add_f32 v[68:69], v[68:69], v[72:73]
	v_pk_add_f32 v[66:67], v[66:67], v[78:79]
	v_pk_add_f32 v[64:65], v[64:65], v[76:77]
	global_store_dwordx4 v[84:85], v[68:71], off offset:512 nt
	global_store_dwordx4 v[84:85], v[64:67], off offset:528 nt
	v_add_u32_e32 v98, 0x90, v144
	v_ashrrev_i32_e32 v99, 31, v98
	v_lshlrev_b64 v[64:65], 11, v[96:97]
	v_lshl_add_u64 v[64:65], v[142:143], 0, v[64:65]
	global_load_dwordx4 v[68:71], v[64:65], off
	global_load_dwordx4 v[72:75], v[64:65], off offset:256
	v_lshlrev_b64 v[64:65], 11, v[98:99]
	v_lshl_add_u64 v[64:65], v[142:143], 0, v[64:65]
	global_load_dwordx4 v[76:79], v[64:65], off
	global_load_dwordx4 v[80:83], v[64:65], off offset:256
	v_add_u32_e32 v100, 0xa0, v144
	v_ashrrev_i32_e32 v101, 31, v100
	v_lshlrev_b64 v[64:65], 11, v[100:101]
	v_lshl_add_u64 v[64:65], v[142:143], 0, v[64:65]
	global_load_dwordx4 v[84:87], v[64:65], off
	global_load_dwordx4 v[88:91], v[64:65], off offset:256
	v_add_u32_e32 v102, 0xb0, v144
	v_ashrrev_i32_e32 v103, 31, v102
	v_lshlrev_b64 v[64:65], 11, v[102:103]
	v_lshl_add_u64 v[104:105], v[142:143], 0, v[64:65]
	global_load_dwordx4 v[92:95], v[104:105], off
	global_load_dwordx4 v[64:67], v[104:105], off offset:256
	v_lshlrev_b64 v[96:97], 12, v[96:97]
	v_lshl_add_u64 v[96:97], s[58:59], 0, v[96:97]
	v_lshl_add_u64 v[96:97], v[96:97], 0, v[140:141]
	s_waitcnt vmcnt(7)
	v_lshlrev_b32_e32 v104, 16, v68
	v_and_b32_e32 v105, 0xffff0000, v68
	v_lshlrev_b32_e32 v68, 16, v69
	v_and_b32_e32 v69, 0xffff0000, v69
	v_lshlrev_b32_e32 v106, 16, v70
	v_and_b32_e32 v107, 0xffff0000, v70
	v_lshlrev_b32_e32 v70, 16, v71
	v_and_b32_e32 v71, 0xffff0000, v71
	v_pk_add_f32 v[62:63], v[62:63], v[68:69]
	v_pk_add_f32 v[60:61], v[60:61], v[104:105]
	global_store_dwordx4 v[96:97], v[60:63], off nt
	v_pk_add_f32 v[58:59], v[58:59], v[70:71]
	v_pk_add_f32 v[56:57], v[56:57], v[106:107]
	s_waitcnt vmcnt(7)
	v_lshlrev_b32_e32 v60, 16, v74
	v_and_b32_e32 v61, 0xffff0000, v74
	v_lshlrev_b32_e32 v62, 16, v75
	v_and_b32_e32 v63, 0xffff0000, v75
	global_store_dwordx4 v[96:97], v[56:59], off offset:16 nt
	v_pk_add_f32 v[38:39], v[38:39], v[62:63]
	v_pk_add_f32 v[36:37], v[36:37], v[60:61]
	v_lshlrev_b32_e32 v56, 16, v72
	v_and_b32_e32 v57, 0xffff0000, v72
	v_lshlrev_b32_e32 v58, 16, v73
	v_and_b32_e32 v59, 0xffff0000, v73
	v_pk_add_f32 v[46:47], v[46:47], v[58:59]
	v_pk_add_f32 v[44:45], v[44:45], v[56:57]
	global_store_dwordx4 v[96:97], v[36:39], off offset:528 nt
	global_store_dwordx4 v[96:97], v[44:47], off offset:512 nt
	s_waitcnt vmcnt(9)
; #define PG8_BAR __builtin_amdgcn_s_barrier()
; template <class Epi, bool ALIGN_EPI, bool SPLITA>
; __device__ __forceinline__ void gemm_phase(LAS unsigned char* lds, const Gemm g, const StaticOrder& S, const Epi& E) {
;     ...
;         if (!has_next) break;
; #pragma unroll
;         for (int a = 0; a < 2; ++a)
; #pragma unroll
;             for (int b = 0; b < 2; ++b)
; #pragma unroll
;                 for (int m = 0; m < 4; ++m)
; #pragma unroll
;                     for (int n = 0; n < 2; ++n) acc[a][b][m][n] = (f32x4){0.f, 0.f, 0.f, 0.f};
;         cur = nxt; cA = nA; cB = nB; mirC = mirN; if constexpr (SPLITA) cA2 = (const char*)g.A2 + (size_t)cur.pm * tstepA; ++ui;
;         if constexpr (ALIGN_EPI) { if (wr == 1) PG8_BAR; }
;     __device__ __forceinline__ void operator()(const Acc& acc, const Unit& u, int wr, int wc, int fr, int fq) const {
;     ...
;             for (int m = 0; m < 4; ++m)
; #pragma unroll
;                 for (int bj = 0; bj < 2; ++bj) { float* rowp = out + (size_t)(row0 + ai * HALF + m * 16) * DM + col0 + bj * HALF; f32x4 a, b; unpack8(xv[m][bj], a, b);
;                     __builtin_nontemporal_store(a + acc[ai][bj][m][0], (f32x4*)(rowp)); __builtin_nontemporal_store(b + acc[ai][bj][m][1], (f32x4*)(rowp + 4)); }
;             asm volatile("" ::: "memory");
	v_lshlrev_b32_e32 v56, 16, v79
	v_lshlrev_b64 v[36:37], 12, v[98:99]
	v_lshl_add_u64 v[36:37], s[58:59], 0, v[36:37]
	v_lshlrev_b32_e32 v46, 16, v78
	v_and_b32_e32 v47, 0xffff0000, v78
	v_and_b32_e32 v57, 0xffff0000, v79
	v_lshl_add_u64 v[44:45], v[36:37], 0, v[140:141]
	v_lshlrev_b32_e32 v36, 16, v76
	v_and_b32_e32 v37, 0xffff0000, v76
	v_lshlrev_b32_e32 v38, 16, v77
	v_and_b32_e32 v39, 0xffff0000, v77
	v_pk_add_f32 v[34:35], v[34:35], v[56:57]
	v_pk_add_f32 v[32:33], v[32:33], v[46:47]
	v_pk_add_f32 v[38:39], v[42:43], v[38:39]
	v_pk_add_f32 v[36:37], v[40:41], v[36:37]
	global_store_dwordx4 v[44:45], v[32:35], off offset:16 nt
	global_store_dwordx4 v[44:45], v[36:39], off nt
	s_waitcnt vmcnt(9)
	v_lshlrev_b32_e32 v40, 16, v87
	v_lshlrev_b32_e32 v32, 16, v80
	v_and_b32_e32 v33, 0xffff0000, v80
	v_lshlrev_b32_e32 v34, 16, v81
	v_and_b32_e32 v35, 0xffff0000, v81
	v_lshlrev_b32_e32 v36, 16, v82
	v_and_b32_e32 v37, 0xffff0000, v82
	v_lshlrev_b32_e32 v38, 16, v83
	v_and_b32_e32 v39, 0xffff0000, v83
	v_pk_add_f32 v[34:35], v[54:55], v[34:35]
	v_pk_add_f32 v[32:33], v[52:53], v[32:33]
	global_store_dwordx4 v[44:45], v[32:35], off offset:512 nt
	v_and_b32_e32 v41, 0xffff0000, v87
	v_pk_add_f32 v[10:11], v[10:11], v[40:41]
	v_pk_add_f32 v[34:35], v[50:51], v[38:39]
	v_pk_add_f32 v[32:33], v[48:49], v[36:37]
	global_store_dwordx4 v[44:45], v[32:35], off offset:528 nt
	v_lshlrev_b32_e32 v38, 16, v86
	v_and_b32_e32 v39, 0xffff0000, v86
	v_lshlrev_b64 v[32:33], 12, v[100:101]
	v_lshl_add_u64 v[32:33], s[58:59], 0, v[32:33]
	v_lshl_add_u64 v[32:33], v[32:33], 0, v[140:141]
	v_lshlrev_b32_e32 v34, 16, v84
	v_and_b32_e32 v35, 0xffff0000, v84
	v_lshlrev_b32_e32 v36, 16, v85
	v_and_b32_e32 v37, 0xffff0000, v85
	v_pk_add_f32 v[8:9], v[8:9], v[38:39]
	v_pk_add_f32 v[22:23], v[22:23], v[36:37]
	v_pk_add_f32 v[20:21], v[20:21], v[34:35]
	global_store_dwordx4 v[32:33], v[8:11], off offset:16 nt
	global_store_dwordx4 v[32:33], v[20:23], off nt
	s_waitcnt vmcnt(12)
	v_lshlrev_b32_e32 v8, 16, v88
	v_and_b32_e32 v9, 0xffff0000, v88
	v_lshlrev_b32_e32 v10, 16, v89
	v_and_b32_e32 v11, 0xffff0000, v89
	v_lshlrev_b32_e32 v20, 16, v90
	v_and_b32_e32 v21, 0xffff0000, v90
	v_lshlrev_b32_e32 v22, 16, v91
	v_and_b32_e32 v23, 0xffff0000, v91
	v_pk_add_f32 v[10:11], v[30:31], v[10:11]
	v_pk_add_f32 v[8:9], v[28:29], v[8:9]
	global_store_dwordx4 v[32:33], v[8:11], off offset:512 nt
	s_nop 1
	v_pk_add_f32 v[10:11], v[26:27], v[22:23]
	v_pk_add_f32 v[8:9], v[24:25], v[20:21]
	global_store_dwordx4 v[32:33], v[8:11], off offset:528 nt
	s_waitcnt vmcnt(13)
	v_lshlrev_b32_e32 v22, 16, v94
	v_and_b32_e32 v23, 0xffff0000, v94
	v_lshlrev_b64 v[8:9], 12, v[102:103]
	v_lshl_add_u64 v[8:9], s[58:59], 0, v[8:9]
	v_lshlrev_b32_e32 v24, 16, v95
	v_and_b32_e32 v25, 0xffff0000, v95
	v_lshl_add_u64 v[8:9], v[8:9], 0, v[140:141]
	v_lshlrev_b32_e32 v10, 16, v92
	v_and_b32_e32 v11, 0xffff0000, v92
	v_lshlrev_b32_e32 v20, 16, v93
	v_and_b32_e32 v21, 0xffff0000, v93
	v_pk_add_f32 v[2:3], v[2:3], v[24:25]
	v_pk_add_f32 v[0:1], v[0:1], v[22:23]
	v_pk_add_f32 v[6:7], v[6:7], v[20:21]
	v_pk_add_f32 v[4:5], v[4:5], v[10:11]
	global_store_dwordx4 v[8:9], v[0:3], off offset:16 nt
	global_store_dwordx4 v[8:9], v[4:7], off nt
	s_waitcnt vmcnt(14)
	v_lshlrev_b32_e32 v0, 16, v64
	v_and_b32_e32 v1, 0xffff0000, v64
	v_lshlrev_b32_e32 v2, 16, v65
	v_and_b32_e32 v3, 0xffff0000, v65
	v_lshlrev_b32_e32 v4, 16, v66
	v_and_b32_e32 v5, 0xffff0000, v66
	v_lshlrev_b32_e32 v6, 16, v67
	v_and_b32_e32 v7, 0xffff0000, v67
	v_pk_add_f32 v[2:3], v[18:19], v[2:3]
	v_pk_add_f32 v[0:1], v[16:17], v[0:1]
	global_store_dwordx4 v[8:9], v[0:3], off offset:512 nt
	s_nop 1
	v_pk_add_f32 v[2:3], v[14:15], v[6:7]
	v_pk_add_f32 v[0:1], v[12:13], v[4:5]
	global_store_dwordx4 v[8:9], v[0:3], off offset:528 nt
	s_cbranch_vccnz .LBB0_863
	s_mov_b32 s99, 0
	s_andn2_b64 vcc, exec, s[4:5]
	s_cbranch_vccnz .LBB0_862
	s_mov_b32 s99, 1
	s_branch .LBB0_862
